# stack: P6 Q and KNT fragment loads batched/prefetched; int8 GEMM epilogues (P1,P12,P4) issue the 8 row-scale loads and column-scale loads together instead of serially
# speedup vs baseline: 1.0029x; 1.0012x over previous
.LBB0_119:
	v_lshl_add_u32 v154, s50, 8, v167
	v_lshl_add_u64 v[50:51], v[154:155], 2, s[30:31]
	global_load_dword v200, v[50:51], off
	v_or_b32_e32 v198, 16, v154
	v_mov_b32_e32 v199, v155
	v_or_b32_e32 v194, 32, v154
	v_mov_b32_e32 v195, v155
	v_or_b32_e32 v190, 48, v154
	v_mov_b32_e32 v191, v155
	v_add_u32_e32 v186, 0x80, v154
	v_mov_b32_e32 v187, v155
	v_add_u32_e32 v182, 0x90, v154
	v_mov_b32_e32 v183, v155
	v_add_u32_e32 v178, 0xa0, v154
	v_mov_b32_e32 v179, v155
	v_add_u32_e32 v168, 0xb0, v154
	v_mov_b32_e32 v169, v155
	s_lshl_b32 s34, s27, 8
	s_ashr_i32 s35, s34, 31
	v_lshl_add_u64 v[142:143], s[34:35], 2, v[156:157]
	v_lshl_add_u64 v[50:51], v[198:199], 2, s[30:31]
	global_load_dword v196, v[50:51], off
	v_lshl_add_u64 v[50:51], v[194:195], 2, s[30:31]
	global_load_dword v192, v[50:51], off
	v_lshl_add_u64 v[50:51], v[190:191], 2, s[30:31]
	global_load_dword v188, v[50:51], off
	v_lshl_add_u64 v[50:51], v[186:187], 2, s[30:31]
	global_load_dword v184, v[50:51], off
	v_lshl_add_u64 v[50:51], v[182:183], 2, s[30:31]
	global_load_dword v180, v[50:51], off
	v_lshl_add_u64 v[50:51], v[178:179], 2, s[30:31]
	global_load_dword v172, v[50:51], off
	v_lshl_add_u64 v[50:51], v[168:169], 2, s[30:31]
	global_load_dword v166, v[50:51], off
	global_load_dwordx4 v[50:53], v[142:143], off offset:16
	global_load_dwordx4 v[54:57], v[142:143], off
	global_load_dwordx4 v[138:141], v[142:143], off offset:528
	s_nop 0
	global_load_dwordx4 v[142:145], v[142:143], off offset:512
	v_cvt_f32_i32_e32 v175, v134
	v_cvt_f32_i32_e32 v174, v126
	v_cvt_f32_i32_e32 v209, v130
	v_cvt_f32_i32_e32 v208, v122
	v_cvt_f32_i32_e32 v135, v135
	v_cvt_f32_i32_e32 v134, v127
	v_cvt_f32_i32_e32 v131, v131
	v_cvt_f32_i32_e32 v130, v123
	v_mov_b64_e32 v[176:177], s[28:29]
	v_mad_u64_u32 v[204:205], s[34:35], v154, s26, v[176:177]
	v_lshl_or_b32 v202, s27, 7, v181
	v_ashrrev_i32_e32 v203, 31, v202
	v_cvt_f32_i32_e32 v119, v119
	v_cvt_f32_i32_e32 v115, v115
	v_cvt_f32_i32_e32 v103, v103
	v_cvt_f32_i32_e32 v99, v99
	v_cvt_f32_i32_e32 v87, v87
	v_cvt_f32_i32_e32 v83, v83
	v_cvt_f32_i32_e32 v71, v71
	v_cvt_f32_i32_e32 v67, v67
	v_cvt_f32_i32_e32 v47, v47
	v_cvt_f32_i32_e32 v43, v43
	v_cvt_f32_i32_e32 v31, v31
	v_cvt_f32_i32_e32 v27, v27
	v_cvt_f32_i32_e32 v15, v15
	v_cvt_f32_i32_e32 v11, v11
	s_mov_b64 s[50:51], -1
	s_andn2_b64 vcc, exec, s[0:1]
	s_waitcnt vmcnt(4)
	s_nop 0
	s_nop 0
	s_nop 0
	s_nop 0
	s_nop 0
	s_nop 0
	s_nop 0
	v_mul_f32_e32 v200, 0x3c010204, v200
	v_mul_f32_e32 v196, 0x3c010204, v196
	v_mul_f32_e32 v192, 0x3c010204, v192
	v_mul_f32_e32 v188, 0x3c010204, v188
	v_mul_f32_e32 v184, 0x3c010204, v184
	v_mul_f32_e32 v180, 0x3c010204, v180
	v_mul_f32_e32 v172, 0x3c010204, v172
	v_mul_f32_e32 v166, 0x3c010204, v166
	s_waitcnt vmcnt(2)
	v_mov_b32_e32 v171, v54
	s_waitcnt vmcnt(0)
	v_mov_b32_e32 v170, v142
	v_pk_mul_f32 v[206:207], v[200:201], v[170:171] op_sel_hi:[0,1]
	v_pk_mul_f32 v[206:207], v[206:207], v[174:175]
	v_mov_b32_e32 v175, v50
	v_mul_f32_e32 v50, 0xbfb8aa3b, v207
	v_exp_f32_e32 v50, v50
	v_mov_b32_e32 v174, v138
	v_pk_mul_f32 v[210:211], v[200:201], v[174:175] op_sel_hi:[0,1]
	v_pk_mul_f32 v[208:209], v[210:211], v[208:209]
	v_add_f32_e32 v50, 1.0, v50
	v_rcp_f32_e32 v50, v50
	v_mov_b32_e32 v54, v143
	v_pk_mul_f32 v[126:127], v[200:201], v[54:55] op_sel_hi:[0,1]
	v_pk_mul_f32 v[126:127], v[126:127], v[134:135]
	v_mul_f32_e32 v50, v207, v50
	v_mul_f32_e32 v142, v206, v50
	v_mul_f32_e32 v50, 0xbfb8aa3b, v209
	v_exp_f32_e32 v50, v50
	v_cvt_f32_i32_e32 v135, v132
	v_cvt_f32_i32_e32 v134, v124
	v_add_f32_e32 v50, 1.0, v50
	v_rcp_f32_e32 v50, v50
	s_nop 0
	v_mul_f32_e32 v50, v209, v50
	v_mul_f32_e32 v154, v208, v50
	v_mov_b32_e32 v50, v139
	v_pk_mul_f32 v[122:123], v[200:201], v[50:51] op_sel_hi:[0,1]
	v_pk_mul_f32 v[122:123], v[122:123], v[130:131]
	v_mul_f32_e32 v130, 0xbfb8aa3b, v127
	v_exp_f32_e32 v130, v130
	s_nop 0
	v_add_f32_e32 v130, 1.0, v130
	v_rcp_f32_e32 v130, v130
	s_nop 0
	v_mul_f32_e32 v127, v127, v130
	v_mul_f32_e32 v143, v126, v127
	v_mul_f32_e32 v126, 0xbfb8aa3b, v123
	v_exp_f32_e32 v126, v126
	v_cvt_f32_i32_e32 v127, v136
	v_add_f32_e32 v126, 1.0, v126
	v_rcp_f32_e32 v126, v126
	s_nop 0
	v_mul_f32_e32 v123, v123, v126
	v_cvt_f32_i32_e32 v126, v128
	v_mul_f32_e32 v169, v122, v123
	v_mov_b32_e32 v122, v144
	v_mov_b32_e32 v123, v56
	v_pk_mul_f32 v[130:131], v[200:201], v[122:123] op_sel_hi:[0,1]
	v_pk_mul_f32 v[130:131], v[130:131], v[126:127]
	v_mov_b32_e32 v127, v52
	v_mul_f32_e32 v52, 0xbfb8aa3b, v131
	v_exp_f32_e32 v52, v52
	v_mov_b32_e32 v126, v140
	v_pk_mul_f32 v[138:139], v[200:201], v[126:127] op_sel_hi:[0,1]
	v_pk_mul_f32 v[134:135], v[138:139], v[134:135]
	v_add_f32_e32 v52, 1.0, v52
	v_rcp_f32_e32 v52, v52
	v_mov_b32_e32 v56, v145
	v_mul_f32_e32 v52, v131, v52
	v_mul_f32_e32 v136, v130, v52
	v_mul_f32_e32 v52, 0xbfb8aa3b, v135
	v_exp_f32_e32 v52, v52
	v_cvt_f32_i32_e32 v131, v137
	v_cvt_f32_i32_e32 v130, v129
	v_pk_mul_f32 v[128:129], v[200:201], v[56:57] op_sel_hi:[0,1]
	v_add_f32_e32 v52, 1.0, v52
	v_rcp_f32_e32 v52, v52
	v_pk_mul_f32 v[128:129], v[128:129], v[130:131]
	v_cvt_f32_i32_e32 v131, v133
	v_cvt_f32_i32_e32 v130, v125
	v_mul_f32_e32 v52, v135, v52
	v_mul_f32_e32 v134, v134, v52
	v_mov_b32_e32 v52, v141
	v_pk_mul_f32 v[124:125], v[200:201], v[52:53] op_sel_hi:[0,1]
	v_pk_mul_f32 v[124:125], v[124:125], v[130:131]
	v_mul_f32_e32 v130, 0xbfb8aa3b, v129
	v_exp_f32_e32 v130, v130
	s_nop 0
	v_add_f32_e32 v130, 1.0, v130
	v_rcp_f32_e32 v130, v130
	s_nop 0
	v_mul_f32_e32 v129, v129, v130
	v_mul_f32_e32 v129, v128, v129
	v_mul_f32_e32 v128, 0xbfb8aa3b, v125
	v_exp_f32_e32 v128, v128
	s_nop 0
	v_add_f32_e32 v128, 1.0, v128
	v_rcp_f32_e32 v128, v128
	s_nop 0
	v_mul_f32_e32 v125, v125, v128
	v_mul_f32_e32 v131, v124, v125
	v_lshlrev_b64 v[124:125], 1, v[202:203]
	v_lshl_add_u64 v[132:133], v[204:205], 0, v[124:125]
	v_cvt_pk_bf16_f32 v128, v142, v143
	v_cvt_pk_bf16_f32 v129, v136, v129
	v_cvt_pk_bf16_f32 v130, v154, v169
	v_cvt_pk_bf16_f32 v131, v134, v131
	global_store_dwordx4 v[132:133], v[128:131], off
	v_pk_mul_f32 v[132:133], v[196:197], v[170:171] op_sel_hi:[0,1]
	v_pk_mul_f32 v[134:135], v[196:197], v[174:175] op_sel_hi:[0,1]
	v_cvt_f32_i32_e32 v131, v118
	v_cvt_f32_i32_e32 v130, v110
	v_cvt_f32_i32_e32 v118, v111
	v_pk_mul_f32 v[110:111], v[196:197], v[54:55] op_sel_hi:[0,1]
	v_mad_u64_u32 v[128:129], s[34:35], v198, s26, v[176:177]
	v_pk_mul_f32 v[130:131], v[132:133], v[130:131]
	v_cvt_f32_i32_e32 v132, v106
	v_mul_f32_e32 v106, 0xbfb8aa3b, v131
	v_exp_f32_e32 v106, v106
	v_cvt_f32_i32_e32 v133, v114
	v_cvt_f32_i32_e32 v114, v107
	v_pk_mul_f32 v[110:111], v[110:111], v[118:119]
	v_add_f32_e32 v106, 1.0, v106
	v_rcp_f32_e32 v106, v106
	v_pk_mul_f32 v[132:133], v[134:135], v[132:133]
	v_mul_f32_e32 v106, v131, v106
	v_mul_f32_e32 v130, v130, v106
	v_mul_f32_e32 v106, 0xbfb8aa3b, v133
	v_exp_f32_e32 v106, v106
	s_nop 0
	v_add_f32_e32 v106, 1.0, v106
	v_rcp_f32_e32 v106, v106
	s_nop 0
	v_mul_f32_e32 v106, v133, v106
	v_mul_f32_e32 v131, v132, v106
	v_pk_mul_f32 v[106:107], v[196:197], v[50:51] op_sel_hi:[0,1]
	v_pk_mul_f32 v[106:107], v[106:107], v[114:115]
	v_mul_f32_e32 v114, 0xbfb8aa3b, v111
	v_exp_f32_e32 v114, v114
	s_nop 0
	v_add_f32_e32 v114, 1.0, v114
	v_rcp_f32_e32 v114, v114
	s_nop 0
	v_mul_f32_e32 v111, v111, v114
	v_mul_f32_e32 v118, v110, v111
	v_mul_f32_e32 v110, 0xbfb8aa3b, v107
	v_exp_f32_e32 v110, v110
	v_pk_mul_f32 v[114:115], v[196:197], v[126:127] op_sel_hi:[0,1]
	v_add_f32_e32 v110, 1.0, v110
	v_rcp_f32_e32 v110, v110
	s_nop 0
	v_mul_f32_e32 v107, v107, v110
	v_mul_f32_e32 v119, v106, v107
	v_cvt_f32_i32_e32 v107, v120
	v_cvt_f32_i32_e32 v106, v112
	v_pk_mul_f32 v[110:111], v[196:197], v[122:123] op_sel_hi:[0,1]
	v_pk_mul_f32 v[106:107], v[110:111], v[106:107]
	v_cvt_f32_i32_e32 v110, v108
	v_mul_f32_e32 v108, 0xbfb8aa3b, v107
	v_exp_f32_e32 v108, v108
	v_cvt_f32_i32_e32 v111, v116
	v_add_f32_e32 v108, 1.0, v108
	v_rcp_f32_e32 v108, v108
	v_pk_mul_f32 v[110:111], v[114:115], v[110:111]
	v_mul_f32_e32 v107, v107, v108
	v_mul_f32_e32 v112, v106, v107
	v_mul_f32_e32 v106, 0xbfb8aa3b, v111
	v_exp_f32_e32 v106, v106
	v_cvt_f32_i32_e32 v107, v121
	v_add_f32_e32 v106, 1.0, v106
	v_rcp_f32_e32 v106, v106
	s_nop 0
	v_mul_f32_e32 v106, v111, v106
	v_mul_f32_e32 v114, v110, v106
	v_cvt_f32_i32_e32 v106, v113
	v_pk_mul_f32 v[110:111], v[196:197], v[56:57] op_sel_hi:[0,1]
	v_pk_mul_f32 v[106:107], v[110:111], v[106:107]
	v_cvt_f32_i32_e32 v111, v117
	v_cvt_f32_i32_e32 v110, v109
	v_pk_mul_f32 v[108:109], v[196:197], v[52:53] op_sel_hi:[0,1]
	v_pk_mul_f32 v[108:109], v[108:109], v[110:111]
	v_mul_f32_e32 v110, 0xbfb8aa3b, v107
	v_exp_f32_e32 v110, v110
	s_nop 0
	v_add_f32_e32 v110, 1.0, v110
	v_rcp_f32_e32 v110, v110
	s_nop 0
	v_mul_f32_e32 v107, v107, v110
	v_mul_f32_e32 v107, v106, v107
	v_mul_f32_e32 v106, 0xbfb8aa3b, v109
	v_exp_f32_e32 v106, v106
	v_lshl_add_u64 v[110:111], v[128:129], 0, v[124:125]
	v_add_f32_e32 v106, 1.0, v106
	v_rcp_f32_e32 v106, v106
	s_nop 0
	v_mul_f32_e32 v106, v109, v106
	v_mul_f32_e32 v109, v108, v106
	v_cvt_pk_bf16_f32 v106, v130, v118
	v_cvt_pk_bf16_f32 v107, v112, v107
	v_cvt_pk_bf16_f32 v108, v131, v119
	v_cvt_pk_bf16_f32 v109, v114, v109
	global_store_dwordx4 v[110:111], v[106:109], off
	v_pk_mul_f32 v[110:111], v[192:193], v[170:171] op_sel_hi:[0,1]
	v_pk_mul_f32 v[112:113], v[192:193], v[174:175] op_sel_hi:[0,1]
	v_cvt_f32_i32_e32 v109, v102
	v_cvt_f32_i32_e32 v108, v94
	v_cvt_f32_i32_e32 v102, v95
	v_pk_mul_f32 v[94:95], v[192:193], v[54:55] op_sel_hi:[0,1]
	v_mad_u64_u32 v[106:107], s[34:35], v194, s26, v[176:177]
	v_pk_mul_f32 v[108:109], v[110:111], v[108:109]
	v_cvt_f32_i32_e32 v110, v90
	v_mul_f32_e32 v90, 0xbfb8aa3b, v109
	v_exp_f32_e32 v90, v90
	v_cvt_f32_i32_e32 v111, v98
	v_cvt_f32_i32_e32 v98, v91
	v_pk_mul_f32 v[94:95], v[94:95], v[102:103]
	v_add_f32_e32 v90, 1.0, v90
	v_rcp_f32_e32 v90, v90
	v_pk_mul_f32 v[110:111], v[112:113], v[110:111]
	v_mul_f32_e32 v90, v109, v90
	v_mul_f32_e32 v108, v108, v90
	v_mul_f32_e32 v90, 0xbfb8aa3b, v111
	v_exp_f32_e32 v90, v90
	s_nop 0
	v_add_f32_e32 v90, 1.0, v90
	v_rcp_f32_e32 v90, v90
	s_nop 0
	v_mul_f32_e32 v90, v111, v90
	v_mul_f32_e32 v109, v110, v90
	v_pk_mul_f32 v[90:91], v[192:193], v[50:51] op_sel_hi:[0,1]
	v_pk_mul_f32 v[90:91], v[90:91], v[98:99]
	v_mul_f32_e32 v98, 0xbfb8aa3b, v95
	v_exp_f32_e32 v98, v98
	s_nop 0
	v_add_f32_e32 v98, 1.0, v98
	v_rcp_f32_e32 v98, v98
	s_nop 0
	v_mul_f32_e32 v95, v95, v98
	v_mul_f32_e32 v102, v94, v95
	v_mul_f32_e32 v94, 0xbfb8aa3b, v91
	v_exp_f32_e32 v94, v94
	v_pk_mul_f32 v[98:99], v[192:193], v[126:127] op_sel_hi:[0,1]
	v_add_f32_e32 v94, 1.0, v94
	v_rcp_f32_e32 v94, v94
	s_nop 0
	v_mul_f32_e32 v91, v91, v94
	v_mul_f32_e32 v103, v90, v91
	v_cvt_f32_i32_e32 v91, v104
	v_cvt_f32_i32_e32 v90, v96
	v_pk_mul_f32 v[94:95], v[192:193], v[122:123] op_sel_hi:[0,1]
	v_pk_mul_f32 v[90:91], v[94:95], v[90:91]
	v_cvt_f32_i32_e32 v94, v92
	v_mul_f32_e32 v92, 0xbfb8aa3b, v91
	v_exp_f32_e32 v92, v92
	v_cvt_f32_i32_e32 v95, v100
	v_add_f32_e32 v92, 1.0, v92
	v_rcp_f32_e32 v92, v92
	v_pk_mul_f32 v[94:95], v[98:99], v[94:95]
	v_mul_f32_e32 v91, v91, v92
	v_mul_f32_e32 v96, v90, v91
	v_mul_f32_e32 v90, 0xbfb8aa3b, v95
	v_exp_f32_e32 v90, v90
	v_cvt_f32_i32_e32 v91, v105
	v_add_f32_e32 v90, 1.0, v90
	v_rcp_f32_e32 v90, v90
	s_nop 0
	v_mul_f32_e32 v90, v95, v90
	v_mul_f32_e32 v98, v94, v90
	v_cvt_f32_i32_e32 v90, v97
	v_pk_mul_f32 v[94:95], v[192:193], v[56:57] op_sel_hi:[0,1]
	v_pk_mul_f32 v[90:91], v[94:95], v[90:91]
	v_cvt_f32_i32_e32 v95, v101
	v_cvt_f32_i32_e32 v94, v93
	v_pk_mul_f32 v[92:93], v[192:193], v[52:53] op_sel_hi:[0,1]
	v_pk_mul_f32 v[92:93], v[92:93], v[94:95]
	v_mul_f32_e32 v94, 0xbfb8aa3b, v91
	v_exp_f32_e32 v94, v94
	s_nop 0
	v_add_f32_e32 v94, 1.0, v94
	v_rcp_f32_e32 v94, v94
	s_nop 0
	v_mul_f32_e32 v91, v91, v94
	v_mul_f32_e32 v91, v90, v91
	v_mul_f32_e32 v90, 0xbfb8aa3b, v93
	v_exp_f32_e32 v90, v90
	v_lshl_add_u64 v[94:95], v[106:107], 0, v[124:125]
	v_add_f32_e32 v90, 1.0, v90
	v_rcp_f32_e32 v90, v90
	s_nop 0
	v_mul_f32_e32 v90, v93, v90
	v_mul_f32_e32 v93, v92, v90
	v_cvt_pk_bf16_f32 v90, v108, v102
	v_cvt_pk_bf16_f32 v91, v96, v91
	v_cvt_pk_bf16_f32 v92, v109, v103
	v_cvt_pk_bf16_f32 v93, v98, v93
	global_store_dwordx4 v[94:95], v[90:93], off
	v_pk_mul_f32 v[94:95], v[188:189], v[170:171] op_sel_hi:[0,1]
	v_pk_mul_f32 v[96:97], v[188:189], v[174:175] op_sel_hi:[0,1]
	v_cvt_f32_i32_e32 v93, v86
	v_cvt_f32_i32_e32 v92, v78
	v_cvt_f32_i32_e32 v86, v79
	v_pk_mul_f32 v[78:79], v[188:189], v[54:55] op_sel_hi:[0,1]
	v_mad_u64_u32 v[90:91], s[34:35], v190, s26, v[176:177]
	v_pk_mul_f32 v[92:93], v[94:95], v[92:93]
	v_cvt_f32_i32_e32 v94, v74
	v_mul_f32_e32 v74, 0xbfb8aa3b, v93
	v_exp_f32_e32 v74, v74
	v_cvt_f32_i32_e32 v95, v82
	v_cvt_f32_i32_e32 v82, v75
	v_pk_mul_f32 v[78:79], v[78:79], v[86:87]
	v_add_f32_e32 v74, 1.0, v74
	v_rcp_f32_e32 v74, v74
	v_pk_mul_f32 v[94:95], v[96:97], v[94:95]
	v_mul_f32_e32 v74, v93, v74
	v_mul_f32_e32 v92, v92, v74
	v_mul_f32_e32 v74, 0xbfb8aa3b, v95
	v_exp_f32_e32 v74, v74
	s_nop 0
	v_add_f32_e32 v74, 1.0, v74
	v_rcp_f32_e32 v74, v74
	s_nop 0
	v_mul_f32_e32 v74, v95, v74
	v_mul_f32_e32 v93, v94, v74
	v_pk_mul_f32 v[74:75], v[188:189], v[50:51] op_sel_hi:[0,1]
	v_pk_mul_f32 v[74:75], v[74:75], v[82:83]
	v_mul_f32_e32 v82, 0xbfb8aa3b, v79
	v_exp_f32_e32 v82, v82
	s_nop 0
	v_add_f32_e32 v82, 1.0, v82
	v_rcp_f32_e32 v82, v82
	s_nop 0
	v_mul_f32_e32 v79, v79, v82
	v_mul_f32_e32 v86, v78, v79
	v_mul_f32_e32 v78, 0xbfb8aa3b, v75
	v_exp_f32_e32 v78, v78
	v_pk_mul_f32 v[82:83], v[188:189], v[126:127] op_sel_hi:[0,1]
	v_add_f32_e32 v78, 1.0, v78
	v_rcp_f32_e32 v78, v78
	s_nop 0
	v_mul_f32_e32 v75, v75, v78
	v_mul_f32_e32 v87, v74, v75
	v_cvt_f32_i32_e32 v75, v88
	v_cvt_f32_i32_e32 v74, v80
	v_pk_mul_f32 v[78:79], v[188:189], v[122:123] op_sel_hi:[0,1]
	v_pk_mul_f32 v[74:75], v[78:79], v[74:75]
	v_cvt_f32_i32_e32 v78, v76
	v_mul_f32_e32 v76, 0xbfb8aa3b, v75
	v_exp_f32_e32 v76, v76
	v_cvt_f32_i32_e32 v79, v84
	v_add_f32_e32 v76, 1.0, v76
	v_rcp_f32_e32 v76, v76
	v_pk_mul_f32 v[78:79], v[82:83], v[78:79]
	v_mul_f32_e32 v75, v75, v76
	v_mul_f32_e32 v80, v74, v75
	v_mul_f32_e32 v74, 0xbfb8aa3b, v79
	v_exp_f32_e32 v74, v74
	v_cvt_f32_i32_e32 v75, v89
	v_add_f32_e32 v74, 1.0, v74
	v_rcp_f32_e32 v74, v74
	s_nop 0
	v_mul_f32_e32 v74, v79, v74
	v_mul_f32_e32 v82, v78, v74
	v_cvt_f32_i32_e32 v74, v81
	v_pk_mul_f32 v[78:79], v[188:189], v[56:57] op_sel_hi:[0,1]
	v_pk_mul_f32 v[74:75], v[78:79], v[74:75]
	v_cvt_f32_i32_e32 v79, v85
	v_cvt_f32_i32_e32 v78, v77
	v_pk_mul_f32 v[76:77], v[188:189], v[52:53] op_sel_hi:[0,1]
	v_pk_mul_f32 v[76:77], v[76:77], v[78:79]
	v_mul_f32_e32 v78, 0xbfb8aa3b, v75
	v_exp_f32_e32 v78, v78
	s_nop 0
	v_add_f32_e32 v78, 1.0, v78
	v_rcp_f32_e32 v78, v78
	s_nop 0
	v_mul_f32_e32 v75, v75, v78
	v_mul_f32_e32 v75, v74, v75
	v_mul_f32_e32 v74, 0xbfb8aa3b, v77
	v_exp_f32_e32 v74, v74
	v_lshl_add_u64 v[78:79], v[90:91], 0, v[124:125]
	v_add_f32_e32 v74, 1.0, v74
	v_rcp_f32_e32 v74, v74
	s_nop 0
	v_mul_f32_e32 v74, v77, v74
	v_mul_f32_e32 v77, v76, v74
	v_cvt_pk_bf16_f32 v74, v92, v86
	v_cvt_pk_bf16_f32 v75, v80, v75
	v_cvt_pk_bf16_f32 v76, v93, v87
	v_cvt_pk_bf16_f32 v77, v82, v77
	global_store_dwordx4 v[78:79], v[74:77], off
	v_pk_mul_f32 v[78:79], v[184:185], v[170:171] op_sel_hi:[0,1]
	v_pk_mul_f32 v[80:81], v[184:185], v[174:175] op_sel_hi:[0,1]
	v_cvt_f32_i32_e32 v77, v70
	v_cvt_f32_i32_e32 v76, v62
	v_cvt_f32_i32_e32 v70, v63
	v_pk_mul_f32 v[62:63], v[184:185], v[54:55] op_sel_hi:[0,1]
	v_mad_u64_u32 v[74:75], s[34:35], v186, s26, v[176:177]
	v_pk_mul_f32 v[76:77], v[78:79], v[76:77]
	v_cvt_f32_i32_e32 v78, v58
	v_mul_f32_e32 v58, 0xbfb8aa3b, v77
	v_exp_f32_e32 v58, v58
	v_cvt_f32_i32_e32 v79, v66
	v_cvt_f32_i32_e32 v66, v59
	v_pk_mul_f32 v[62:63], v[62:63], v[70:71]
	v_add_f32_e32 v58, 1.0, v58
	v_rcp_f32_e32 v58, v58
	v_pk_mul_f32 v[78:79], v[80:81], v[78:79]
	v_mul_f32_e32 v58, v77, v58
	v_mul_f32_e32 v76, v76, v58
	v_mul_f32_e32 v58, 0xbfb8aa3b, v79
	v_exp_f32_e32 v58, v58
	s_nop 0
	v_add_f32_e32 v58, 1.0, v58
	v_rcp_f32_e32 v58, v58
	s_nop 0
	v_mul_f32_e32 v58, v79, v58
	v_mul_f32_e32 v77, v78, v58
	v_pk_mul_f32 v[58:59], v[184:185], v[50:51] op_sel_hi:[0,1]
	v_pk_mul_f32 v[58:59], v[58:59], v[66:67]
	v_mul_f32_e32 v66, 0xbfb8aa3b, v63
	v_exp_f32_e32 v66, v66
	s_nop 0
	v_add_f32_e32 v66, 1.0, v66
	v_rcp_f32_e32 v66, v66
	s_nop 0
	v_mul_f32_e32 v63, v63, v66
	v_mul_f32_e32 v70, v62, v63
	v_mul_f32_e32 v62, 0xbfb8aa3b, v59
	v_exp_f32_e32 v62, v62
	v_pk_mul_f32 v[66:67], v[184:185], v[126:127] op_sel_hi:[0,1]
	v_add_f32_e32 v62, 1.0, v62
	v_rcp_f32_e32 v62, v62
	s_nop 0
	v_mul_f32_e32 v59, v59, v62
	v_mul_f32_e32 v71, v58, v59
	v_cvt_f32_i32_e32 v59, v72
	v_cvt_f32_i32_e32 v58, v64
	v_pk_mul_f32 v[62:63], v[184:185], v[122:123] op_sel_hi:[0,1]
	v_pk_mul_f32 v[58:59], v[62:63], v[58:59]
	v_cvt_f32_i32_e32 v62, v60
	v_mul_f32_e32 v60, 0xbfb8aa3b, v59
	v_exp_f32_e32 v60, v60
	v_cvt_f32_i32_e32 v63, v68
	v_add_f32_e32 v60, 1.0, v60
	v_rcp_f32_e32 v60, v60
	v_pk_mul_f32 v[62:63], v[66:67], v[62:63]
	v_mul_f32_e32 v59, v59, v60
	v_mul_f32_e32 v64, v58, v59
	v_mul_f32_e32 v58, 0xbfb8aa3b, v63
	v_exp_f32_e32 v58, v58
	v_cvt_f32_i32_e32 v59, v73
	v_add_f32_e32 v58, 1.0, v58
	v_rcp_f32_e32 v58, v58
	s_nop 0
	v_mul_f32_e32 v58, v63, v58
	v_mul_f32_e32 v66, v62, v58
	v_cvt_f32_i32_e32 v58, v65
	v_pk_mul_f32 v[62:63], v[184:185], v[56:57] op_sel_hi:[0,1]
	v_pk_mul_f32 v[58:59], v[62:63], v[58:59]
	v_cvt_f32_i32_e32 v63, v69
	v_cvt_f32_i32_e32 v62, v61
	v_pk_mul_f32 v[60:61], v[184:185], v[52:53] op_sel_hi:[0,1]
	v_pk_mul_f32 v[60:61], v[60:61], v[62:63]
	v_mul_f32_e32 v62, 0xbfb8aa3b, v59
	v_exp_f32_e32 v62, v62
	s_nop 0
	v_add_f32_e32 v62, 1.0, v62
	v_rcp_f32_e32 v62, v62
	s_nop 0
	v_mul_f32_e32 v59, v59, v62
	v_mul_f32_e32 v59, v58, v59
	v_mul_f32_e32 v58, 0xbfb8aa3b, v61
	v_exp_f32_e32 v58, v58
	v_lshl_add_u64 v[62:63], v[74:75], 0, v[124:125]
	v_add_f32_e32 v58, 1.0, v58
	v_rcp_f32_e32 v58, v58
	s_nop 0
	v_mul_f32_e32 v58, v61, v58
	v_mul_f32_e32 v61, v60, v58
	v_cvt_pk_bf16_f32 v58, v76, v70
	v_cvt_pk_bf16_f32 v59, v64, v59
	v_cvt_pk_bf16_f32 v60, v77, v71
	v_cvt_pk_bf16_f32 v61, v66, v61
	global_store_dwordx4 v[62:63], v[58:61], off
	v_pk_mul_f32 v[62:63], v[180:181], v[170:171] op_sel_hi:[0,1]
	v_pk_mul_f32 v[64:65], v[180:181], v[174:175] op_sel_hi:[0,1]
	v_cvt_f32_i32_e32 v61, v46
	v_cvt_f32_i32_e32 v60, v38
	v_cvt_f32_i32_e32 v46, v39
	v_pk_mul_f32 v[38:39], v[180:181], v[54:55] op_sel_hi:[0,1]
	v_mad_u64_u32 v[58:59], s[34:35], v182, s26, v[176:177]
	v_pk_mul_f32 v[60:61], v[62:63], v[60:61]
	v_cvt_f32_i32_e32 v62, v34
	v_mul_f32_e32 v34, 0xbfb8aa3b, v61
	v_exp_f32_e32 v34, v34
	v_cvt_f32_i32_e32 v63, v42
	v_cvt_f32_i32_e32 v42, v35
	v_pk_mul_f32 v[38:39], v[38:39], v[46:47]
	v_add_f32_e32 v34, 1.0, v34
	v_rcp_f32_e32 v34, v34
	v_pk_mul_f32 v[62:63], v[64:65], v[62:63]
	v_mul_f32_e32 v34, v61, v34
	v_mul_f32_e32 v60, v60, v34
	v_mul_f32_e32 v34, 0xbfb8aa3b, v63
	v_exp_f32_e32 v34, v34
	s_nop 0
	v_add_f32_e32 v34, 1.0, v34
	v_rcp_f32_e32 v34, v34
	s_nop 0
	v_mul_f32_e32 v34, v63, v34
	v_mul_f32_e32 v61, v62, v34
	v_pk_mul_f32 v[34:35], v[180:181], v[50:51] op_sel_hi:[0,1]
	v_pk_mul_f32 v[34:35], v[34:35], v[42:43]
	v_mul_f32_e32 v42, 0xbfb8aa3b, v39
	v_exp_f32_e32 v42, v42
	s_nop 0
	v_add_f32_e32 v42, 1.0, v42
	v_rcp_f32_e32 v42, v42
	s_nop 0
	v_mul_f32_e32 v39, v39, v42
	v_mul_f32_e32 v46, v38, v39
	v_mul_f32_e32 v38, 0xbfb8aa3b, v35
	v_exp_f32_e32 v38, v38
	v_pk_mul_f32 v[42:43], v[180:181], v[126:127] op_sel_hi:[0,1]
	v_add_f32_e32 v38, 1.0, v38
	v_rcp_f32_e32 v38, v38
	s_nop 0
	v_mul_f32_e32 v35, v35, v38
	v_mul_f32_e32 v47, v34, v35
	v_cvt_f32_i32_e32 v35, v48
	v_cvt_f32_i32_e32 v34, v40
	v_pk_mul_f32 v[38:39], v[180:181], v[122:123] op_sel_hi:[0,1]
	v_pk_mul_f32 v[34:35], v[38:39], v[34:35]
	v_cvt_f32_i32_e32 v38, v36
	v_mul_f32_e32 v36, 0xbfb8aa3b, v35
	v_exp_f32_e32 v36, v36
	v_cvt_f32_i32_e32 v39, v44
	v_add_f32_e32 v36, 1.0, v36
	v_rcp_f32_e32 v36, v36
	v_pk_mul_f32 v[38:39], v[42:43], v[38:39]
	v_mul_f32_e32 v35, v35, v36
	v_mul_f32_e32 v40, v34, v35
	v_mul_f32_e32 v34, 0xbfb8aa3b, v39
	v_exp_f32_e32 v34, v34
	v_cvt_f32_i32_e32 v35, v49
	v_add_f32_e32 v34, 1.0, v34
	v_rcp_f32_e32 v34, v34
	s_nop 0
	v_mul_f32_e32 v34, v39, v34
	v_mul_f32_e32 v42, v38, v34
	v_cvt_f32_i32_e32 v34, v41
	v_pk_mul_f32 v[38:39], v[180:181], v[56:57] op_sel_hi:[0,1]
	v_pk_mul_f32 v[34:35], v[38:39], v[34:35]
	v_cvt_f32_i32_e32 v39, v45
	v_cvt_f32_i32_e32 v38, v37
	v_pk_mul_f32 v[36:37], v[180:181], v[52:53] op_sel_hi:[0,1]
	v_pk_mul_f32 v[36:37], v[36:37], v[38:39]
	v_mul_f32_e32 v38, 0xbfb8aa3b, v35
	v_exp_f32_e32 v38, v38
	s_nop 0
	v_add_f32_e32 v38, 1.0, v38
	v_rcp_f32_e32 v38, v38
	s_nop 0
	v_mul_f32_e32 v35, v35, v38
	v_mul_f32_e32 v35, v34, v35
	v_mul_f32_e32 v34, 0xbfb8aa3b, v37
	v_exp_f32_e32 v34, v34
	v_lshl_add_u64 v[38:39], v[58:59], 0, v[124:125]
	v_add_f32_e32 v34, 1.0, v34
	v_rcp_f32_e32 v34, v34
	s_nop 0
	v_mul_f32_e32 v34, v37, v34
	v_mul_f32_e32 v37, v36, v34
	v_cvt_pk_bf16_f32 v34, v60, v46
	v_cvt_pk_bf16_f32 v35, v40, v35
	v_cvt_pk_bf16_f32 v36, v61, v47
	v_cvt_pk_bf16_f32 v37, v42, v37
	global_store_dwordx4 v[38:39], v[34:37], off
	v_pk_mul_f32 v[38:39], v[172:173], v[170:171] op_sel_hi:[0,1]
	v_pk_mul_f32 v[40:41], v[172:173], v[174:175] op_sel_hi:[0,1]
	v_cvt_f32_i32_e32 v37, v30
	v_cvt_f32_i32_e32 v36, v22
	v_cvt_f32_i32_e32 v30, v23
	v_pk_mul_f32 v[22:23], v[172:173], v[54:55] op_sel_hi:[0,1]
	v_mad_u64_u32 v[34:35], s[34:35], v178, s26, v[176:177]
	v_pk_mul_f32 v[36:37], v[38:39], v[36:37]
	v_cvt_f32_i32_e32 v38, v18
	v_mul_f32_e32 v18, 0xbfb8aa3b, v37
	v_exp_f32_e32 v18, v18
	v_cvt_f32_i32_e32 v39, v26
	v_cvt_f32_i32_e32 v26, v19
	v_pk_mul_f32 v[22:23], v[22:23], v[30:31]
	v_add_f32_e32 v18, 1.0, v18
	v_rcp_f32_e32 v18, v18
	v_pk_mul_f32 v[38:39], v[40:41], v[38:39]
	v_mul_f32_e32 v18, v37, v18
	v_mul_f32_e32 v36, v36, v18
	v_mul_f32_e32 v18, 0xbfb8aa3b, v39
	v_exp_f32_e32 v18, v18
	s_nop 0
	v_add_f32_e32 v18, 1.0, v18
	v_rcp_f32_e32 v18, v18
	s_nop 0
	v_mul_f32_e32 v18, v39, v18
	v_mul_f32_e32 v37, v38, v18
	v_pk_mul_f32 v[18:19], v[172:173], v[50:51] op_sel_hi:[0,1]
	v_pk_mul_f32 v[18:19], v[18:19], v[26:27]
	v_mul_f32_e32 v26, 0xbfb8aa3b, v23
	v_exp_f32_e32 v26, v26
	s_nop 0
	v_add_f32_e32 v26, 1.0, v26
	v_rcp_f32_e32 v26, v26
	s_nop 0
	v_mul_f32_e32 v23, v23, v26
	v_mul_f32_e32 v30, v22, v23
	v_mul_f32_e32 v22, 0xbfb8aa3b, v19
	v_exp_f32_e32 v22, v22
	v_pk_mul_f32 v[26:27], v[172:173], v[126:127] op_sel_hi:[0,1]
	v_add_f32_e32 v22, 1.0, v22
	v_rcp_f32_e32 v22, v22
	s_nop 0
	v_mul_f32_e32 v19, v19, v22
	v_mul_f32_e32 v31, v18, v19
	v_cvt_f32_i32_e32 v19, v32
	v_cvt_f32_i32_e32 v18, v24
	v_pk_mul_f32 v[22:23], v[172:173], v[122:123] op_sel_hi:[0,1]
	v_pk_mul_f32 v[18:19], v[22:23], v[18:19]
	v_cvt_f32_i32_e32 v22, v20
	v_mul_f32_e32 v20, 0xbfb8aa3b, v19
	v_exp_f32_e32 v20, v20
	v_cvt_f32_i32_e32 v23, v28
	v_add_f32_e32 v20, 1.0, v20
	v_rcp_f32_e32 v20, v20
	v_pk_mul_f32 v[22:23], v[26:27], v[22:23]
	v_mul_f32_e32 v19, v19, v20
	v_mul_f32_e32 v24, v18, v19
	v_mul_f32_e32 v18, 0xbfb8aa3b, v23
	v_exp_f32_e32 v18, v18
	v_cvt_f32_i32_e32 v19, v33
	v_add_f32_e32 v18, 1.0, v18
	v_rcp_f32_e32 v18, v18
	s_nop 0
	v_mul_f32_e32 v18, v23, v18
	v_mul_f32_e32 v26, v22, v18
	v_cvt_f32_i32_e32 v18, v25
	v_pk_mul_f32 v[22:23], v[172:173], v[56:57] op_sel_hi:[0,1]
	v_pk_mul_f32 v[18:19], v[22:23], v[18:19]
	v_cvt_f32_i32_e32 v23, v29
	v_cvt_f32_i32_e32 v22, v21
	v_pk_mul_f32 v[20:21], v[172:173], v[52:53] op_sel_hi:[0,1]
	v_pk_mul_f32 v[20:21], v[20:21], v[22:23]
	v_mul_f32_e32 v22, 0xbfb8aa3b, v19
	v_exp_f32_e32 v22, v22
	s_nop 0
	v_add_f32_e32 v22, 1.0, v22
	v_rcp_f32_e32 v22, v22
	s_nop 0
	v_mul_f32_e32 v19, v19, v22
	v_mul_f32_e32 v19, v18, v19
	v_mul_f32_e32 v18, 0xbfb8aa3b, v21
	v_exp_f32_e32 v18, v18
	v_lshl_add_u64 v[22:23], v[34:35], 0, v[124:125]
	v_add_f32_e32 v18, 1.0, v18
	v_rcp_f32_e32 v18, v18
	s_nop 0
	v_mul_f32_e32 v18, v21, v18
	v_mul_f32_e32 v21, v20, v18
	v_cvt_pk_bf16_f32 v18, v36, v30
	v_cvt_pk_bf16_f32 v19, v24, v19
	v_cvt_pk_bf16_f32 v20, v37, v31
	v_cvt_pk_bf16_f32 v21, v26, v21
	global_store_dwordx4 v[22:23], v[18:21], off
	v_pk_mul_f32 v[22:23], v[166:167], v[170:171] op_sel_hi:[0,1]
	v_pk_mul_f32 v[24:25], v[166:167], v[174:175] op_sel_hi:[0,1]
	v_cvt_f32_i32_e32 v21, v14
	v_cvt_f32_i32_e32 v20, v6
	v_cvt_f32_i32_e32 v14, v7
	v_pk_mul_f32 v[6:7], v[166:167], v[54:55] op_sel_hi:[0,1]
	v_mad_u64_u32 v[18:19], s[34:35], v168, s26, v[176:177]
	v_pk_mul_f32 v[20:21], v[22:23], v[20:21]
	v_cvt_f32_i32_e32 v22, v2
	v_mul_f32_e32 v2, 0xbfb8aa3b, v21
	v_exp_f32_e32 v2, v2
	v_cvt_f32_i32_e32 v23, v10
	v_cvt_f32_i32_e32 v10, v3
	v_pk_mul_f32 v[6:7], v[6:7], v[14:15]
	v_add_f32_e32 v2, 1.0, v2
	v_rcp_f32_e32 v2, v2
	v_pk_mul_f32 v[22:23], v[24:25], v[22:23]
	v_mul_f32_e32 v2, v21, v2
	v_mul_f32_e32 v20, v20, v2
	v_mul_f32_e32 v2, 0xbfb8aa3b, v23
	v_exp_f32_e32 v2, v2
	s_nop 0
	v_add_f32_e32 v2, 1.0, v2
	v_rcp_f32_e32 v2, v2
	s_nop 0
	v_mul_f32_e32 v2, v23, v2
	v_mul_f32_e32 v21, v22, v2
	v_pk_mul_f32 v[2:3], v[166:167], v[50:51] op_sel_hi:[0,1]
	v_pk_mul_f32 v[2:3], v[2:3], v[10:11]
	v_mul_f32_e32 v10, 0xbfb8aa3b, v7
	v_exp_f32_e32 v10, v10
	s_nop 0
	v_add_f32_e32 v10, 1.0, v10
	v_rcp_f32_e32 v10, v10
	s_nop 0
	v_mul_f32_e32 v7, v7, v10
	v_mul_f32_e32 v14, v6, v7
	v_mul_f32_e32 v6, 0xbfb8aa3b, v3
	v_exp_f32_e32 v6, v6
	v_pk_mul_f32 v[10:11], v[166:167], v[126:127] op_sel_hi:[0,1]
	v_add_f32_e32 v6, 1.0, v6
	v_rcp_f32_e32 v6, v6
	s_nop 0
	v_mul_f32_e32 v3, v3, v6
	v_mul_f32_e32 v15, v2, v3
	v_cvt_f32_i32_e32 v3, v16
	v_cvt_f32_i32_e32 v2, v8
	v_pk_mul_f32 v[6:7], v[166:167], v[122:123] op_sel_hi:[0,1]
	v_pk_mul_f32 v[2:3], v[6:7], v[2:3]
	v_cvt_f32_i32_e32 v6, v4
	v_mul_f32_e32 v4, 0xbfb8aa3b, v3
	v_exp_f32_e32 v4, v4
	v_cvt_f32_i32_e32 v7, v12
	v_add_f32_e32 v4, 1.0, v4
	v_rcp_f32_e32 v4, v4
	v_pk_mul_f32 v[6:7], v[10:11], v[6:7]
	v_mul_f32_e32 v3, v3, v4
	v_mul_f32_e32 v8, v2, v3
	v_mul_f32_e32 v2, 0xbfb8aa3b, v7
	v_exp_f32_e32 v2, v2
	v_cvt_f32_i32_e32 v3, v17
	v_add_f32_e32 v2, 1.0, v2
	v_rcp_f32_e32 v2, v2
	s_nop 0
	v_mul_f32_e32 v2, v7, v2
	v_mul_f32_e32 v10, v6, v2
	v_cvt_f32_i32_e32 v2, v9
	v_pk_mul_f32 v[6:7], v[166:167], v[56:57] op_sel_hi:[0,1]
	v_pk_mul_f32 v[2:3], v[6:7], v[2:3]
	v_cvt_f32_i32_e32 v7, v13
	v_cvt_f32_i32_e32 v6, v5
	v_pk_mul_f32 v[4:5], v[166:167], v[52:53] op_sel_hi:[0,1]
	v_pk_mul_f32 v[4:5], v[4:5], v[6:7]
	v_mul_f32_e32 v6, 0xbfb8aa3b, v3
	v_exp_f32_e32 v6, v6
	s_nop 0
	v_add_f32_e32 v6, 1.0, v6
	v_rcp_f32_e32 v6, v6
	s_nop 0
	v_mul_f32_e32 v3, v3, v6
	v_mul_f32_e32 v3, v2, v3
	v_mul_f32_e32 v2, 0xbfb8aa3b, v5
	v_exp_f32_e32 v2, v2
	v_lshl_add_u64 v[6:7], v[18:19], 0, v[124:125]
	v_add_f32_e32 v2, 1.0, v2
	v_rcp_f32_e32 v2, v2
	s_nop 0
	v_mul_f32_e32 v2, v5, v2
	v_mul_f32_e32 v5, v4, v2
	v_cvt_pk_bf16_f32 v2, v20, v14
	v_cvt_pk_bf16_f32 v3, v8, v3
	v_cvt_pk_bf16_f32 v4, v21, v15
	v_cvt_pk_bf16_f32 v5, v10, v5
	global_store_dwordx4 v[6:7], v[2:5], off
	s_cbranch_vccnz .LBB0_112
	s_andn2_b64 vcc, exec, s[10:11]
	s_cbranch_vccnz .LBB0_111
	s_barrier
	s_branch .LBB0_111

.LBB0_438:
	v_ashrrev_i32_e32 v165, 31, v164
	v_lshl_add_u64 v[74:75], v[164:165], 2, s[6:7]
	global_load_dword v183, v[74:75], off
	s_lshl_b32 s46, s55, 8
	s_add_i32 s39, s46, 0xfffff800
	s_cmp_lt_i32 s55, 8
	s_mov_b32 s37, 0x1c002000
	s_cselect_b32 s47, 0x6000, s37
	s_movk_i32 s37, 0x3800
	s_cselect_b32 s37, s37, 0x3000
	s_cselect_b32 s39, s46, s39
	s_add_u32 s48, s2, s47
	s_addc_u32 s49, s3, 0
	s_ashr_i32 s47, s46, 31
	v_lshl_add_u64 v[78:79], s[46:47], 2, v[156:157]
	global_load_dword v182, v[74:75], off offset:64
	global_load_dword v181, v[74:75], off offset:128
	global_load_dword v180, v[74:75], off offset:192
	global_load_dword v178, v[74:75], off offset:512
	global_load_dword v177, v[74:75], off offset:576
	global_load_dword v176, v[74:75], off offset:640
	global_load_dword v165, v[74:75], off offset:704
	global_load_dwordx4 v[90:93], v[78:79], off offset:16
	global_load_dwordx4 v[94:97], v[78:79], off
	global_load_dwordx4 v[74:77], v[78:79], off offset:528
	s_nop 0
	global_load_dwordx4 v[78:81], v[78:79], off offset:512
	v_cvt_f32_i32_e32 v142, v142
	v_cvt_f32_i32_e32 v138, v138
	v_cvt_f32_i32_e32 v139, v139
	v_cvt_f32_i32_e32 v140, v140
	v_cvt_f32_i32_e32 v141, v141
	v_or_b32_e32 v166, s39, v172
	v_ashrrev_i32_e32 v167, 31, v166
	v_cvt_f32_i32_e32 v134, v134
	v_lshl_add_u64 v[166:167], v[166:167], 1, s[48:49]
	v_mad_i64_i32 v[168:169], s[46:47], s37, v164, 0
	v_cvt_f32_i32_e32 v130, v130
	v_lshl_add_u64 v[168:169], v[168:169], 1, v[166:167]
	v_cvt_f32_i32_e32 v131, v131
	v_cvt_f32_i32_e32 v132, v132
	v_cvt_f32_i32_e32 v133, v133
	v_cvt_f32_i32_e32 v126, v126
	v_cvt_f32_i32_e32 v122, v122
	v_cvt_f32_i32_e32 v123, v123
	v_cvt_f32_i32_e32 v124, v124
	v_cvt_f32_i32_e32 v125, v125
	v_cvt_f32_i32_e32 v118, v118
	v_cvt_f32_i32_e32 v114, v114
	v_cvt_f32_i32_e32 v115, v115
	v_cvt_f32_i32_e32 v116, v116
	v_cvt_f32_i32_e32 v117, v117
	v_cvt_f32_i32_e32 v110, v110
	v_cvt_f32_i32_e32 v106, v106
	v_cvt_f32_i32_e32 v107, v107
	v_cvt_f32_i32_e32 v108, v108
	v_cvt_f32_i32_e32 v109, v109
	v_cvt_f32_i32_e32 v102, v102
	v_cvt_f32_i32_e32 v98, v98
	v_cvt_f32_i32_e32 v99, v99
	v_cvt_f32_i32_e32 v100, v100
	v_cvt_f32_i32_e32 v101, v101
	v_cvt_f32_i32_e32 v86, v86
	v_cvt_f32_i32_e32 v82, v82
	v_cvt_f32_i32_e32 v83, v83
	v_cvt_f32_i32_e32 v84, v84
	v_cvt_f32_i32_e32 v85, v85
	v_cvt_f32_i32_e32 v70, v70
	v_cvt_f32_i32_e32 v66, v66
	v_cvt_f32_i32_e32 v67, v67
	v_cvt_f32_i32_e32 v68, v68
	v_cvt_f32_i32_e32 v69, v69
	v_cvt_f32_i32_e32 v62, v62
	v_cvt_f32_i32_e32 v58, v58
	v_cvt_f32_i32_e32 v59, v59
	v_cvt_f32_i32_e32 v60, v60
	v_cvt_f32_i32_e32 v61, v61
	v_add_u32_e32 v179, 0x80, v164
	v_cvt_f32_i32_e32 v54, v54
	v_cvt_f32_i32_e32 v50, v50
	v_cvt_f32_i32_e32 v51, v51
	v_cvt_f32_i32_e32 v52, v52
	v_cvt_f32_i32_e32 v53, v53
	v_cvt_f32_i32_e32 v46, v46
	v_cvt_f32_i32_e32 v42, v42
	v_cvt_f32_i32_e32 v43, v43
	v_cvt_f32_i32_e32 v44, v44
	v_cvt_f32_i32_e32 v45, v45
	v_cvt_f32_i32_e32 v38, v38
	v_cvt_f32_i32_e32 v34, v34
	v_cvt_f32_i32_e32 v35, v35
	v_cvt_f32_i32_e32 v36, v36
	v_cvt_f32_i32_e32 v37, v37
	s_waitcnt vmcnt(4)
	v_mul_f32_e32 v183, 0x3c010204, v183
	v_cvt_f32_i32_e32 v30, v30
	v_cvt_f32_i32_e32 v26, v26
	v_cvt_f32_i32_e32 v27, v27
	v_cvt_f32_i32_e32 v28, v28
	v_cvt_f32_i32_e32 v29, v29
	v_cvt_f32_i32_e32 v22, v22
	v_cvt_f32_i32_e32 v18, v18
	v_cvt_f32_i32_e32 v19, v19
	v_cvt_f32_i32_e32 v20, v20
	v_cvt_f32_i32_e32 v21, v21
	v_cvt_f32_i32_e32 v14, v14
	v_cvt_f32_i32_e32 v10, v10
	v_cvt_f32_i32_e32 v11, v11
	v_cvt_f32_i32_e32 v12, v12
	v_cvt_f32_i32_e32 v13, v13
	v_cvt_f32_i32_e32 v6, v6
	v_cvt_f32_i32_e32 v2, v2
	v_cvt_f32_i32_e32 v3, v3
	v_cvt_f32_i32_e32 v4, v4
	v_cvt_f32_i32_e32 v5, v5
	s_nop 0
	v_mul_f32_e32 v182, 0x3c010204, v182
	s_nop 0
	v_mul_f32_e32 v181, 0x3c010204, v181
	s_nop 0
	v_mul_f32_e32 v180, 0x3c010204, v180
	s_nop 0
	v_mul_f32_e32 v178, 0x3c010204, v178
	s_nop 0
	v_mul_f32_e32 v177, 0x3c010204, v177
	s_nop 0
	v_mul_f32_e32 v176, 0x3c010204, v176
	s_nop 0
	v_mul_f32_e32 v165, 0x3c010204, v165
	s_waitcnt vmcnt(2)
	v_mul_f32_e32 v184, v183, v94
	v_mul_f32_e32 v142, v184, v142
	v_mul_f32_e32 v184, v183, v90
	v_mul_f32_e32 v184, v184, v138
	v_cvt_f32_i32_e32 v138, v143
	v_mul_f32_e32 v143, v183, v95
	v_mul_f32_e32 v138, v143, v138
	v_mul_f32_e32 v143, v183, v91
	v_mul_f32_e32 v143, v143, v139
	v_cvt_f32_i32_e32 v139, v144
	v_mul_f32_e32 v144, v183, v96
	v_cvt_pk_bf16_f32 v138, v142, v138
	v_mul_f32_e32 v139, v144, v139
	v_mul_f32_e32 v144, v183, v92
	v_mul_f32_e32 v144, v144, v140
	v_cvt_f32_i32_e32 v140, v145
	v_mul_f32_e32 v145, v183, v97
	v_mul_f32_e32 v140, v145, v140
	v_mul_f32_e32 v145, v183, v93
	v_mul_f32_e32 v141, v145, v141
	v_cvt_pk_bf16_f32 v139, v139, v140
	v_cvt_pk_bf16_f32 v140, v184, v143
	v_cvt_pk_bf16_f32 v141, v144, v141
	global_store_dwordx4 v[168:169], v[138:141], off
	s_waitcnt vmcnt(1)
	s_nop 0
	v_mul_f32_e32 v138, v183, v78
	v_mul_f32_e32 v134, v138, v134
	v_mul_f32_e32 v138, v183, v74
	v_mul_f32_e32 v138, v138, v130
	v_cvt_f32_i32_e32 v130, v135
	v_mul_f32_e32 v135, v183, v79
	v_mul_f32_e32 v130, v135, v130
	v_mul_f32_e32 v135, v183, v75
	v_mul_f32_e32 v135, v135, v131
	v_cvt_f32_i32_e32 v131, v136
	v_mul_f32_e32 v136, v183, v80
	v_cvt_pk_bf16_f32 v130, v134, v130
	v_mul_f32_e32 v131, v136, v131
	v_mul_f32_e32 v136, v183, v76
	v_mul_f32_e32 v136, v136, v132
	v_cvt_f32_i32_e32 v132, v137
	v_mul_f32_e32 v137, v183, v81
	v_mul_f32_e32 v132, v137, v132
	v_mul_f32_e32 v137, v183, v77
	v_mul_f32_e32 v133, v137, v133
	v_cvt_pk_bf16_f32 v131, v131, v132
	v_cvt_pk_bf16_f32 v132, v138, v135
	v_cvt_pk_bf16_f32 v133, v136, v133
	global_store_dwordx4 v[168:169], v[130:133], off offset:256
	s_nop 1
	v_mul_f32_e32 v132, v182, v94
	v_mul_f32_e32 v126, v132, v126
	v_mul_f32_e32 v132, v182, v90
	v_mul_f32_e32 v132, v132, v122
	v_cvt_f32_i32_e32 v122, v127
	v_mul_f32_e32 v127, v182, v95
	v_or_b32_e32 v130, 16, v164
	v_mad_i64_i32 v[130:131], s[46:47], s37, v130, 0
	v_mul_f32_e32 v122, v127, v122
	v_mul_f32_e32 v127, v182, v91
	v_mul_f32_e32 v127, v127, v123
	v_cvt_f32_i32_e32 v123, v128
	v_mul_f32_e32 v128, v182, v96
	v_lshl_add_u64 v[130:131], v[130:131], 1, v[166:167]
	v_cvt_pk_bf16_f32 v122, v126, v122
	v_mul_f32_e32 v123, v128, v123
	v_mul_f32_e32 v128, v182, v92
	v_mul_f32_e32 v128, v128, v124
	v_cvt_f32_i32_e32 v124, v129
	v_mul_f32_e32 v129, v182, v97
	v_mul_f32_e32 v124, v129, v124
	v_mul_f32_e32 v129, v182, v93
	v_mul_f32_e32 v125, v129, v125
	v_cvt_pk_bf16_f32 v123, v123, v124
	v_cvt_pk_bf16_f32 v124, v132, v127
	v_cvt_pk_bf16_f32 v125, v128, v125
	global_store_dwordx4 v[130:131], v[122:125], off
	s_nop 1
	v_mul_f32_e32 v122, v182, v78
	v_mul_f32_e32 v118, v122, v118
	v_mul_f32_e32 v122, v182, v74
	v_mul_f32_e32 v122, v122, v114
	v_cvt_f32_i32_e32 v114, v119
	v_mul_f32_e32 v119, v182, v79
	v_mul_f32_e32 v114, v119, v114
	v_mul_f32_e32 v119, v182, v75
	v_mul_f32_e32 v119, v119, v115
	v_cvt_f32_i32_e32 v115, v120
	v_mul_f32_e32 v120, v182, v80
	v_cvt_pk_bf16_f32 v114, v118, v114
	v_mul_f32_e32 v115, v120, v115
	v_mul_f32_e32 v120, v182, v76
	v_mul_f32_e32 v120, v120, v116
	v_cvt_f32_i32_e32 v116, v121
	v_mul_f32_e32 v121, v182, v81
	v_mul_f32_e32 v116, v121, v116
	v_mul_f32_e32 v121, v182, v77
	v_mul_f32_e32 v117, v121, v117
	v_cvt_pk_bf16_f32 v115, v115, v116
	v_cvt_pk_bf16_f32 v116, v122, v119
	v_cvt_pk_bf16_f32 v117, v120, v117
	global_store_dwordx4 v[130:131], v[114:117], off offset:256
	s_nop 1
	v_mul_f32_e32 v116, v181, v94
	v_mul_f32_e32 v110, v116, v110
	v_mul_f32_e32 v116, v181, v90
	v_mul_f32_e32 v116, v116, v106
	v_cvt_f32_i32_e32 v106, v111
	v_mul_f32_e32 v111, v181, v95
	v_or_b32_e32 v114, 32, v164
	v_mad_i64_i32 v[114:115], s[46:47], s37, v114, 0
	v_mul_f32_e32 v106, v111, v106
	v_mul_f32_e32 v111, v181, v91
	v_mul_f32_e32 v111, v111, v107
	v_cvt_f32_i32_e32 v107, v112
	v_mul_f32_e32 v112, v181, v96
	v_lshl_add_u64 v[114:115], v[114:115], 1, v[166:167]
	v_cvt_pk_bf16_f32 v106, v110, v106
	v_mul_f32_e32 v107, v112, v107
	v_mul_f32_e32 v112, v181, v92
	v_mul_f32_e32 v112, v112, v108
	v_cvt_f32_i32_e32 v108, v113
	v_mul_f32_e32 v113, v181, v97
	v_mul_f32_e32 v108, v113, v108
	v_mul_f32_e32 v113, v181, v93
	v_mul_f32_e32 v109, v113, v109
	v_cvt_pk_bf16_f32 v107, v107, v108
	v_cvt_pk_bf16_f32 v108, v116, v111
	v_cvt_pk_bf16_f32 v109, v112, v109
	global_store_dwordx4 v[114:115], v[106:109], off
	s_nop 1
	v_mul_f32_e32 v106, v181, v78
	v_mul_f32_e32 v102, v106, v102
	v_mul_f32_e32 v106, v181, v74
	v_mul_f32_e32 v106, v106, v98
	v_cvt_f32_i32_e32 v98, v103
	v_mul_f32_e32 v103, v181, v79
	v_mul_f32_e32 v98, v103, v98
	v_mul_f32_e32 v103, v181, v75
	v_mul_f32_e32 v103, v103, v99
	v_cvt_f32_i32_e32 v99, v104
	v_mul_f32_e32 v104, v181, v80
	v_cvt_pk_bf16_f32 v98, v102, v98
	v_mul_f32_e32 v99, v104, v99
	v_mul_f32_e32 v104, v181, v76
	v_mul_f32_e32 v104, v104, v100
	v_cvt_f32_i32_e32 v100, v105
	v_mul_f32_e32 v105, v181, v81
	v_mul_f32_e32 v100, v105, v100
	v_mul_f32_e32 v105, v181, v77
	v_mul_f32_e32 v101, v105, v101
	v_cvt_pk_bf16_f32 v99, v99, v100
	v_cvt_pk_bf16_f32 v100, v106, v103
	v_cvt_pk_bf16_f32 v101, v104, v101
	global_store_dwordx4 v[114:115], v[98:101], off offset:256
	s_nop 1
	v_mul_f32_e32 v100, v180, v94
	v_mul_f32_e32 v86, v100, v86
	v_mul_f32_e32 v100, v180, v90
	v_mul_f32_e32 v100, v100, v82
	v_cvt_f32_i32_e32 v82, v87
	v_mul_f32_e32 v87, v180, v95
	v_or_b32_e32 v98, 48, v164
	v_mad_i64_i32 v[98:99], s[46:47], s37, v98, 0
	v_mul_f32_e32 v82, v87, v82
	v_mul_f32_e32 v87, v180, v91
	v_mul_f32_e32 v87, v87, v83
	v_cvt_f32_i32_e32 v83, v88
	v_mul_f32_e32 v88, v180, v96
	v_lshl_add_u64 v[98:99], v[98:99], 1, v[166:167]
	v_cvt_pk_bf16_f32 v82, v86, v82
	v_mul_f32_e32 v83, v88, v83
	v_mul_f32_e32 v88, v180, v92
	v_mul_f32_e32 v88, v88, v84
	v_cvt_f32_i32_e32 v84, v89
	v_mul_f32_e32 v89, v180, v97
	v_mul_f32_e32 v84, v89, v84
	v_mul_f32_e32 v89, v180, v93
	v_mul_f32_e32 v85, v89, v85
	v_cvt_pk_bf16_f32 v83, v83, v84
	v_cvt_pk_bf16_f32 v84, v100, v87
	v_cvt_pk_bf16_f32 v85, v88, v85
	global_store_dwordx4 v[98:99], v[82:85], off
	s_nop 1
	v_mul_f32_e32 v82, v180, v78
	v_mul_f32_e32 v70, v82, v70
	v_mul_f32_e32 v82, v180, v74
	v_mul_f32_e32 v82, v82, v66
	v_cvt_f32_i32_e32 v66, v71
	v_mul_f32_e32 v71, v180, v79
	v_mul_f32_e32 v66, v71, v66
	v_mul_f32_e32 v71, v180, v75
	v_mul_f32_e32 v71, v71, v67
	v_cvt_f32_i32_e32 v67, v72
	v_mul_f32_e32 v72, v180, v80
	v_cvt_pk_bf16_f32 v66, v70, v66
	v_mul_f32_e32 v67, v72, v67
	v_mul_f32_e32 v72, v180, v76
	v_mul_f32_e32 v72, v72, v68
	v_cvt_f32_i32_e32 v68, v73
	v_mul_f32_e32 v73, v180, v81
	v_mul_f32_e32 v68, v73, v68
	v_mul_f32_e32 v73, v180, v77
	v_mul_f32_e32 v69, v73, v69
	v_cvt_pk_bf16_f32 v67, v67, v68
	v_cvt_pk_bf16_f32 v68, v82, v71
	v_cvt_pk_bf16_f32 v69, v72, v69
	global_store_dwordx4 v[98:99], v[66:69], off offset:256
	s_nop 1
	v_mul_f32_e32 v68, v178, v94
	v_mul_f32_e32 v62, v68, v62
	v_mul_f32_e32 v68, v178, v90
	v_mul_f32_e32 v68, v68, v58
	v_cvt_f32_i32_e32 v58, v63
	v_mul_f32_e32 v63, v178, v95
	v_mad_i64_i32 v[66:67], s[46:47], s37, v179, 0
	v_mul_f32_e32 v58, v63, v58
	v_mul_f32_e32 v63, v178, v91
	v_mul_f32_e32 v63, v63, v59
	v_cvt_f32_i32_e32 v59, v64
	v_mul_f32_e32 v64, v178, v96
	v_lshl_add_u64 v[66:67], v[66:67], 1, v[166:167]
	v_cvt_pk_bf16_f32 v58, v62, v58
	v_mul_f32_e32 v59, v64, v59
	v_mul_f32_e32 v64, v178, v92
	v_mul_f32_e32 v64, v64, v60
	v_cvt_f32_i32_e32 v60, v65
	v_mul_f32_e32 v65, v178, v97
	v_mul_f32_e32 v60, v65, v60
	v_mul_f32_e32 v65, v178, v93
	v_mul_f32_e32 v61, v65, v61
	v_cvt_pk_bf16_f32 v59, v59, v60
	v_cvt_pk_bf16_f32 v60, v68, v63
	v_cvt_pk_bf16_f32 v61, v64, v61
	global_store_dwordx4 v[66:67], v[58:61], off
	s_nop 1
	v_mul_f32_e32 v58, v178, v78
	v_mul_f32_e32 v54, v58, v54
	v_mul_f32_e32 v58, v178, v74
	v_mul_f32_e32 v58, v58, v50
	v_cvt_f32_i32_e32 v50, v55
	v_mul_f32_e32 v55, v178, v79
	v_mul_f32_e32 v50, v55, v50
	v_mul_f32_e32 v55, v178, v75
	v_mul_f32_e32 v55, v55, v51
	v_cvt_f32_i32_e32 v51, v56
	v_mul_f32_e32 v56, v178, v80
	v_cvt_pk_bf16_f32 v50, v54, v50
	v_mul_f32_e32 v51, v56, v51
	v_mul_f32_e32 v56, v178, v76
	v_mul_f32_e32 v56, v56, v52
	v_cvt_f32_i32_e32 v52, v57
	v_mul_f32_e32 v57, v178, v81
	v_mul_f32_e32 v52, v57, v52
	v_mul_f32_e32 v57, v178, v77
	v_mul_f32_e32 v53, v57, v53
	v_cvt_pk_bf16_f32 v51, v51, v52
	v_cvt_pk_bf16_f32 v52, v58, v55
	v_cvt_pk_bf16_f32 v53, v56, v53
	global_store_dwordx4 v[66:67], v[50:53], off offset:256
	s_nop 1
	v_mul_f32_e32 v52, v177, v94
	v_mul_f32_e32 v46, v52, v46
	v_mul_f32_e32 v52, v177, v90
	v_mul_f32_e32 v52, v52, v42
	v_cvt_f32_i32_e32 v42, v47
	v_mul_f32_e32 v47, v177, v95
	v_add_u32_e32 v50, 0x90, v164
	v_mad_i64_i32 v[50:51], s[46:47], s37, v50, 0
	v_mul_f32_e32 v42, v47, v42
	v_mul_f32_e32 v47, v177, v91
	v_mul_f32_e32 v47, v47, v43
	v_cvt_f32_i32_e32 v43, v48
	v_mul_f32_e32 v48, v177, v96
	v_lshl_add_u64 v[50:51], v[50:51], 1, v[166:167]
	v_cvt_pk_bf16_f32 v42, v46, v42
	v_mul_f32_e32 v43, v48, v43
	v_mul_f32_e32 v48, v177, v92
	v_mul_f32_e32 v48, v48, v44
	v_cvt_f32_i32_e32 v44, v49
	v_mul_f32_e32 v49, v177, v97
	v_mul_f32_e32 v44, v49, v44
	v_mul_f32_e32 v49, v177, v93
	v_mul_f32_e32 v45, v49, v45
	v_cvt_pk_bf16_f32 v43, v43, v44
	v_cvt_pk_bf16_f32 v44, v52, v47
	v_cvt_pk_bf16_f32 v45, v48, v45
	global_store_dwordx4 v[50:51], v[42:45], off
	s_nop 1
	v_mul_f32_e32 v42, v177, v78
	v_mul_f32_e32 v38, v42, v38
	v_mul_f32_e32 v42, v177, v74
	v_mul_f32_e32 v42, v42, v34
	v_cvt_f32_i32_e32 v34, v39
	v_mul_f32_e32 v39, v177, v79
	v_mul_f32_e32 v34, v39, v34
	v_mul_f32_e32 v39, v177, v75
	v_mul_f32_e32 v39, v39, v35
	v_cvt_f32_i32_e32 v35, v40
	v_mul_f32_e32 v40, v177, v80
	v_cvt_pk_bf16_f32 v34, v38, v34
	v_mul_f32_e32 v35, v40, v35
	v_mul_f32_e32 v40, v177, v76
	v_mul_f32_e32 v40, v40, v36
	v_cvt_f32_i32_e32 v36, v41
	v_mul_f32_e32 v41, v177, v81
	v_mul_f32_e32 v36, v41, v36
	v_mul_f32_e32 v41, v177, v77
	v_mul_f32_e32 v37, v41, v37
	v_cvt_pk_bf16_f32 v35, v35, v36
	v_cvt_pk_bf16_f32 v36, v42, v39
	v_cvt_pk_bf16_f32 v37, v40, v37
	global_store_dwordx4 v[50:51], v[34:37], off offset:256
	s_nop 1
	v_mul_f32_e32 v36, v176, v94
	v_mul_f32_e32 v30, v36, v30
	v_mul_f32_e32 v36, v176, v90
	v_mul_f32_e32 v36, v36, v26
	v_cvt_f32_i32_e32 v26, v31
	v_mul_f32_e32 v31, v176, v95
	v_add_u32_e32 v34, 0xa0, v164
	v_mad_i64_i32 v[34:35], s[46:47], s37, v34, 0
	v_mul_f32_e32 v26, v31, v26
	v_mul_f32_e32 v31, v176, v91
	v_mul_f32_e32 v31, v31, v27
	v_cvt_f32_i32_e32 v27, v32
	v_mul_f32_e32 v32, v176, v96
	v_lshl_add_u64 v[34:35], v[34:35], 1, v[166:167]
	v_cvt_pk_bf16_f32 v26, v30, v26
	v_mul_f32_e32 v27, v32, v27
	v_mul_f32_e32 v32, v176, v92
	v_mul_f32_e32 v32, v32, v28
	v_cvt_f32_i32_e32 v28, v33
	v_mul_f32_e32 v33, v176, v97
	v_mul_f32_e32 v28, v33, v28
	v_mul_f32_e32 v33, v176, v93
	v_mul_f32_e32 v29, v33, v29
	v_cvt_pk_bf16_f32 v27, v27, v28
	v_cvt_pk_bf16_f32 v28, v36, v31
	v_cvt_pk_bf16_f32 v29, v32, v29
	global_store_dwordx4 v[34:35], v[26:29], off
	s_nop 1
	v_mul_f32_e32 v26, v176, v78
	v_mul_f32_e32 v22, v26, v22
	v_mul_f32_e32 v26, v176, v74
	v_mul_f32_e32 v26, v26, v18
	v_cvt_f32_i32_e32 v18, v23
	v_mul_f32_e32 v23, v176, v79
	v_mul_f32_e32 v18, v23, v18
	v_mul_f32_e32 v23, v176, v75
	v_mul_f32_e32 v23, v23, v19
	v_cvt_f32_i32_e32 v19, v24
	v_mul_f32_e32 v24, v176, v80
	v_cvt_pk_bf16_f32 v18, v22, v18
	v_mul_f32_e32 v19, v24, v19
	v_mul_f32_e32 v24, v176, v76
	v_mul_f32_e32 v24, v24, v20
	v_cvt_f32_i32_e32 v20, v25
	v_mul_f32_e32 v25, v176, v81
	v_mul_f32_e32 v20, v25, v20
	v_mul_f32_e32 v25, v176, v77
	v_mul_f32_e32 v21, v25, v21
	v_cvt_pk_bf16_f32 v19, v19, v20
	v_cvt_pk_bf16_f32 v20, v26, v23
	v_cvt_pk_bf16_f32 v21, v24, v21
	global_store_dwordx4 v[34:35], v[18:21], off offset:256
	s_nop 1
	v_mul_f32_e32 v20, v165, v94
	v_mul_f32_e32 v14, v20, v14
	v_mul_f32_e32 v20, v165, v90
	v_mul_f32_e32 v20, v20, v10
	v_cvt_f32_i32_e32 v10, v15
	v_mul_f32_e32 v15, v165, v95
	v_add_u32_e32 v18, 0xb0, v164
	v_mad_i64_i32 v[18:19], s[46:47], s37, v18, 0
	v_mul_f32_e32 v10, v15, v10
	v_mul_f32_e32 v15, v165, v91
	v_mul_f32_e32 v15, v15, v11
	v_cvt_f32_i32_e32 v11, v16
	v_mul_f32_e32 v16, v165, v96
	v_lshl_add_u64 v[18:19], v[18:19], 1, v[166:167]
	v_cvt_pk_bf16_f32 v10, v14, v10
	v_mul_f32_e32 v11, v16, v11
	v_mul_f32_e32 v16, v165, v92
	v_mul_f32_e32 v16, v16, v12
	v_cvt_f32_i32_e32 v12, v17
	v_mul_f32_e32 v17, v165, v97
	v_mul_f32_e32 v12, v17, v12
	v_mul_f32_e32 v17, v165, v93
	v_mul_f32_e32 v13, v17, v13
	v_cvt_pk_bf16_f32 v11, v11, v12
	v_cvt_pk_bf16_f32 v12, v20, v15
	v_cvt_pk_bf16_f32 v13, v16, v13
	global_store_dwordx4 v[18:19], v[10:13], off
	s_nop 1
	v_mul_f32_e32 v10, v165, v78
	v_mul_f32_e32 v6, v10, v6
	v_mul_f32_e32 v10, v165, v74
	v_mul_f32_e32 v10, v10, v2
	v_cvt_f32_i32_e32 v2, v7
	v_mul_f32_e32 v7, v165, v79
	v_mul_f32_e32 v2, v7, v2
	v_mul_f32_e32 v7, v165, v75
	v_mul_f32_e32 v7, v7, v3
	v_cvt_f32_i32_e32 v3, v8
	v_mul_f32_e32 v8, v165, v80
	v_cvt_pk_bf16_f32 v2, v6, v2
	v_mul_f32_e32 v3, v8, v3
	v_mul_f32_e32 v8, v165, v76
	v_mul_f32_e32 v8, v8, v4
	v_cvt_f32_i32_e32 v4, v9
	v_mul_f32_e32 v9, v165, v81
	v_mul_f32_e32 v4, v9, v4
	v_mul_f32_e32 v9, v165, v77
	v_mul_f32_e32 v5, v9, v5
	v_cvt_pk_bf16_f32 v3, v3, v4
	v_cvt_pk_bf16_f32 v4, v10, v7
	v_cvt_pk_bf16_f32 v5, v8, v5
	global_store_dwordx4 v[18:19], v[2:5], off offset:256
	s_andn2_b64 vcc, exec, s[40:41]
	s_mov_b64 s[40:41], -1
	s_cbranch_vccnz .LBB0_418

.LBB0_685:
	s_or_b64 exec, exec, s[62:63]
	s_waitcnt lgkmcnt(0)
	v_sub_f32_e32 v43, v131, v43
	v_mul_f32_e32 v43, 0x3fb8aa3b, v43
	v_sub_f32_e32 v42, v131, v42
	v_exp_f32_e32 v43, v43
	v_mul_f32_e32 v42, 0x3fb8aa3b, v42
	v_sub_f32_e32 v41, v131, v41
	v_exp_f32_e32 v42, v42
	v_mul_f32_e32 v41, 0x3fb8aa3b, v41
	v_sub_f32_e32 v40, v131, v40
	v_exp_f32_e32 v41, v41
	v_mul_f32_e32 v40, 0x3fb8aa3b, v40
	v_mul_f32_e32 v44, 0x3db504f3, v49
	v_exp_f32_e32 v40, v40
	v_mul_f32_e32 v43, v44, v43
	v_mul_f32_e32 v44, 0x3db504f3, v48
	v_mul_f32_e32 v42, v44, v42
	v_mul_f32_e32 v44, 0x3db504f3, v47
	v_mul_f32_e32 v41, v44, v41
	v_mul_f32_e32 v44, 0x3db504f3, v46
	v_sub_f32_e32 v45, v162, v131
	v_mul_f32_e32 v40, v44, v40
	v_sub_f32_e32 v44, v162, v130
	v_mul_f32_e32 v45, 0x3fb8aa3b, v45
	v_mul_f32_e32 v44, 0x3fb8aa3b, v44
	v_exp_f32_e32 v45, v45
	v_exp_f32_e32 v44, v44
	v_mul_f32_e32 v17, v17, v163
	v_mul_f32_e32 v33, v33, v163
	v_mul_f32_e32 v17, v17, v45
	v_mul_f32_e32 v211, v33, v44
	v_cndmask_b32_e64 v62, 0, v17, s[60:61]
	v_sub_f32_e32 v17, v160, v130
	v_sub_f32_e32 v33, v160, v131
	v_mul_f32_e32 v17, 0x3fb8aa3b, v17
	v_mul_f32_e32 v33, 0x3fb8aa3b, v33
	v_exp_f32_e32 v17, v17
	v_exp_f32_e32 v33, v33
	v_mul_f32_e32 v32, v32, v161
	v_mul_f32_e32 v16, v16, v161
	v_mul_f32_e32 v212, v32, v17
	v_mul_f32_e32 v16, v16, v33
	v_sub_f32_e32 v17, v158, v131
	v_cndmask_b32_e64 v66, 0, v16, s[58:59]
	v_sub_f32_e32 v16, v158, v130
	v_mul_f32_e32 v17, 0x3fb8aa3b, v17
	v_mul_f32_e32 v16, 0x3fb8aa3b, v16
	v_exp_f32_e32 v17, v17
	v_exp_f32_e32 v16, v16
	v_mul_f32_e32 v15, v15, v159
	v_mul_f32_e32 v31, v31, v159
	v_mul_f32_e32 v15, v15, v17
	v_mul_f32_e32 v213, v31, v16
	v_cndmask_b32_e64 v70, 0, v15, s[56:57]
	v_sub_f32_e32 v15, v156, v130
	v_sub_f32_e32 v16, v156, v131
	v_mul_f32_e32 v15, 0x3fb8aa3b, v15
	v_mul_f32_e32 v16, 0x3fb8aa3b, v16
	v_exp_f32_e32 v15, v15
	v_exp_f32_e32 v16, v16
	v_mul_f32_e32 v17, v30, v157
	v_mul_f32_e32 v14, v14, v157
	v_mul_f32_e32 v214, v17, v15
	v_mul_f32_e32 v14, v14, v16
	v_sub_f32_e32 v15, v154, v130
	v_sub_f32_e32 v16, v154, v131
	v_mul_f32_e32 v15, 0x3fb8aa3b, v15
	v_mul_f32_e32 v16, 0x3fb8aa3b, v16
	v_exp_f32_e32 v15, v15
	v_exp_f32_e32 v16, v16
	v_mul_f32_e32 v17, v29, v155
	v_mul_f32_e32 v13, v13, v155
	v_mul_f32_e32 v215, v17, v15
	v_mul_f32_e32 v13, v13, v16
	v_sub_f32_e32 v15, v152, v131
	v_cndmask_b32_e64 v74, 0, v13, s[52:53]
	v_sub_f32_e32 v13, v152, v130
	v_mul_f32_e32 v15, 0x3fb8aa3b, v15
	v_mul_f32_e32 v13, 0x3fb8aa3b, v13
	v_exp_f32_e32 v15, v15
	v_exp_f32_e32 v13, v13
	v_mul_f32_e32 v12, v12, v153
	v_mul_f32_e32 v16, v28, v153
	v_mul_f32_e32 v12, v12, v15
	v_mul_f32_e32 v216, v16, v13
	v_cndmask_b32_e64 v28, 0, v12, s[50:51]
	v_sub_f32_e32 v12, v150, v130
	v_sub_f32_e32 v13, v150, v131
	v_mul_f32_e32 v12, 0x3fb8aa3b, v12
	v_mul_f32_e32 v13, 0x3fb8aa3b, v13
	v_exp_f32_e32 v12, v12
	v_exp_f32_e32 v13, v13
	v_mul_f32_e32 v15, v27, v151
	v_mul_f32_e32 v11, v11, v151
	v_mul_f32_e32 v217, v15, v12
	v_mul_f32_e32 v11, v11, v13
	v_sub_f32_e32 v12, v148, v131
	v_cndmask_b32_e64 v78, 0, v11, s[48:49]
	v_sub_f32_e32 v11, v148, v130
	v_mul_f32_e32 v12, 0x3fb8aa3b, v12
	v_mul_f32_e32 v11, 0x3fb8aa3b, v11
	v_exp_f32_e32 v12, v12
	v_exp_f32_e32 v11, v11
	v_mul_f32_e32 v10, v10, v149
	v_mul_f32_e32 v13, v26, v149
	v_mul_f32_e32 v10, v10, v12
	v_mul_f32_e32 v218, v13, v11
	v_cndmask_b32_e64 v82, 0, v10, s[46:47]
	v_sub_f32_e32 v10, v146, v130
	v_sub_f32_e32 v11, v146, v131
	v_mul_f32_e32 v10, 0x3fb8aa3b, v10
	v_mul_f32_e32 v11, 0x3fb8aa3b, v11
	v_exp_f32_e32 v10, v10
	v_exp_f32_e32 v11, v11
	v_mul_f32_e32 v12, v25, v147
	v_mul_f32_e32 v9, v9, v147
	v_mul_f32_e32 v219, v12, v10
	v_mul_f32_e32 v9, v9, v11
	v_sub_f32_e32 v10, v144, v131
	v_cndmask_b32_e64 v84, 0, v9, s[44:45]
	v_sub_f32_e32 v9, v144, v130
	v_mul_f32_e32 v10, 0x3fb8aa3b, v10
	v_mul_f32_e32 v9, 0x3fb8aa3b, v9
	v_exp_f32_e32 v10, v10
	v_exp_f32_e32 v9, v9
	v_mul_f32_e32 v8, v8, v145
	v_mul_f32_e32 v11, v24, v145
	v_mul_f32_e32 v8, v8, v10
	v_mul_f32_e32 v220, v11, v9
	v_cndmask_b32_e64 v24, 0, v8, s[42:43]
	v_sub_f32_e32 v8, v142, v130
	v_sub_f32_e32 v9, v142, v131
	v_mul_f32_e32 v8, 0x3fb8aa3b, v8
	v_mul_f32_e32 v9, 0x3fb8aa3b, v9
	v_exp_f32_e32 v8, v8
	v_exp_f32_e32 v9, v9
	v_mul_f32_e32 v10, v23, v143
	v_mul_f32_e32 v7, v7, v143
	v_mul_f32_e32 v221, v10, v8
	v_mul_f32_e32 v7, v7, v9
	v_sub_f32_e32 v8, v140, v131
	v_cndmask_b32_e64 v142, 0, v7, s[40:41]
	v_sub_f32_e32 v7, v140, v130
	v_mul_f32_e32 v8, 0x3fb8aa3b, v8
	v_mul_f32_e32 v7, 0x3fb8aa3b, v7
	v_exp_f32_e32 v8, v8
	v_exp_f32_e32 v7, v7
	v_mul_f32_e32 v6, v6, v141
	v_mul_f32_e32 v9, v22, v141
	v_mul_f32_e32 v6, v6, v8
	v_sub_f32_e32 v8, v138, v131
	v_mul_f32_e32 v222, v9, v7
	v_sub_f32_e32 v7, v138, v130
	v_mul_f32_e32 v8, 0x3fb8aa3b, v8
	v_mul_f32_e32 v7, 0x3fb8aa3b, v7
	v_exp_f32_e32 v8, v8
	v_exp_f32_e32 v7, v7
	v_mul_f32_e32 v5, v5, v139
	v_mul_f32_e32 v9, v21, v139
	v_mul_f32_e32 v5, v5, v8
	v_mul_f32_e32 v223, v9, v7
	v_cndmask_b32_e64 v140, 0, v5, s[8:9]
	v_sub_f32_e32 v5, v136, v130
	v_sub_f32_e32 v7, v136, v131
	v_mul_f32_e32 v5, 0x3fb8aa3b, v5
	v_mul_f32_e32 v7, 0x3fb8aa3b, v7
	v_exp_f32_e32 v5, v5
	v_exp_f32_e32 v7, v7
	v_mul_f32_e32 v8, v20, v137
	v_mul_f32_e32 v4, v4, v137
	v_mul_f32_e32 v224, v8, v5
	v_mul_f32_e32 v4, v4, v7
	v_sub_f32_e32 v5, v134, v131
	v_cndmask_b32_e64 v144, 0, v4, s[6:7]
	v_sub_f32_e32 v4, v134, v130
	v_mul_f32_e32 v5, 0x3fb8aa3b, v5
	v_mul_f32_e32 v4, 0x3fb8aa3b, v4
	v_exp_f32_e32 v5, v5
	v_exp_f32_e32 v4, v4
	v_mul_f32_e32 v3, v3, v135
	v_mul_f32_e32 v7, v19, v135
	v_mul_f32_e32 v3, v3, v5
	v_mul_f32_e32 v225, v7, v4
	v_cndmask_b32_e64 v146, v3, 0, s[4:5]
	v_sub_f32_e32 v3, v132, v130
	v_sub_f32_e32 v4, v132, v131
	v_mul_f32_e32 v3, 0x3fb8aa3b, v3
	v_mul_f32_e32 v4, 0x3fb8aa3b, v4
	v_exp_f32_e32 v3, v3
	v_exp_f32_e32 v4, v4
	v_mul_f32_e32 v5, v18, v133
	v_mul_f32_e32 v2, v2, v133
	v_mul_f32_e32 v226, v5, v3
	v_mul_f32_e32 v2, v2, v4
	v_cvt_pk_bf16_f32 v4, v40, v41
	v_cvt_pk_bf16_f32 v5, v42, v43
	global_store_dwordx2 v[34:35], v[4:5], off offset:48
	v_cvt_pk_bf16_f32 v4, v36, v38
	v_cvt_pk_bf16_f32 v5, v37, v39
	global_store_dwordx2 v[34:35], v[4:5], off offset:112
	v_cndmask_b32_e64 v14, 0, v14, s[54:55]
	v_cndmask_b32_e64 v6, 0, v6, s[38:39]
	v_cndmask_b32_e64 v2, 0, v2, s[0:1]
	v_lshlrev_b64 v[86:87], 1, v[128:129]
	s_add_u32 s0, s94, s28
	v_lshl_add_u64 v[4:5], v[122:123], 0, v[86:87]
	s_addc_u32 s1, s95, s29
	v_lshl_add_u64 v[98:99], s[0:1], 0, v[4:5]
	s_mov_b32 s4, 0x9000000
	v_add_co_u32_e32 v4, vcc, s4, v98
	s_mov_b32 s4, 0x9001000
	s_nop 0
	v_addc_co_u32_e32 v5, vcc, 0, v99, vcc
	v_add_co_u32_e32 v8, vcc, s4, v98
	v_lshlrev_b32_e32 v90, 4, v126
	s_nop 0
	v_addc_co_u32_e32 v9, vcc, 0, v99, vcc
	v_cmp_eq_u32_e32 vcc, 63, v126
	global_load_dwordx4 v[58:61], v[4:5], off offset:32
	global_load_dwordx4 v[54:57], v[4:5], off offset:64
	global_load_dwordx4 v[18:21], v[8:9], off offset:-4096
	global_load_dwordx4 v[50:53], v[4:5], off offset:96
	global_load_dwordx4 v[46:49], v[8:9], off
	global_load_dwordx4 v[42:45], v[8:9], off offset:32
	global_load_dwordx4 v[38:41], v[8:9], off offset:64
	global_load_dwordx4 v[34:37], v[8:9], off offset:96
	v_cndmask_b32_e64 v89, 0, 1.0, vcc
	v_cmp_eq_u32_e32 vcc, 62, v126
	v_add_u32_e32 v92, 0x1000, v90
	v_ashrrev_i32_e32 v93, 31, v92
	v_cndmask_b32_e64 v3, 0, 1.0, vcc
	v_cmp_eq_u32_e32 vcc, 61, v126
	v_lshl_add_u64 v[120:121], v[92:93], 1, s[0:1]
	v_add_u32_e32 v92, 0x1400, v90
	v_cndmask_b32_e64 v4, 0, 1.0, vcc
	v_cmp_eq_u32_e32 vcc, 60, v126
	v_ashrrev_i32_e32 v93, 31, v92
	v_lshl_add_u64 v[112:113], v[92:93], 1, s[0:1]
	v_cndmask_b32_e64 v8, 0, 1.0, vcc
	v_cmp_eq_u32_e32 vcc, 59, v126
	v_add_u32_e32 v92, 0x800, v90
	v_ashrrev_i32_e32 v91, 31, v90
	v_cndmask_b32_e64 v5, 0, 1.0, vcc
	v_cmp_eq_u32_e32 vcc, 58, v126
	v_ashrrev_i32_e32 v93, 31, v92
	v_add_u32_e32 v100, 0x1800, v90
	v_cndmask_b32_e64 v9, 0, 1.0, vcc
	v_cmp_eq_u32_e32 vcc, 57, v126
	v_lshl_add_u64 v[108:109], v[92:93], 1, s[0:1]
	v_add_u32_e32 v92, 0xc00, v90
	v_cndmask_b32_e64 v95, 0, 1.0, vcc
	v_cmp_eq_u32_e32 vcc, 56, v126
	s_nop 7
	s_mov_b32 s54, 62
	s_nop 0
	v_readlane_b32 s4, v62, s54
	s_nop 1
	v_fma_f32 v3, -s4, v89, v3
	s_mov_b32 s55, 61
	v_cndmask_b32_e64 v181, 0, 1.0, vcc
	v_cmp_eq_u32_e32 vcc, 55, v126
	v_add_f32_e32 v88, 0, v3
	s_nop 0
	v_readlane_b32 s4, v66, s55
	s_nop 1
	v_fma_f32 v4, -s4, v88, v4
	v_ashrrev_i32_e32 v101, 31, v100
	v_cndmask_b32_e64 v11, 0, 1.0, vcc
	v_cmp_eq_u32_e32 vcc, 54, v126
	s_nop 0
	v_readlane_b32 s4, v62, s55
	s_nop 1
	v_fma_f32 v4, -s4, v89, v4
	v_lshl_add_u64 v[106:107], v[100:101], 1, s[0:1]
	v_ashrrev_i32_e32 v93, 31, v92
	v_cndmask_b32_e64 v97, 0, 1.0, vcc
	v_cmp_eq_u32_e32 vcc, 53, v126
	s_mov_b32 s56, 60
	v_lshl_add_u64 v[102:103], v[92:93], 1, s[0:1]
	v_cndmask_b32_e64 v13, 0, 1.0, vcc
	v_cmp_eq_u32_e32 vcc, 52, v126
	v_mov_b32_e32 v93, v123
	v_mov_b32_e32 v92, v123
	v_cndmask_b32_e64 v105, 0, 1.0, vcc
	v_cmp_eq_u32_e32 vcc, 51, v126
	s_mov_b32 s57, 59
	s_mov_b32 s53, 26
	v_cndmask_b32_e64 v17, 0, 1.0, vcc
	v_cmp_eq_u32_e32 vcc, 50, v126
	s_mov_b32 s58, 58
	v_mov_b32_e32 v94, v123
	v_cndmask_b32_e64 v111, 0, 1.0, vcc
	v_cmp_eq_u32_e32 vcc, 49, v126
	s_mov_b32 s52, 25
	s_mov_b32 s59, 57
	v_cndmask_b32_e64 v23, 0, 1.0, vcc
	v_cmp_eq_u32_e32 vcc, 48, v126
	v_mul_f32_e32 v10, 0x3fb8aa3b, v166
	v_mov_b32_e32 v180, v123
	v_cndmask_b32_e64 v115, 0, 1.0, vcc
	v_cmp_eq_u32_e32 vcc, 47, v126
	v_exp_f32_e32 v10, v10
	s_mov_b32 s51, 24
	v_cndmask_b32_e64 v27, 0, 1.0, vcc
	v_cmp_eq_u32_e32 vcc, 46, v126
	s_mov_b32 s60, 56
	v_mul_f32_e32 v210, v193, v10
	v_cndmask_b32_e64 v117, 0, 1.0, vcc
	v_cmp_eq_u32_e32 vcc, 45, v126
	v_mov_b32_e32 v10, v123
	s_mov_b32 s70, 23
	v_cndmask_b32_e64 v31, 0, 1.0, vcc
	v_cmp_eq_u32_e32 vcc, 44, v126
	s_mov_b32 s61, 55
	v_mov_b32_e32 v96, v123
	v_cndmask_b32_e64 v119, 0, 1.0, vcc
	v_cmp_eq_u32_e32 vcc, 43, v126
	s_mov_b32 s62, 54
	s_mov_b32 s71, 22
	v_cndmask_b32_e64 v33, 0, 1.0, vcc
	v_cmp_eq_u32_e32 vcc, 42, v126
	v_mov_b32_e32 v12, v123
	s_mov_b32 s63, 53
	v_cndmask_b32_e64 v129, 0, 1.0, vcc
	v_cmp_eq_u32_e32 vcc, 41, v126
	s_mov_b32 s72, 21
	v_mov_b32_e32 v104, v123
	v_cndmask_b32_e64 v65, 0, 1.0, vcc
	v_cmp_eq_u32_e32 vcc, 40, v126
	s_mov_b32 s73, 20
	v_mov_b32_e32 v16, v123
	v_cndmask_b32_e64 v131, 0, 1.0, vcc
	v_cmp_eq_u32_e32 vcc, 39, v126
	s_mov_b32 s64, 51
	s_mov_b32 s50, 19
	v_cndmask_b32_e64 v69, 0, 1.0, vcc
	v_cmp_eq_u32_e32 vcc, 38, v126
	v_mov_b32_e32 v110, v123
	s_mov_b32 s49, 18
	v_cndmask_b32_e64 v133, 0, 1.0, vcc
	v_cmp_eq_u32_e32 vcc, 37, v126
	s_mov_b32 s65, 50
	v_mov_b32_e32 v22, v123
	v_cndmask_b32_e64 v73, 0, 1.0, vcc
	v_cmp_eq_u32_e32 vcc, 36, v126
	s_mov_b32 s48, 17
	v_mov_b32_e32 v114, v123
	v_cndmask_b32_e64 v135, 0, 1.0, vcc
	v_cmp_eq_u32_e32 vcc, 35, v126
	s_mov_b32 s47, 16
	v_mov_b32_e32 v26, v123
	v_cndmask_b32_e64 v77, 0, 1.0, vcc
	v_cmp_eq_u32_e32 vcc, 34, v126
	s_mov_b32 s45, 15
	s_mov_b32 s66, 47
	v_cndmask_b32_e64 v137, 0, 1.0, vcc
	v_cmp_eq_u32_e32 vcc, 33, v126
	v_mov_b32_e32 v116, v123
	s_mov_b32 s39, 14
	v_cndmask_b32_e64 v81, 0, 1.0, vcc
	v_cmp_eq_u32_e32 vcc, 32, v126
	v_mov_b32_e32 v30, v123
	s_mov_b32 s38, 13
	v_cndmask_b32_e64 v139, 0, 1.0, vcc
	v_cmp_eq_u32_e32 vcc, 31, v126
	v_mov_b32_e32 v118, v123
	s_mov_b32 s43, 12
	v_cndmask_b32_e64 v153, 0, 1.0, vcc
	v_cmp_eq_u32_e32 vcc, 30, v126
	v_mov_b32_e32 v32, v123
	s_mov_b32 s67, 43
	v_cndmask_b32_e64 v141, 0, 1.0, vcc
	v_cmp_eq_u32_e32 vcc, 29, v126
	s_mov_b32 s42, 11
	v_mov_b32_e32 v128, v123
	v_cndmask_b32_e64 v159, 0, 1.0, vcc
	v_cmp_eq_u32_e32 vcc, 28, v126
	s_mov_b32 s46, 10
	s_lshl_b32 s4, s20, 4
	v_cndmask_b32_e64 v143, 0, 1.0, vcc
	v_cmp_eq_u32_e32 vcc, 27, v126
	v_mov_b32_e32 v64, v123
	s_or_b32 s4, s37, s4
	v_cndmask_b32_e64 v167, 0, 1.0, vcc
	v_cmp_eq_u32_e32 vcc, 26, v126
	s_mov_b32 s37, 9
	v_mov_b32_e32 v130, v123
	v_cndmask_b32_e64 v145, 0, 1.0, vcc
	v_cmp_eq_u32_e32 vcc, 25, v126
	s_mov_b32 s40, 8
	v_mov_b32_e32 v68, v123
	v_cndmask_b32_e64 v171, 0, 1.0, vcc
	v_cmp_eq_u32_e32 vcc, 24, v126
	s_mov_b32 s44, 7
	s_mov_b32 s68, 39
	v_cndmask_b32_e64 v147, 0, 1.0, vcc
	v_cmp_eq_u32_e32 vcc, 23, v126
	v_mov_b32_e32 v132, v123
	v_mov_b32_e32 v72, v123
	v_cndmask_b32_e64 v175, 0, 1.0, vcc
	v_cmp_eq_u32_e32 vcc, 22, v126
	v_mov_b32_e32 v134, v123
	v_mov_b32_e32 v76, v123
	v_cndmask_b32_e64 v149, 0, 1.0, vcc
	v_cmp_eq_u32_e32 vcc, 21, v126
	s_mov_b32 s69, 35
	s_mov_b32 s12, 3
	v_cndmask_b32_e64 v179, 0, 1.0, vcc
	v_cmp_eq_u32_e32 vcc, 20, v126
	v_mov_b32_e32 v136, v123
	v_mov_b32_e32 v80, v123
	v_cndmask_b32_e64 v151, 0, 1.0, vcc
	v_cmp_eq_u32_e32 vcc, 19, v126
	v_mov_b32_e32 v138, v123
	v_mov_b32_e32 v152, v123
	v_cndmask_b32_e64 v177, 0, 1.0, vcc
	v_cmp_eq_u32_e32 vcc, 18, v126
	s_mov_b32 s41, 31
	s_mov_b32 s20, 63
	v_cndmask_b32_e64 v157, 0, 1.0, vcc
	v_cmp_eq_u32_e32 vcc, 17, v126
	v_mov_b32_e32 v158, v123
	v_mov_b32_e32 v166, v123
	v_cndmask_b32_e64 v173, 0, 1.0, vcc
	v_cmp_eq_u32_e32 vcc, 16, v126
	v_mov_b32_e32 v170, v123
	v_mov_b32_e32 v174, v123
	v_cndmask_b32_e64 v165, 0, 1.0, vcc
	v_cmp_eq_u32_e32 vcc, 15, v126
	v_mov_b32_e32 v148, v123
	v_mov_b32_e32 v178, v123
	v_cndmask_b32_e64 v169, 0, 1.0, vcc
	v_cmp_eq_u32_e32 vcc, 14, v126
	v_mov_b32_e32 v150, v123
	v_mov_b32_e32 v176, v123
	v_cndmask_b32_e64 v163, 0, 1.0, vcc
	v_cmp_eq_u32_e32 vcc, 13, v126
	v_mov_b32_e32 v156, v123
	v_mov_b32_e32 v172, v123
	v_cndmask_b32_e64 v161, 0, 1.0, vcc
	v_cmp_eq_u32_e32 vcc, 12, v126
	v_mov_b32_e32 v164, v123
	v_mov_b32_e32 v168, v123
	v_cndmask_b32_e64 v155, 0, 1.0, vcc
	v_cmp_eq_u32_e32 vcc, 11, v126
	v_mov_b32_e32 v162, v123
	v_mov_b32_e32 v160, v123
	v_cndmask_b32_e64 v85, 0, 1.0, vcc
	v_cmp_eq_u32_e32 vcc, 10, v126
	v_mov_b32_e32 v154, v123
	s_ashr_i32 s5, s4, 31
	v_cndmask_b32_e64 v83, 0, 1.0, vcc
	v_cmp_eq_u32_e32 vcc, 9, v126
	s_nop 1
	v_cndmask_b32_e64 v79, 0, 1.0, vcc
	v_cmp_eq_u32_e32 vcc, 8, v126
	s_nop 1
	v_cndmask_b32_e64 v75, 0, 1.0, vcc
	v_cmp_eq_u32_e32 vcc, 7, v126
	s_nop 1
	v_cndmask_b32_e64 v71, 0, 1.0, vcc
	v_cmp_eq_u32_e32 vcc, 6, v126
	s_nop 1
	v_cndmask_b32_e64 v67, 0, 1.0, vcc
	v_cmp_eq_u32_e32 vcc, 5, v126
	s_nop 1
	v_cndmask_b32_e64 v63, 0, 1.0, vcc
	v_cmp_eq_u32_e32 vcc, 4, v126
	s_nop 1
	v_cndmask_b32_e64 v29, 0, 1.0, vcc
	v_cmp_eq_u32_e32 vcc, 3, v126
	s_nop 1
	v_cndmask_b32_e64 v25, 0, 1.0, vcc
	v_cmp_eq_u32_e32 vcc, 2, v126
	s_nop 1
	v_cndmask_b32_e64 v15, 0, 1.0, vcc
	v_cmp_eq_u32_e32 vcc, 1, v126
	s_nop 1
	v_cndmask_b32_e64 v7, 0, 1.0, vcc
	v_cmp_eq_u32_e32 vcc, 0, v126
	v_lshl_add_u64 v[126:127], v[90:91], 1, s[0:1]
	v_add_u32_e32 v90, 0x1c00, v90
	v_ashrrev_i32_e32 v91, 31, v90
	v_lshl_add_u64 v[100:101], v[90:91], 1, s[0:1]
	v_add_f32_e32 v91, 0, v4
	s_nop 0
	v_readlane_b32 s6, v70, s56
	s_nop 1
	v_fma_f32 v8, -s6, v91, v8
	v_mov_b32_e32 v4, v123
	s_nop 0
	v_readlane_b32 s6, v66, s56
	s_nop 1
	v_fma_f32 v8, -s6, v88, v8
	v_cndmask_b32_e64 v3, 0, 1.0, vcc
	s_nop 0
	v_readlane_b32 s6, v62, s56
	s_nop 1
	v_fma_f32 v8, -s6, v89, v8
	s_nop 0
	v_add_f32_e32 v90, 0, v8
	s_nop 0
	v_readlane_b32 s6, v14, s57
	v_readlane_b32 s7, v70, s57
	v_readlane_b32 s8, v66, s57
	v_readlane_b32 s9, v62, s57
	v_fma_f32 v5, -s6, v90, v5
	v_fma_f32 v93, -s7, v91, v93
	v_fma_f32 v92, -s8, v88, v92
	v_fma_f32 v4, -s9, v89, v4
	v_mov_b32_e32 v8, v123
	v_pk_add_f32 v[4:5], v[92:93], v[4:5]
	v_mov_b32_e32 v93, v123
	v_mov_b32_e32 v92, v123
	v_pk_add_f32 v[4:5], v[4:5], v[4:5] op_sel:[0,1] op_sel_hi:[1,0]
	s_nop 0
	s_nop 0
	v_readlane_b32 s6, v62, s53
	v_readlane_b32 s7, v14, s58
	v_readlane_b32 s8, v70, s58
	v_readlane_b32 s9, v66, s58
	v_fma_f32 v9, -s6, v4, v9
	v_fma_f32 v93, -s7, v90, v93
	v_fma_f32 v92, -s8, v91, v92
	v_fma_f32 v8, -s9, v88, v8
	s_nop 0
	s_nop 0
	v_readlane_b32 s6, v62, s58
	s_nop 1
	v_fma_f32 v9, -s6, v89, v9
	s_nop 0
	v_pk_add_f32 v[8:9], v[92:93], v[8:9]
	s_nop 0
	v_pk_add_f32 v[92:93], v[8:9], v[8:9] op_sel:[0,1] op_sel_hi:[1,0]
	v_mov_b32_e32 v9, v123
	v_mov_b32_e32 v8, v123
	s_nop 0
	v_readlane_b32 s6, v66, s52
	v_readlane_b32 s7, v62, s52
	v_readlane_b32 s8, v14, s59
	v_readlane_b32 s9, v70, s59
	v_fma_f32 v95, -s6, v92, v95
	v_fma_f32 v9, -s7, v4, v9
	v_fma_f32 v8, -s8, v90, v8
	v_fma_f32 v94, -s9, v91, v94
	v_mov_b32_e32 v93, v4
	s_nop 0
	v_readlane_b32 s6, v66, s59
	s_nop 1
	v_fma_f32 v95, -s6, v88, v95
	s_nop 0
	s_nop 0
	v_readlane_b32 s6, v62, s59
	s_nop 1
	v_fma_f32 v95, -s6, v89, v95
	s_nop 0
	v_pk_add_f32 v[8:9], v[8:9], v[94:95]
	v_mov_b32_e32 v95, v123
	v_mov_b32_e32 v94, v123
	v_pk_add_f32 v[8:9], v[8:9], v[8:9] op_sel:[0,1] op_sel_hi:[1,0]
	s_nop 0
	s_nop 0
	v_readlane_b32 s6, v70, s51
	v_readlane_b32 s7, v66, s51
	v_readlane_b32 s8, v62, s51
	v_readlane_b32 s9, v14, s60
	v_fma_f32 v181, -s6, v8, v181
	v_fma_f32 v95, -s7, v92, v95
	v_fma_f32 v94, -s8, v4, v94
	v_fma_f32 v180, -s9, v90, v180
	s_nop 0
	s_nop 0
	v_readlane_b32 s6, v70, s60
	s_nop 1
	v_fma_f32 v181, -s6, v91, v181
	s_nop 0
	s_nop 0
	v_readlane_b32 s6, v66, s60
	s_nop 1
	v_fma_f32 v181, -s6, v88, v181
	s_nop 0
	s_nop 0
	v_readlane_b32 s6, v62, s60
	s_nop 1
	v_fma_f32 v181, -s6, v89, v181
	s_nop 0
	v_pk_add_f32 v[94:95], v[94:95], v[180:181]
	v_mov_b32_e32 v181, v123
	v_mov_b32_e32 v180, v123
	v_pk_add_f32 v[94:95], v[94:95], v[94:95] op_sel:[0,1] op_sel_hi:[1,0]
	s_nop 0
	s_nop 0
	v_readlane_b32 s6, v14, s70
	v_readlane_b32 s7, v70, s70
	v_readlane_b32 s8, v66, s70
	v_readlane_b32 s9, v62, s70
	v_fma_f32 v11, -s6, v94, v11
	v_fma_f32 v181, -s7, v8, v181
	v_fma_f32 v180, -s8, v92, v180
	v_fma_f32 v10, -s9, v4, v10
	v_mov_b32_e32 v95, v8
	s_nop 0
	v_readlane_b32 s6, v14, s61
	v_readlane_b32 s7, v70, s61
	v_readlane_b32 s8, v66, s61
	v_readlane_b32 s9, v62, s61
	v_fma_f32 v11, -s6, v90, v11
	v_fma_f32 v181, -s7, v91, v181
	v_fma_f32 v180, -s8, v88, v180
	v_fma_f32 v10, -s9, v89, v10
	s_nop 0
	v_pk_add_f32 v[10:11], v[180:181], v[10:11]
	v_mov_b32_e32 v181, v123
	v_mov_b32_e32 v180, v123
	v_pk_add_f32 v[10:11], v[10:11], v[10:11] op_sel:[0,1] op_sel_hi:[1,0]
	s_nop 0
	s_nop 0
	v_readlane_b32 s6, v74, s62
	v_readlane_b32 s7, v14, s71
	v_readlane_b32 s8, v70, s71
	v_readlane_b32 s9, v66, s71
	v_fma_f32 v97, -s6, v10, v97
	v_fma_f32 v181, -s7, v94, v181
	v_fma_f32 v180, -s8, v8, v180
	v_fma_f32 v96, -s9, v92, v96
	s_nop 0
	s_nop 0
	v_readlane_b32 s6, v62, s71
	v_readlane_b32 s7, v14, s62
	v_readlane_b32 s8, v70, s62
	v_readlane_b32 s9, v66, s62
	v_fma_f32 v97, -s6, v4, v97
	v_fma_f32 v181, -s7, v90, v181
	v_fma_f32 v180, -s8, v91, v180
	v_fma_f32 v96, -s9, v88, v96
	s_nop 0
	s_nop 0
	v_readlane_b32 s6, v62, s62
	s_nop 1
	v_fma_f32 v97, -s6, v89, v97
	s_nop 0
	v_pk_add_f32 v[96:97], v[180:181], v[96:97]
	v_mov_b32_e32 v181, v123
	v_mov_b32_e32 v180, v123
	v_pk_add_f32 v[96:97], v[96:97], v[96:97] op_sel:[0,1] op_sel_hi:[1,0]
	s_nop 0
	s_nop 0
	v_readlane_b32 s6, v28, s63
	v_readlane_b32 s7, v74, s63
	v_readlane_b32 s8, v14, s72
	v_readlane_b32 s9, v70, s72
	v_fma_f32 v13, -s6, v96, v13
	v_fma_f32 v181, -s7, v10, v181
	v_fma_f32 v180, -s8, v94, v180
	v_fma_f32 v12, -s9, v8, v12
	v_mov_b32_e32 v97, v10
	s_nop 0
	v_readlane_b32 s6, v66, s72
	v_readlane_b32 s7, v62, s72
	v_readlane_b32 s8, v14, s63
	v_readlane_b32 s9, v70, s63
	v_fma_f32 v13, -s6, v92, v13
	v_fma_f32 v181, -s7, v4, v181
	v_fma_f32 v180, -s8, v90, v180
	v_fma_f32 v12, -s9, v91, v12
	s_nop 0
	s_nop 0
	v_readlane_b32 s6, v66, s63
	s_nop 1
	v_fma_f32 v13, -s6, v88, v13
	s_nop 0
	s_nop 0
	v_readlane_b32 s6, v62, s63
	s_nop 1
	v_fma_f32 v13, -s6, v89, v13
	s_nop 0
	v_pk_add_f32 v[12:13], v[180:181], v[12:13]
	v_mov_b32_e32 v181, v123
	v_mov_b32_e32 v180, v123
	v_pk_add_f32 v[12:13], v[12:13], v[12:13] op_sel:[0,1] op_sel_hi:[1,0]
	s_nop 0
	s_nop 0
	v_readlane_b32 s6, v78, s22
	v_readlane_b32 s7, v28, s22
	v_readlane_b32 s8, v74, s22
	v_readlane_b32 s9, v14, s73
	v_fma_f32 v105, -s6, v12, v105
	v_fma_f32 v181, -s7, v96, v181
	v_fma_f32 v180, -s8, v10, v180
	v_fma_f32 v104, -s9, v94, v104
	s_nop 0
	s_nop 0
	v_readlane_b32 s6, v70, s73
	v_readlane_b32 s7, v66, s73
	v_readlane_b32 s8, v62, s73
	v_readlane_b32 s9, v14, s22
	v_fma_f32 v105, -s6, v8, v105
	v_fma_f32 v181, -s7, v92, v181
	v_fma_f32 v180, -s8, v4, v180
	v_fma_f32 v104, -s9, v90, v104
	s_nop 0
	s_nop 0
	v_readlane_b32 s6, v70, s22
	s_nop 1
	v_fma_f32 v105, -s6, v91, v105
	s_nop 0
	s_nop 0
	v_readlane_b32 s6, v66, s22
	s_nop 1
	v_fma_f32 v105, -s6, v88, v105
	s_nop 0
	s_nop 0
	v_readlane_b32 s6, v62, s22
	s_nop 1
	v_fma_f32 v105, -s6, v89, v105
	s_nop 0
	v_pk_add_f32 v[104:105], v[180:181], v[104:105]
	v_mov_b32_e32 v181, v123
	v_mov_b32_e32 v180, v123
	v_pk_add_f32 v[104:105], v[104:105], v[104:105] op_sel:[0,1] op_sel_hi:[1,0]
	s_nop 0
	s_nop 0
	v_readlane_b32 s6, v82, s64
	v_readlane_b32 s7, v78, s64
	v_readlane_b32 s8, v28, s64
	v_readlane_b32 s9, v74, s64
	v_fma_f32 v17, -s6, v104, v17
	v_fma_f32 v181, -s7, v12, v181
	v_fma_f32 v180, -s8, v96, v180
	v_fma_f32 v16, -s9, v10, v16
	v_mov_b32_e32 v105, v12
	s_nop 0
	v_readlane_b32 s6, v14, s50
	v_readlane_b32 s7, v70, s50
	v_readlane_b32 s8, v66, s50
	v_readlane_b32 s9, v62, s50
	v_fma_f32 v17, -s6, v94, v17
	v_fma_f32 v181, -s7, v8, v181
	v_fma_f32 v180, -s8, v92, v180
	v_fma_f32 v16, -s9, v4, v16
	s_nop 0
	s_nop 0
	v_readlane_b32 s6, v14, s64
	v_readlane_b32 s7, v70, s64
	v_readlane_b32 s8, v66, s64
	v_readlane_b32 s9, v62, s64
	v_fma_f32 v17, -s6, v90, v17
	v_fma_f32 v181, -s7, v91, v181
	v_fma_f32 v180, -s8, v88, v180
	v_fma_f32 v16, -s9, v89, v16
	s_nop 0
	v_pk_add_f32 v[16:17], v[180:181], v[16:17]
	v_mov_b32_e32 v181, v123
	v_mov_b32_e32 v180, v123
	v_pk_add_f32 v[16:17], v[16:17], v[16:17] op_sel:[0,1] op_sel_hi:[1,0]
	s_nop 0
	s_nop 0
	v_readlane_b32 s6, v74, s49
	v_readlane_b32 s7, v82, s65
	v_readlane_b32 s8, v78, s65
	v_readlane_b32 s9, v28, s65
	v_fma_f32 v111, -s6, v16, v111
	v_fma_f32 v181, -s7, v104, v181
	v_fma_f32 v180, -s8, v12, v180
	v_fma_f32 v110, -s9, v96, v110
	s_nop 0
	s_nop 0
	v_readlane_b32 s6, v74, s65
	v_readlane_b32 s7, v14, s49
	v_readlane_b32 s8, v70, s49
	v_readlane_b32 s9, v66, s49
	v_fma_f32 v111, -s6, v10, v111
	v_fma_f32 v181, -s7, v94, v181
	v_fma_f32 v180, -s8, v8, v180
	v_fma_f32 v110, -s9, v92, v110
	s_nop 0
	s_nop 0
	v_readlane_b32 s6, v62, s49
	v_readlane_b32 s7, v14, s65
	v_readlane_b32 s8, v70, s65
	v_readlane_b32 s9, v66, s65
	v_fma_f32 v111, -s6, v4, v111
	v_fma_f32 v181, -s7, v90, v181
	v_fma_f32 v180, -s8, v91, v180
	v_fma_f32 v110, -s9, v88, v110
	s_nop 0
	s_nop 0
	v_readlane_b32 s6, v62, s65
	s_nop 1
	v_fma_f32 v111, -s6, v89, v111
	s_nop 0
	v_pk_add_f32 v[110:111], v[180:181], v[110:111]
	v_mov_b32_e32 v181, v123
	v_mov_b32_e32 v180, v123
	v_pk_add_f32 v[110:111], v[110:111], v[110:111] op_sel:[0,1] op_sel_hi:[1,0]
	s_nop 0
	s_nop 0
	v_readlane_b32 s6, v28, s48
	v_readlane_b32 s7, v74, s48
	v_readlane_b32 s8, v82, s21
	v_readlane_b32 s9, v78, s21
	v_fma_f32 v23, -s6, v110, v23
	v_fma_f32 v181, -s7, v16, v181
	v_fma_f32 v180, -s8, v104, v180
	v_fma_f32 v22, -s9, v12, v22
	v_mov_b32_e32 v111, v16
	s_nop 0
	v_readlane_b32 s6, v28, s21
	v_readlane_b32 s7, v74, s21
	v_readlane_b32 s8, v14, s48
	v_readlane_b32 s9, v70, s48
	v_fma_f32 v23, -s6, v96, v23
	v_fma_f32 v181, -s7, v10, v181
	v_fma_f32 v180, -s8, v94, v180
	v_fma_f32 v22, -s9, v8, v22
	s_nop 0
	s_nop 0
	v_readlane_b32 s6, v66, s48
	v_readlane_b32 s7, v62, s48
	v_readlane_b32 s8, v14, s21
	v_readlane_b32 s9, v70, s21
	v_fma_f32 v23, -s6, v92, v23
	v_fma_f32 v181, -s7, v4, v181
	v_fma_f32 v180, -s8, v90, v180
	v_fma_f32 v22, -s9, v91, v22
	s_nop 0
	s_nop 0
	v_readlane_b32 s6, v66, s21
	s_nop 1
	v_fma_f32 v23, -s6, v88, v23
	s_nop 0
	s_nop 0
	v_readlane_b32 s6, v62, s21
	s_nop 1
	v_fma_f32 v23, -s6, v89, v23
	s_nop 0
	v_pk_add_f32 v[22:23], v[180:181], v[22:23]
	v_mov_b32_e32 v181, v123
	v_mov_b32_e32 v180, v123
	v_pk_add_f32 v[22:23], v[22:23], v[22:23] op_sel:[0,1] op_sel_hi:[1,0]
	s_nop 0
	s_nop 0
	v_readlane_b32 s6, v78, s47
	v_readlane_b32 s7, v28, s47
	v_readlane_b32 s8, v74, s47
	v_readlane_b32 s9, v82, s34
	v_fma_f32 v115, -s6, v22, v115
	v_fma_f32 v181, -s7, v110, v181
	v_fma_f32 v180, -s8, v16, v180
	v_fma_f32 v114, -s9, v104, v114
	s_nop 0
	s_nop 0
	v_readlane_b32 s6, v78, s34
	v_readlane_b32 s7, v28, s34
	v_readlane_b32 s8, v74, s34
	v_readlane_b32 s9, v14, s47
	v_fma_f32 v115, -s6, v12, v115
	v_fma_f32 v181, -s7, v96, v181
	v_fma_f32 v180, -s8, v10, v180
	v_fma_f32 v114, -s9, v94, v114
	s_nop 0
	s_nop 0
	v_readlane_b32 s6, v70, s47
	v_readlane_b32 s7, v66, s47
	v_readlane_b32 s8, v62, s47
	v_readlane_b32 s9, v14, s34
	v_fma_f32 v115, -s6, v8, v115
	v_fma_f32 v181, -s7, v92, v181
	v_fma_f32 v180, -s8, v4, v180
	v_fma_f32 v114, -s9, v90, v114
	s_nop 0
	s_nop 0
	v_readlane_b32 s6, v70, s34
	s_nop 1
	v_fma_f32 v115, -s6, v91, v115
	s_nop 0
	s_nop 0
	v_readlane_b32 s6, v66, s34
	s_nop 1
	v_fma_f32 v115, -s6, v88, v115
	s_nop 0
	s_nop 0
	v_readlane_b32 s6, v62, s34
	s_nop 1
	v_fma_f32 v115, -s6, v89, v115
	s_nop 0
	v_pk_add_f32 v[114:115], v[180:181], v[114:115]
	v_mov_b32_e32 v181, v123
	v_mov_b32_e32 v180, v123
	v_pk_add_f32 v[114:115], v[114:115], v[114:115] op_sel:[0,1] op_sel_hi:[1,0]
	s_nop 0
	s_nop 0
	v_readlane_b32 s6, v82, s45
	v_readlane_b32 s7, v78, s45
	v_readlane_b32 s8, v28, s45
	v_readlane_b32 s9, v74, s45
	v_fma_f32 v27, -s6, v114, v27
	v_fma_f32 v181, -s7, v22, v181
	v_fma_f32 v180, -s8, v110, v180
	v_fma_f32 v26, -s9, v16, v26
	v_mov_b32_e32 v115, v22
	s_nop 0
	v_readlane_b32 s6, v82, s66
	v_readlane_b32 s7, v78, s66
	v_readlane_b32 s8, v28, s66
	v_readlane_b32 s9, v74, s66
	v_fma_f32 v27, -s6, v104, v27
	v_fma_f32 v181, -s7, v12, v181
	v_fma_f32 v180, -s8, v96, v180
	v_fma_f32 v26, -s9, v10, v26
	s_nop 0
	s_nop 0
	v_readlane_b32 s6, v14, s45
	v_readlane_b32 s7, v70, s45
	v_readlane_b32 s8, v66, s45
	v_readlane_b32 s9, v62, s45
	v_fma_f32 v27, -s6, v94, v27
	v_fma_f32 v181, -s7, v8, v181
	v_fma_f32 v180, -s8, v92, v180
	v_fma_f32 v26, -s9, v4, v26
	s_nop 0
	s_nop 0
	v_readlane_b32 s6, v14, s66
	v_readlane_b32 s7, v70, s66
	v_readlane_b32 s8, v66, s66
	v_readlane_b32 s9, v62, s66
	v_fma_f32 v27, -s6, v90, v27
	v_fma_f32 v181, -s7, v91, v181
	v_fma_f32 v180, -s8, v88, v180
	v_fma_f32 v26, -s9, v89, v26
	s_nop 0
	v_pk_add_f32 v[26:27], v[180:181], v[26:27]
	v_mov_b32_e32 v181, v123
	v_mov_b32_e32 v180, v123
	v_pk_add_f32 v[26:27], v[26:27], v[26:27] op_sel:[0,1] op_sel_hi:[1,0]
	s_nop 0
	s_nop 0
	v_readlane_b32 s6, v84, s14
	v_readlane_b32 s7, v82, s39
	v_readlane_b32 s8, v78, s39
	v_readlane_b32 s9, v28, s39
	v_fma_f32 v117, -s6, v26, v117
	v_fma_f32 v181, -s7, v114, v181
	v_fma_f32 v180, -s8, v22, v180
	v_fma_f32 v116, -s9, v110, v116
	s_nop 0
	s_nop 0
	v_readlane_b32 s6, v74, s39
	v_readlane_b32 s7, v82, s14
	v_readlane_b32 s8, v78, s14
	v_readlane_b32 s9, v28, s14
	v_fma_f32 v117, -s6, v16, v117
	v_fma_f32 v181, -s7, v104, v181
	v_fma_f32 v180, -s8, v12, v180
	v_fma_f32 v116, -s9, v96, v116
	s_nop 0
	s_nop 0
	v_readlane_b32 s6, v74, s14
	v_readlane_b32 s7, v14, s39
	v_readlane_b32 s8, v70, s39
	v_readlane_b32 s9, v66, s39
	v_fma_f32 v117, -s6, v10, v117
	v_fma_f32 v181, -s7, v94, v181
	v_fma_f32 v180, -s8, v8, v180
	v_fma_f32 v116, -s9, v92, v116
	s_nop 0
	s_nop 0
	v_readlane_b32 s6, v62, s39
	v_readlane_b32 s7, v14, s14
	v_readlane_b32 s8, v70, s14
	v_readlane_b32 s9, v66, s14
	v_fma_f32 v117, -s6, v4, v117
	v_fma_f32 v181, -s7, v90, v181
	v_fma_f32 v180, -s8, v91, v180
	v_fma_f32 v116, -s9, v88, v116
	s_nop 0
	s_nop 0
	v_readlane_b32 s6, v62, s14
	s_nop 1
	v_fma_f32 v117, -s6, v89, v117
	s_nop 0
	v_pk_add_f32 v[116:117], v[180:181], v[116:117]
	v_mov_b32_e32 v181, v123
	v_mov_b32_e32 v180, v123
	v_pk_add_f32 v[116:117], v[116:117], v[116:117] op_sel:[0,1] op_sel_hi:[1,0]
	s_nop 0
	s_nop 0
	v_readlane_b32 s6, v24, s11
	v_readlane_b32 s7, v84, s11
	v_readlane_b32 s8, v82, s38
	v_readlane_b32 s9, v78, s38
	v_fma_f32 v31, -s6, v116, v31
	v_fma_f32 v181, -s7, v26, v181
	v_fma_f32 v180, -s8, v114, v180
	v_fma_f32 v30, -s9, v22, v30
	v_mov_b32_e32 v117, v26
	s_nop 0
	v_readlane_b32 s6, v28, s38
	v_readlane_b32 s7, v74, s38
	v_readlane_b32 s8, v82, s11
	v_readlane_b32 s9, v78, s11
	v_fma_f32 v31, -s6, v110, v31
	v_fma_f32 v181, -s7, v16, v181
	v_fma_f32 v180, -s8, v104, v180
	v_fma_f32 v30, -s9, v12, v30
	s_nop 0
	s_nop 0
	v_readlane_b32 s6, v28, s11
	v_readlane_b32 s7, v74, s11
	v_readlane_b32 s8, v14, s38
	v_readlane_b32 s9, v70, s38
	v_fma_f32 v31, -s6, v96, v31
	v_fma_f32 v181, -s7, v10, v181
	v_fma_f32 v180, -s8, v94, v180
	v_fma_f32 v30, -s9, v8, v30
	s_nop 0
	s_nop 0
	v_readlane_b32 s6, v66, s38
	v_readlane_b32 s7, v62, s38
	v_readlane_b32 s8, v14, s11
	v_readlane_b32 s9, v70, s11
	v_fma_f32 v31, -s6, v92, v31
	v_fma_f32 v181, -s7, v4, v181
	v_fma_f32 v180, -s8, v90, v180
	v_fma_f32 v30, -s9, v91, v30
	s_nop 0
	s_nop 0
	v_readlane_b32 s6, v66, s11
	s_nop 1
	v_fma_f32 v31, -s6, v88, v31
	s_nop 0
	s_nop 0
	v_readlane_b32 s6, v62, s11
	s_nop 1
	v_fma_f32 v31, -s6, v89, v31
	s_nop 0
	v_pk_add_f32 v[30:31], v[180:181], v[30:31]
	v_mov_b32_e32 v181, v123
	v_mov_b32_e32 v180, v123
	v_pk_add_f32 v[30:31], v[30:31], v[30:31] op_sel:[0,1] op_sel_hi:[1,0]
	s_nop 0
	s_nop 0
	v_readlane_b32 s6, v142, s27
	v_readlane_b32 s7, v24, s27
	v_readlane_b32 s8, v84, s27
	v_readlane_b32 s9, v82, s43
	v_fma_f32 v119, -s6, v30, v119
	v_fma_f32 v181, -s7, v116, v181
	v_fma_f32 v180, -s8, v26, v180
	v_fma_f32 v118, -s9, v114, v118
	s_nop 0
	s_nop 0
	v_readlane_b32 s6, v78, s43
	v_readlane_b32 s7, v28, s43
	v_readlane_b32 s8, v74, s43
	v_readlane_b32 s9, v82, s27
	v_fma_f32 v119, -s6, v22, v119
	v_fma_f32 v181, -s7, v110, v181
	v_fma_f32 v180, -s8, v16, v180
	v_fma_f32 v118, -s9, v104, v118
	s_nop 0
	s_nop 0
	v_readlane_b32 s6, v78, s27
	v_readlane_b32 s7, v28, s27
	v_readlane_b32 s8, v74, s27
	v_readlane_b32 s9, v14, s43
	v_fma_f32 v119, -s6, v12, v119
	v_fma_f32 v181, -s7, v96, v181
	v_fma_f32 v180, -s8, v10, v180
	v_fma_f32 v118, -s9, v94, v118
	s_nop 0
	s_nop 0
	v_readlane_b32 s6, v70, s43
	v_readlane_b32 s7, v66, s43
	v_readlane_b32 s8, v62, s43
	v_readlane_b32 s9, v14, s27
	v_fma_f32 v119, -s6, v8, v119
	v_fma_f32 v181, -s7, v92, v181
	v_fma_f32 v180, -s8, v4, v180
	v_fma_f32 v118, -s9, v90, v118
	s_nop 0
	s_nop 0
	v_readlane_b32 s6, v70, s27
	s_nop 1
	v_fma_f32 v119, -s6, v91, v119
	s_nop 0
	s_nop 0
	v_readlane_b32 s6, v66, s27
	s_nop 1
	v_fma_f32 v119, -s6, v88, v119
	s_nop 0
	s_nop 0
	v_readlane_b32 s6, v62, s27
	s_nop 1
	v_fma_f32 v119, -s6, v89, v119
	s_nop 0
	v_pk_add_f32 v[118:119], v[180:181], v[118:119]
	v_mov_b32_e32 v181, v123
	v_mov_b32_e32 v180, v123
	v_pk_add_f32 v[118:119], v[118:119], v[118:119] op_sel:[0,1] op_sel_hi:[1,0]
	s_nop 0
	s_nop 0
	v_readlane_b32 s6, v6, s67
	v_readlane_b32 s7, v142, s67
	v_readlane_b32 s8, v24, s67
	v_readlane_b32 s9, v84, s67
	v_fma_f32 v33, -s6, v118, v33
	v_fma_f32 v181, -s7, v30, v181
	v_fma_f32 v180, -s8, v116, v180
	v_fma_f32 v32, -s9, v26, v32
	v_mov_b32_e32 v119, v30
	s_nop 0
	v_readlane_b32 s6, v82, s42
	v_readlane_b32 s7, v78, s42
	v_readlane_b32 s8, v28, s42
	v_readlane_b32 s9, v74, s42
	v_fma_f32 v33, -s6, v114, v33
	v_fma_f32 v181, -s7, v22, v181
	v_fma_f32 v180, -s8, v110, v180
	v_fma_f32 v32, -s9, v16, v32
	s_nop 0
	s_nop 0
	v_readlane_b32 s6, v82, s67
	v_readlane_b32 s7, v78, s67
	v_readlane_b32 s8, v28, s67
	v_readlane_b32 s9, v74, s67
	v_fma_f32 v33, -s6, v104, v33
	v_fma_f32 v181, -s7, v12, v181
	v_fma_f32 v180, -s8, v96, v180
	v_fma_f32 v32, -s9, v10, v32
	s_nop 0
	s_nop 0
	v_readlane_b32 s6, v14, s42
	v_readlane_b32 s7, v70, s42
	v_readlane_b32 s8, v66, s42
	v_readlane_b32 s9, v62, s42
	v_fma_f32 v33, -s6, v94, v33
	v_fma_f32 v181, -s7, v8, v181
	v_fma_f32 v180, -s8, v92, v180
	v_fma_f32 v32, -s9, v4, v32
	s_nop 0
	s_nop 0
	v_readlane_b32 s6, v14, s67
	v_readlane_b32 s7, v70, s67
	v_readlane_b32 s8, v66, s67
	v_readlane_b32 s9, v62, s67
	v_fma_f32 v33, -s6, v90, v33
	v_fma_f32 v181, -s7, v91, v181
	v_fma_f32 v180, -s8, v88, v180
	v_fma_f32 v32, -s9, v89, v32
	s_nop 0
	v_pk_add_f32 v[32:33], v[180:181], v[32:33]
	v_mov_b32_e32 v181, v123
	v_mov_b32_e32 v180, v123
	v_pk_add_f32 v[32:33], v[32:33], v[32:33] op_sel:[0,1] op_sel_hi:[1,0]
	s_nop 0
	s_nop 0
	v_readlane_b32 s6, v84, s46
	v_readlane_b32 s7, v6, s2
	v_readlane_b32 s8, v142, s2
	v_readlane_b32 s9, v24, s2
	v_fma_f32 v129, -s6, v32, v129
	v_fma_f32 v181, -s7, v118, v181
	v_fma_f32 v180, -s8, v30, v180
	v_fma_f32 v128, -s9, v116, v128
	s_nop 0
	s_nop 0
	v_readlane_b32 s6, v84, s2
	v_readlane_b32 s7, v82, s46
	v_readlane_b32 s8, v78, s46
	v_readlane_b32 s9, v28, s46
	v_fma_f32 v129, -s6, v26, v129
	v_fma_f32 v181, -s7, v114, v181
	v_fma_f32 v180, -s8, v22, v180
	v_fma_f32 v128, -s9, v110, v128
	s_nop 0
	s_nop 0
	v_readlane_b32 s6, v74, s46
	v_readlane_b32 s7, v82, s2
	v_readlane_b32 s8, v78, s2
	v_readlane_b32 s9, v28, s2
	v_fma_f32 v129, -s6, v16, v129
	v_fma_f32 v181, -s7, v104, v181
	v_fma_f32 v180, -s8, v12, v180
	v_fma_f32 v128, -s9, v96, v128
	s_nop 0
	s_nop 0
	v_readlane_b32 s6, v74, s2
	v_readlane_b32 s7, v14, s46
	v_readlane_b32 s8, v70, s46
	v_readlane_b32 s9, v66, s46
	v_fma_f32 v129, -s6, v10, v129
	v_fma_f32 v181, -s7, v94, v181
	v_fma_f32 v180, -s8, v8, v180
	v_fma_f32 v128, -s9, v92, v128
	s_nop 0
	s_nop 0
	v_readlane_b32 s6, v62, s46
	v_readlane_b32 s7, v14, s2
	v_readlane_b32 s8, v70, s2
	v_readlane_b32 s9, v66, s2
	v_fma_f32 v129, -s6, v4, v129
	v_fma_f32 v181, -s7, v90, v181
	v_fma_f32 v180, -s8, v91, v180
	v_fma_f32 v128, -s9, v88, v128
	s_nop 0
	s_nop 0
	v_readlane_b32 s6, v62, s2
	s_nop 1
	v_fma_f32 v129, -s6, v89, v129
	s_nop 0
	v_pk_add_f32 v[128:129], v[180:181], v[128:129]
	v_mov_b32_e32 v181, v123
	v_mov_b32_e32 v180, v123
	v_pk_add_f32 v[128:129], v[128:129], v[128:129] op_sel:[0,1] op_sel_hi:[1,0]
	s_nop 0
	s_nop 0
	v_readlane_b32 s6, v24, s37
	v_readlane_b32 s7, v84, s37
	v_readlane_b32 s8, v6, s18
	v_readlane_b32 s9, v142, s18
	v_fma_f32 v65, -s6, v128, v65
	v_fma_f32 v181, -s7, v32, v181
	v_fma_f32 v180, -s8, v118, v180
	v_fma_f32 v64, -s9, v30, v64
	v_mov_b32_e32 v129, v32
	s_nop 0
	v_readlane_b32 s6, v24, s18
	v_readlane_b32 s7, v84, s18
	v_readlane_b32 s8, v82, s37
	v_readlane_b32 s9, v78, s37
	v_fma_f32 v65, -s6, v116, v65
	v_fma_f32 v181, -s7, v26, v181
	v_fma_f32 v180, -s8, v114, v180
	v_fma_f32 v64, -s9, v22, v64
	s_nop 0
	s_nop 0
	v_readlane_b32 s6, v28, s37
	v_readlane_b32 s7, v74, s37
	v_readlane_b32 s8, v82, s18
	v_readlane_b32 s9, v78, s18
	v_fma_f32 v65, -s6, v110, v65
	v_fma_f32 v181, -s7, v16, v181
	v_fma_f32 v180, -s8, v104, v180
	v_fma_f32 v64, -s9, v12, v64
	s_nop 0
	s_nop 0
	v_readlane_b32 s6, v28, s18
	v_readlane_b32 s7, v74, s18
	v_readlane_b32 s8, v14, s37
	v_readlane_b32 s9, v70, s37
	v_fma_f32 v65, -s6, v96, v65
	v_fma_f32 v181, -s7, v10, v181
	v_fma_f32 v180, -s8, v94, v180
	v_fma_f32 v64, -s9, v8, v64
	s_nop 0
	s_nop 0
	v_readlane_b32 s6, v66, s37
	v_readlane_b32 s7, v62, s37
	v_readlane_b32 s8, v14, s18
	v_readlane_b32 s9, v70, s18
	v_fma_f32 v65, -s6, v92, v65
	v_fma_f32 v181, -s7, v4, v181
	v_fma_f32 v180, -s8, v90, v180
	v_fma_f32 v64, -s9, v91, v64
	s_nop 0
	s_nop 0
	v_readlane_b32 s6, v66, s18
	s_nop 1
	v_fma_f32 v65, -s6, v88, v65
	s_nop 0
	s_nop 0
	v_readlane_b32 s6, v62, s18
	s_nop 1
	v_fma_f32 v65, -s6, v89, v65
	s_nop 0
	v_pk_add_f32 v[64:65], v[180:181], v[64:65]
	v_mov_b32_e32 v181, v123
	v_mov_b32_e32 v180, v123
	v_pk_add_f32 v[64:65], v[64:65], v[64:65] op_sel:[0,1] op_sel_hi:[1,0]
	s_nop 0
	s_nop 0
	v_readlane_b32 s6, v142, s40
	v_readlane_b32 s7, v24, s40
	v_readlane_b32 s8, v84, s40
	v_readlane_b32 s9, v6, s19
	v_fma_f32 v131, -s6, v64, v131
	v_fma_f32 v181, -s7, v128, v181
	v_fma_f32 v180, -s8, v32, v180
	v_fma_f32 v130, -s9, v118, v130
	s_nop 0
	s_nop 0
	v_readlane_b32 s6, v142, s19
	v_readlane_b32 s7, v24, s19
	v_readlane_b32 s8, v84, s19
	v_readlane_b32 s9, v82, s40
	v_fma_f32 v131, -s6, v30, v131
	v_fma_f32 v181, -s7, v116, v181
	v_fma_f32 v180, -s8, v26, v180
	v_fma_f32 v130, -s9, v114, v130
	s_nop 0
	s_nop 0
	v_readlane_b32 s6, v78, s40
	v_readlane_b32 s7, v28, s40
	v_readlane_b32 s8, v74, s40
	v_readlane_b32 s9, v82, s19
	v_fma_f32 v131, -s6, v22, v131
	v_fma_f32 v181, -s7, v110, v181
	v_fma_f32 v180, -s8, v16, v180
	v_fma_f32 v130, -s9, v104, v130
	s_nop 0
	s_nop 0
	v_readlane_b32 s6, v78, s19
	v_readlane_b32 s7, v28, s19
	v_readlane_b32 s8, v74, s19
	v_readlane_b32 s9, v14, s40
	v_fma_f32 v131, -s6, v12, v131
	v_fma_f32 v181, -s7, v96, v181
	v_fma_f32 v180, -s8, v10, v180
	v_fma_f32 v130, -s9, v94, v130
	s_nop 0
	s_nop 0
	v_readlane_b32 s6, v70, s40
	v_readlane_b32 s7, v66, s40
	v_readlane_b32 s8, v62, s40
	v_readlane_b32 s9, v14, s19
	v_fma_f32 v131, -s6, v8, v131
	v_fma_f32 v181, -s7, v92, v181
	v_fma_f32 v180, -s8, v4, v180
	v_fma_f32 v130, -s9, v90, v130
	s_nop 0
	s_nop 0
	v_readlane_b32 s6, v70, s19
	s_nop 1
	v_fma_f32 v131, -s6, v91, v131
	s_nop 0
	s_nop 0
	v_readlane_b32 s6, v66, s19
	s_nop 1
	v_fma_f32 v131, -s6, v88, v131
	s_nop 0
	s_nop 0
	v_readlane_b32 s6, v62, s19
	s_nop 1
	v_fma_f32 v131, -s6, v89, v131
	s_nop 0
	v_pk_add_f32 v[130:131], v[180:181], v[130:131]
	v_mov_b32_e32 v181, v123
	v_mov_b32_e32 v180, v123
	v_pk_add_f32 v[130:131], v[130:131], v[130:131] op_sel:[0,1] op_sel_hi:[1,0]
	s_nop 0
	s_nop 0
	v_readlane_b32 s6, v6, s44
	v_readlane_b32 s7, v142, s44
	v_readlane_b32 s8, v24, s44
	v_readlane_b32 s9, v84, s44
	v_fma_f32 v69, -s6, v130, v69
	v_fma_f32 v181, -s7, v64, v181
	v_fma_f32 v180, -s8, v128, v180
	v_fma_f32 v68, -s9, v32, v68
	v_mov_b32_e32 v131, v64
	s_nop 0
	v_readlane_b32 s6, v6, s68
	v_readlane_b32 s7, v142, s68
	v_readlane_b32 s8, v24, s68
	v_readlane_b32 s9, v84, s68
	v_fma_f32 v69, -s6, v118, v69
	v_fma_f32 v181, -s7, v30, v181
	v_fma_f32 v180, -s8, v116, v180
	v_fma_f32 v68, -s9, v26, v68
	s_nop 0
	s_nop 0
	v_readlane_b32 s6, v82, s44
	v_readlane_b32 s7, v78, s44
	v_readlane_b32 s8, v28, s44
	v_readlane_b32 s9, v74, s44
	v_fma_f32 v69, -s6, v114, v69
	v_fma_f32 v181, -s7, v22, v181
	v_fma_f32 v180, -s8, v110, v180
	v_fma_f32 v68, -s9, v16, v68
	s_nop 0
	s_nop 0
	v_readlane_b32 s6, v82, s68
	v_readlane_b32 s7, v78, s68
	v_readlane_b32 s8, v28, s68
	v_readlane_b32 s9, v74, s68
	v_fma_f32 v69, -s6, v104, v69
	v_fma_f32 v181, -s7, v12, v181
	v_fma_f32 v180, -s8, v96, v180
	v_fma_f32 v68, -s9, v10, v68
	s_nop 0
	s_nop 0
	v_readlane_b32 s6, v14, s44
	v_readlane_b32 s7, v70, s44
	v_readlane_b32 s8, v66, s44
	v_readlane_b32 s9, v62, s44
	v_fma_f32 v69, -s6, v94, v69
	v_fma_f32 v181, -s7, v8, v181
	v_fma_f32 v180, -s8, v92, v180
	v_fma_f32 v68, -s9, v4, v68
	s_nop 0
	s_nop 0
	v_readlane_b32 s6, v14, s68
	v_readlane_b32 s7, v70, s68
	v_readlane_b32 s8, v66, s68
	v_readlane_b32 s9, v62, s68
	v_fma_f32 v69, -s6, v90, v69
	v_fma_f32 v181, -s7, v91, v181
	v_fma_f32 v180, -s8, v88, v180
	v_fma_f32 v68, -s9, v89, v68
	s_nop 0
	v_pk_add_f32 v[68:69], v[180:181], v[68:69]
	v_mov_b32_e32 v181, v123
	v_mov_b32_e32 v180, v123
	v_pk_add_f32 v[68:69], v[68:69], v[68:69] op_sel:[0,1] op_sel_hi:[1,0]
	s_nop 0
	s_nop 0
	v_readlane_b32 s6, v140, s3
	v_readlane_b32 s7, v6, s35
	v_readlane_b32 s8, v142, s35
	v_readlane_b32 s9, v24, s35
	v_fma_f32 v133, -s6, v68, v133
	v_fma_f32 v181, -s7, v130, v181
	v_fma_f32 v180, -s8, v64, v180
	v_fma_f32 v132, -s9, v128, v132
	s_nop 0
	s_nop 0
	v_readlane_b32 s6, v84, s35
	v_readlane_b32 s7, v6, s3
	v_readlane_b32 s8, v142, s3
	v_readlane_b32 s9, v24, s3
	v_fma_f32 v133, -s6, v32, v133
	v_fma_f32 v181, -s7, v118, v181
	v_fma_f32 v180, -s8, v30, v180
	v_fma_f32 v132, -s9, v116, v132
	s_nop 0
	s_nop 0
	v_readlane_b32 s6, v84, s3
	v_readlane_b32 s7, v82, s35
	v_readlane_b32 s8, v78, s35
	v_readlane_b32 s9, v28, s35
	v_fma_f32 v133, -s6, v26, v133
	v_fma_f32 v181, -s7, v114, v181
	v_fma_f32 v180, -s8, v22, v180
	v_fma_f32 v132, -s9, v110, v132
	s_nop 0
	s_nop 0
	v_readlane_b32 s6, v74, s35
	v_readlane_b32 s7, v82, s3
	v_readlane_b32 s8, v78, s3
	v_readlane_b32 s9, v28, s3
	v_fma_f32 v133, -s6, v16, v133
	v_fma_f32 v181, -s7, v104, v181
	v_fma_f32 v180, -s8, v12, v180
	v_fma_f32 v132, -s9, v96, v132
	s_nop 0
	s_nop 0
	v_readlane_b32 s6, v74, s3
	v_readlane_b32 s7, v14, s35
	v_readlane_b32 s8, v70, s35
	v_readlane_b32 s9, v66, s35
	v_fma_f32 v133, -s6, v10, v133
	v_fma_f32 v181, -s7, v94, v181
	v_fma_f32 v180, -s8, v8, v180
	v_fma_f32 v132, -s9, v92, v132
	s_nop 0
	s_nop 0
	v_readlane_b32 s6, v62, s35
	v_readlane_b32 s7, v14, s3
	v_readlane_b32 s8, v70, s3
	v_readlane_b32 s9, v66, s3
	v_fma_f32 v133, -s6, v4, v133
	v_fma_f32 v181, -s7, v90, v181
	v_fma_f32 v180, -s8, v91, v180
	v_fma_f32 v132, -s9, v88, v132
	s_nop 0
	s_nop 0
	v_readlane_b32 s6, v62, s3
	s_nop 1
	v_fma_f32 v133, -s6, v89, v133
	s_nop 0
	v_pk_add_f32 v[132:133], v[180:181], v[132:133]
	v_mov_b32_e32 v181, v123
	v_mov_b32_e32 v180, v123
	v_pk_add_f32 v[132:133], v[132:133], v[132:133] op_sel:[0,1] op_sel_hi:[1,0]
	s_nop 0
	s_nop 0
	v_readlane_b32 s6, v144, s16
	v_readlane_b32 s7, v140, s16
	v_readlane_b32 s8, v6, s30
	v_readlane_b32 s9, v142, s30
	v_fma_f32 v73, -s6, v132, v73
	v_fma_f32 v181, -s7, v68, v181
	v_fma_f32 v180, -s8, v130, v180
	v_fma_f32 v72, -s9, v64, v72
	v_mov_b32_e32 v133, v68
	s_nop 0
	v_readlane_b32 s6, v24, s30
	v_readlane_b32 s7, v84, s30
	v_readlane_b32 s8, v6, s16
	v_readlane_b32 s9, v142, s16
	v_fma_f32 v73, -s6, v128, v73
	v_fma_f32 v181, -s7, v32, v181
	v_fma_f32 v180, -s8, v118, v180
	v_fma_f32 v72, -s9, v30, v72
	s_nop 0
	s_nop 0
	v_readlane_b32 s6, v24, s16
	v_readlane_b32 s7, v84, s16
	v_readlane_b32 s8, v82, s30
	v_readlane_b32 s9, v78, s30
	v_fma_f32 v73, -s6, v116, v73
	v_fma_f32 v181, -s7, v26, v181
	v_fma_f32 v180, -s8, v114, v180
	v_fma_f32 v72, -s9, v22, v72
	s_nop 0
	s_nop 0
	v_readlane_b32 s6, v28, s30
	v_readlane_b32 s7, v74, s30
	v_readlane_b32 s8, v82, s16
	v_readlane_b32 s9, v78, s16
	v_fma_f32 v73, -s6, v110, v73
	v_fma_f32 v181, -s7, v16, v181
	v_fma_f32 v180, -s8, v104, v180
	v_fma_f32 v72, -s9, v12, v72
	s_nop 0
	s_nop 0
	v_readlane_b32 s6, v28, s16
	v_readlane_b32 s7, v74, s16
	v_readlane_b32 s8, v14, s30
	v_readlane_b32 s9, v70, s30
	v_fma_f32 v73, -s6, v96, v73
	v_fma_f32 v181, -s7, v10, v181
	v_fma_f32 v180, -s8, v94, v180
	v_fma_f32 v72, -s9, v8, v72
	s_nop 0
	s_nop 0
	v_readlane_b32 s6, v66, s30
	v_readlane_b32 s7, v62, s30
	v_readlane_b32 s8, v14, s16
	v_readlane_b32 s9, v70, s16
	v_fma_f32 v73, -s6, v92, v73
	v_fma_f32 v181, -s7, v4, v181
	v_fma_f32 v180, -s8, v90, v180
	v_fma_f32 v72, -s9, v91, v72
	s_nop 0
	s_nop 0
	v_readlane_b32 s6, v66, s16
	s_nop 1
	v_fma_f32 v73, -s6, v88, v73
	s_nop 0
	s_nop 0
	v_readlane_b32 s6, v62, s16
	s_nop 1
	v_fma_f32 v73, -s6, v89, v73
	s_nop 0
	v_pk_add_f32 v[72:73], v[180:181], v[72:73]
	v_mov_b32_e32 v181, v123
	v_mov_b32_e32 v180, v123
	v_pk_add_f32 v[72:73], v[72:73], v[72:73] op_sel:[0,1] op_sel_hi:[1,0]
	s_nop 0
	s_nop 0
	v_readlane_b32 s6, v146, s17
	v_readlane_b32 s7, v144, s17
	v_readlane_b32 s8, v140, s17
	v_readlane_b32 s9, v6, s36
	v_fma_f32 v135, -s6, v72, v135
	v_fma_f32 v181, -s7, v132, v181
	v_fma_f32 v180, -s8, v68, v180
	v_fma_f32 v134, -s9, v130, v134
	s_nop 0
	s_nop 0
	v_readlane_b32 s6, v142, s36
	v_readlane_b32 s7, v24, s36
	v_readlane_b32 s8, v84, s36
	v_readlane_b32 s9, v6, s17
	v_fma_f32 v135, -s6, v64, v135
	v_fma_f32 v181, -s7, v128, v181
	v_fma_f32 v180, -s8, v32, v180
	v_fma_f32 v134, -s9, v118, v134
	s_nop 0
	s_nop 0
	v_readlane_b32 s6, v142, s17
	v_readlane_b32 s7, v24, s17
	v_readlane_b32 s8, v84, s17
	v_readlane_b32 s9, v82, s36
	v_fma_f32 v135, -s6, v30, v135
	v_fma_f32 v181, -s7, v116, v181
	v_fma_f32 v180, -s8, v26, v180
	v_fma_f32 v134, -s9, v114, v134
	s_nop 0
	s_nop 0
	v_readlane_b32 s6, v78, s36
	v_readlane_b32 s7, v28, s36
	v_readlane_b32 s8, v74, s36
	v_readlane_b32 s9, v82, s17
	v_fma_f32 v135, -s6, v22, v135
	v_fma_f32 v181, -s7, v110, v181
	v_fma_f32 v180, -s8, v16, v180
	v_fma_f32 v134, -s9, v104, v134
	s_nop 0
	s_nop 0
	v_readlane_b32 s6, v78, s17
	v_readlane_b32 s7, v28, s17
	v_readlane_b32 s8, v74, s17
	v_readlane_b32 s9, v14, s36
	v_fma_f32 v135, -s6, v12, v135
	v_fma_f32 v181, -s7, v96, v181
	v_fma_f32 v180, -s8, v10, v180
	v_fma_f32 v134, -s9, v94, v134
	s_nop 0
	s_nop 0
	v_readlane_b32 s6, v70, s36
	v_readlane_b32 s7, v66, s36
	v_readlane_b32 s8, v62, s36
	v_readlane_b32 s9, v14, s17
	v_fma_f32 v135, -s6, v8, v135
	v_fma_f32 v181, -s7, v92, v181
	v_fma_f32 v180, -s8, v4, v180
	v_fma_f32 v134, -s9, v90, v134
	s_nop 0
	s_nop 0
	v_readlane_b32 s6, v70, s17
	s_nop 1
	v_fma_f32 v135, -s6, v91, v135
	s_nop 0
	s_nop 0
	v_readlane_b32 s6, v66, s17
	s_nop 1
	v_fma_f32 v135, -s6, v88, v135
	s_nop 0
	s_nop 0
	v_readlane_b32 s6, v62, s17
	s_nop 1
	v_fma_f32 v135, -s6, v89, v135
	s_nop 0
	v_pk_add_f32 v[134:135], v[180:181], v[134:135]
	v_mov_b32_e32 v181, v123
	v_mov_b32_e32 v180, v123
	v_pk_add_f32 v[134:135], v[134:135], v[134:135] op_sel:[0,1] op_sel_hi:[1,0]
	s_nop 0
	s_nop 0
	v_readlane_b32 s6, v2, s69
	v_readlane_b32 s7, v146, s69
	v_readlane_b32 s8, v144, s69
	v_readlane_b32 s9, v140, s69
	v_fma_f32 v77, -s6, v134, v77
	v_fma_f32 v181, -s7, v72, v181
	v_fma_f32 v180, -s8, v132, v180
	v_fma_f32 v76, -s9, v68, v76
	v_mov_b32_e32 v135, v72
	s_nop 0
	v_readlane_b32 s6, v6, s12
	v_readlane_b32 s7, v142, s12
	v_readlane_b32 s8, v24, s12
	v_readlane_b32 s9, v84, s12
	v_fma_f32 v77, -s6, v130, v77
	v_fma_f32 v181, -s7, v64, v181
	v_fma_f32 v180, -s8, v128, v180
	v_fma_f32 v76, -s9, v32, v76
	s_nop 0
	s_nop 0
	v_readlane_b32 s6, v6, s69
	v_readlane_b32 s7, v142, s69
	v_readlane_b32 s8, v24, s69
	v_readlane_b32 s9, v84, s69
	v_fma_f32 v77, -s6, v118, v77
	v_fma_f32 v181, -s7, v30, v181
	v_fma_f32 v180, -s8, v116, v180
	v_fma_f32 v76, -s9, v26, v76
	s_nop 0
	s_nop 0
	v_readlane_b32 s6, v82, s12
	v_readlane_b32 s7, v78, s12
	v_readlane_b32 s8, v28, s12
	v_readlane_b32 s9, v74, s12
	v_fma_f32 v77, -s6, v114, v77
	v_fma_f32 v181, -s7, v22, v181
	v_fma_f32 v180, -s8, v110, v180
	v_fma_f32 v76, -s9, v16, v76
	s_nop 0
	s_nop 0
	v_readlane_b32 s6, v82, s69
	v_readlane_b32 s7, v78, s69
	v_readlane_b32 s8, v28, s69
	v_readlane_b32 s9, v74, s69
	v_fma_f32 v77, -s6, v104, v77
	v_fma_f32 v181, -s7, v12, v181
	v_fma_f32 v180, -s8, v96, v180
	v_fma_f32 v76, -s9, v10, v76
	s_nop 0
	s_nop 0
	v_readlane_b32 s6, v14, s12
	v_readlane_b32 s7, v70, s12
	v_readlane_b32 s8, v66, s12
	v_readlane_b32 s9, v62, s12
	v_fma_f32 v77, -s6, v94, v77
	v_fma_f32 v181, -s7, v8, v181
	v_fma_f32 v180, -s8, v92, v180
	v_fma_f32 v76, -s9, v4, v76
	s_nop 0
	s_nop 0
	v_readlane_b32 s6, v14, s69
	v_readlane_b32 s7, v70, s69
	v_readlane_b32 s8, v66, s69
	v_readlane_b32 s9, v62, s69
	v_fma_f32 v77, -s6, v90, v77
	v_fma_f32 v181, -s7, v91, v181
	v_fma_f32 v180, -s8, v88, v180
	v_fma_f32 v76, -s9, v89, v76
	s_nop 0
	v_pk_add_f32 v[76:77], v[180:181], v[76:77]
	v_mov_b32_e32 v181, v123
	v_mov_b32_e32 v180, v123
	v_pk_add_f32 v[76:77], v[76:77], v[76:77] op_sel:[0,1] op_sel_hi:[1,0]
	s_nop 0
	s_nop 0
	v_readlane_b32 s6, v140, s15
	v_readlane_b32 s7, v2, s23
	v_readlane_b32 s8, v146, s23
	v_readlane_b32 s9, v144, s23
	v_fma_f32 v137, -s6, v76, v137
	v_fma_f32 v181, -s7, v134, v181
	v_fma_f32 v180, -s8, v72, v180
	v_fma_f32 v136, -s9, v132, v136
	s_nop 0
	s_nop 0
	v_readlane_b32 s6, v140, s23
	v_readlane_b32 s7, v6, s15
	v_readlane_b32 s8, v142, s15
	v_readlane_b32 s9, v24, s15
	v_fma_f32 v137, -s6, v68, v137
	v_fma_f32 v181, -s7, v130, v181
	v_fma_f32 v180, -s8, v64, v180
	v_fma_f32 v136, -s9, v128, v136
	s_nop 0
	s_nop 0
	v_readlane_b32 s6, v84, s15
	v_readlane_b32 s7, v6, s23
	v_readlane_b32 s8, v142, s23
	v_readlane_b32 s9, v24, s23
	v_fma_f32 v137, -s6, v32, v137
	v_fma_f32 v181, -s7, v118, v181
	v_fma_f32 v180, -s8, v30, v180
	v_fma_f32 v136, -s9, v116, v136
	s_nop 0
	s_nop 0
	v_readlane_b32 s6, v84, s23
	v_readlane_b32 s7, v82, s15
	v_readlane_b32 s8, v78, s15
	v_readlane_b32 s9, v28, s15
	v_fma_f32 v137, -s6, v26, v137
	v_fma_f32 v181, -s7, v114, v181
	v_fma_f32 v180, -s8, v22, v180
	v_fma_f32 v136, -s9, v110, v136
	s_nop 0
	s_nop 0
	v_readlane_b32 s6, v74, s15
	v_readlane_b32 s7, v82, s23
	v_readlane_b32 s8, v78, s23
	v_readlane_b32 s9, v28, s23
	v_fma_f32 v137, -s6, v16, v137
	v_fma_f32 v181, -s7, v104, v181
	v_fma_f32 v180, -s8, v12, v180
	v_fma_f32 v136, -s9, v96, v136
	s_nop 0
	s_nop 0
	v_readlane_b32 s6, v74, s23
	v_readlane_b32 s7, v14, s15
	v_readlane_b32 s8, v70, s15
	v_readlane_b32 s9, v66, s15
	v_fma_f32 v137, -s6, v10, v137
	v_fma_f32 v181, -s7, v94, v181
	v_fma_f32 v180, -s8, v8, v180
	v_fma_f32 v136, -s9, v92, v136
	s_nop 0
	s_nop 0
	v_readlane_b32 s6, v62, s15
	v_readlane_b32 s7, v14, s23
	v_readlane_b32 s8, v70, s23
	v_readlane_b32 s9, v66, s23
	v_fma_f32 v137, -s6, v4, v137
	v_fma_f32 v181, -s7, v90, v181
	v_fma_f32 v180, -s8, v91, v180
	v_fma_f32 v136, -s9, v88, v136
	s_nop 0
	s_nop 0
	v_readlane_b32 s6, v62, s23
	s_nop 1
	v_fma_f32 v137, -s6, v89, v137
	s_nop 0
	v_pk_add_f32 v[136:137], v[180:181], v[136:137]
	v_mov_b32_e32 v181, v123
	v_mov_b32_e32 v180, v123
	v_pk_add_f32 v[136:137], v[136:137], v[136:137] op_sel:[0,1] op_sel_hi:[1,0]
	s_nop 0
	s_nop 0
	v_readlane_b32 s6, v144, s26
	v_readlane_b32 s7, v140, s26
	v_readlane_b32 s8, v2, s10
	v_readlane_b32 s9, v146, s10
	v_fma_f32 v81, -s6, v136, v81
	v_fma_f32 v181, -s7, v76, v181
	v_fma_f32 v180, -s8, v134, v180
	v_fma_f32 v80, -s9, v72, v80
	v_mov_b32_e32 v137, v76
	s_nop 0
	v_readlane_b32 s6, v144, s10
	v_readlane_b32 s7, v140, s10
	v_readlane_b32 s8, v6, s26
	v_readlane_b32 s9, v142, s26
	v_fma_f32 v81, -s6, v132, v81
	v_fma_f32 v181, -s7, v68, v181
	v_fma_f32 v180, -s8, v130, v180
	v_fma_f32 v80, -s9, v64, v80
	s_nop 0
	s_nop 0
	v_readlane_b32 s6, v24, s26
	v_readlane_b32 s7, v84, s26
	v_readlane_b32 s8, v6, s10
	v_readlane_b32 s9, v142, s10
	v_fma_f32 v81, -s6, v128, v81
	v_fma_f32 v181, -s7, v32, v181
	v_fma_f32 v180, -s8, v118, v180
	v_fma_f32 v80, -s9, v30, v80
	s_nop 0
	s_nop 0
	v_readlane_b32 s6, v24, s10
	v_readlane_b32 s7, v84, s10
	v_readlane_b32 s8, v82, s26
	v_readlane_b32 s9, v78, s26
	v_fma_f32 v81, -s6, v116, v81
	v_fma_f32 v181, -s7, v26, v181
	v_fma_f32 v180, -s8, v114, v180
	v_fma_f32 v80, -s9, v22, v80
	s_nop 0
	s_nop 0
	v_readlane_b32 s6, v28, s26
	v_readlane_b32 s7, v74, s26
	v_readlane_b32 s8, v82, s10
	v_readlane_b32 s9, v78, s10
	v_fma_f32 v81, -s6, v110, v81
	v_fma_f32 v181, -s7, v16, v181
	v_fma_f32 v180, -s8, v104, v180
	v_fma_f32 v80, -s9, v12, v80
	s_nop 0
	s_nop 0
	v_readlane_b32 s6, v28, s10
	v_readlane_b32 s7, v74, s10
	v_readlane_b32 s8, v14, s26
	v_readlane_b32 s9, v70, s26
	v_fma_f32 v81, -s6, v96, v81
	v_fma_f32 v181, -s7, v10, v181
	v_fma_f32 v180, -s8, v94, v180
	v_fma_f32 v80, -s9, v8, v80
	s_nop 0
	s_nop 0
	v_readlane_b32 s6, v66, s26
	v_readlane_b32 s7, v62, s26
	v_readlane_b32 s8, v14, s10
	v_readlane_b32 s9, v70, s10
	v_fma_f32 v81, -s6, v92, v81
	v_fma_f32 v181, -s7, v4, v181
	v_fma_f32 v180, -s8, v90, v180
	v_fma_f32 v80, -s9, v91, v80
	s_nop 0
	s_nop 0
	v_readlane_b32 s6, v66, s10
	s_nop 1
	v_fma_f32 v81, -s6, v88, v81
	s_nop 0
	s_nop 0
	v_readlane_b32 s6, v62, s10
	s_nop 1
	v_fma_f32 v81, -s6, v89, v81
	s_nop 0
	v_pk_add_f32 v[80:81], v[180:181], v[80:81]
	v_mov_b32_e32 v181, v123
	v_mov_b32_e32 v180, v123
	v_pk_add_f32 v[80:81], v[80:81], v[80:81] op_sel:[0,1] op_sel_hi:[1,0]
	s_nop 0
	s_nop 0
	v_readlane_b32 s6, v146, s13
	v_readlane_b32 s7, v144, s13
	v_readlane_b32 s8, v140, s13
	v_readlane_b32 s9, v2, s31
	v_fma_f32 v139, -s6, v80, v139
	v_fma_f32 v181, -s7, v136, v181
	v_fma_f32 v180, -s8, v76, v180
	v_fma_f32 v138, -s9, v134, v138
	v_mov_b32_e32 v2, v123
	s_nop 0
	v_readlane_b32 s6, v146, s31
	v_readlane_b32 s7, v144, s31
	v_readlane_b32 s8, v140, s31
	v_readlane_b32 s9, v6, s13
	v_fma_f32 v139, -s6, v72, v139
	v_fma_f32 v181, -s7, v132, v181
	v_fma_f32 v180, -s8, v68, v180
	v_fma_f32 v138, -s9, v130, v138
	v_mov_b32_e32 v140, v123
	s_nop 0
	v_readlane_b32 s6, v142, s13
	v_readlane_b32 s7, v24, s13
	v_readlane_b32 s8, v84, s13
	v_readlane_b32 s9, v6, s31
	v_fma_f32 v139, -s6, v64, v139
	v_fma_f32 v181, -s7, v128, v181
	v_fma_f32 v180, -s8, v32, v180
	v_fma_f32 v138, -s9, v118, v138
	v_mov_b32_e32 v144, v123
	s_nop 0
	v_readlane_b32 s6, v142, s31
	v_readlane_b32 s7, v24, s31
	v_readlane_b32 s8, v84, s31
	v_readlane_b32 s9, v82, s13
	v_fma_f32 v139, -s6, v30, v139
	v_fma_f32 v181, -s7, v116, v181
	v_fma_f32 v180, -s8, v26, v180
	v_fma_f32 v138, -s9, v114, v138
	v_mov_b32_e32 v142, v123
	s_nop 0
	v_readlane_b32 s6, v78, s13
	v_readlane_b32 s7, v28, s13
	v_readlane_b32 s8, v74, s13
	v_readlane_b32 s9, v82, s31
	v_fma_f32 v139, -s6, v22, v139
	v_fma_f32 v181, -s7, v110, v181
	v_fma_f32 v180, -s8, v16, v180
	v_fma_f32 v138, -s9, v104, v138
	v_mov_b32_e32 v146, v123
	s_nop 0
	v_readlane_b32 s6, v78, s31
	v_readlane_b32 s7, v28, s31
	v_readlane_b32 s8, v74, s31
	v_readlane_b32 s9, v14, s13
	v_fma_f32 v139, -s6, v12, v139
	v_fma_f32 v181, -s7, v96, v181
	v_fma_f32 v180, -s8, v10, v180
	v_fma_f32 v138, -s9, v94, v138
	v_mov_b32_e32 v84, v123
	s_nop 0
	v_readlane_b32 s6, v70, s13
	v_readlane_b32 s7, v66, s13
	v_readlane_b32 s8, v62, s13
	v_readlane_b32 s9, v14, s31
	v_fma_f32 v139, -s6, v8, v139
	v_fma_f32 v181, -s7, v92, v181
	v_fma_f32 v180, -s8, v4, v180
	v_fma_f32 v138, -s9, v90, v138
	v_mov_b32_e32 v82, v123
	s_nop 0
	v_readlane_b32 s6, v70, s31
	s_nop 1
	v_fma_f32 v139, -s6, v91, v139
	v_mov_b32_e32 v78, v123
	s_nop 0
	v_readlane_b32 s6, v66, s31
	s_nop 1
	v_fma_f32 v139, -s6, v88, v139
	v_mov_b32_e32 v74, v123
	s_nop 0
	v_readlane_b32 s6, v62, s31
	s_nop 1
	v_fma_f32 v139, -s6, v89, v139
	v_mov_b32_e32 v70, v123
	v_pk_add_f32 v[138:139], v[180:181], v[138:139]
	v_mov_b32_e32 v181, v123
	v_mov_b32_e32 v180, v123
	v_pk_add_f32 v[138:139], v[138:139], v[138:139] op_sel:[0,1] op_sel_hi:[1,0]
	v_mov_b32_e32 v66, v123
	s_nop 0
	v_readlane_b32 s6, v226, s41
	v_readlane_b32 s7, v225, s41
	v_readlane_b32 s8, v224, s41
	v_readlane_b32 s9, v223, s41
	v_fma_f32 v153, -s6, v138, v153
	v_fma_f32 v181, -s7, v80, v181
	v_fma_f32 v180, -s8, v136, v180
	v_fma_f32 v152, -s9, v76, v152
	v_mov_b32_e32 v62, v123
	s_nop 0
	v_readlane_b32 s6, v226, s20
	v_readlane_b32 s7, v225, s20
	v_readlane_b32 s8, v224, s20
	v_readlane_b32 s9, v223, s20
	v_fma_f32 v153, -s6, v134, v153
	v_fma_f32 v181, -s7, v72, v181
	v_fma_f32 v180, -s8, v132, v180
	v_fma_f32 v152, -s9, v68, v152
	v_mov_b32_e32 v28, v123
	s_nop 0
	v_readlane_b32 s6, v222, s41
	v_readlane_b32 s7, v221, s41
	v_readlane_b32 s8, v220, s41
	v_readlane_b32 s9, v219, s41
	v_fma_f32 v153, -s6, v130, v153
	v_fma_f32 v181, -s7, v64, v181
	v_fma_f32 v180, -s8, v128, v180
	v_fma_f32 v152, -s9, v32, v152
	v_mov_b32_e32 v24, v123
	s_nop 0
	v_readlane_b32 s6, v222, s20
	v_readlane_b32 s7, v221, s20
	v_readlane_b32 s8, v220, s20
	v_readlane_b32 s9, v219, s20
	v_fma_f32 v153, -s6, v118, v153
	v_fma_f32 v181, -s7, v30, v181
	v_fma_f32 v180, -s8, v116, v180
	v_fma_f32 v152, -s9, v26, v152
	v_mov_b32_e32 v14, v123
	s_nop 0
	v_readlane_b32 s6, v218, s41
	v_readlane_b32 s7, v217, s41
	v_readlane_b32 s8, v216, s41
	v_readlane_b32 s9, v215, s41
	v_fma_f32 v153, -s6, v114, v153
	v_fma_f32 v181, -s7, v22, v181
	v_fma_f32 v180, -s8, v110, v180
	v_fma_f32 v152, -s9, v16, v152
	v_mov_b32_e32 v6, v123
	s_nop 0
	v_readlane_b32 s6, v218, s20
	v_readlane_b32 s7, v217, s20
	v_readlane_b32 s8, v216, s20
	v_readlane_b32 s9, v215, s20
	v_fma_f32 v153, -s6, v104, v153
	v_fma_f32 v181, -s7, v12, v181
	v_fma_f32 v180, -s8, v96, v180
	v_fma_f32 v152, -s9, v10, v152
	v_mov_b32_e32 v139, v80
	s_nop 0
	v_readlane_b32 s6, v214, s41
	v_readlane_b32 s7, v213, s41
	v_readlane_b32 s8, v212, s41
	v_readlane_b32 s9, v211, s41
	v_fma_f32 v153, -s6, v94, v153
	v_fma_f32 v181, -s7, v8, v181
	v_fma_f32 v180, -s8, v92, v180
	v_fma_f32 v152, -s9, v4, v152
	s_nop 0
	s_nop 0
	v_readlane_b32 s6, v214, s20
	v_readlane_b32 s7, v213, s20
	v_readlane_b32 s8, v212, s20
	v_readlane_b32 s9, v211, s20
	v_fma_f32 v153, -s6, v90, v153
	v_fma_f32 v181, -s7, v91, v181
	v_fma_f32 v180, -s8, v88, v180
	v_fma_f32 v152, -s9, v89, v152
	s_mov_b32 s20, 30
	v_pk_add_f32 v[152:153], v[180:181], v[152:153]
	v_mov_b32_e32 v181, v123
	v_mov_b32_e32 v180, v123
	v_pk_add_f32 v[152:153], v[152:153], v[152:153] op_sel:[0,1] op_sel_hi:[1,0]
	s_nop 0
	s_nop 0
	v_readlane_b32 s6, v209, s54
	v_readlane_b32 s7, v226, s20
	v_readlane_b32 s8, v225, s20
	v_readlane_b32 s9, v224, s20
	v_fma_f32 v141, -s6, v152, v141
	v_fma_f32 v181, -s7, v138, v181
	v_fma_f32 v180, -s8, v80, v180
	v_fma_f32 v140, -s9, v136, v140
	s_nop 0
	s_nop 0
	v_readlane_b32 s6, v223, s20
	v_readlane_b32 s7, v226, s54
	v_readlane_b32 s8, v225, s54
	v_readlane_b32 s9, v224, s54
	v_fma_f32 v141, -s6, v76, v141
	v_fma_f32 v181, -s7, v134, v181
	v_fma_f32 v180, -s8, v72, v180
	v_fma_f32 v140, -s9, v132, v140
	s_nop 0
	s_nop 0
	v_readlane_b32 s6, v223, s54
	v_readlane_b32 s7, v222, s20
	v_readlane_b32 s8, v221, s20
	v_readlane_b32 s9, v220, s20
	v_fma_f32 v141, -s6, v68, v141
	v_fma_f32 v181, -s7, v130, v181
	v_fma_f32 v180, -s8, v64, v180
	v_fma_f32 v140, -s9, v128, v140
	s_nop 0
	s_nop 0
	v_readlane_b32 s6, v219, s20
	v_readlane_b32 s7, v222, s54
	v_readlane_b32 s8, v221, s54
	v_readlane_b32 s9, v220, s54
	v_fma_f32 v141, -s6, v32, v141
	v_fma_f32 v181, -s7, v118, v181
	v_fma_f32 v180, -s8, v30, v180
	v_fma_f32 v140, -s9, v116, v140
	s_nop 0
	s_nop 0
	v_readlane_b32 s6, v219, s54
	v_readlane_b32 s7, v218, s20
	v_readlane_b32 s8, v217, s20
	v_readlane_b32 s9, v216, s20
	v_fma_f32 v141, -s6, v26, v141
	v_fma_f32 v181, -s7, v114, v181
	v_fma_f32 v180, -s8, v22, v180
	v_fma_f32 v140, -s9, v110, v140
	s_nop 0
	s_nop 0
	v_readlane_b32 s6, v215, s20
	v_readlane_b32 s7, v218, s54
	v_readlane_b32 s8, v217, s54
	v_readlane_b32 s9, v216, s54
	v_fma_f32 v141, -s6, v16, v141
	v_fma_f32 v181, -s7, v104, v181
	v_fma_f32 v180, -s8, v12, v180
	v_fma_f32 v140, -s9, v96, v140
	s_nop 0
	s_nop 0
	v_readlane_b32 s6, v215, s54
	v_readlane_b32 s7, v214, s20
	v_readlane_b32 s8, v213, s20
	v_readlane_b32 s9, v212, s20
	v_fma_f32 v141, -s6, v10, v141
	v_fma_f32 v181, -s7, v94, v181
	v_fma_f32 v180, -s8, v8, v180
	v_fma_f32 v140, -s9, v92, v140
	s_nop 0
	s_nop 0
	v_readlane_b32 s6, v211, s20
	v_readlane_b32 s7, v214, s54
	v_readlane_b32 s8, v213, s54
	v_readlane_b32 s9, v212, s54
	v_fma_f32 v141, -s6, v4, v141
	v_fma_f32 v181, -s7, v90, v181
	v_fma_f32 v180, -s8, v91, v180
	v_fma_f32 v140, -s9, v88, v140
	s_mov_b32 s20, 29
	s_nop 0
	v_readlane_b32 s6, v211, s54
	s_nop 1
	v_fma_f32 v141, -s6, v89, v141
	s_nop 0
	v_pk_add_f32 v[140:141], v[180:181], v[140:141]
	v_mov_b32_e32 v181, v123
	v_mov_b32_e32 v180, v123
	v_pk_add_f32 v[140:141], v[140:141], v[140:141] op_sel:[0,1] op_sel_hi:[1,0]
	s_nop 0
	s_nop 0
	v_readlane_b32 s6, v207, s55
	v_readlane_b32 s7, v209, s55
	v_readlane_b32 s8, v226, s20
	v_readlane_b32 s9, v225, s20
	v_fma_f32 v159, -s6, v140, v159
	v_fma_f32 v181, -s7, v152, v181
	v_fma_f32 v180, -s8, v138, v180
	v_fma_f32 v158, -s9, v80, v158
	v_mov_b32_e32 v141, v152
	s_nop 0
	v_readlane_b32 s6, v224, s20
	v_readlane_b32 s7, v223, s20
	v_readlane_b32 s8, v226, s55
	v_readlane_b32 s9, v225, s55
	v_fma_f32 v159, -s6, v136, v159
	v_fma_f32 v181, -s7, v76, v181
	v_fma_f32 v180, -s8, v134, v180
	v_fma_f32 v158, -s9, v72, v158
	s_nop 0
	s_nop 0
	v_readlane_b32 s6, v224, s55
	v_readlane_b32 s7, v223, s55
	v_readlane_b32 s8, v222, s20
	v_readlane_b32 s9, v221, s20
	v_fma_f32 v159, -s6, v132, v159
	v_fma_f32 v181, -s7, v68, v181
	v_fma_f32 v180, -s8, v130, v180
	v_fma_f32 v158, -s9, v64, v158
	s_nop 0
	s_nop 0
	v_readlane_b32 s6, v220, s20
	v_readlane_b32 s7, v219, s20
	v_readlane_b32 s8, v222, s55
	v_readlane_b32 s9, v221, s55
	v_fma_f32 v159, -s6, v128, v159
	v_fma_f32 v181, -s7, v32, v181
	v_fma_f32 v180, -s8, v118, v180
	v_fma_f32 v158, -s9, v30, v158
	s_nop 0
	s_nop 0
	v_readlane_b32 s6, v220, s55
	v_readlane_b32 s7, v219, s55
	v_readlane_b32 s8, v218, s20
	v_readlane_b32 s9, v217, s20
	v_fma_f32 v159, -s6, v116, v159
	v_fma_f32 v181, -s7, v26, v181
	v_fma_f32 v180, -s8, v114, v180
	v_fma_f32 v158, -s9, v22, v158
	s_nop 0
	s_nop 0
	v_readlane_b32 s6, v216, s20
	v_readlane_b32 s7, v215, s20
	v_readlane_b32 s8, v218, s55
	v_readlane_b32 s9, v217, s55
	v_fma_f32 v159, -s6, v110, v159
	v_fma_f32 v181, -s7, v16, v181
	v_fma_f32 v180, -s8, v104, v180
	v_fma_f32 v158, -s9, v12, v158
	s_nop 0
	s_nop 0
	v_readlane_b32 s6, v216, s55
	v_readlane_b32 s7, v215, s55
	v_readlane_b32 s8, v214, s20
	v_readlane_b32 s9, v213, s20
	v_fma_f32 v159, -s6, v96, v159
	v_fma_f32 v181, -s7, v10, v181
	v_fma_f32 v180, -s8, v94, v180
	v_fma_f32 v158, -s9, v8, v158
	s_nop 0
	s_nop 0
	v_readlane_b32 s6, v212, s20
	v_readlane_b32 s7, v211, s20
	v_readlane_b32 s8, v214, s55
	v_readlane_b32 s9, v213, s55
	v_fma_f32 v159, -s6, v92, v159
	v_fma_f32 v181, -s7, v4, v181
	v_fma_f32 v180, -s8, v90, v180
	v_fma_f32 v158, -s9, v91, v158
	s_mov_b32 s20, 28
	s_nop 0
	v_readlane_b32 s6, v212, s55
	s_nop 1
	v_fma_f32 v159, -s6, v88, v159
	s_nop 0
	s_nop 0
	v_readlane_b32 s6, v211, s55
	s_nop 1
	v_fma_f32 v159, -s6, v89, v159
	s_nop 0
	v_pk_add_f32 v[158:159], v[180:181], v[158:159]
	v_mov_b32_e32 v181, v123
	v_mov_b32_e32 v180, v123
	v_pk_add_f32 v[158:159], v[158:159], v[158:159] op_sel:[0,1] op_sel_hi:[1,0]
	s_nop 0
	s_nop 0
	v_readlane_b32 s6, v208, s56
	v_readlane_b32 s7, v207, s56
	v_readlane_b32 s8, v209, s56
	v_readlane_b32 s9, v226, s20
	v_fma_f32 v143, -s6, v158, v143
	v_fma_f32 v181, -s7, v140, v181
	v_fma_f32 v180, -s8, v152, v180
	v_fma_f32 v142, -s9, v138, v142
	s_nop 0
	s_nop 0
	v_readlane_b32 s6, v225, s20
	v_readlane_b32 s7, v224, s20
	v_readlane_b32 s8, v223, s20
	v_readlane_b32 s9, v226, s56
	v_fma_f32 v143, -s6, v80, v143
	v_fma_f32 v181, -s7, v136, v181
	v_fma_f32 v180, -s8, v76, v180
	v_fma_f32 v142, -s9, v134, v142
	s_nop 0
	s_nop 0
	v_readlane_b32 s6, v225, s56
	v_readlane_b32 s7, v224, s56
	v_readlane_b32 s8, v223, s56
	v_readlane_b32 s9, v222, s20
	v_fma_f32 v143, -s6, v72, v143
	v_fma_f32 v181, -s7, v132, v181
	v_fma_f32 v180, -s8, v68, v180
	v_fma_f32 v142, -s9, v130, v142
	s_nop 0
	s_nop 0
	v_readlane_b32 s6, v221, s20
	v_readlane_b32 s7, v220, s20
	v_readlane_b32 s8, v219, s20
	v_readlane_b32 s9, v222, s56
	v_fma_f32 v143, -s6, v64, v143
	v_fma_f32 v181, -s7, v128, v181
	v_fma_f32 v180, -s8, v32, v180
	v_fma_f32 v142, -s9, v118, v142
	s_nop 0
	s_nop 0
	v_readlane_b32 s6, v221, s56
	v_readlane_b32 s7, v220, s56
	v_readlane_b32 s8, v219, s56
	v_readlane_b32 s9, v218, s20
	v_fma_f32 v143, -s6, v30, v143
	v_fma_f32 v181, -s7, v116, v181
	v_fma_f32 v180, -s8, v26, v180
	v_fma_f32 v142, -s9, v114, v142
	s_nop 0
	s_nop 0
	v_readlane_b32 s6, v217, s20
	v_readlane_b32 s7, v216, s20
	v_readlane_b32 s8, v215, s20
	v_readlane_b32 s9, v218, s56
	v_fma_f32 v143, -s6, v22, v143
	v_fma_f32 v181, -s7, v110, v181
	v_fma_f32 v180, -s8, v16, v180
	v_fma_f32 v142, -s9, v104, v142
	s_nop 0
	s_nop 0
	v_readlane_b32 s6, v217, s56
	v_readlane_b32 s7, v216, s56
	v_readlane_b32 s8, v215, s56
	v_readlane_b32 s9, v214, s20
	v_fma_f32 v143, -s6, v12, v143
	v_fma_f32 v181, -s7, v96, v181
	v_fma_f32 v180, -s8, v10, v180
	v_fma_f32 v142, -s9, v94, v142
	s_nop 0
	s_nop 0
	v_readlane_b32 s6, v213, s20
	v_readlane_b32 s7, v212, s20
	v_readlane_b32 s8, v211, s20
	v_readlane_b32 s9, v214, s56
	v_fma_f32 v143, -s6, v8, v143
	v_fma_f32 v181, -s7, v92, v181
	v_fma_f32 v180, -s8, v4, v180
	v_fma_f32 v142, -s9, v90, v142
	s_mov_b32 s20, 27
	s_nop 0
	v_readlane_b32 s6, v213, s56
	s_nop 1
	v_fma_f32 v143, -s6, v91, v143
	s_nop 0
	s_nop 0
	v_readlane_b32 s6, v212, s56
	s_nop 1
	v_fma_f32 v143, -s6, v88, v143
	s_nop 0
	s_nop 0
	v_readlane_b32 s6, v211, s56
	s_nop 1
	v_fma_f32 v143, -s6, v89, v143
	s_nop 0
	v_pk_add_f32 v[142:143], v[180:181], v[142:143]
	v_mov_b32_e32 v181, v123
	v_mov_b32_e32 v180, v123
	v_pk_add_f32 v[142:143], v[142:143], v[142:143] op_sel:[0,1] op_sel_hi:[1,0]
	s_nop 0
	s_nop 0
	v_readlane_b32 s6, v205, s57
	v_readlane_b32 s7, v208, s57
	v_readlane_b32 s8, v207, s57
	v_readlane_b32 s9, v209, s57
	v_fma_f32 v167, -s6, v142, v167
	v_fma_f32 v181, -s7, v158, v181
	v_fma_f32 v180, -s8, v140, v180
	v_fma_f32 v166, -s9, v152, v166
	v_mov_b32_e32 v143, v158
	s_nop 0
	v_readlane_b32 s6, v226, s20
	v_readlane_b32 s7, v225, s20
	v_readlane_b32 s8, v224, s20
	v_readlane_b32 s9, v223, s20
	v_fma_f32 v167, -s6, v138, v167
	v_fma_f32 v181, -s7, v80, v181
	v_fma_f32 v180, -s8, v136, v180
	v_fma_f32 v166, -s9, v76, v166
	s_nop 0
	s_nop 0
	v_readlane_b32 s6, v226, s57
	v_readlane_b32 s7, v225, s57
	v_readlane_b32 s8, v224, s57
	v_readlane_b32 s9, v223, s57
	v_fma_f32 v167, -s6, v134, v167
	v_fma_f32 v181, -s7, v72, v181
	v_fma_f32 v180, -s8, v132, v180
	v_fma_f32 v166, -s9, v68, v166
	s_nop 0
	s_nop 0
	v_readlane_b32 s6, v222, s20
	v_readlane_b32 s7, v221, s20
	v_readlane_b32 s8, v220, s20
	v_readlane_b32 s9, v219, s20
	v_fma_f32 v167, -s6, v130, v167
	v_fma_f32 v181, -s7, v64, v181
	v_fma_f32 v180, -s8, v128, v180
	v_fma_f32 v166, -s9, v32, v166
	s_nop 0
	s_nop 0
	v_readlane_b32 s6, v222, s57
	v_readlane_b32 s7, v221, s57
	v_readlane_b32 s8, v220, s57
	v_readlane_b32 s9, v219, s57
	v_fma_f32 v167, -s6, v118, v167
	v_fma_f32 v181, -s7, v30, v181
	v_fma_f32 v180, -s8, v116, v180
	v_fma_f32 v166, -s9, v26, v166
	s_nop 0
	s_nop 0
	v_readlane_b32 s6, v218, s20
	v_readlane_b32 s7, v217, s20
	v_readlane_b32 s8, v216, s20
	v_readlane_b32 s9, v215, s20
	v_fma_f32 v167, -s6, v114, v167
	v_fma_f32 v181, -s7, v22, v181
	v_fma_f32 v180, -s8, v110, v180
	v_fma_f32 v166, -s9, v16, v166
	s_nop 0
	s_nop 0
	v_readlane_b32 s6, v218, s57
	v_readlane_b32 s7, v217, s57
	v_readlane_b32 s8, v216, s57
	v_readlane_b32 s9, v215, s57
	v_fma_f32 v167, -s6, v104, v167
	v_fma_f32 v181, -s7, v12, v181
	v_fma_f32 v180, -s8, v96, v180
	v_fma_f32 v166, -s9, v10, v166
	s_nop 0
	s_nop 0
	v_readlane_b32 s6, v214, s20
	v_readlane_b32 s7, v213, s20
	v_readlane_b32 s8, v212, s20
	v_readlane_b32 s9, v211, s20
	v_fma_f32 v167, -s6, v94, v167
	v_fma_f32 v181, -s7, v8, v181
	v_fma_f32 v180, -s8, v92, v180
	v_fma_f32 v166, -s9, v4, v166
	s_nop 0
	s_nop 0
	v_readlane_b32 s6, v214, s57
	v_readlane_b32 s7, v213, s57
	v_readlane_b32 s8, v212, s57
	v_readlane_b32 s9, v211, s57
	v_fma_f32 v167, -s6, v90, v167
	v_fma_f32 v181, -s7, v91, v181
	v_fma_f32 v180, -s8, v88, v180
	v_fma_f32 v166, -s9, v89, v166
	s_nop 0
	v_pk_add_f32 v[166:167], v[180:181], v[166:167]
	v_mov_b32_e32 v181, v123
	v_mov_b32_e32 v180, v123
	v_pk_add_f32 v[166:167], v[166:167], v[166:167] op_sel:[0,1] op_sel_hi:[1,0]
	s_nop 0
	s_nop 0
	v_readlane_b32 s6, v209, s53
	v_readlane_b32 s7, v205, s58
	v_readlane_b32 s8, v208, s58
	v_readlane_b32 s9, v207, s58
	v_fma_f32 v145, -s6, v166, v145
	v_fma_f32 v181, -s7, v142, v181
	v_fma_f32 v180, -s8, v158, v180
	v_fma_f32 v144, -s9, v140, v144
	s_nop 0
	s_nop 0
	v_readlane_b32 s6, v209, s58
	v_readlane_b32 s7, v226, s53
	v_readlane_b32 s8, v225, s53
	v_readlane_b32 s9, v224, s53
	v_fma_f32 v145, -s6, v152, v145
	v_fma_f32 v181, -s7, v138, v181
	v_fma_f32 v180, -s8, v80, v180
	v_fma_f32 v144, -s9, v136, v144
	s_nop 0
	s_nop 0
	v_readlane_b32 s6, v223, s53
	v_readlane_b32 s7, v226, s58
	v_readlane_b32 s8, v225, s58
	v_readlane_b32 s9, v224, s58
	v_fma_f32 v145, -s6, v76, v145
	v_fma_f32 v181, -s7, v134, v181
	v_fma_f32 v180, -s8, v72, v180
	v_fma_f32 v144, -s9, v132, v144
	s_nop 0
	s_nop 0
	v_readlane_b32 s6, v223, s58
	v_readlane_b32 s7, v222, s53
	v_readlane_b32 s8, v221, s53
	v_readlane_b32 s9, v220, s53
	v_fma_f32 v145, -s6, v68, v145
	v_fma_f32 v181, -s7, v130, v181
	v_fma_f32 v180, -s8, v64, v180
	v_fma_f32 v144, -s9, v128, v144
	s_nop 0
	s_nop 0
	v_readlane_b32 s6, v219, s53
	v_readlane_b32 s7, v222, s58
	v_readlane_b32 s8, v221, s58
	v_readlane_b32 s9, v220, s58
	v_fma_f32 v145, -s6, v32, v145
	v_fma_f32 v181, -s7, v118, v181
	v_fma_f32 v180, -s8, v30, v180
	v_fma_f32 v144, -s9, v116, v144
	s_nop 0
	s_nop 0
	v_readlane_b32 s6, v219, s58
	v_readlane_b32 s7, v218, s53
	v_readlane_b32 s8, v217, s53
	v_readlane_b32 s9, v216, s53
	v_fma_f32 v145, -s6, v26, v145
	v_fma_f32 v181, -s7, v114, v181
	v_fma_f32 v180, -s8, v22, v180
	v_fma_f32 v144, -s9, v110, v144
	s_nop 0
	s_nop 0
	v_readlane_b32 s6, v215, s53
	v_readlane_b32 s7, v218, s58
	v_readlane_b32 s8, v217, s58
	v_readlane_b32 s9, v216, s58
	v_fma_f32 v145, -s6, v16, v145
	v_fma_f32 v181, -s7, v104, v181
	v_fma_f32 v180, -s8, v12, v180
	v_fma_f32 v144, -s9, v96, v144
	s_nop 0
	s_nop 0
	v_readlane_b32 s6, v215, s58
	v_readlane_b32 s7, v214, s53
	v_readlane_b32 s8, v213, s53
	v_readlane_b32 s9, v212, s53
	v_fma_f32 v145, -s6, v10, v145
	v_fma_f32 v181, -s7, v94, v181
	v_fma_f32 v180, -s8, v8, v180
	v_fma_f32 v144, -s9, v92, v144
	s_nop 0
	s_nop 0
	v_readlane_b32 s6, v211, s53
	v_readlane_b32 s7, v214, s58
	v_readlane_b32 s8, v213, s58
	v_readlane_b32 s9, v212, s58
	v_fma_f32 v145, -s6, v4, v145
	v_fma_f32 v181, -s7, v90, v181
	v_fma_f32 v180, -s8, v91, v180
	v_fma_f32 v144, -s9, v88, v144
	s_nop 0
	s_nop 0
	v_readlane_b32 s6, v211, s58
	s_nop 1
	v_fma_f32 v145, -s6, v89, v145
	s_nop 0
	v_pk_add_f32 v[144:145], v[180:181], v[144:145]
	v_mov_b32_e32 v181, v123
	v_mov_b32_e32 v180, v123
	v_pk_add_f32 v[144:145], v[144:145], v[144:145] op_sel:[0,1] op_sel_hi:[1,0]
	s_nop 0
	s_nop 0
	v_readlane_b32 s6, v207, s52
	v_readlane_b32 s7, v209, s52
	v_readlane_b32 s8, v205, s59
	v_readlane_b32 s9, v208, s59
	v_fma_f32 v171, -s6, v144, v171
	v_fma_f32 v181, -s7, v166, v181
	v_fma_f32 v180, -s8, v142, v180
	v_fma_f32 v170, -s9, v158, v170
	v_mov_b32_e32 v145, v166
	s_nop 0
	v_readlane_b32 s6, v207, s59
	v_readlane_b32 s7, v209, s59
	v_readlane_b32 s8, v226, s52
	v_readlane_b32 s9, v225, s52
	v_fma_f32 v171, -s6, v140, v171
	v_fma_f32 v181, -s7, v152, v181
	v_fma_f32 v180, -s8, v138, v180
	v_fma_f32 v170, -s9, v80, v170
	s_nop 0
	s_nop 0
	v_readlane_b32 s6, v224, s52
	v_readlane_b32 s7, v223, s52
	v_readlane_b32 s8, v226, s59
	v_readlane_b32 s9, v225, s59
	v_fma_f32 v171, -s6, v136, v171
	v_fma_f32 v181, -s7, v76, v181
	v_fma_f32 v180, -s8, v134, v180
	v_fma_f32 v170, -s9, v72, v170
	s_nop 0
	s_nop 0
	v_readlane_b32 s6, v224, s59
	v_readlane_b32 s7, v223, s59
	v_readlane_b32 s8, v222, s52
	v_readlane_b32 s9, v221, s52
	v_fma_f32 v171, -s6, v132, v171
	v_fma_f32 v181, -s7, v68, v181
	v_fma_f32 v180, -s8, v130, v180
	v_fma_f32 v170, -s9, v64, v170
	s_nop 0
	s_nop 0
	v_readlane_b32 s6, v220, s52
	v_readlane_b32 s7, v219, s52
	v_readlane_b32 s8, v222, s59
	v_readlane_b32 s9, v221, s59
	v_fma_f32 v171, -s6, v128, v171
	v_fma_f32 v181, -s7, v32, v181
	v_fma_f32 v180, -s8, v118, v180
	v_fma_f32 v170, -s9, v30, v170
	s_nop 0
	s_nop 0
	v_readlane_b32 s6, v220, s59
	v_readlane_b32 s7, v219, s59
	v_readlane_b32 s8, v218, s52
	v_readlane_b32 s9, v217, s52
	v_fma_f32 v171, -s6, v116, v171
	v_fma_f32 v181, -s7, v26, v181
	v_fma_f32 v180, -s8, v114, v180
	v_fma_f32 v170, -s9, v22, v170
	s_nop 0
	s_nop 0
	v_readlane_b32 s6, v216, s52
	v_readlane_b32 s7, v215, s52
	v_readlane_b32 s8, v218, s59
	v_readlane_b32 s9, v217, s59
	v_fma_f32 v171, -s6, v110, v171
	v_fma_f32 v181, -s7, v16, v181
	v_fma_f32 v180, -s8, v104, v180
	v_fma_f32 v170, -s9, v12, v170
	s_nop 0
	s_nop 0
	v_readlane_b32 s6, v216, s59
	v_readlane_b32 s7, v215, s59
	v_readlane_b32 s8, v214, s52
	v_readlane_b32 s9, v213, s52
	v_fma_f32 v171, -s6, v96, v171
	v_fma_f32 v181, -s7, v10, v181
	v_fma_f32 v180, -s8, v94, v180
	v_fma_f32 v170, -s9, v8, v170
	s_nop 0
	s_nop 0
	v_readlane_b32 s6, v212, s52
	v_readlane_b32 s7, v211, s52
	v_readlane_b32 s8, v214, s59
	v_readlane_b32 s9, v213, s59
	v_fma_f32 v171, -s6, v92, v171
	v_fma_f32 v181, -s7, v4, v181
	v_fma_f32 v180, -s8, v90, v180
	v_fma_f32 v170, -s9, v91, v170
	s_nop 0
	s_nop 0
	v_readlane_b32 s6, v212, s59
	s_nop 1
	v_fma_f32 v171, -s6, v88, v171
	s_nop 0
	s_nop 0
	v_readlane_b32 s6, v211, s59
	s_nop 1
	v_fma_f32 v171, -s6, v89, v171
	s_nop 0
	v_pk_add_f32 v[170:171], v[180:181], v[170:171]
	v_mov_b32_e32 v181, v123
	v_mov_b32_e32 v180, v123
	v_pk_add_f32 v[170:171], v[170:171], v[170:171] op_sel:[0,1] op_sel_hi:[1,0]
	s_nop 0
	s_nop 0
	v_readlane_b32 s6, v208, s51
	v_readlane_b32 s7, v207, s51
	v_readlane_b32 s8, v209, s51
	v_readlane_b32 s9, v205, s60
	v_fma_f32 v147, -s6, v170, v147
	v_fma_f32 v181, -s7, v144, v181
	v_fma_f32 v180, -s8, v166, v180
	v_fma_f32 v146, -s9, v142, v146
	s_nop 0
	s_nop 0
	v_readlane_b32 s6, v208, s60
	v_readlane_b32 s7, v207, s60
	v_readlane_b32 s8, v209, s60
	v_readlane_b32 s9, v226, s51
	v_fma_f32 v147, -s6, v158, v147
	v_fma_f32 v181, -s7, v140, v181
	v_fma_f32 v180, -s8, v152, v180
	v_fma_f32 v146, -s9, v138, v146
	s_nop 0
	s_nop 0
	v_readlane_b32 s6, v225, s51
	v_readlane_b32 s7, v224, s51
	v_readlane_b32 s8, v223, s51
	v_readlane_b32 s9, v226, s60
	v_fma_f32 v147, -s6, v80, v147
	v_fma_f32 v181, -s7, v136, v181
	v_fma_f32 v180, -s8, v76, v180
	v_fma_f32 v146, -s9, v134, v146
	s_nop 0
	s_nop 0
	v_readlane_b32 s6, v225, s60
	v_readlane_b32 s7, v224, s60
	v_readlane_b32 s8, v223, s60
	v_readlane_b32 s9, v222, s51
	v_fma_f32 v147, -s6, v72, v147
	v_fma_f32 v181, -s7, v132, v181
	v_fma_f32 v180, -s8, v68, v180
	v_fma_f32 v146, -s9, v130, v146
	s_nop 0
	s_nop 0
	v_readlane_b32 s6, v221, s51
	v_readlane_b32 s7, v220, s51
	v_readlane_b32 s8, v219, s51
	v_readlane_b32 s9, v222, s60
	v_fma_f32 v147, -s6, v64, v147
	v_fma_f32 v181, -s7, v128, v181
	v_fma_f32 v180, -s8, v32, v180
	v_fma_f32 v146, -s9, v118, v146
	s_nop 0
	s_nop 0
	v_readlane_b32 s6, v221, s60
	v_readlane_b32 s7, v220, s60
	v_readlane_b32 s8, v219, s60
	v_readlane_b32 s9, v218, s51
	v_fma_f32 v147, -s6, v30, v147
	v_fma_f32 v181, -s7, v116, v181
	v_fma_f32 v180, -s8, v26, v180
	v_fma_f32 v146, -s9, v114, v146
	s_nop 0
	s_nop 0
	v_readlane_b32 s6, v217, s51
	v_readlane_b32 s7, v216, s51
	v_readlane_b32 s8, v215, s51
	v_readlane_b32 s9, v218, s60
	v_fma_f32 v147, -s6, v22, v147
	v_fma_f32 v181, -s7, v110, v181
	v_fma_f32 v180, -s8, v16, v180
	v_fma_f32 v146, -s9, v104, v146
	s_nop 0
	s_nop 0
	v_readlane_b32 s6, v217, s60
	v_readlane_b32 s7, v216, s60
	v_readlane_b32 s8, v215, s60
	v_readlane_b32 s9, v214, s51
	v_fma_f32 v147, -s6, v12, v147
	v_fma_f32 v181, -s7, v96, v181
	v_fma_f32 v180, -s8, v10, v180
	v_fma_f32 v146, -s9, v94, v146
	s_nop 0
	s_nop 0
	v_readlane_b32 s6, v213, s51
	v_readlane_b32 s7, v212, s51
	v_readlane_b32 s8, v211, s51
	v_readlane_b32 s9, v214, s60
	v_fma_f32 v147, -s6, v8, v147
	v_fma_f32 v181, -s7, v92, v181
	v_fma_f32 v180, -s8, v4, v180
	v_fma_f32 v146, -s9, v90, v146
	s_nop 0
	s_nop 0
	v_readlane_b32 s6, v213, s60
	s_nop 1
	v_fma_f32 v147, -s6, v91, v147
	s_nop 0
	s_nop 0
	v_readlane_b32 s6, v212, s60
	s_nop 1
	v_fma_f32 v147, -s6, v88, v147
	s_nop 0
	s_nop 0
	v_readlane_b32 s6, v211, s60
	s_nop 1
	v_fma_f32 v147, -s6, v89, v147
	s_nop 0
	v_pk_add_f32 v[146:147], v[180:181], v[146:147]
	v_mov_b32_e32 v181, v123
	v_mov_b32_e32 v180, v123
	v_pk_add_f32 v[146:147], v[146:147], v[146:147] op_sel:[0,1] op_sel_hi:[1,0]
	s_nop 0
	s_nop 0
	v_readlane_b32 s6, v205, s70
	v_readlane_b32 s7, v208, s70
	v_readlane_b32 s8, v207, s70
	v_readlane_b32 s9, v209, s70
	v_fma_f32 v175, -s6, v146, v175
	v_fma_f32 v181, -s7, v170, v181
	v_fma_f32 v180, -s8, v144, v180
	v_fma_f32 v174, -s9, v166, v174
	v_mov_b32_e32 v147, v170
	s_nop 0
	v_readlane_b32 s6, v205, s61
	v_readlane_b32 s7, v208, s61
	v_readlane_b32 s8, v207, s61
	v_readlane_b32 s9, v209, s61
	v_fma_f32 v175, -s6, v142, v175
	v_fma_f32 v181, -s7, v158, v181
	v_fma_f32 v180, -s8, v140, v180
	v_fma_f32 v174, -s9, v152, v174
	s_nop 0
	s_nop 0
	v_readlane_b32 s6, v226, s70
	v_readlane_b32 s7, v225, s70
	v_readlane_b32 s8, v224, s70
	v_readlane_b32 s9, v223, s70
	v_fma_f32 v175, -s6, v138, v175
	v_fma_f32 v181, -s7, v80, v181
	v_fma_f32 v180, -s8, v136, v180
	v_fma_f32 v174, -s9, v76, v174
	s_nop 0
	s_nop 0
	v_readlane_b32 s6, v226, s61
	v_readlane_b32 s7, v225, s61
	v_readlane_b32 s8, v224, s61
	v_readlane_b32 s9, v223, s61
	v_fma_f32 v175, -s6, v134, v175
	v_fma_f32 v181, -s7, v72, v181
	v_fma_f32 v180, -s8, v132, v180
	v_fma_f32 v174, -s9, v68, v174
	s_nop 0
	s_nop 0
	v_readlane_b32 s6, v222, s70
	v_readlane_b32 s7, v221, s70
	v_readlane_b32 s8, v220, s70
	v_readlane_b32 s9, v219, s70
	v_fma_f32 v175, -s6, v130, v175
	v_fma_f32 v181, -s7, v64, v181
	v_fma_f32 v180, -s8, v128, v180
	v_fma_f32 v174, -s9, v32, v174
	s_nop 0
	s_nop 0
	v_readlane_b32 s6, v222, s61
	v_readlane_b32 s7, v221, s61
	v_readlane_b32 s8, v220, s61
	v_readlane_b32 s9, v219, s61
	v_fma_f32 v175, -s6, v118, v175
	v_fma_f32 v181, -s7, v30, v181
	v_fma_f32 v180, -s8, v116, v180
	v_fma_f32 v174, -s9, v26, v174
	s_nop 0
	s_nop 0
	v_readlane_b32 s6, v218, s70
	v_readlane_b32 s7, v217, s70
	v_readlane_b32 s8, v216, s70
	v_readlane_b32 s9, v215, s70
	v_fma_f32 v175, -s6, v114, v175
	v_fma_f32 v181, -s7, v22, v181
	v_fma_f32 v180, -s8, v110, v180
	v_fma_f32 v174, -s9, v16, v174
	s_nop 0
	s_nop 0
	v_readlane_b32 s6, v218, s61
	v_readlane_b32 s7, v217, s61
	v_readlane_b32 s8, v216, s61
	v_readlane_b32 s9, v215, s61
	v_fma_f32 v175, -s6, v104, v175
	v_fma_f32 v181, -s7, v12, v181
	v_fma_f32 v180, -s8, v96, v180
	v_fma_f32 v174, -s9, v10, v174
	s_nop 0
	s_nop 0
	v_readlane_b32 s6, v214, s70
	v_readlane_b32 s7, v213, s70
	v_readlane_b32 s8, v212, s70
	v_readlane_b32 s9, v211, s70
	v_fma_f32 v175, -s6, v94, v175
	v_fma_f32 v181, -s7, v8, v181
	v_fma_f32 v180, -s8, v92, v180
	v_fma_f32 v174, -s9, v4, v174
	s_nop 0
	s_nop 0
	v_readlane_b32 s6, v214, s61
	v_readlane_b32 s7, v213, s61
	v_readlane_b32 s8, v212, s61
	v_readlane_b32 s9, v211, s61
	v_fma_f32 v175, -s6, v90, v175
	v_fma_f32 v181, -s7, v91, v181
	v_fma_f32 v180, -s8, v88, v180
	v_fma_f32 v174, -s9, v89, v174
	s_nop 0
	v_pk_add_f32 v[174:175], v[180:181], v[174:175]
	v_mov_b32_e32 v181, v123
	v_mov_b32_e32 v180, v123
	v_pk_add_f32 v[174:175], v[174:175], v[174:175] op_sel:[0,1] op_sel_hi:[1,0]
	s_nop 0
	s_nop 0
	v_readlane_b32 s6, v206, s62
	v_readlane_b32 s7, v205, s71
	v_readlane_b32 s8, v208, s71
	v_readlane_b32 s9, v207, s71
	v_fma_f32 v149, -s6, v174, v149
	v_fma_f32 v181, -s7, v146, v181
	v_fma_f32 v180, -s8, v170, v180
	v_fma_f32 v148, -s9, v144, v148
	s_nop 0
	s_nop 0
	v_readlane_b32 s6, v209, s71
	v_readlane_b32 s7, v205, s62
	v_readlane_b32 s8, v208, s62
	v_readlane_b32 s9, v207, s62
	v_fma_f32 v149, -s6, v166, v149
	v_fma_f32 v181, -s7, v142, v181
	v_fma_f32 v180, -s8, v158, v180
	v_fma_f32 v148, -s9, v140, v148
	s_nop 0
	s_nop 0
	v_readlane_b32 s6, v209, s62
	v_readlane_b32 s7, v226, s71
	v_readlane_b32 s8, v225, s71
	v_readlane_b32 s9, v224, s71
	v_fma_f32 v149, -s6, v152, v149
	v_fma_f32 v181, -s7, v138, v181
	v_fma_f32 v180, -s8, v80, v180
	v_fma_f32 v148, -s9, v136, v148
	s_nop 0
	s_nop 0
	v_readlane_b32 s6, v223, s71
	v_readlane_b32 s7, v226, s62
	v_readlane_b32 s8, v225, s62
	v_readlane_b32 s9, v224, s62
	v_fma_f32 v149, -s6, v76, v149
	v_fma_f32 v181, -s7, v134, v181
	v_fma_f32 v180, -s8, v72, v180
	v_fma_f32 v148, -s9, v132, v148
	s_nop 0
	s_nop 0
	v_readlane_b32 s6, v223, s62
	v_readlane_b32 s7, v222, s71
	v_readlane_b32 s8, v221, s71
	v_readlane_b32 s9, v220, s71
	v_fma_f32 v149, -s6, v68, v149
	v_fma_f32 v181, -s7, v130, v181
	v_fma_f32 v180, -s8, v64, v180
	v_fma_f32 v148, -s9, v128, v148
	s_nop 0
	s_nop 0
	v_readlane_b32 s6, v219, s71
	v_readlane_b32 s7, v222, s62
	v_readlane_b32 s8, v221, s62
	v_readlane_b32 s9, v220, s62
	v_fma_f32 v149, -s6, v32, v149
	v_fma_f32 v181, -s7, v118, v181
	v_fma_f32 v180, -s8, v30, v180
	v_fma_f32 v148, -s9, v116, v148
	s_nop 0
	s_nop 0
	v_readlane_b32 s6, v219, s62
	v_readlane_b32 s7, v218, s71
	v_readlane_b32 s8, v217, s71
	v_readlane_b32 s9, v216, s71
	v_fma_f32 v149, -s6, v26, v149
	v_fma_f32 v181, -s7, v114, v181
	v_fma_f32 v180, -s8, v22, v180
	v_fma_f32 v148, -s9, v110, v148
	s_nop 0
	s_nop 0
	v_readlane_b32 s6, v215, s71
	v_readlane_b32 s7, v218, s62
	v_readlane_b32 s8, v217, s62
	v_readlane_b32 s9, v216, s62
	v_fma_f32 v149, -s6, v16, v149
	v_fma_f32 v181, -s7, v104, v181
	v_fma_f32 v180, -s8, v12, v180
	v_fma_f32 v148, -s9, v96, v148
	s_nop 0
	s_nop 0
	v_readlane_b32 s6, v215, s62
	v_readlane_b32 s7, v214, s71
	v_readlane_b32 s8, v213, s71
	v_readlane_b32 s9, v212, s71
	v_fma_f32 v149, -s6, v10, v149
	v_fma_f32 v181, -s7, v94, v181
	v_fma_f32 v180, -s8, v8, v180
	v_fma_f32 v148, -s9, v92, v148
	s_nop 0
	s_nop 0
	v_readlane_b32 s6, v211, s71
	v_readlane_b32 s7, v214, s62
	v_readlane_b32 s8, v213, s62
	v_readlane_b32 s9, v212, s62
	v_fma_f32 v149, -s6, v4, v149
	v_fma_f32 v181, -s7, v90, v181
	v_fma_f32 v180, -s8, v91, v180
	v_fma_f32 v148, -s9, v88, v148
	s_nop 0
	s_nop 0
	v_readlane_b32 s6, v211, s62
	s_nop 1
	v_fma_f32 v149, -s6, v89, v149
	s_nop 0
	v_pk_add_f32 v[148:149], v[180:181], v[148:149]
	v_mov_b32_e32 v181, v123
	v_mov_b32_e32 v180, v123
	v_pk_add_f32 v[148:149], v[148:149], v[148:149] op_sel:[0,1] op_sel_hi:[1,0]
	s_nop 0
	s_nop 0
	v_readlane_b32 s6, v203, s63
	v_readlane_b32 s7, v206, s63
	v_readlane_b32 s8, v205, s72
	v_readlane_b32 s9, v208, s72
	v_fma_f32 v179, -s6, v148, v179
	v_fma_f32 v181, -s7, v174, v181
	v_fma_f32 v180, -s8, v146, v180
	v_fma_f32 v178, -s9, v170, v178
	v_mov_b32_e32 v149, v174
	s_nop 0
	v_readlane_b32 s6, v207, s72
	v_readlane_b32 s7, v209, s72
	v_readlane_b32 s8, v205, s63
	v_readlane_b32 s9, v208, s63
	v_fma_f32 v179, -s6, v144, v179
	v_fma_f32 v181, -s7, v166, v181
	v_fma_f32 v180, -s8, v142, v180
	v_fma_f32 v178, -s9, v158, v178
	s_nop 0
	s_nop 0
	v_readlane_b32 s6, v207, s63
	v_readlane_b32 s7, v209, s63
	v_readlane_b32 s8, v226, s72
	v_readlane_b32 s9, v225, s72
	v_fma_f32 v179, -s6, v140, v179
	v_fma_f32 v181, -s7, v152, v181
	v_fma_f32 v180, -s8, v138, v180
	v_fma_f32 v178, -s9, v80, v178
	s_nop 0
	s_nop 0
	v_readlane_b32 s6, v224, s72
	v_readlane_b32 s7, v223, s72
	v_readlane_b32 s8, v226, s63
	v_readlane_b32 s9, v225, s63
	v_fma_f32 v179, -s6, v136, v179
	v_fma_f32 v181, -s7, v76, v181
	v_fma_f32 v180, -s8, v134, v180
	v_fma_f32 v178, -s9, v72, v178
	s_nop 0
	s_nop 0
	v_readlane_b32 s6, v224, s63
	v_readlane_b32 s7, v223, s63
	v_readlane_b32 s8, v222, s72
	v_readlane_b32 s9, v221, s72
	v_fma_f32 v179, -s6, v132, v179
	v_fma_f32 v181, -s7, v68, v181
	v_fma_f32 v180, -s8, v130, v180
	v_fma_f32 v178, -s9, v64, v178
	s_nop 0
	s_nop 0
	v_readlane_b32 s6, v220, s72
	v_readlane_b32 s7, v219, s72
	v_readlane_b32 s8, v222, s63
	v_readlane_b32 s9, v221, s63
	v_fma_f32 v179, -s6, v128, v179
	v_fma_f32 v181, -s7, v32, v181
	v_fma_f32 v180, -s8, v118, v180
	v_fma_f32 v178, -s9, v30, v178
	s_nop 0
	s_nop 0
	v_readlane_b32 s6, v220, s63
	v_readlane_b32 s7, v219, s63
	v_readlane_b32 s8, v218, s72
	v_readlane_b32 s9, v217, s72
	v_fma_f32 v179, -s6, v116, v179
	v_fma_f32 v181, -s7, v26, v181
	v_fma_f32 v180, -s8, v114, v180
	v_fma_f32 v178, -s9, v22, v178
	s_nop 0
	s_nop 0
	v_readlane_b32 s6, v216, s72
	v_readlane_b32 s7, v215, s72
	v_readlane_b32 s8, v218, s63
	v_readlane_b32 s9, v217, s63
	v_fma_f32 v179, -s6, v110, v179
	v_fma_f32 v181, -s7, v16, v181
	v_fma_f32 v180, -s8, v104, v180
	v_fma_f32 v178, -s9, v12, v178
	s_nop 0
	s_nop 0
	v_readlane_b32 s6, v216, s63
	v_readlane_b32 s7, v215, s63
	v_readlane_b32 s8, v214, s72
	v_readlane_b32 s9, v213, s72
	v_fma_f32 v179, -s6, v96, v179
	v_fma_f32 v181, -s7, v10, v181
	v_fma_f32 v180, -s8, v94, v180
	v_fma_f32 v178, -s9, v8, v178
	s_nop 0
	s_nop 0
	v_readlane_b32 s6, v212, s72
	v_readlane_b32 s7, v211, s72
	v_readlane_b32 s8, v214, s63
	v_readlane_b32 s9, v213, s63
	v_fma_f32 v179, -s6, v92, v179
	v_fma_f32 v181, -s7, v4, v181
	v_fma_f32 v180, -s8, v90, v180
	v_fma_f32 v178, -s9, v91, v178
	s_nop 0
	s_nop 0
	v_readlane_b32 s6, v212, s63
	s_nop 1
	v_fma_f32 v179, -s6, v88, v179
	s_nop 0
	s_nop 0
	v_readlane_b32 s6, v211, s63
	s_nop 1
	v_fma_f32 v179, -s6, v89, v179
	s_nop 0
	v_pk_add_f32 v[178:179], v[180:181], v[178:179]
	v_mov_b32_e32 v181, v123
	v_mov_b32_e32 v180, v123
	v_pk_add_f32 v[178:179], v[178:179], v[178:179] op_sel:[0,1] op_sel_hi:[1,0]
	s_nop 0
	s_nop 0
	v_readlane_b32 s6, v204, s22
	v_readlane_b32 s7, v203, s22
	v_readlane_b32 s8, v206, s22
	v_readlane_b32 s9, v205, s73
	v_fma_f32 v151, -s6, v178, v151
	v_fma_f32 v181, -s7, v148, v181
	v_fma_f32 v180, -s8, v174, v180
	v_fma_f32 v150, -s9, v146, v150
	s_nop 0
	s_nop 0
	v_readlane_b32 s6, v208, s73
	v_readlane_b32 s7, v207, s73
	v_readlane_b32 s8, v209, s73
	v_readlane_b32 s9, v205, s22
	v_fma_f32 v151, -s6, v170, v151
	v_fma_f32 v181, -s7, v144, v181
	v_fma_f32 v180, -s8, v166, v180
	v_fma_f32 v150, -s9, v142, v150
	s_nop 0
	s_nop 0
	v_readlane_b32 s6, v208, s22
	v_readlane_b32 s7, v207, s22
	v_readlane_b32 s8, v209, s22
	v_readlane_b32 s9, v226, s73
	v_fma_f32 v151, -s6, v158, v151
	v_fma_f32 v181, -s7, v140, v181
	v_fma_f32 v180, -s8, v152, v180
	v_fma_f32 v150, -s9, v138, v150
	s_nop 0
	s_nop 0
	v_readlane_b32 s6, v225, s73
	v_readlane_b32 s7, v224, s73
	v_readlane_b32 s8, v223, s73
	v_readlane_b32 s9, v226, s22
	v_fma_f32 v151, -s6, v80, v151
	v_fma_f32 v181, -s7, v136, v181
	v_fma_f32 v180, -s8, v76, v180
	v_fma_f32 v150, -s9, v134, v150
	s_nop 0
	s_nop 0
	v_readlane_b32 s6, v225, s22
	v_readlane_b32 s7, v224, s22
	v_readlane_b32 s8, v223, s22
	v_readlane_b32 s9, v222, s73
	v_fma_f32 v151, -s6, v72, v151
	v_fma_f32 v181, -s7, v132, v181
	v_fma_f32 v180, -s8, v68, v180
	v_fma_f32 v150, -s9, v130, v150
	s_nop 0
	s_nop 0
	v_readlane_b32 s6, v221, s73
	v_readlane_b32 s7, v220, s73
	v_readlane_b32 s8, v219, s73
	v_readlane_b32 s9, v222, s22
	v_fma_f32 v151, -s6, v64, v151
	v_fma_f32 v181, -s7, v128, v181
	v_fma_f32 v180, -s8, v32, v180
	v_fma_f32 v150, -s9, v118, v150
	s_nop 0
	s_nop 0
	v_readlane_b32 s6, v221, s22
	v_readlane_b32 s7, v220, s22
	v_readlane_b32 s8, v219, s22
	v_readlane_b32 s9, v218, s73
	v_fma_f32 v151, -s6, v30, v151
	v_fma_f32 v181, -s7, v116, v181
	v_fma_f32 v180, -s8, v26, v180
	v_fma_f32 v150, -s9, v114, v150
	s_nop 0
	s_nop 0
	v_readlane_b32 s6, v217, s73
	v_readlane_b32 s7, v216, s73
	v_readlane_b32 s8, v215, s73
	v_readlane_b32 s9, v218, s22
	v_fma_f32 v151, -s6, v22, v151
	v_fma_f32 v181, -s7, v110, v181
	v_fma_f32 v180, -s8, v16, v180
	v_fma_f32 v150, -s9, v104, v150
	s_nop 0
	s_nop 0
	v_readlane_b32 s6, v217, s22
	v_readlane_b32 s7, v216, s22
	v_readlane_b32 s8, v215, s22
	v_readlane_b32 s9, v214, s73
	v_fma_f32 v151, -s6, v12, v151
	v_fma_f32 v181, -s7, v96, v181
	v_fma_f32 v180, -s8, v10, v180
	v_fma_f32 v150, -s9, v94, v150
	s_nop 0
	s_nop 0
	v_readlane_b32 s6, v213, s73
	v_readlane_b32 s7, v212, s73
	v_readlane_b32 s8, v211, s73
	v_readlane_b32 s9, v214, s22
	v_fma_f32 v151, -s6, v8, v151
	v_fma_f32 v181, -s7, v92, v181
	v_fma_f32 v180, -s8, v4, v180
	v_fma_f32 v150, -s9, v90, v150
	s_nop 0
	s_nop 0
	v_readlane_b32 s6, v213, s22
	s_nop 1
	v_fma_f32 v151, -s6, v91, v151
	s_nop 0
	s_nop 0
	v_readlane_b32 s6, v212, s22
	s_nop 1
	v_fma_f32 v151, -s6, v88, v151
	s_nop 0
	s_nop 0
	v_readlane_b32 s6, v211, s22
	s_nop 1
	v_fma_f32 v151, -s6, v89, v151
	s_nop 0
	v_pk_add_f32 v[150:151], v[180:181], v[150:151]
	v_mov_b32_e32 v181, v123
	v_mov_b32_e32 v180, v123
	v_pk_add_f32 v[150:151], v[150:151], v[150:151] op_sel:[0,1] op_sel_hi:[1,0]
	s_nop 0
	s_nop 0
	v_readlane_b32 s6, v201, s64
	v_readlane_b32 s7, v204, s64
	v_readlane_b32 s8, v203, s64
	v_readlane_b32 s9, v206, s64
	v_fma_f32 v177, -s6, v150, v177
	v_fma_f32 v181, -s7, v178, v181
	v_fma_f32 v180, -s8, v148, v180
	v_fma_f32 v176, -s9, v174, v176
	v_mov_b32_e32 v151, v178
	s_nop 0
	v_readlane_b32 s6, v205, s50
	v_readlane_b32 s7, v208, s50
	v_readlane_b32 s8, v207, s50
	v_readlane_b32 s9, v209, s50
	v_fma_f32 v177, -s6, v146, v177
	v_fma_f32 v181, -s7, v170, v181
	v_fma_f32 v180, -s8, v144, v180
	v_fma_f32 v176, -s9, v166, v176
	s_nop 0
	s_nop 0
	v_readlane_b32 s6, v205, s64
	v_readlane_b32 s7, v208, s64
	v_readlane_b32 s8, v207, s64
	v_readlane_b32 s9, v209, s64
	v_fma_f32 v177, -s6, v142, v177
	v_fma_f32 v181, -s7, v158, v181
	v_fma_f32 v180, -s8, v140, v180
	v_fma_f32 v176, -s9, v152, v176
	s_nop 0
	s_nop 0
	v_readlane_b32 s6, v226, s50
	v_readlane_b32 s7, v225, s50
	v_readlane_b32 s8, v224, s50
	v_readlane_b32 s9, v223, s50
	v_fma_f32 v177, -s6, v138, v177
	v_fma_f32 v181, -s7, v80, v181
	v_fma_f32 v180, -s8, v136, v180
	v_fma_f32 v176, -s9, v76, v176
	s_nop 0
	s_nop 0
	v_readlane_b32 s6, v226, s64
	v_readlane_b32 s7, v225, s64
	v_readlane_b32 s8, v224, s64
	v_readlane_b32 s9, v223, s64
	v_fma_f32 v177, -s6, v134, v177
	v_fma_f32 v181, -s7, v72, v181
	v_fma_f32 v180, -s8, v132, v180
	v_fma_f32 v176, -s9, v68, v176
	s_nop 0
	s_nop 0
	v_readlane_b32 s6, v222, s50
	v_readlane_b32 s7, v221, s50
	v_readlane_b32 s8, v220, s50
	v_readlane_b32 s9, v219, s50
	v_fma_f32 v177, -s6, v130, v177
	v_fma_f32 v181, -s7, v64, v181
	v_fma_f32 v180, -s8, v128, v180
	v_fma_f32 v176, -s9, v32, v176
	s_nop 0
	s_nop 0
	v_readlane_b32 s6, v222, s64
	v_readlane_b32 s7, v221, s64
	v_readlane_b32 s8, v220, s64
	v_readlane_b32 s9, v219, s64
	v_fma_f32 v177, -s6, v118, v177
	v_fma_f32 v181, -s7, v30, v181
	v_fma_f32 v180, -s8, v116, v180
	v_fma_f32 v176, -s9, v26, v176
	s_nop 0
	s_nop 0
	v_readlane_b32 s6, v218, s50
	v_readlane_b32 s7, v217, s50
	v_readlane_b32 s8, v216, s50
	v_readlane_b32 s9, v215, s50
	v_fma_f32 v177, -s6, v114, v177
	v_fma_f32 v181, -s7, v22, v181
	v_fma_f32 v180, -s8, v110, v180
	v_fma_f32 v176, -s9, v16, v176
	s_nop 0
	s_nop 0
	v_readlane_b32 s6, v218, s64
	v_readlane_b32 s7, v217, s64
	v_readlane_b32 s8, v216, s64
	v_readlane_b32 s9, v215, s64
	v_fma_f32 v177, -s6, v104, v177
	v_fma_f32 v181, -s7, v12, v181
	v_fma_f32 v180, -s8, v96, v180
	v_fma_f32 v176, -s9, v10, v176
	s_nop 0
	s_nop 0
	v_readlane_b32 s6, v214, s50
	v_readlane_b32 s7, v213, s50
	v_readlane_b32 s8, v212, s50
	v_readlane_b32 s9, v211, s50
	v_fma_f32 v177, -s6, v94, v177
	v_fma_f32 v181, -s7, v8, v181
	v_fma_f32 v180, -s8, v92, v180
	v_fma_f32 v176, -s9, v4, v176
	s_nop 0
	s_nop 0
	v_readlane_b32 s6, v214, s64
	v_readlane_b32 s7, v213, s64
	v_readlane_b32 s8, v212, s64
	v_readlane_b32 s9, v211, s64
	v_fma_f32 v177, -s6, v90, v177
	v_fma_f32 v181, -s7, v91, v181
	v_fma_f32 v180, -s8, v88, v180
	v_fma_f32 v176, -s9, v89, v176
	s_nop 0
	v_pk_add_f32 v[176:177], v[180:181], v[176:177]
	v_mov_b32_e32 v181, v123
	v_mov_b32_e32 v180, v123
	v_pk_add_f32 v[176:177], v[176:177], v[176:177] op_sel:[0,1] op_sel_hi:[1,0]
	s_nop 0
	s_nop 0
	v_readlane_b32 s6, v206, s49
	v_readlane_b32 s7, v201, s65
	v_readlane_b32 s8, v204, s65
	v_readlane_b32 s9, v203, s65
	v_fma_f32 v157, -s6, v176, v157
	v_fma_f32 v181, -s7, v150, v181
	v_fma_f32 v180, -s8, v178, v180
	v_fma_f32 v156, -s9, v148, v156
	s_nop 0
	s_nop 0
	v_readlane_b32 s6, v206, s65
	v_readlane_b32 s7, v205, s49
	v_readlane_b32 s8, v208, s49
	v_readlane_b32 s9, v207, s49
	v_fma_f32 v157, -s6, v174, v157
	v_fma_f32 v181, -s7, v146, v181
	v_fma_f32 v180, -s8, v170, v180
	v_fma_f32 v156, -s9, v144, v156
	s_nop 0
	s_nop 0
	v_readlane_b32 s6, v209, s49
	v_readlane_b32 s7, v205, s65
	v_readlane_b32 s8, v208, s65
	v_readlane_b32 s9, v207, s65
	v_fma_f32 v157, -s6, v166, v157
	v_fma_f32 v181, -s7, v142, v181
	v_fma_f32 v180, -s8, v158, v180
	v_fma_f32 v156, -s9, v140, v156
	s_nop 0
	s_nop 0
	v_readlane_b32 s6, v209, s65
	v_readlane_b32 s7, v226, s49
	v_readlane_b32 s8, v225, s49
	v_readlane_b32 s9, v224, s49
	v_fma_f32 v157, -s6, v152, v157
	v_fma_f32 v181, -s7, v138, v181
	v_fma_f32 v180, -s8, v80, v180
	v_fma_f32 v156, -s9, v136, v156
	s_nop 0
	s_nop 0
	v_readlane_b32 s6, v223, s49
	v_readlane_b32 s7, v226, s65
	v_readlane_b32 s8, v225, s65
	v_readlane_b32 s9, v224, s65
	v_fma_f32 v157, -s6, v76, v157
	v_fma_f32 v181, -s7, v134, v181
	v_fma_f32 v180, -s8, v72, v180
	v_fma_f32 v156, -s9, v132, v156
	s_nop 0
	s_nop 0
	v_readlane_b32 s6, v223, s65
	v_readlane_b32 s7, v222, s49
	v_readlane_b32 s8, v221, s49
	v_readlane_b32 s9, v220, s49
	v_fma_f32 v157, -s6, v68, v157
	v_fma_f32 v181, -s7, v130, v181
	v_fma_f32 v180, -s8, v64, v180
	v_fma_f32 v156, -s9, v128, v156
	s_nop 0
	s_nop 0
	v_readlane_b32 s6, v219, s49
	v_readlane_b32 s7, v222, s65
	v_readlane_b32 s8, v221, s65
	v_readlane_b32 s9, v220, s65
	v_fma_f32 v157, -s6, v32, v157
	v_fma_f32 v181, -s7, v118, v181
	v_fma_f32 v180, -s8, v30, v180
	v_fma_f32 v156, -s9, v116, v156
	s_nop 0
	s_nop 0
	v_readlane_b32 s6, v219, s65
	v_readlane_b32 s7, v218, s49
	v_readlane_b32 s8, v217, s49
	v_readlane_b32 s9, v216, s49
	v_fma_f32 v157, -s6, v26, v157
	v_fma_f32 v181, -s7, v114, v181
	v_fma_f32 v180, -s8, v22, v180
	v_fma_f32 v156, -s9, v110, v156
	s_nop 0
	s_nop 0
	v_readlane_b32 s6, v215, s49
	v_readlane_b32 s7, v218, s65
	v_readlane_b32 s8, v217, s65
	v_readlane_b32 s9, v216, s65
	v_fma_f32 v157, -s6, v16, v157
	v_fma_f32 v181, -s7, v104, v181
	v_fma_f32 v180, -s8, v12, v180
	v_fma_f32 v156, -s9, v96, v156
	s_nop 0
	s_nop 0
	v_readlane_b32 s6, v215, s65
	v_readlane_b32 s7, v214, s49
	v_readlane_b32 s8, v213, s49
	v_readlane_b32 s9, v212, s49
	v_fma_f32 v157, -s6, v10, v157
	v_fma_f32 v181, -s7, v94, v181
	v_fma_f32 v180, -s8, v8, v180
	v_fma_f32 v156, -s9, v92, v156
	s_nop 0
	s_nop 0
	v_readlane_b32 s6, v211, s49
	v_readlane_b32 s7, v214, s65
	v_readlane_b32 s8, v213, s65
	v_readlane_b32 s9, v212, s65
	v_fma_f32 v157, -s6, v4, v157
	v_fma_f32 v181, -s7, v90, v181
	v_fma_f32 v180, -s8, v91, v180
	v_fma_f32 v156, -s9, v88, v156
	s_nop 0
	s_nop 0
	v_readlane_b32 s6, v211, s65
	s_nop 1
	v_fma_f32 v157, -s6, v89, v157
	s_nop 0
	v_pk_add_f32 v[156:157], v[180:181], v[156:157]
	v_mov_b32_e32 v181, v123
	v_mov_b32_e32 v180, v123
	v_pk_add_f32 v[156:157], v[156:157], v[156:157] op_sel:[0,1] op_sel_hi:[1,0]
	s_nop 0
	s_nop 0
	v_readlane_b32 s6, v203, s48
	v_readlane_b32 s7, v206, s48
	v_readlane_b32 s8, v201, s21
	v_readlane_b32 s9, v204, s21
	v_fma_f32 v173, -s6, v156, v173
	v_fma_f32 v181, -s7, v176, v181
	v_fma_f32 v180, -s8, v150, v180
	v_fma_f32 v172, -s9, v178, v172
	v_mov_b32_e32 v157, v176
	s_nop 0
	v_readlane_b32 s6, v203, s21
	v_readlane_b32 s7, v206, s21
	v_readlane_b32 s8, v205, s48
	v_readlane_b32 s9, v208, s48
	v_fma_f32 v173, -s6, v148, v173
	v_fma_f32 v181, -s7, v174, v181
	v_fma_f32 v180, -s8, v146, v180
	v_fma_f32 v172, -s9, v170, v172
	s_nop 0
	s_nop 0
	v_readlane_b32 s6, v207, s48
	v_readlane_b32 s7, v209, s48
	v_readlane_b32 s8, v205, s21
	v_readlane_b32 s9, v208, s21
	v_fma_f32 v173, -s6, v144, v173
	v_fma_f32 v181, -s7, v166, v181
	v_fma_f32 v180, -s8, v142, v180
	v_fma_f32 v172, -s9, v158, v172
	s_nop 0
	s_nop 0
	v_readlane_b32 s6, v207, s21
	v_readlane_b32 s7, v209, s21
	v_readlane_b32 s8, v226, s48
	v_readlane_b32 s9, v225, s48
	v_fma_f32 v173, -s6, v140, v173
	v_fma_f32 v181, -s7, v152, v181
	v_fma_f32 v180, -s8, v138, v180
	v_fma_f32 v172, -s9, v80, v172
	s_nop 0
	s_nop 0
	v_readlane_b32 s6, v224, s48
	v_readlane_b32 s7, v223, s48
	v_readlane_b32 s8, v226, s21
	v_readlane_b32 s9, v225, s21
	v_fma_f32 v173, -s6, v136, v173
	v_fma_f32 v181, -s7, v76, v181
	v_fma_f32 v180, -s8, v134, v180
	v_fma_f32 v172, -s9, v72, v172
	s_nop 0
	s_nop 0
	v_readlane_b32 s6, v224, s21
	v_readlane_b32 s7, v223, s21
	v_readlane_b32 s8, v222, s48
	v_readlane_b32 s9, v221, s48
	v_fma_f32 v173, -s6, v132, v173
	v_fma_f32 v181, -s7, v68, v181
	v_fma_f32 v180, -s8, v130, v180
	v_fma_f32 v172, -s9, v64, v172
	s_nop 0
	s_nop 0
	v_readlane_b32 s6, v220, s48
	v_readlane_b32 s7, v219, s48
	v_readlane_b32 s8, v222, s21
	v_readlane_b32 s9, v221, s21
	v_fma_f32 v173, -s6, v128, v173
	v_fma_f32 v181, -s7, v32, v181
	v_fma_f32 v180, -s8, v118, v180
	v_fma_f32 v172, -s9, v30, v172
	s_nop 0
	s_nop 0
	v_readlane_b32 s6, v220, s21
	v_readlane_b32 s7, v219, s21
	v_readlane_b32 s8, v218, s48
	v_readlane_b32 s9, v217, s48
	v_fma_f32 v173, -s6, v116, v173
	v_fma_f32 v181, -s7, v26, v181
	v_fma_f32 v180, -s8, v114, v180
	v_fma_f32 v172, -s9, v22, v172
	s_nop 0
	s_nop 0
	v_readlane_b32 s6, v216, s48
	v_readlane_b32 s7, v215, s48
	v_readlane_b32 s8, v218, s21
	v_readlane_b32 s9, v217, s21
	v_fma_f32 v173, -s6, v110, v173
	v_fma_f32 v181, -s7, v16, v181
	v_fma_f32 v180, -s8, v104, v180
	v_fma_f32 v172, -s9, v12, v172
	s_nop 0
	s_nop 0
	v_readlane_b32 s6, v216, s21
	v_readlane_b32 s7, v215, s21
	v_readlane_b32 s8, v214, s48
	v_readlane_b32 s9, v213, s48
	v_fma_f32 v173, -s6, v96, v173
	v_fma_f32 v181, -s7, v10, v181
	v_fma_f32 v180, -s8, v94, v180
	v_fma_f32 v172, -s9, v8, v172
	s_nop 0
	s_nop 0
	v_readlane_b32 s6, v212, s48
	v_readlane_b32 s7, v211, s48
	v_readlane_b32 s8, v214, s21
	v_readlane_b32 s9, v213, s21
	v_fma_f32 v173, -s6, v92, v173
	v_fma_f32 v181, -s7, v4, v181
	v_fma_f32 v180, -s8, v90, v180
	v_fma_f32 v172, -s9, v91, v172
	s_nop 0
	s_nop 0
	v_readlane_b32 s6, v212, s21
	s_nop 1
	v_fma_f32 v173, -s6, v88, v173
	s_nop 0
	s_nop 0
	v_readlane_b32 s6, v211, s21
	s_nop 1
	v_fma_f32 v173, -s6, v89, v173
	s_nop 0
	v_pk_add_f32 v[172:173], v[180:181], v[172:173]
	v_mov_b32_e32 v181, v123
	v_mov_b32_e32 v180, v123
	v_pk_add_f32 v[172:173], v[172:173], v[172:173] op_sel:[0,1] op_sel_hi:[1,0]
	s_nop 0
	s_nop 0
	v_readlane_b32 s6, v204, s47
	v_readlane_b32 s7, v203, s47
	v_readlane_b32 s8, v206, s47
	v_readlane_b32 s9, v201, s34
	v_fma_f32 v165, -s6, v172, v165
	v_fma_f32 v181, -s7, v156, v181
	v_fma_f32 v180, -s8, v176, v180
	v_fma_f32 v164, -s9, v150, v164
	s_nop 0
	s_nop 0
	v_readlane_b32 s6, v204, s34
	v_readlane_b32 s7, v203, s34
	v_readlane_b32 s8, v206, s34
	v_readlane_b32 s9, v205, s47
	v_fma_f32 v165, -s6, v178, v165
	v_fma_f32 v181, -s7, v148, v181
	v_fma_f32 v180, -s8, v174, v180
	v_fma_f32 v164, -s9, v146, v164
	s_nop 0
	s_nop 0
	v_readlane_b32 s6, v208, s47
	v_readlane_b32 s7, v207, s47
	v_readlane_b32 s8, v209, s47
	v_readlane_b32 s9, v205, s34
	v_fma_f32 v165, -s6, v170, v165
	v_fma_f32 v181, -s7, v144, v181
	v_fma_f32 v180, -s8, v166, v180
	v_fma_f32 v164, -s9, v142, v164
	s_nop 0
	s_nop 0
	v_readlane_b32 s6, v208, s34
	v_readlane_b32 s7, v207, s34
	v_readlane_b32 s8, v209, s34
	v_readlane_b32 s9, v226, s47
	v_fma_f32 v165, -s6, v158, v165
	v_fma_f32 v181, -s7, v140, v181
	v_fma_f32 v180, -s8, v152, v180
	v_fma_f32 v164, -s9, v138, v164
	s_nop 0
	s_nop 0
	v_readlane_b32 s6, v225, s47
	v_readlane_b32 s7, v224, s47
	v_readlane_b32 s8, v223, s47
	v_readlane_b32 s9, v226, s34
	v_fma_f32 v165, -s6, v80, v165
	v_fma_f32 v181, -s7, v136, v181
	v_fma_f32 v180, -s8, v76, v180
	v_fma_f32 v164, -s9, v134, v164
	s_nop 0
	s_nop 0
	v_readlane_b32 s6, v225, s34
	v_readlane_b32 s7, v224, s34
	v_readlane_b32 s8, v223, s34
	v_readlane_b32 s9, v222, s47
	v_fma_f32 v165, -s6, v72, v165
	v_fma_f32 v181, -s7, v132, v181
	v_fma_f32 v180, -s8, v68, v180
	v_fma_f32 v164, -s9, v130, v164
	s_nop 0
	s_nop 0
	v_readlane_b32 s6, v221, s47
	v_readlane_b32 s7, v220, s47
	v_readlane_b32 s8, v219, s47
	v_readlane_b32 s9, v222, s34
	v_fma_f32 v165, -s6, v64, v165
	v_fma_f32 v181, -s7, v128, v181
	v_fma_f32 v180, -s8, v32, v180
	v_fma_f32 v164, -s9, v118, v164
	s_nop 0
	s_nop 0
	v_readlane_b32 s6, v221, s34
	v_readlane_b32 s7, v220, s34
	v_readlane_b32 s8, v219, s34
	v_readlane_b32 s9, v218, s47
	v_fma_f32 v165, -s6, v30, v165
	v_fma_f32 v181, -s7, v116, v181
	v_fma_f32 v180, -s8, v26, v180
	v_fma_f32 v164, -s9, v114, v164
	s_nop 0
	s_nop 0
	v_readlane_b32 s6, v217, s47
	v_readlane_b32 s7, v216, s47
	v_readlane_b32 s8, v215, s47
	v_readlane_b32 s9, v218, s34
	v_fma_f32 v165, -s6, v22, v165
	v_fma_f32 v181, -s7, v110, v181
	v_fma_f32 v180, -s8, v16, v180
	v_fma_f32 v164, -s9, v104, v164
	s_nop 0
	s_nop 0
	v_readlane_b32 s6, v217, s34
	v_readlane_b32 s7, v216, s34
	v_readlane_b32 s8, v215, s34
	v_readlane_b32 s9, v214, s47
	v_fma_f32 v165, -s6, v12, v165
	v_fma_f32 v181, -s7, v96, v181
	v_fma_f32 v180, -s8, v10, v180
	v_fma_f32 v164, -s9, v94, v164
	s_nop 0
	s_nop 0
	v_readlane_b32 s6, v213, s47
	v_readlane_b32 s7, v212, s47
	v_readlane_b32 s8, v211, s47
	v_readlane_b32 s9, v214, s34
	v_fma_f32 v165, -s6, v8, v165
	v_fma_f32 v181, -s7, v92, v181
	v_fma_f32 v180, -s8, v4, v180
	v_fma_f32 v164, -s9, v90, v164
	s_nop 0
	s_nop 0
	v_readlane_b32 s6, v213, s34
	s_nop 1
	v_fma_f32 v165, -s6, v91, v165
	s_nop 0
	s_nop 0
	v_readlane_b32 s6, v212, s34
	s_nop 1
	v_fma_f32 v165, -s6, v88, v165
	s_nop 0
	s_nop 0
	v_readlane_b32 s6, v211, s34
	s_nop 1
	v_fma_f32 v165, -s6, v89, v165
	s_nop 0
	v_pk_add_f32 v[164:165], v[180:181], v[164:165]
	v_mov_b32_e32 v181, v123
	v_mov_b32_e32 v180, v123
	v_pk_add_f32 v[164:165], v[164:165], v[164:165] op_sel:[0,1] op_sel_hi:[1,0]
	s_nop 0
	s_nop 0
	v_readlane_b32 s6, v201, s45
	v_readlane_b32 s7, v204, s45
	v_readlane_b32 s8, v203, s45
	v_readlane_b32 s9, v206, s45
	v_fma_f32 v169, -s6, v164, v169
	v_fma_f32 v181, -s7, v172, v181
	v_fma_f32 v180, -s8, v156, v180
	v_fma_f32 v168, -s9, v176, v168
	v_mov_b32_e32 v165, v172
	s_nop 0
	v_readlane_b32 s6, v201, s66
	v_readlane_b32 s7, v204, s66
	v_readlane_b32 s8, v203, s66
	v_readlane_b32 s9, v206, s66
	v_fma_f32 v169, -s6, v150, v169
	v_fma_f32 v181, -s7, v178, v181
	v_fma_f32 v180, -s8, v148, v180
	v_fma_f32 v168, -s9, v174, v168
	s_nop 0
	s_nop 0
	v_readlane_b32 s6, v205, s45
	v_readlane_b32 s7, v208, s45
	v_readlane_b32 s8, v207, s45
	v_readlane_b32 s9, v209, s45
	v_fma_f32 v169, -s6, v146, v169
	v_fma_f32 v181, -s7, v170, v181
	v_fma_f32 v180, -s8, v144, v180
	v_fma_f32 v168, -s9, v166, v168
	s_nop 0
	s_nop 0
	v_readlane_b32 s6, v205, s66
	v_readlane_b32 s7, v208, s66
	v_readlane_b32 s8, v207, s66
	v_readlane_b32 s9, v209, s66
	v_fma_f32 v169, -s6, v142, v169
	v_fma_f32 v181, -s7, v158, v181
	v_fma_f32 v180, -s8, v140, v180
	v_fma_f32 v168, -s9, v152, v168
	s_nop 0
	s_nop 0
	v_readlane_b32 s6, v226, s45
	v_readlane_b32 s7, v225, s45
	v_readlane_b32 s8, v224, s45
	v_readlane_b32 s9, v223, s45
	v_fma_f32 v169, -s6, v138, v169
	v_fma_f32 v181, -s7, v80, v181
	v_fma_f32 v180, -s8, v136, v180
	v_fma_f32 v168, -s9, v76, v168
	s_nop 0
	s_nop 0
	v_readlane_b32 s6, v226, s66
	v_readlane_b32 s7, v225, s66
	v_readlane_b32 s8, v224, s66
	v_readlane_b32 s9, v223, s66
	v_fma_f32 v169, -s6, v134, v169
	v_fma_f32 v181, -s7, v72, v181
	v_fma_f32 v180, -s8, v132, v180
	v_fma_f32 v168, -s9, v68, v168
	s_nop 0
	s_nop 0
	v_readlane_b32 s6, v222, s45
	v_readlane_b32 s7, v221, s45
	v_readlane_b32 s8, v220, s45
	v_readlane_b32 s9, v219, s45
	v_fma_f32 v169, -s6, v130, v169
	v_fma_f32 v181, -s7, v64, v181
	v_fma_f32 v180, -s8, v128, v180
	v_fma_f32 v168, -s9, v32, v168
	s_nop 0
	s_nop 0
	v_readlane_b32 s6, v222, s66
	v_readlane_b32 s7, v221, s66
	v_readlane_b32 s8, v220, s66
	v_readlane_b32 s9, v219, s66
	v_fma_f32 v169, -s6, v118, v169
	v_fma_f32 v181, -s7, v30, v181
	v_fma_f32 v180, -s8, v116, v180
	v_fma_f32 v168, -s9, v26, v168
	s_nop 0
	s_nop 0
	v_readlane_b32 s6, v218, s45
	v_readlane_b32 s7, v217, s45
	v_readlane_b32 s8, v216, s45
	v_readlane_b32 s9, v215, s45
	v_fma_f32 v169, -s6, v114, v169
	v_fma_f32 v181, -s7, v22, v181
	v_fma_f32 v180, -s8, v110, v180
	v_fma_f32 v168, -s9, v16, v168
	s_nop 0
	s_nop 0
	v_readlane_b32 s6, v218, s66
	v_readlane_b32 s7, v217, s66
	v_readlane_b32 s8, v216, s66
	v_readlane_b32 s9, v215, s66
	v_fma_f32 v169, -s6, v104, v169
	v_fma_f32 v181, -s7, v12, v181
	v_fma_f32 v180, -s8, v96, v180
	v_fma_f32 v168, -s9, v10, v168
	s_nop 0
	s_nop 0
	v_readlane_b32 s6, v214, s45
	v_readlane_b32 s7, v213, s45
	v_readlane_b32 s8, v212, s45
	v_readlane_b32 s9, v211, s45
	v_fma_f32 v169, -s6, v94, v169
	v_fma_f32 v181, -s7, v8, v181
	v_fma_f32 v180, -s8, v92, v180
	v_fma_f32 v168, -s9, v4, v168
	s_nop 0
	s_nop 0
	v_readlane_b32 s6, v214, s66
	v_readlane_b32 s7, v213, s66
	v_readlane_b32 s8, v212, s66
	v_readlane_b32 s9, v211, s66
	v_fma_f32 v169, -s6, v90, v169
	v_fma_f32 v181, -s7, v91, v181
	v_fma_f32 v180, -s8, v88, v180
	v_fma_f32 v168, -s9, v89, v168
	s_nop 0
	v_pk_add_f32 v[168:169], v[180:181], v[168:169]
	s_nop 0
	v_pk_add_f32 v[180:181], v[168:169], v[168:169] op_sel:[0,1] op_sel_hi:[1,0]
	v_mov_b32_e32 v169, v123
	v_mov_b32_e32 v168, v123
	s_nop 0
	v_readlane_b32 s6, v202, s14
	v_readlane_b32 s7, v201, s39
	v_readlane_b32 s8, v204, s39
	v_readlane_b32 s9, v203, s39
	v_fma_f32 v163, -s6, v180, v163
	v_fma_f32 v169, -s7, v164, v169
	v_fma_f32 v168, -s8, v172, v168
	v_fma_f32 v162, -s9, v156, v162
	s_nop 0
	s_nop 0
	v_readlane_b32 s6, v206, s39
	v_readlane_b32 s7, v201, s14
	v_readlane_b32 s8, v204, s14
	v_readlane_b32 s9, v203, s14
	v_fma_f32 v163, -s6, v176, v163
	v_fma_f32 v169, -s7, v150, v169
	v_fma_f32 v168, -s8, v178, v168
	v_fma_f32 v162, -s9, v148, v162
	s_nop 0
	s_nop 0
	v_readlane_b32 s6, v206, s14
	v_readlane_b32 s7, v205, s39
	v_readlane_b32 s8, v208, s39
	v_readlane_b32 s9, v207, s39
	v_fma_f32 v163, -s6, v174, v163
	v_fma_f32 v169, -s7, v146, v169
	v_fma_f32 v168, -s8, v170, v168
	v_fma_f32 v162, -s9, v144, v162
	s_nop 0
	s_nop 0
	v_readlane_b32 s6, v209, s39
	v_readlane_b32 s7, v205, s14
	v_readlane_b32 s8, v208, s14
	v_readlane_b32 s9, v207, s14
	v_fma_f32 v163, -s6, v166, v163
	v_fma_f32 v169, -s7, v142, v169
	v_fma_f32 v168, -s8, v158, v168
	v_fma_f32 v162, -s9, v140, v162
	s_nop 0
	s_nop 0
	v_readlane_b32 s6, v209, s14
	v_readlane_b32 s7, v226, s39
	v_readlane_b32 s8, v225, s39
	v_readlane_b32 s9, v224, s39
	v_fma_f32 v163, -s6, v152, v163
	v_fma_f32 v169, -s7, v138, v169
	v_fma_f32 v168, -s8, v80, v168
	v_fma_f32 v162, -s9, v136, v162
	s_nop 0
	s_nop 0
	v_readlane_b32 s6, v223, s39
	v_readlane_b32 s7, v226, s14
	v_readlane_b32 s8, v225, s14
	v_readlane_b32 s9, v224, s14
	v_fma_f32 v163, -s6, v76, v163
	v_fma_f32 v169, -s7, v134, v169
	v_fma_f32 v168, -s8, v72, v168
	v_fma_f32 v162, -s9, v132, v162
	s_nop 0
	s_nop 0
	v_readlane_b32 s6, v223, s14
	v_readlane_b32 s7, v222, s39
	v_readlane_b32 s8, v221, s39
	v_readlane_b32 s9, v220, s39
	v_fma_f32 v163, -s6, v68, v163
	v_fma_f32 v169, -s7, v130, v169
	v_fma_f32 v168, -s8, v64, v168
	v_fma_f32 v162, -s9, v128, v162
	s_nop 0
	s_nop 0
	v_readlane_b32 s6, v219, s39
	v_readlane_b32 s7, v222, s14
	v_readlane_b32 s8, v221, s14
	v_readlane_b32 s9, v220, s14
	v_fma_f32 v163, -s6, v32, v163
	v_fma_f32 v169, -s7, v118, v169
	v_fma_f32 v168, -s8, v30, v168
	v_fma_f32 v162, -s9, v116, v162
	s_nop 0
	s_nop 0
	v_readlane_b32 s6, v219, s14
	v_readlane_b32 s7, v218, s39
	v_readlane_b32 s8, v217, s39
	v_readlane_b32 s9, v216, s39
	v_fma_f32 v163, -s6, v26, v163
	v_fma_f32 v169, -s7, v114, v169
	v_fma_f32 v168, -s8, v22, v168
	v_fma_f32 v162, -s9, v110, v162
	s_nop 0
	s_nop 0
	v_readlane_b32 s6, v215, s39
	v_readlane_b32 s7, v218, s14
	v_readlane_b32 s8, v217, s14
	v_readlane_b32 s9, v216, s14
	v_fma_f32 v163, -s6, v16, v163
	v_fma_f32 v169, -s7, v104, v169
	v_fma_f32 v168, -s8, v12, v168
	v_fma_f32 v162, -s9, v96, v162
	s_nop 0
	s_nop 0
	v_readlane_b32 s6, v215, s14
	v_readlane_b32 s7, v214, s39
	v_readlane_b32 s8, v213, s39
	v_readlane_b32 s9, v212, s39
	v_fma_f32 v163, -s6, v10, v163
	v_fma_f32 v169, -s7, v94, v169
	v_fma_f32 v168, -s8, v8, v168
	v_fma_f32 v162, -s9, v92, v162
	s_nop 0
	s_nop 0
	v_readlane_b32 s6, v211, s39
	v_readlane_b32 s7, v214, s14
	v_readlane_b32 s8, v213, s14
	v_readlane_b32 s9, v212, s14
	v_fma_f32 v163, -s6, v4, v163
	v_fma_f32 v169, -s7, v90, v169
	v_fma_f32 v168, -s8, v91, v168
	v_fma_f32 v162, -s9, v88, v162
	s_nop 0
	s_nop 0
	v_readlane_b32 s6, v211, s14
	s_nop 1
	v_fma_f32 v163, -s6, v89, v163
	s_nop 0
	v_pk_add_f32 v[162:163], v[168:169], v[162:163]
	v_mov_b32_e32 v169, v123
	v_mov_b32_e32 v168, v123
	v_pk_add_f32 v[162:163], v[162:163], v[162:163] op_sel:[0,1] op_sel_hi:[1,0]
	s_nop 0
	s_nop 0
	v_readlane_b32 s6, v199, s11
	v_readlane_b32 s7, v202, s11
	v_readlane_b32 s8, v201, s38
	v_readlane_b32 s9, v204, s38
	v_fma_f32 v161, -s6, v162, v161
	v_fma_f32 v169, -s7, v180, v169
	v_fma_f32 v168, -s8, v164, v168
	v_fma_f32 v160, -s9, v172, v160
	v_mov_b32_e32 v163, v180
	s_nop 0
	v_readlane_b32 s6, v203, s38
	v_readlane_b32 s7, v206, s38
	v_readlane_b32 s8, v201, s11
	v_readlane_b32 s9, v204, s11
	v_fma_f32 v161, -s6, v156, v161
	v_fma_f32 v169, -s7, v176, v169
	v_fma_f32 v168, -s8, v150, v168
	v_fma_f32 v160, -s9, v178, v160
	s_nop 0
	s_nop 0
	v_readlane_b32 s6, v203, s11
	v_readlane_b32 s7, v206, s11
	v_readlane_b32 s8, v205, s38
	v_readlane_b32 s9, v208, s38
	v_fma_f32 v161, -s6, v148, v161
	v_fma_f32 v169, -s7, v174, v169
	v_fma_f32 v168, -s8, v146, v168
	v_fma_f32 v160, -s9, v170, v160
	s_nop 0
	s_nop 0
	v_readlane_b32 s6, v207, s38
	v_readlane_b32 s7, v209, s38
	v_readlane_b32 s8, v205, s11
	v_readlane_b32 s9, v208, s11
	v_fma_f32 v161, -s6, v144, v161
	v_fma_f32 v169, -s7, v166, v169
	v_fma_f32 v168, -s8, v142, v168
	v_fma_f32 v160, -s9, v158, v160
	s_nop 0
	s_nop 0
	v_readlane_b32 s6, v207, s11
	v_readlane_b32 s7, v209, s11
	v_readlane_b32 s8, v226, s38
	v_readlane_b32 s9, v225, s38
	v_fma_f32 v161, -s6, v140, v161
	v_fma_f32 v169, -s7, v152, v169
	v_fma_f32 v168, -s8, v138, v168
	v_fma_f32 v160, -s9, v80, v160
	s_nop 0
	s_nop 0
	v_readlane_b32 s6, v224, s38
	v_readlane_b32 s7, v223, s38
	v_readlane_b32 s8, v226, s11
	v_readlane_b32 s9, v225, s11
	v_fma_f32 v161, -s6, v136, v161
	v_fma_f32 v169, -s7, v76, v169
	v_fma_f32 v168, -s8, v134, v168
	v_fma_f32 v160, -s9, v72, v160
	s_nop 0
	s_nop 0
	v_readlane_b32 s6, v224, s11
	v_readlane_b32 s7, v223, s11
	v_readlane_b32 s8, v222, s38
	v_readlane_b32 s9, v221, s38
	v_fma_f32 v161, -s6, v132, v161
	v_fma_f32 v169, -s7, v68, v169
	v_fma_f32 v168, -s8, v130, v168
	v_fma_f32 v160, -s9, v64, v160
	s_nop 0
	s_nop 0
	v_readlane_b32 s6, v220, s38
	v_readlane_b32 s7, v219, s38
	v_readlane_b32 s8, v222, s11
	v_readlane_b32 s9, v221, s11
	v_fma_f32 v161, -s6, v128, v161
	v_fma_f32 v169, -s7, v32, v169
	v_fma_f32 v168, -s8, v118, v168
	v_fma_f32 v160, -s9, v30, v160
	s_nop 0
	s_nop 0
	v_readlane_b32 s6, v220, s11
	v_readlane_b32 s7, v219, s11
	v_readlane_b32 s8, v218, s38
	v_readlane_b32 s9, v217, s38
	v_fma_f32 v161, -s6, v116, v161
	v_fma_f32 v169, -s7, v26, v169
	v_fma_f32 v168, -s8, v114, v168
	v_fma_f32 v160, -s9, v22, v160
	s_nop 0
	s_nop 0
	v_readlane_b32 s6, v216, s38
	v_readlane_b32 s7, v215, s38
	v_readlane_b32 s8, v218, s11
	v_readlane_b32 s9, v217, s11
	v_fma_f32 v161, -s6, v110, v161
	v_fma_f32 v169, -s7, v16, v169
	v_fma_f32 v168, -s8, v104, v168
	v_fma_f32 v160, -s9, v12, v160
	s_nop 0
	s_nop 0
	v_readlane_b32 s6, v216, s11
	v_readlane_b32 s7, v215, s11
	v_readlane_b32 s8, v214, s38
	v_readlane_b32 s9, v213, s38
	v_fma_f32 v161, -s6, v96, v161
	v_fma_f32 v169, -s7, v10, v169
	v_fma_f32 v168, -s8, v94, v168
	v_fma_f32 v160, -s9, v8, v160
	s_nop 0
	s_nop 0
	v_readlane_b32 s6, v212, s38
	v_readlane_b32 s7, v211, s38
	v_readlane_b32 s8, v214, s11
	v_readlane_b32 s9, v213, s11
	v_fma_f32 v161, -s6, v92, v161
	v_fma_f32 v169, -s7, v4, v169
	v_fma_f32 v168, -s8, v90, v168
	v_fma_f32 v160, -s9, v91, v160
	s_nop 0
	s_nop 0
	v_readlane_b32 s6, v212, s11
	s_nop 1
	v_fma_f32 v161, -s6, v88, v161
	s_nop 0
	s_nop 0
	v_readlane_b32 s6, v211, s11
	s_nop 1
	v_fma_f32 v161, -s6, v89, v161
	s_nop 0
	v_pk_add_f32 v[160:161], v[168:169], v[160:161]
	s_nop 0
	v_pk_add_f32 v[184:185], v[160:161], v[160:161] op_sel:[0,1] op_sel_hi:[1,0]
	v_mov_b32_e32 v161, v123
	v_mov_b32_e32 v160, v123
	s_nop 0
	v_readlane_b32 s6, v200, s27
	v_readlane_b32 s7, v199, s27
	v_readlane_b32 s8, v202, s27
	v_readlane_b32 s9, v201, s43
	v_fma_f32 v155, -s6, v184, v155
	v_fma_f32 v161, -s7, v162, v161
	v_fma_f32 v160, -s8, v180, v160
	v_fma_f32 v154, -s9, v164, v154
	s_nop 0
	s_nop 0
	v_readlane_b32 s6, v204, s43
	v_readlane_b32 s7, v203, s43
	v_readlane_b32 s8, v206, s43
	v_readlane_b32 s9, v201, s27
	v_fma_f32 v155, -s6, v172, v155
	v_fma_f32 v161, -s7, v156, v161
	v_fma_f32 v160, -s8, v176, v160
	v_fma_f32 v154, -s9, v150, v154
	s_nop 0
	s_nop 0
	v_readlane_b32 s6, v204, s27
	v_readlane_b32 s7, v203, s27
	v_readlane_b32 s8, v206, s27
	v_readlane_b32 s9, v205, s43
	v_fma_f32 v155, -s6, v178, v155
	v_fma_f32 v161, -s7, v148, v161
	v_fma_f32 v160, -s8, v174, v160
	v_fma_f32 v154, -s9, v146, v154
	s_nop 0
	s_nop 0
	v_readlane_b32 s6, v208, s43
	v_readlane_b32 s7, v207, s43
	v_readlane_b32 s8, v209, s43
	v_readlane_b32 s9, v205, s27
	v_fma_f32 v155, -s6, v170, v155
	v_fma_f32 v161, -s7, v144, v161
	v_fma_f32 v160, -s8, v166, v160
	v_fma_f32 v154, -s9, v142, v154
	s_nop 0
	s_nop 0
	v_readlane_b32 s6, v208, s27
	v_readlane_b32 s7, v207, s27
	v_readlane_b32 s8, v209, s27
	v_readlane_b32 s9, v226, s43
	v_fma_f32 v155, -s6, v158, v155
	v_fma_f32 v161, -s7, v140, v161
	v_fma_f32 v160, -s8, v152, v160
	v_fma_f32 v154, -s9, v138, v154
	s_nop 0
	s_nop 0
	v_readlane_b32 s6, v225, s43
	v_readlane_b32 s7, v224, s43
	v_readlane_b32 s8, v223, s43
	v_readlane_b32 s9, v226, s27
	v_fma_f32 v155, -s6, v80, v155
	v_fma_f32 v161, -s7, v136, v161
	v_fma_f32 v160, -s8, v76, v160
	v_fma_f32 v154, -s9, v134, v154
	s_nop 0
	s_nop 0
	v_readlane_b32 s6, v225, s27
	v_readlane_b32 s7, v224, s27
	v_readlane_b32 s8, v223, s27
	v_readlane_b32 s9, v222, s43
	v_fma_f32 v155, -s6, v72, v155
	v_fma_f32 v161, -s7, v132, v161
	v_fma_f32 v160, -s8, v68, v160
	v_fma_f32 v154, -s9, v130, v154
	s_nop 0
	s_nop 0
	v_readlane_b32 s6, v221, s43
	v_readlane_b32 s7, v220, s43
	v_readlane_b32 s8, v219, s43
	v_readlane_b32 s9, v222, s27
	v_fma_f32 v155, -s6, v64, v155
	v_fma_f32 v161, -s7, v128, v161
	v_fma_f32 v160, -s8, v32, v160
	v_fma_f32 v154, -s9, v118, v154
	s_nop 0
	s_nop 0
	v_readlane_b32 s6, v221, s27
	v_readlane_b32 s7, v220, s27
	v_readlane_b32 s8, v219, s27
	v_readlane_b32 s9, v218, s43
	v_fma_f32 v155, -s6, v30, v155
	v_fma_f32 v161, -s7, v116, v161
	v_fma_f32 v160, -s8, v26, v160
	v_fma_f32 v154, -s9, v114, v154
	s_nop 0
	s_nop 0
	v_readlane_b32 s6, v217, s43
	v_readlane_b32 s7, v216, s43
	v_readlane_b32 s8, v215, s43
	v_readlane_b32 s9, v218, s27
	v_fma_f32 v155, -s6, v22, v155
	v_fma_f32 v161, -s7, v110, v161
	v_fma_f32 v160, -s8, v16, v160
	v_fma_f32 v154, -s9, v104, v154
	s_nop 0
	s_nop 0
	v_readlane_b32 s6, v217, s27
	v_readlane_b32 s7, v216, s27
	v_readlane_b32 s8, v215, s27
	v_readlane_b32 s9, v214, s43
	v_fma_f32 v155, -s6, v12, v155
	v_fma_f32 v161, -s7, v96, v161
	v_fma_f32 v160, -s8, v10, v160
	v_fma_f32 v154, -s9, v94, v154
	s_nop 0
	s_nop 0
	v_readlane_b32 s6, v213, s43
	v_readlane_b32 s7, v212, s43
	v_readlane_b32 s8, v211, s43
	v_readlane_b32 s9, v214, s27
	v_fma_f32 v155, -s6, v8, v155
	v_fma_f32 v161, -s7, v92, v161
	v_fma_f32 v160, -s8, v4, v160
	v_fma_f32 v154, -s9, v90, v154
	s_nop 0
	s_nop 0
	v_readlane_b32 s6, v213, s27
	s_nop 1
	v_fma_f32 v155, -s6, v91, v155
	s_nop 0
	s_nop 0
	v_readlane_b32 s6, v212, s27
	s_nop 1
	v_fma_f32 v155, -s6, v88, v155
	s_nop 0
	s_nop 0
	v_readlane_b32 s6, v211, s27
	s_nop 1
	v_fma_f32 v155, -s6, v89, v155
	s_nop 0
	v_pk_add_f32 v[154:155], v[160:161], v[154:155]
	v_mov_b32_e32 v161, v123
	v_mov_b32_e32 v160, v123
	v_pk_add_f32 v[154:155], v[154:155], v[154:155] op_sel:[0,1] op_sel_hi:[1,0]
	s_nop 0
	s_nop 0
	v_readlane_b32 s6, v197, s67
	v_readlane_b32 s7, v200, s67
	v_readlane_b32 s8, v199, s67
	v_readlane_b32 s9, v202, s67
	v_fma_f32 v85, -s6, v154, v85
	v_fma_f32 v161, -s7, v184, v161
	v_fma_f32 v160, -s8, v162, v160
	v_fma_f32 v84, -s9, v180, v84
	v_mov_b32_e32 v155, v184
	s_nop 0
	v_readlane_b32 s6, v201, s42
	v_readlane_b32 s7, v204, s42
	v_readlane_b32 s8, v203, s42
	v_readlane_b32 s9, v206, s42
	v_fma_f32 v85, -s6, v164, v85
	v_fma_f32 v161, -s7, v172, v161
	v_fma_f32 v160, -s8, v156, v160
	v_fma_f32 v84, -s9, v176, v84
	s_nop 0
	s_nop 0
	v_readlane_b32 s6, v201, s67
	v_readlane_b32 s7, v204, s67
	v_readlane_b32 s8, v203, s67
	v_readlane_b32 s9, v206, s67
	v_fma_f32 v85, -s6, v150, v85
	v_fma_f32 v161, -s7, v178, v161
	v_fma_f32 v160, -s8, v148, v160
	v_fma_f32 v84, -s9, v174, v84
	s_nop 0
	s_nop 0
	v_readlane_b32 s6, v205, s42
	v_readlane_b32 s7, v208, s42
	v_readlane_b32 s8, v207, s42
	v_readlane_b32 s9, v209, s42
	v_fma_f32 v85, -s6, v146, v85
	v_fma_f32 v161, -s7, v170, v161
	v_fma_f32 v160, -s8, v144, v160
	v_fma_f32 v84, -s9, v166, v84
	s_nop 0
	s_nop 0
	v_readlane_b32 s6, v205, s67
	v_readlane_b32 s7, v208, s67
	v_readlane_b32 s8, v207, s67
	v_readlane_b32 s9, v209, s67
	v_fma_f32 v85, -s6, v142, v85
	v_fma_f32 v161, -s7, v158, v161
	v_fma_f32 v160, -s8, v140, v160
	v_fma_f32 v84, -s9, v152, v84
	s_nop 0
	s_nop 0
	v_readlane_b32 s6, v226, s42
	v_readlane_b32 s7, v225, s42
	v_readlane_b32 s8, v224, s42
	v_readlane_b32 s9, v223, s42
	v_fma_f32 v85, -s6, v138, v85
	v_fma_f32 v161, -s7, v80, v161
	v_fma_f32 v160, -s8, v136, v160
	v_fma_f32 v84, -s9, v76, v84
	s_nop 0
	s_nop 0
	v_readlane_b32 s6, v226, s67
	v_readlane_b32 s7, v225, s67
	v_readlane_b32 s8, v224, s67
	v_readlane_b32 s9, v223, s67
	v_fma_f32 v85, -s6, v134, v85
	v_fma_f32 v161, -s7, v72, v161
	v_fma_f32 v160, -s8, v132, v160
	v_fma_f32 v84, -s9, v68, v84
	s_nop 0
	s_nop 0
	v_readlane_b32 s6, v222, s42
	v_readlane_b32 s7, v221, s42
	v_readlane_b32 s8, v220, s42
	v_readlane_b32 s9, v219, s42
	v_fma_f32 v85, -s6, v130, v85
	v_fma_f32 v161, -s7, v64, v161
	v_fma_f32 v160, -s8, v128, v160
	v_fma_f32 v84, -s9, v32, v84
	s_nop 0
	s_nop 0
	v_readlane_b32 s6, v222, s67
	v_readlane_b32 s7, v221, s67
	v_readlane_b32 s8, v220, s67
	v_readlane_b32 s9, v219, s67
	v_fma_f32 v85, -s6, v118, v85
	v_fma_f32 v161, -s7, v30, v161
	v_fma_f32 v160, -s8, v116, v160
	v_fma_f32 v84, -s9, v26, v84
	s_nop 0
	s_nop 0
	v_readlane_b32 s6, v218, s42
	v_readlane_b32 s7, v217, s42
	v_readlane_b32 s8, v216, s42
	v_readlane_b32 s9, v215, s42
	v_fma_f32 v85, -s6, v114, v85
	v_fma_f32 v161, -s7, v22, v161
	v_fma_f32 v160, -s8, v110, v160
	v_fma_f32 v84, -s9, v16, v84
	s_nop 0
	s_nop 0
	v_readlane_b32 s6, v218, s67
	v_readlane_b32 s7, v217, s67
	v_readlane_b32 s8, v216, s67
	v_readlane_b32 s9, v215, s67
	v_fma_f32 v85, -s6, v104, v85
	v_fma_f32 v161, -s7, v12, v161
	v_fma_f32 v160, -s8, v96, v160
	v_fma_f32 v84, -s9, v10, v84
	s_nop 0
	s_nop 0
	v_readlane_b32 s6, v214, s42
	v_readlane_b32 s7, v213, s42
	v_readlane_b32 s8, v212, s42
	v_readlane_b32 s9, v211, s42
	v_fma_f32 v85, -s6, v94, v85
	v_fma_f32 v161, -s7, v8, v161
	v_fma_f32 v160, -s8, v92, v160
	v_fma_f32 v84, -s9, v4, v84
	s_nop 0
	s_nop 0
	v_readlane_b32 s6, v214, s67
	v_readlane_b32 s7, v213, s67
	v_readlane_b32 s8, v212, s67
	v_readlane_b32 s9, v211, s67
	v_fma_f32 v85, -s6, v90, v85
	v_fma_f32 v161, -s7, v91, v161
	v_fma_f32 v160, -s8, v88, v160
	v_fma_f32 v84, -s9, v89, v84
	s_nop 0
	v_pk_add_f32 v[84:85], v[160:161], v[84:85]
	v_mov_b32_e32 v161, v123
	v_mov_b32_e32 v160, v123
	v_pk_add_f32 v[84:85], v[84:85], v[84:85] op_sel:[0,1] op_sel_hi:[1,0]
	s_nop 0
	s_nop 0
	v_readlane_b32 s6, v202, s46
	v_readlane_b32 s7, v197, s2
	v_readlane_b32 s8, v200, s2
	v_readlane_b32 s9, v199, s2
	v_fma_f32 v83, -s6, v84, v83
	v_fma_f32 v161, -s7, v154, v161
	v_fma_f32 v160, -s8, v184, v160
	v_fma_f32 v82, -s9, v162, v82
	s_nop 0
	s_nop 0
	v_readlane_b32 s6, v202, s2
	v_readlane_b32 s7, v201, s46
	v_readlane_b32 s8, v204, s46
	v_readlane_b32 s9, v203, s46
	v_fma_f32 v83, -s6, v180, v83
	v_fma_f32 v161, -s7, v164, v161
	v_fma_f32 v160, -s8, v172, v160
	v_fma_f32 v82, -s9, v156, v82
	s_nop 0
	s_nop 0
	v_readlane_b32 s6, v206, s46
	v_readlane_b32 s7, v201, s2
	v_readlane_b32 s8, v204, s2
	v_readlane_b32 s9, v203, s2
	v_fma_f32 v83, -s6, v176, v83
	v_fma_f32 v161, -s7, v150, v161
	v_fma_f32 v160, -s8, v178, v160
	v_fma_f32 v82, -s9, v148, v82
	s_nop 0
	s_nop 0
	v_readlane_b32 s6, v206, s2
	v_readlane_b32 s7, v205, s46
	v_readlane_b32 s8, v208, s46
	v_readlane_b32 s9, v207, s46
	v_fma_f32 v83, -s6, v174, v83
	v_fma_f32 v161, -s7, v146, v161
	v_fma_f32 v160, -s8, v170, v160
	v_fma_f32 v82, -s9, v144, v82
	s_nop 0
	s_nop 0
	v_readlane_b32 s6, v209, s46
	v_readlane_b32 s7, v205, s2
	v_readlane_b32 s8, v208, s2
	v_readlane_b32 s9, v207, s2
	v_fma_f32 v83, -s6, v166, v83
	v_fma_f32 v161, -s7, v142, v161
	v_fma_f32 v160, -s8, v158, v160
	v_fma_f32 v82, -s9, v140, v82
	s_nop 0
	s_nop 0
	v_readlane_b32 s6, v209, s2
	v_readlane_b32 s7, v226, s46
	v_readlane_b32 s8, v225, s46
	v_readlane_b32 s9, v224, s46
	v_fma_f32 v83, -s6, v152, v83
	v_fma_f32 v161, -s7, v138, v161
	v_fma_f32 v160, -s8, v80, v160
	v_fma_f32 v82, -s9, v136, v82
	s_nop 0
	s_nop 0
	v_readlane_b32 s6, v223, s46
	v_readlane_b32 s7, v226, s2
	v_readlane_b32 s8, v225, s2
	v_readlane_b32 s9, v224, s2
	v_fma_f32 v83, -s6, v76, v83
	v_fma_f32 v161, -s7, v134, v161
	v_fma_f32 v160, -s8, v72, v160
	v_fma_f32 v82, -s9, v132, v82
	s_nop 0
	s_nop 0
	v_readlane_b32 s6, v223, s2
	v_readlane_b32 s7, v222, s46
	v_readlane_b32 s8, v221, s46
	v_readlane_b32 s9, v220, s46
	v_fma_f32 v83, -s6, v68, v83
	v_fma_f32 v161, -s7, v130, v161
	v_fma_f32 v160, -s8, v64, v160
	v_fma_f32 v82, -s9, v128, v82
	s_nop 0
	s_nop 0
	v_readlane_b32 s6, v219, s46
	v_readlane_b32 s7, v222, s2
	v_readlane_b32 s8, v221, s2
	v_readlane_b32 s9, v220, s2
	v_fma_f32 v83, -s6, v32, v83
	v_fma_f32 v161, -s7, v118, v161
	v_fma_f32 v160, -s8, v30, v160
	v_fma_f32 v82, -s9, v116, v82
	s_nop 0
	s_nop 0
	v_readlane_b32 s6, v219, s2
	v_readlane_b32 s7, v218, s46
	v_readlane_b32 s8, v217, s46
	v_readlane_b32 s9, v216, s46
	v_fma_f32 v83, -s6, v26, v83
	v_fma_f32 v161, -s7, v114, v161
	v_fma_f32 v160, -s8, v22, v160
	v_fma_f32 v82, -s9, v110, v82
	s_nop 0
	s_nop 0
	v_readlane_b32 s6, v215, s46
	v_readlane_b32 s7, v218, s2
	v_readlane_b32 s8, v217, s2
	v_readlane_b32 s9, v216, s2
	v_fma_f32 v83, -s6, v16, v83
	v_fma_f32 v161, -s7, v104, v161
	v_fma_f32 v160, -s8, v12, v160
	v_fma_f32 v82, -s9, v96, v82
	s_nop 0
	s_nop 0
	v_readlane_b32 s6, v215, s2
	v_readlane_b32 s7, v214, s46
	v_readlane_b32 s8, v213, s46
	v_readlane_b32 s9, v212, s46
	v_fma_f32 v83, -s6, v10, v83
	v_fma_f32 v161, -s7, v94, v161
	v_fma_f32 v160, -s8, v8, v160
	v_fma_f32 v82, -s9, v92, v82
	s_nop 0
	s_nop 0
	v_readlane_b32 s6, v211, s46
	v_readlane_b32 s7, v214, s2
	v_readlane_b32 s8, v213, s2
	v_readlane_b32 s9, v212, s2
	v_fma_f32 v83, -s6, v4, v83
	v_fma_f32 v161, -s7, v90, v161
	v_fma_f32 v160, -s8, v91, v160
	v_fma_f32 v82, -s9, v88, v82
	s_nop 0
	s_nop 0
	v_readlane_b32 s6, v211, s2
	s_nop 1
	v_fma_f32 v83, -s6, v89, v83
	s_nop 0
	v_pk_add_f32 v[82:83], v[160:161], v[82:83]
	s_nop 0
	v_pk_add_f32 v[160:161], v[82:83], v[82:83] op_sel:[0,1] op_sel_hi:[1,0]
	v_mov_b32_e32 v83, v123
	v_mov_b32_e32 v82, v123
	s_nop 0
	v_readlane_b32 s6, v199, s37
	v_readlane_b32 s7, v202, s37
	v_readlane_b32 s8, v197, s18
	v_readlane_b32 s9, v200, s18
	v_fma_f32 v79, -s6, v160, v79
	v_fma_f32 v83, -s7, v84, v83
	v_fma_f32 v82, -s8, v154, v82
	v_fma_f32 v78, -s9, v184, v78
	v_mov_b32_e32 v161, v84
	s_nop 0
	v_readlane_b32 s6, v199, s18
	v_readlane_b32 s7, v202, s18
	v_readlane_b32 s8, v201, s37
	v_readlane_b32 s9, v204, s37
	v_fma_f32 v79, -s6, v162, v79
	v_fma_f32 v83, -s7, v180, v83
	v_fma_f32 v82, -s8, v164, v82
	v_fma_f32 v78, -s9, v172, v78
	s_nop 0
	s_nop 0
	v_readlane_b32 s6, v203, s37
	v_readlane_b32 s7, v206, s37
	v_readlane_b32 s8, v201, s18
	v_readlane_b32 s9, v204, s18
	v_fma_f32 v79, -s6, v156, v79
	v_fma_f32 v83, -s7, v176, v83
	v_fma_f32 v82, -s8, v150, v82
	v_fma_f32 v78, -s9, v178, v78
	s_nop 0
	s_nop 0
	v_readlane_b32 s6, v203, s18
	v_readlane_b32 s7, v206, s18
	v_readlane_b32 s8, v205, s37
	v_readlane_b32 s9, v208, s37
	v_fma_f32 v79, -s6, v148, v79
	v_fma_f32 v83, -s7, v174, v83
	v_fma_f32 v82, -s8, v146, v82
	v_fma_f32 v78, -s9, v170, v78
	s_nop 0
	s_nop 0
	v_readlane_b32 s6, v207, s37
	v_readlane_b32 s7, v209, s37
	v_readlane_b32 s8, v205, s18
	v_readlane_b32 s9, v208, s18
	v_fma_f32 v79, -s6, v144, v79
	v_fma_f32 v83, -s7, v166, v83
	v_fma_f32 v82, -s8, v142, v82
	v_fma_f32 v78, -s9, v158, v78
	s_nop 0
	s_nop 0
	v_readlane_b32 s6, v207, s18
	v_readlane_b32 s7, v209, s18
	v_readlane_b32 s8, v226, s37
	v_readlane_b32 s9, v225, s37
	v_fma_f32 v79, -s6, v140, v79
	v_fma_f32 v83, -s7, v152, v83
	v_fma_f32 v82, -s8, v138, v82
	v_fma_f32 v78, -s9, v80, v78
	s_nop 0
	s_nop 0
	v_readlane_b32 s6, v224, s37
	v_readlane_b32 s7, v223, s37
	v_readlane_b32 s8, v226, s18
	v_readlane_b32 s9, v225, s18
	v_fma_f32 v79, -s6, v136, v79
	v_fma_f32 v83, -s7, v76, v83
	v_fma_f32 v82, -s8, v134, v82
	v_fma_f32 v78, -s9, v72, v78
	s_nop 0
	s_nop 0
	v_readlane_b32 s6, v224, s18
	v_readlane_b32 s7, v223, s18
	v_readlane_b32 s8, v222, s37
	v_readlane_b32 s9, v221, s37
	v_fma_f32 v79, -s6, v132, v79
	v_fma_f32 v83, -s7, v68, v83
	v_fma_f32 v82, -s8, v130, v82
	v_fma_f32 v78, -s9, v64, v78
	s_nop 0
	s_nop 0
	v_readlane_b32 s6, v220, s37
	v_readlane_b32 s7, v219, s37
	v_readlane_b32 s8, v222, s18
	v_readlane_b32 s9, v221, s18
	v_fma_f32 v79, -s6, v128, v79
	v_fma_f32 v83, -s7, v32, v83
	v_fma_f32 v82, -s8, v118, v82
	v_fma_f32 v78, -s9, v30, v78
	s_nop 0
	s_nop 0
	v_readlane_b32 s6, v220, s18
	v_readlane_b32 s7, v219, s18
	v_readlane_b32 s8, v218, s37
	v_readlane_b32 s9, v217, s37
	v_fma_f32 v79, -s6, v116, v79
	v_fma_f32 v83, -s7, v26, v83
	v_fma_f32 v82, -s8, v114, v82
	v_fma_f32 v78, -s9, v22, v78
	s_nop 0
	s_nop 0
	v_readlane_b32 s6, v216, s37
	v_readlane_b32 s7, v215, s37
	v_readlane_b32 s8, v218, s18
	v_readlane_b32 s9, v217, s18
	v_fma_f32 v79, -s6, v110, v79
	v_fma_f32 v83, -s7, v16, v83
	v_fma_f32 v82, -s8, v104, v82
	v_fma_f32 v78, -s9, v12, v78
	s_nop 0
	s_nop 0
	v_readlane_b32 s6, v216, s18
	v_readlane_b32 s7, v215, s18
	v_readlane_b32 s8, v214, s37
	v_readlane_b32 s9, v213, s37
	v_fma_f32 v79, -s6, v96, v79
	v_fma_f32 v83, -s7, v10, v83
	v_fma_f32 v82, -s8, v94, v82
	v_fma_f32 v78, -s9, v8, v78
	s_nop 0
	s_nop 0
	v_readlane_b32 s6, v212, s37
	v_readlane_b32 s7, v211, s37
	v_readlane_b32 s8, v214, s18
	v_readlane_b32 s9, v213, s18
	v_fma_f32 v79, -s6, v92, v79
	v_fma_f32 v83, -s7, v4, v83
	v_fma_f32 v82, -s8, v90, v82
	v_fma_f32 v78, -s9, v91, v78
	s_nop 0
	s_nop 0
	v_readlane_b32 s6, v212, s18
	s_nop 1
	v_fma_f32 v79, -s6, v88, v79
	s_nop 0
	s_nop 0
	v_readlane_b32 s6, v211, s18
	s_nop 1
	v_fma_f32 v79, -s6, v89, v79
	s_nop 0
	v_pk_add_f32 v[78:79], v[82:83], v[78:79]
	v_mov_b32_e32 v83, v123
	v_mov_b32_e32 v82, v123
	v_pk_add_f32 v[78:79], v[78:79], v[78:79] op_sel:[0,1] op_sel_hi:[1,0]
	s_nop 0
	s_nop 0
	v_readlane_b32 s6, v200, s40
	v_readlane_b32 s7, v199, s40
	v_readlane_b32 s8, v202, s40
	v_readlane_b32 s9, v197, s19
	v_fma_f32 v75, -s6, v78, v75
	v_fma_f32 v83, -s7, v160, v83
	v_fma_f32 v82, -s8, v84, v82
	v_fma_f32 v74, -s9, v154, v74
	s_nop 0
	s_nop 0
	v_readlane_b32 s6, v200, s19
	v_readlane_b32 s7, v199, s19
	v_readlane_b32 s8, v202, s19
	v_readlane_b32 s9, v201, s40
	v_fma_f32 v75, -s6, v184, v75
	v_fma_f32 v83, -s7, v162, v83
	v_fma_f32 v82, -s8, v180, v82
	v_fma_f32 v74, -s9, v164, v74
	s_nop 0
	s_nop 0
	v_readlane_b32 s6, v204, s40
	v_readlane_b32 s7, v203, s40
	v_readlane_b32 s8, v206, s40
	v_readlane_b32 s9, v201, s19
	v_fma_f32 v75, -s6, v172, v75
	v_fma_f32 v83, -s7, v156, v83
	v_fma_f32 v82, -s8, v176, v82
	v_fma_f32 v74, -s9, v150, v74
	s_nop 0
	s_nop 0
	v_readlane_b32 s6, v204, s19
	v_readlane_b32 s7, v203, s19
	v_readlane_b32 s8, v206, s19
	v_readlane_b32 s9, v205, s40
	v_fma_f32 v75, -s6, v178, v75
	v_fma_f32 v83, -s7, v148, v83
	v_fma_f32 v82, -s8, v174, v82
	v_fma_f32 v74, -s9, v146, v74
	s_nop 0
	s_nop 0
	v_readlane_b32 s6, v208, s40
	v_readlane_b32 s7, v207, s40
	v_readlane_b32 s8, v209, s40
	v_readlane_b32 s9, v205, s19
	v_fma_f32 v75, -s6, v170, v75
	v_fma_f32 v83, -s7, v144, v83
	v_fma_f32 v82, -s8, v166, v82
	v_fma_f32 v74, -s9, v142, v74
	s_nop 0
	s_nop 0
	v_readlane_b32 s6, v208, s19
	v_readlane_b32 s7, v207, s19
	v_readlane_b32 s8, v209, s19
	v_readlane_b32 s9, v226, s40
	v_fma_f32 v75, -s6, v158, v75
	v_fma_f32 v83, -s7, v140, v83
	v_fma_f32 v82, -s8, v152, v82
	v_fma_f32 v74, -s9, v138, v74
	s_nop 0
	s_nop 0
	v_readlane_b32 s6, v225, s40
	v_readlane_b32 s7, v224, s40
	v_readlane_b32 s8, v223, s40
	v_readlane_b32 s9, v226, s19
	v_fma_f32 v75, -s6, v80, v75
	v_fma_f32 v83, -s7, v136, v83
	v_fma_f32 v82, -s8, v76, v82
	v_fma_f32 v74, -s9, v134, v74
	s_nop 0
	s_nop 0
	v_readlane_b32 s6, v225, s19
	v_readlane_b32 s7, v224, s19
	v_readlane_b32 s8, v223, s19
	v_readlane_b32 s9, v222, s40
	v_fma_f32 v75, -s6, v72, v75
	v_fma_f32 v83, -s7, v132, v83
	v_fma_f32 v82, -s8, v68, v82
	v_fma_f32 v74, -s9, v130, v74
	s_nop 0
	s_nop 0
	v_readlane_b32 s6, v221, s40
	v_readlane_b32 s7, v220, s40
	v_readlane_b32 s8, v219, s40
	v_readlane_b32 s9, v222, s19
	v_fma_f32 v75, -s6, v64, v75
	v_fma_f32 v83, -s7, v128, v83
	v_fma_f32 v82, -s8, v32, v82
	v_fma_f32 v74, -s9, v118, v74
	s_nop 0
	s_nop 0
	v_readlane_b32 s6, v221, s19
	v_readlane_b32 s7, v220, s19
	v_readlane_b32 s8, v219, s19
	v_readlane_b32 s9, v218, s40
	v_fma_f32 v75, -s6, v30, v75
	v_fma_f32 v83, -s7, v116, v83
	v_fma_f32 v82, -s8, v26, v82
	v_fma_f32 v74, -s9, v114, v74
	s_nop 0
	s_nop 0
	v_readlane_b32 s6, v217, s40
	v_readlane_b32 s7, v216, s40
	v_readlane_b32 s8, v215, s40
	v_readlane_b32 s9, v218, s19
	v_fma_f32 v75, -s6, v22, v75
	v_fma_f32 v83, -s7, v110, v83
	v_fma_f32 v82, -s8, v16, v82
	v_fma_f32 v74, -s9, v104, v74
	s_nop 0
	s_nop 0
	v_readlane_b32 s6, v217, s19
	v_readlane_b32 s7, v216, s19
	v_readlane_b32 s8, v215, s19
	v_readlane_b32 s9, v214, s40
	v_fma_f32 v75, -s6, v12, v75
	v_fma_f32 v83, -s7, v96, v83
	v_fma_f32 v82, -s8, v10, v82
	v_fma_f32 v74, -s9, v94, v74
	s_nop 0
	s_nop 0
	v_readlane_b32 s6, v213, s40
	v_readlane_b32 s7, v212, s40
	v_readlane_b32 s8, v211, s40
	v_readlane_b32 s9, v214, s19
	v_fma_f32 v75, -s6, v8, v75
	v_fma_f32 v83, -s7, v92, v83
	v_fma_f32 v82, -s8, v4, v82
	v_fma_f32 v74, -s9, v90, v74
	s_nop 0
	s_nop 0
	v_readlane_b32 s6, v213, s19
	s_nop 1
	v_fma_f32 v75, -s6, v91, v75
	s_nop 0
	s_nop 0
	v_readlane_b32 s6, v212, s19
	s_nop 1
	v_fma_f32 v75, -s6, v88, v75
	s_nop 0
	s_nop 0
	v_readlane_b32 s6, v211, s19
	s_nop 1
	v_fma_f32 v75, -s6, v89, v75
	s_nop 0
	v_pk_add_f32 v[74:75], v[82:83], v[74:75]
	s_nop 0
	v_pk_add_f32 v[168:169], v[74:75], v[74:75] op_sel:[0,1] op_sel_hi:[1,0]
	v_mov_b32_e32 v75, v123
	v_mov_b32_e32 v74, v123
	s_nop 0
	v_readlane_b32 s6, v197, s44
	v_readlane_b32 s7, v200, s44
	v_readlane_b32 s8, v199, s44
	v_readlane_b32 s9, v202, s44
	v_fma_f32 v71, -s6, v168, v71
	v_fma_f32 v75, -s7, v78, v75
	v_fma_f32 v74, -s8, v160, v74
	v_fma_f32 v70, -s9, v84, v70
	v_mov_b32_e32 v169, v78
	s_nop 0
	v_readlane_b32 s6, v197, s68
	v_readlane_b32 s7, v200, s68
	v_readlane_b32 s8, v199, s68
	v_readlane_b32 s9, v202, s68
	v_fma_f32 v71, -s6, v154, v71
	v_fma_f32 v75, -s7, v184, v75
	v_fma_f32 v74, -s8, v162, v74
	v_fma_f32 v70, -s9, v180, v70
	s_nop 0
	s_nop 0
	v_readlane_b32 s6, v201, s44
	v_readlane_b32 s7, v204, s44
	v_readlane_b32 s8, v203, s44
	v_readlane_b32 s9, v206, s44
	v_fma_f32 v71, -s6, v164, v71
	v_fma_f32 v75, -s7, v172, v75
	v_fma_f32 v74, -s8, v156, v74
	v_fma_f32 v70, -s9, v176, v70
	s_nop 0
	s_nop 0
	v_readlane_b32 s6, v201, s68
	v_readlane_b32 s7, v204, s68
	v_readlane_b32 s8, v203, s68
	v_readlane_b32 s9, v206, s68
	v_fma_f32 v71, -s6, v150, v71
	v_fma_f32 v75, -s7, v178, v75
	v_fma_f32 v74, -s8, v148, v74
	v_fma_f32 v70, -s9, v174, v70
	s_nop 0
	s_nop 0
	v_readlane_b32 s6, v205, s44
	v_readlane_b32 s7, v208, s44
	v_readlane_b32 s8, v207, s44
	v_readlane_b32 s9, v209, s44
	v_fma_f32 v71, -s6, v146, v71
	v_fma_f32 v75, -s7, v170, v75
	v_fma_f32 v74, -s8, v144, v74
	v_fma_f32 v70, -s9, v166, v70
	s_nop 0
	s_nop 0
	v_readlane_b32 s6, v205, s68
	v_readlane_b32 s7, v208, s68
	v_readlane_b32 s8, v207, s68
	v_readlane_b32 s9, v209, s68
	v_fma_f32 v71, -s6, v142, v71
	v_fma_f32 v75, -s7, v158, v75
	v_fma_f32 v74, -s8, v140, v74
	v_fma_f32 v70, -s9, v152, v70
	s_nop 0
	s_nop 0
	v_readlane_b32 s6, v226, s44
	v_readlane_b32 s7, v225, s44
	v_readlane_b32 s8, v224, s44
	v_readlane_b32 s9, v223, s44
	v_fma_f32 v71, -s6, v138, v71
	v_fma_f32 v75, -s7, v80, v75
	v_fma_f32 v74, -s8, v136, v74
	v_fma_f32 v70, -s9, v76, v70
	s_nop 0
	s_nop 0
	v_readlane_b32 s6, v226, s68
	v_readlane_b32 s7, v225, s68
	v_readlane_b32 s8, v224, s68
	v_readlane_b32 s9, v223, s68
	v_fma_f32 v71, -s6, v134, v71
	v_fma_f32 v75, -s7, v72, v75
	v_fma_f32 v74, -s8, v132, v74
	v_fma_f32 v70, -s9, v68, v70
	s_nop 0
	s_nop 0
	v_readlane_b32 s6, v222, s44
	v_readlane_b32 s7, v221, s44
	v_readlane_b32 s8, v220, s44
	v_readlane_b32 s9, v219, s44
	v_fma_f32 v71, -s6, v130, v71
	v_fma_f32 v75, -s7, v64, v75
	v_fma_f32 v74, -s8, v128, v74
	v_fma_f32 v70, -s9, v32, v70
	s_nop 0
	s_nop 0
	v_readlane_b32 s6, v222, s68
	v_readlane_b32 s7, v221, s68
	v_readlane_b32 s8, v220, s68
	v_readlane_b32 s9, v219, s68
	v_fma_f32 v71, -s6, v118, v71
	v_fma_f32 v75, -s7, v30, v75
	v_fma_f32 v74, -s8, v116, v74
	v_fma_f32 v70, -s9, v26, v70
	s_nop 0
	s_nop 0
	v_readlane_b32 s6, v218, s44
	v_readlane_b32 s7, v217, s44
	v_readlane_b32 s8, v216, s44
	v_readlane_b32 s9, v215, s44
	v_fma_f32 v71, -s6, v114, v71
	v_fma_f32 v75, -s7, v22, v75
	v_fma_f32 v74, -s8, v110, v74
	v_fma_f32 v70, -s9, v16, v70
	s_nop 0
	s_nop 0
	v_readlane_b32 s6, v218, s68
	v_readlane_b32 s7, v217, s68
	v_readlane_b32 s8, v216, s68
	v_readlane_b32 s9, v215, s68
	v_fma_f32 v71, -s6, v104, v71
	v_fma_f32 v75, -s7, v12, v75
	v_fma_f32 v74, -s8, v96, v74
	v_fma_f32 v70, -s9, v10, v70
	s_nop 0
	s_nop 0
	v_readlane_b32 s6, v214, s44
	v_readlane_b32 s7, v213, s44
	v_readlane_b32 s8, v212, s44
	v_readlane_b32 s9, v211, s44
	v_fma_f32 v71, -s6, v94, v71
	v_fma_f32 v75, -s7, v8, v75
	v_fma_f32 v74, -s8, v92, v74
	v_fma_f32 v70, -s9, v4, v70
	s_nop 0
	s_nop 0
	v_readlane_b32 s6, v214, s68
	v_readlane_b32 s7, v213, s68
	v_readlane_b32 s8, v212, s68
	v_readlane_b32 s9, v211, s68
	v_fma_f32 v71, -s6, v90, v71
	v_fma_f32 v75, -s7, v91, v75
	v_fma_f32 v74, -s8, v88, v74
	v_fma_f32 v70, -s9, v89, v70
	s_nop 0
	v_pk_add_f32 v[70:71], v[74:75], v[70:71]
	v_mov_b32_e32 v75, v123
	v_mov_b32_e32 v74, v123
	v_pk_add_f32 v[70:71], v[70:71], v[70:71] op_sel:[0,1] op_sel_hi:[1,0]
	s_nop 0
	s_nop 0
	v_readlane_b32 s6, v198, s3
	v_readlane_b32 s7, v197, s35
	v_readlane_b32 s8, v200, s35
	v_readlane_b32 s9, v199, s35
	v_fma_f32 v67, -s6, v70, v67
	v_fma_f32 v75, -s7, v168, v75
	v_fma_f32 v74, -s8, v78, v74
	v_fma_f32 v66, -s9, v160, v66
	s_nop 0
	s_nop 0
	v_readlane_b32 s6, v202, s35
	v_readlane_b32 s7, v197, s3
	v_readlane_b32 s8, v200, s3
	v_readlane_b32 s9, v199, s3
	v_fma_f32 v67, -s6, v84, v67
	v_fma_f32 v75, -s7, v154, v75
	v_fma_f32 v74, -s8, v184, v74
	v_fma_f32 v66, -s9, v162, v66
	s_nop 0
	s_nop 0
	v_readlane_b32 s6, v202, s3
	v_readlane_b32 s7, v201, s35
	v_readlane_b32 s8, v204, s35
	v_readlane_b32 s9, v203, s35
	v_fma_f32 v67, -s6, v180, v67
	v_fma_f32 v75, -s7, v164, v75
	v_fma_f32 v74, -s8, v172, v74
	v_fma_f32 v66, -s9, v156, v66
	s_nop 0
	s_nop 0
	v_readlane_b32 s6, v206, s35
	v_readlane_b32 s7, v201, s3
	v_readlane_b32 s8, v204, s3
	v_readlane_b32 s9, v203, s3
	v_fma_f32 v67, -s6, v176, v67
	v_fma_f32 v75, -s7, v150, v75
	v_fma_f32 v74, -s8, v178, v74
	v_fma_f32 v66, -s9, v148, v66
	s_nop 0
	s_nop 0
	v_readlane_b32 s6, v206, s3
	v_readlane_b32 s7, v205, s35
	v_readlane_b32 s8, v208, s35
	v_readlane_b32 s9, v207, s35
	v_fma_f32 v67, -s6, v174, v67
	v_fma_f32 v75, -s7, v146, v75
	v_fma_f32 v74, -s8, v170, v74
	v_fma_f32 v66, -s9, v144, v66
	s_nop 0
	s_nop 0
	v_readlane_b32 s6, v209, s35
	v_readlane_b32 s7, v205, s3
	v_readlane_b32 s8, v208, s3
	v_readlane_b32 s9, v207, s3
	v_fma_f32 v67, -s6, v166, v67
	v_fma_f32 v75, -s7, v142, v75
	v_fma_f32 v74, -s8, v158, v74
	v_fma_f32 v66, -s9, v140, v66
	s_nop 0
	s_nop 0
	v_readlane_b32 s6, v209, s3
	v_readlane_b32 s7, v226, s35
	v_readlane_b32 s8, v225, s35
	v_readlane_b32 s9, v224, s35
	v_fma_f32 v67, -s6, v152, v67
	v_fma_f32 v75, -s7, v138, v75
	v_fma_f32 v74, -s8, v80, v74
	v_fma_f32 v66, -s9, v136, v66
	s_nop 0
	s_nop 0
	v_readlane_b32 s6, v223, s35
	v_readlane_b32 s7, v226, s3
	v_readlane_b32 s8, v225, s3
	v_readlane_b32 s9, v224, s3
	v_fma_f32 v67, -s6, v76, v67
	v_fma_f32 v75, -s7, v134, v75
	v_fma_f32 v74, -s8, v72, v74
	v_fma_f32 v66, -s9, v132, v66
	s_nop 0
	s_nop 0
	v_readlane_b32 s6, v223, s3
	v_readlane_b32 s7, v222, s35
	v_readlane_b32 s8, v221, s35
	v_readlane_b32 s9, v220, s35
	v_fma_f32 v67, -s6, v68, v67
	v_fma_f32 v75, -s7, v130, v75
	v_fma_f32 v74, -s8, v64, v74
	v_fma_f32 v66, -s9, v128, v66
	s_nop 0
	s_nop 0
	v_readlane_b32 s6, v219, s35
	v_readlane_b32 s7, v222, s3
	v_readlane_b32 s8, v221, s3
	v_readlane_b32 s9, v220, s3
	v_fma_f32 v67, -s6, v32, v67
	v_fma_f32 v75, -s7, v118, v75
	v_fma_f32 v74, -s8, v30, v74
	v_fma_f32 v66, -s9, v116, v66
	s_nop 0
	s_nop 0
	v_readlane_b32 s6, v219, s3
	v_readlane_b32 s7, v218, s35
	v_readlane_b32 s8, v217, s35
	v_readlane_b32 s9, v216, s35
	v_fma_f32 v67, -s6, v26, v67
	v_fma_f32 v75, -s7, v114, v75
	v_fma_f32 v74, -s8, v22, v74
	v_fma_f32 v66, -s9, v110, v66
	s_nop 0
	s_nop 0
	v_readlane_b32 s6, v215, s35
	v_readlane_b32 s7, v218, s3
	v_readlane_b32 s8, v217, s3
	v_readlane_b32 s9, v216, s3
	v_fma_f32 v67, -s6, v16, v67
	v_fma_f32 v75, -s7, v104, v75
	v_fma_f32 v74, -s8, v12, v74
	v_fma_f32 v66, -s9, v96, v66
	s_nop 0
	s_nop 0
	v_readlane_b32 s6, v215, s3
	v_readlane_b32 s7, v214, s35
	v_readlane_b32 s8, v213, s35
	v_readlane_b32 s9, v212, s35
	v_fma_f32 v67, -s6, v10, v67
	v_fma_f32 v75, -s7, v94, v75
	v_fma_f32 v74, -s8, v8, v74
	v_fma_f32 v66, -s9, v92, v66
	s_nop 0
	s_nop 0
	v_readlane_b32 s6, v211, s35
	v_readlane_b32 s7, v214, s3
	v_readlane_b32 s8, v213, s3
	v_readlane_b32 s9, v212, s3
	v_fma_f32 v67, -s6, v4, v67
	v_fma_f32 v75, -s7, v90, v75
	v_fma_f32 v74, -s8, v91, v74
	v_fma_f32 v66, -s9, v88, v66
	s_nop 0
	s_nop 0
	v_readlane_b32 s6, v211, s3
	s_nop 1
	v_fma_f32 v67, -s6, v89, v67
	s_nop 0
	v_pk_add_f32 v[66:67], v[74:75], v[66:67]
	s_nop 0
	v_pk_add_f32 v[182:183], v[66:67], v[66:67] op_sel:[0,1] op_sel_hi:[1,0]
	v_mov_b32_e32 v67, v123
	v_mov_b32_e32 v66, v123
	s_nop 0
	v_readlane_b32 s6, v195, s16
	v_readlane_b32 s7, v198, s16
	v_readlane_b32 s8, v197, s30
	v_readlane_b32 s9, v200, s30
	v_fma_f32 v63, -s6, v182, v63
	v_fma_f32 v67, -s7, v70, v67
	v_fma_f32 v66, -s8, v168, v66
	v_fma_f32 v62, -s9, v78, v62
	v_mov_b32_e32 v183, v70
	s_nop 0
	v_readlane_b32 s6, v199, s30
	v_readlane_b32 s7, v202, s30
	v_readlane_b32 s8, v197, s16
	v_readlane_b32 s9, v200, s16
	v_fma_f32 v63, -s6, v160, v63
	v_fma_f32 v67, -s7, v84, v67
	v_fma_f32 v66, -s8, v154, v66
	v_fma_f32 v62, -s9, v184, v62
	s_nop 0
	s_nop 0
	v_readlane_b32 s6, v199, s16
	v_readlane_b32 s7, v202, s16
	v_readlane_b32 s8, v201, s30
	v_readlane_b32 s9, v204, s30
	v_fma_f32 v63, -s6, v162, v63
	v_fma_f32 v67, -s7, v180, v67
	v_fma_f32 v66, -s8, v164, v66
	v_fma_f32 v62, -s9, v172, v62
	s_nop 0
	s_nop 0
	v_readlane_b32 s6, v203, s30
	v_readlane_b32 s7, v206, s30
	v_readlane_b32 s8, v201, s16
	v_readlane_b32 s9, v204, s16
	v_fma_f32 v63, -s6, v156, v63
	v_fma_f32 v67, -s7, v176, v67
	v_fma_f32 v66, -s8, v150, v66
	v_fma_f32 v62, -s9, v178, v62
	s_nop 0
	s_nop 0
	v_readlane_b32 s6, v203, s16
	v_readlane_b32 s7, v206, s16
	v_readlane_b32 s8, v205, s30
	v_readlane_b32 s9, v208, s30
	v_fma_f32 v63, -s6, v148, v63
	v_fma_f32 v67, -s7, v174, v67
	v_fma_f32 v66, -s8, v146, v66
	v_fma_f32 v62, -s9, v170, v62
	s_nop 0
	s_nop 0
	v_readlane_b32 s6, v207, s30
	v_readlane_b32 s7, v209, s30
	v_readlane_b32 s8, v205, s16
	v_readlane_b32 s9, v208, s16
	v_fma_f32 v63, -s6, v144, v63
	v_fma_f32 v67, -s7, v166, v67
	v_fma_f32 v66, -s8, v142, v66
	v_fma_f32 v62, -s9, v158, v62
	s_nop 0
	s_nop 0
	v_readlane_b32 s6, v207, s16
	v_readlane_b32 s7, v209, s16
	v_readlane_b32 s8, v226, s30
	v_readlane_b32 s9, v225, s30
	v_fma_f32 v63, -s6, v140, v63
	v_fma_f32 v67, -s7, v152, v67
	v_fma_f32 v66, -s8, v138, v66
	v_fma_f32 v62, -s9, v80, v62
	s_nop 0
	s_nop 0
	v_readlane_b32 s6, v224, s30
	v_readlane_b32 s7, v223, s30
	v_readlane_b32 s8, v226, s16
	v_readlane_b32 s9, v225, s16
	v_fma_f32 v63, -s6, v136, v63
	v_fma_f32 v67, -s7, v76, v67
	v_fma_f32 v66, -s8, v134, v66
	v_fma_f32 v62, -s9, v72, v62
	s_nop 0
	s_nop 0
	v_readlane_b32 s6, v224, s16
	v_readlane_b32 s7, v223, s16
	v_readlane_b32 s8, v222, s30
	v_readlane_b32 s9, v221, s30
	v_fma_f32 v63, -s6, v132, v63
	v_fma_f32 v67, -s7, v68, v67
	v_fma_f32 v66, -s8, v130, v66
	v_fma_f32 v62, -s9, v64, v62
	s_nop 0
	s_nop 0
	v_readlane_b32 s6, v220, s30
	v_readlane_b32 s7, v219, s30
	v_readlane_b32 s8, v222, s16
	v_readlane_b32 s9, v221, s16
	v_fma_f32 v63, -s6, v128, v63
	v_fma_f32 v67, -s7, v32, v67
	v_fma_f32 v66, -s8, v118, v66
	v_fma_f32 v62, -s9, v30, v62
	s_nop 0
	s_nop 0
	v_readlane_b32 s6, v220, s16
	v_readlane_b32 s7, v219, s16
	v_readlane_b32 s8, v218, s30
	v_readlane_b32 s9, v217, s30
	v_fma_f32 v63, -s6, v116, v63
	v_fma_f32 v67, -s7, v26, v67
	v_fma_f32 v66, -s8, v114, v66
	v_fma_f32 v62, -s9, v22, v62
	s_nop 0
	s_nop 0
	v_readlane_b32 s6, v216, s30
	v_readlane_b32 s7, v215, s30
	v_readlane_b32 s8, v218, s16
	v_readlane_b32 s9, v217, s16
	v_fma_f32 v63, -s6, v110, v63
	v_fma_f32 v67, -s7, v16, v67
	v_fma_f32 v66, -s8, v104, v66
	v_fma_f32 v62, -s9, v12, v62
	s_nop 0
	s_nop 0
	v_readlane_b32 s6, v216, s16
	v_readlane_b32 s7, v215, s16
	v_readlane_b32 s8, v214, s30
	v_readlane_b32 s9, v213, s30
	v_fma_f32 v63, -s6, v96, v63
	v_fma_f32 v67, -s7, v10, v67
	v_fma_f32 v66, -s8, v94, v66
	v_fma_f32 v62, -s9, v8, v62
	s_nop 0
	s_nop 0
	v_readlane_b32 s6, v212, s30
	v_readlane_b32 s7, v211, s30
	v_readlane_b32 s8, v214, s16
	v_readlane_b32 s9, v213, s16
	v_fma_f32 v63, -s6, v92, v63
	v_fma_f32 v67, -s7, v4, v67
	v_fma_f32 v66, -s8, v90, v66
	v_fma_f32 v62, -s9, v91, v62
	s_nop 0
	s_nop 0
	v_readlane_b32 s6, v212, s16
	s_nop 1
	v_fma_f32 v63, -s6, v88, v63
	s_nop 0
	s_nop 0
	v_readlane_b32 s6, v211, s16
	s_nop 1
	v_fma_f32 v63, -s6, v89, v63
	s_nop 0
	v_pk_add_f32 v[62:63], v[66:67], v[62:63]
	v_mov_b32_e32 v67, v123
	v_mov_b32_e32 v66, v123
	v_pk_add_f32 v[62:63], v[62:63], v[62:63] op_sel:[0,1] op_sel_hi:[1,0]
	s_nop 0
	s_nop 0
	v_readlane_b32 s6, v196, s17
	v_readlane_b32 s7, v195, s17
	v_readlane_b32 s8, v198, s17
	v_readlane_b32 s9, v197, s36
	v_fma_f32 v29, -s6, v62, v29
	v_fma_f32 v67, -s7, v182, v67
	v_fma_f32 v66, -s8, v70, v66
	v_fma_f32 v28, -s9, v168, v28
	s_nop 0
	s_nop 0
	v_readlane_b32 s6, v200, s36
	v_readlane_b32 s7, v199, s36
	v_readlane_b32 s8, v202, s36
	v_readlane_b32 s9, v197, s17
	v_fma_f32 v29, -s6, v78, v29
	v_fma_f32 v67, -s7, v160, v67
	v_fma_f32 v66, -s8, v84, v66
	v_fma_f32 v28, -s9, v154, v28
	s_nop 0
	s_nop 0
	v_readlane_b32 s6, v200, s17
	v_readlane_b32 s7, v199, s17
	v_readlane_b32 s8, v202, s17
	v_readlane_b32 s9, v201, s36
	v_fma_f32 v29, -s6, v184, v29
	v_fma_f32 v67, -s7, v162, v67
	v_fma_f32 v66, -s8, v180, v66
	v_fma_f32 v28, -s9, v164, v28
	s_nop 0
	s_nop 0
	v_readlane_b32 s6, v204, s36
	v_readlane_b32 s7, v203, s36
	v_readlane_b32 s8, v206, s36
	v_readlane_b32 s9, v201, s17
	v_fma_f32 v29, -s6, v172, v29
	v_fma_f32 v67, -s7, v156, v67
	v_fma_f32 v66, -s8, v176, v66
	v_fma_f32 v28, -s9, v150, v28
	s_nop 0
	s_nop 0
	v_readlane_b32 s6, v204, s17
	v_readlane_b32 s7, v203, s17
	v_readlane_b32 s8, v206, s17
	v_readlane_b32 s9, v205, s36
	v_fma_f32 v29, -s6, v178, v29
	v_fma_f32 v67, -s7, v148, v67
	v_fma_f32 v66, -s8, v174, v66
	v_fma_f32 v28, -s9, v146, v28
	s_nop 0
	s_nop 0
	v_readlane_b32 s6, v208, s36
	v_readlane_b32 s7, v207, s36
	v_readlane_b32 s8, v209, s36
	v_readlane_b32 s9, v205, s17
	v_fma_f32 v29, -s6, v170, v29
	v_fma_f32 v67, -s7, v144, v67
	v_fma_f32 v66, -s8, v166, v66
	v_fma_f32 v28, -s9, v142, v28
	s_nop 0
	s_nop 0
	v_readlane_b32 s6, v208, s17
	v_readlane_b32 s7, v207, s17
	v_readlane_b32 s8, v209, s17
	v_readlane_b32 s9, v226, s36
	v_fma_f32 v29, -s6, v158, v29
	v_fma_f32 v67, -s7, v140, v67
	v_fma_f32 v66, -s8, v152, v66
	v_fma_f32 v28, -s9, v138, v28
	s_nop 0
	s_nop 0
	v_readlane_b32 s6, v225, s36
	v_readlane_b32 s7, v224, s36
	v_readlane_b32 s8, v223, s36
	v_readlane_b32 s9, v226, s17
	v_fma_f32 v29, -s6, v80, v29
	v_fma_f32 v67, -s7, v136, v67
	v_fma_f32 v66, -s8, v76, v66
	v_fma_f32 v28, -s9, v134, v28
	s_nop 0
	s_nop 0
	v_readlane_b32 s6, v225, s17
	v_readlane_b32 s7, v224, s17
	v_readlane_b32 s8, v223, s17
	v_readlane_b32 s9, v222, s36
	v_fma_f32 v29, -s6, v72, v29
	v_fma_f32 v67, -s7, v132, v67
	v_fma_f32 v66, -s8, v68, v66
	v_fma_f32 v28, -s9, v130, v28
	s_nop 0
	s_nop 0
	v_readlane_b32 s6, v221, s36
	v_readlane_b32 s7, v220, s36
	v_readlane_b32 s8, v219, s36
	v_readlane_b32 s9, v222, s17
	v_fma_f32 v29, -s6, v64, v29
	v_fma_f32 v67, -s7, v128, v67
	v_fma_f32 v66, -s8, v32, v66
	v_fma_f32 v28, -s9, v118, v28
	s_nop 0
	s_nop 0
	v_readlane_b32 s6, v221, s17
	v_readlane_b32 s7, v220, s17
	v_readlane_b32 s8, v219, s17
	v_readlane_b32 s9, v218, s36
	v_fma_f32 v29, -s6, v30, v29
	v_fma_f32 v67, -s7, v116, v67
	v_fma_f32 v66, -s8, v26, v66
	v_fma_f32 v28, -s9, v114, v28
	s_nop 0
	s_nop 0
	v_readlane_b32 s6, v217, s36
	v_readlane_b32 s7, v216, s36
	v_readlane_b32 s8, v215, s36
	v_readlane_b32 s9, v218, s17
	v_fma_f32 v29, -s6, v22, v29
	v_fma_f32 v67, -s7, v110, v67
	v_fma_f32 v66, -s8, v16, v66
	v_fma_f32 v28, -s9, v104, v28
	s_nop 0
	s_nop 0
	v_readlane_b32 s6, v217, s17
	v_readlane_b32 s7, v216, s17
	v_readlane_b32 s8, v215, s17
	v_readlane_b32 s9, v214, s36
	v_fma_f32 v29, -s6, v12, v29
	v_fma_f32 v67, -s7, v96, v67
	v_fma_f32 v66, -s8, v10, v66
	v_fma_f32 v28, -s9, v94, v28
	s_nop 0
	s_nop 0
	v_readlane_b32 s6, v213, s36
	v_readlane_b32 s7, v212, s36
	v_readlane_b32 s8, v211, s36
	v_readlane_b32 s9, v214, s17
	v_fma_f32 v29, -s6, v8, v29
	v_fma_f32 v67, -s7, v92, v67
	v_fma_f32 v66, -s8, v4, v66
	v_fma_f32 v28, -s9, v90, v28
	s_nop 0
	s_nop 0
	v_readlane_b32 s6, v213, s17
	s_nop 1
	v_fma_f32 v29, -s6, v91, v29
	s_nop 0
	s_nop 0
	v_readlane_b32 s6, v212, s17
	s_nop 1
	v_fma_f32 v29, -s6, v88, v29
	s_nop 0
	s_nop 0
	v_readlane_b32 s6, v211, s17
	s_nop 1
	v_fma_f32 v29, -s6, v89, v29
	s_nop 0
	v_pk_add_f32 v[28:29], v[66:67], v[28:29]
	s_nop 0
	v_pk_add_f32 v[186:187], v[28:29], v[28:29] op_sel:[0,1] op_sel_hi:[1,0]
	v_mov_b32_e32 v29, v123
	v_mov_b32_e32 v28, v123
	s_nop 0
	v_readlane_b32 s6, v194, s69
	v_readlane_b32 s7, v196, s69
	v_readlane_b32 s8, v195, s69
	v_readlane_b32 s9, v198, s69
	v_fma_f32 v25, -s6, v186, v25
	v_fma_f32 v29, -s7, v62, v29
	v_fma_f32 v28, -s8, v182, v28
	v_fma_f32 v24, -s9, v70, v24
	v_mov_b32_e32 v187, v62
	s_nop 0
	v_readlane_b32 s6, v197, s12
	v_readlane_b32 s7, v200, s12
	v_readlane_b32 s8, v199, s12
	v_readlane_b32 s9, v202, s12
	v_fma_f32 v25, -s6, v168, v25
	v_fma_f32 v29, -s7, v78, v29
	v_fma_f32 v28, -s8, v160, v28
	v_fma_f32 v24, -s9, v84, v24
	s_nop 0
	s_nop 0
	v_readlane_b32 s6, v197, s69
	v_readlane_b32 s7, v200, s69
	v_readlane_b32 s8, v199, s69
	v_readlane_b32 s9, v202, s69
	v_fma_f32 v25, -s6, v154, v25
	v_fma_f32 v29, -s7, v184, v29
	v_fma_f32 v28, -s8, v162, v28
	v_fma_f32 v24, -s9, v180, v24
	s_nop 0
	s_nop 0
	v_readlane_b32 s6, v201, s12
	v_readlane_b32 s7, v204, s12
	v_readlane_b32 s8, v203, s12
	v_readlane_b32 s9, v206, s12
	v_fma_f32 v25, -s6, v164, v25
	v_fma_f32 v29, -s7, v172, v29
	v_fma_f32 v28, -s8, v156, v28
	v_fma_f32 v24, -s9, v176, v24
	s_nop 0
	s_nop 0
	v_readlane_b32 s6, v201, s69
	v_readlane_b32 s7, v204, s69
	v_readlane_b32 s8, v203, s69
	v_readlane_b32 s9, v206, s69
	v_fma_f32 v25, -s6, v150, v25
	v_fma_f32 v29, -s7, v178, v29
	v_fma_f32 v28, -s8, v148, v28
	v_fma_f32 v24, -s9, v174, v24
	s_nop 0
	s_nop 0
	v_readlane_b32 s6, v205, s12
	v_readlane_b32 s7, v208, s12
	v_readlane_b32 s8, v207, s12
	v_readlane_b32 s9, v209, s12
	v_fma_f32 v25, -s6, v146, v25
	v_fma_f32 v29, -s7, v170, v29
	v_fma_f32 v28, -s8, v144, v28
	v_fma_f32 v24, -s9, v166, v24
	s_nop 0
	s_nop 0
	v_readlane_b32 s6, v205, s69
	v_readlane_b32 s7, v208, s69
	v_readlane_b32 s8, v207, s69
	v_readlane_b32 s9, v209, s69
	v_fma_f32 v25, -s6, v142, v25
	v_fma_f32 v29, -s7, v158, v29
	v_fma_f32 v28, -s8, v140, v28
	v_fma_f32 v24, -s9, v152, v24
	s_nop 0
	s_nop 0
	v_readlane_b32 s6, v226, s12
	v_readlane_b32 s7, v225, s12
	v_readlane_b32 s8, v224, s12
	v_readlane_b32 s9, v223, s12
	v_fma_f32 v25, -s6, v138, v25
	v_fma_f32 v29, -s7, v80, v29
	v_fma_f32 v28, -s8, v136, v28
	v_fma_f32 v24, -s9, v76, v24
	s_nop 0
	s_nop 0
	v_readlane_b32 s6, v226, s69
	v_readlane_b32 s7, v225, s69
	v_readlane_b32 s8, v224, s69
	v_readlane_b32 s9, v223, s69
	v_fma_f32 v25, -s6, v134, v25
	v_fma_f32 v29, -s7, v72, v29
	v_fma_f32 v28, -s8, v132, v28
	v_fma_f32 v24, -s9, v68, v24
	s_nop 0
	s_nop 0
	v_readlane_b32 s6, v222, s12
	v_readlane_b32 s7, v221, s12
	v_readlane_b32 s8, v220, s12
	v_readlane_b32 s9, v219, s12
	v_fma_f32 v25, -s6, v130, v25
	v_fma_f32 v29, -s7, v64, v29
	v_fma_f32 v28, -s8, v128, v28
	v_fma_f32 v24, -s9, v32, v24
	s_nop 0
	s_nop 0
	v_readlane_b32 s6, v222, s69
	v_readlane_b32 s7, v221, s69
	v_readlane_b32 s8, v220, s69
	v_readlane_b32 s9, v219, s69
	v_fma_f32 v25, -s6, v118, v25
	v_fma_f32 v29, -s7, v30, v29
	v_fma_f32 v28, -s8, v116, v28
	v_fma_f32 v24, -s9, v26, v24
	s_nop 0
	s_nop 0
	v_readlane_b32 s6, v218, s12
	v_readlane_b32 s7, v217, s12
	v_readlane_b32 s8, v216, s12
	v_readlane_b32 s9, v215, s12
	v_fma_f32 v25, -s6, v114, v25
	v_fma_f32 v29, -s7, v22, v29
	v_fma_f32 v28, -s8, v110, v28
	v_fma_f32 v24, -s9, v16, v24
	s_nop 0
	s_nop 0
	v_readlane_b32 s6, v218, s69
	v_readlane_b32 s7, v217, s69
	v_readlane_b32 s8, v216, s69
	v_readlane_b32 s9, v215, s69
	v_fma_f32 v25, -s6, v104, v25
	v_fma_f32 v29, -s7, v12, v29
	v_fma_f32 v28, -s8, v96, v28
	v_fma_f32 v24, -s9, v10, v24
	s_nop 0
	s_nop 0
	v_readlane_b32 s6, v214, s12
	v_readlane_b32 s7, v213, s12
	v_readlane_b32 s8, v212, s12
	v_readlane_b32 s9, v211, s12
	v_fma_f32 v25, -s6, v94, v25
	v_fma_f32 v29, -s7, v8, v29
	v_fma_f32 v28, -s8, v92, v28
	v_fma_f32 v24, -s9, v4, v24
	s_nop 0
	s_nop 0
	v_readlane_b32 s6, v214, s69
	v_readlane_b32 s7, v213, s69
	v_readlane_b32 s8, v212, s69
	v_readlane_b32 s9, v211, s69
	v_fma_f32 v25, -s6, v90, v25
	v_fma_f32 v29, -s7, v91, v29
	v_fma_f32 v28, -s8, v88, v28
	v_fma_f32 v24, -s9, v89, v24
	s_nop 0
	v_pk_add_f32 v[24:25], v[28:29], v[24:25]
	v_mov_b32_e32 v29, v123
	v_mov_b32_e32 v28, v123
	v_pk_add_f32 v[24:25], v[24:25], v[24:25] op_sel:[0,1] op_sel_hi:[1,0]
	s_nop 0
	s_nop 0
	v_readlane_b32 s6, v198, s15
	v_readlane_b32 s7, v194, s23
	v_readlane_b32 s8, v196, s23
	v_readlane_b32 s9, v195, s23
	v_fma_f32 v15, -s6, v24, v15
	v_fma_f32 v29, -s7, v186, v29
	v_fma_f32 v28, -s8, v62, v28
	v_fma_f32 v14, -s9, v182, v14
	s_nop 0
	s_nop 0
	v_readlane_b32 s6, v198, s23
	v_readlane_b32 s7, v197, s15
	v_readlane_b32 s8, v200, s15
	v_readlane_b32 s9, v199, s15
	v_fma_f32 v15, -s6, v70, v15
	v_fma_f32 v29, -s7, v168, v29
	v_fma_f32 v28, -s8, v78, v28
	v_fma_f32 v14, -s9, v160, v14
	s_nop 0
	s_nop 0
	v_readlane_b32 s6, v202, s15
	v_readlane_b32 s7, v197, s23
	v_readlane_b32 s8, v200, s23
	v_readlane_b32 s9, v199, s23
	v_fma_f32 v15, -s6, v84, v15
	v_fma_f32 v29, -s7, v154, v29
	v_fma_f32 v28, -s8, v184, v28
	v_fma_f32 v14, -s9, v162, v14
	s_nop 0
	s_nop 0
	v_readlane_b32 s6, v202, s23
	v_readlane_b32 s7, v201, s15
	v_readlane_b32 s8, v204, s15
	v_readlane_b32 s9, v203, s15
	v_fma_f32 v15, -s6, v180, v15
	v_fma_f32 v29, -s7, v164, v29
	v_fma_f32 v28, -s8, v172, v28
	v_fma_f32 v14, -s9, v156, v14
	s_nop 0
	s_nop 0
	v_readlane_b32 s6, v206, s15
	v_readlane_b32 s7, v201, s23
	v_readlane_b32 s8, v204, s23
	v_readlane_b32 s9, v203, s23
	v_fma_f32 v15, -s6, v176, v15
	v_fma_f32 v29, -s7, v150, v29
	v_fma_f32 v28, -s8, v178, v28
	v_fma_f32 v14, -s9, v148, v14
	s_nop 0
	s_nop 0
	v_readlane_b32 s6, v206, s23
	v_readlane_b32 s7, v205, s15
	v_readlane_b32 s8, v208, s15
	v_readlane_b32 s9, v207, s15
	v_fma_f32 v15, -s6, v174, v15
	v_fma_f32 v29, -s7, v146, v29
	v_fma_f32 v28, -s8, v170, v28
	v_fma_f32 v14, -s9, v144, v14
	s_nop 0
	s_nop 0
	v_readlane_b32 s6, v209, s15
	v_readlane_b32 s7, v205, s23
	v_readlane_b32 s8, v208, s23
	v_readlane_b32 s9, v207, s23
	v_fma_f32 v15, -s6, v166, v15
	v_fma_f32 v29, -s7, v142, v29
	v_fma_f32 v28, -s8, v158, v28
	v_fma_f32 v14, -s9, v140, v14
	s_nop 0
	s_nop 0
	v_readlane_b32 s6, v209, s23
	v_readlane_b32 s7, v226, s15
	v_readlane_b32 s8, v225, s15
	v_readlane_b32 s9, v224, s15
	v_fma_f32 v15, -s6, v152, v15
	v_fma_f32 v29, -s7, v138, v29
	v_fma_f32 v28, -s8, v80, v28
	v_fma_f32 v14, -s9, v136, v14
	s_nop 0
	s_nop 0
	v_readlane_b32 s6, v223, s15
	v_readlane_b32 s7, v226, s23
	v_readlane_b32 s8, v225, s23
	v_readlane_b32 s9, v224, s23
	v_fma_f32 v15, -s6, v76, v15
	v_fma_f32 v29, -s7, v134, v29
	v_fma_f32 v28, -s8, v72, v28
	v_fma_f32 v14, -s9, v132, v14
	s_nop 0
	s_nop 0
	v_readlane_b32 s6, v223, s23
	v_readlane_b32 s7, v222, s15
	v_readlane_b32 s8, v221, s15
	v_readlane_b32 s9, v220, s15
	v_fma_f32 v15, -s6, v68, v15
	v_fma_f32 v29, -s7, v130, v29
	v_fma_f32 v28, -s8, v64, v28
	v_fma_f32 v14, -s9, v128, v14
	s_nop 0
	s_nop 0
	v_readlane_b32 s6, v219, s15
	v_readlane_b32 s7, v222, s23
	v_readlane_b32 s8, v221, s23
	v_readlane_b32 s9, v220, s23
	v_fma_f32 v15, -s6, v32, v15
	v_fma_f32 v29, -s7, v118, v29
	v_fma_f32 v28, -s8, v30, v28
	v_fma_f32 v14, -s9, v116, v14
	s_nop 0
	s_nop 0
	v_readlane_b32 s6, v219, s23
	v_readlane_b32 s7, v218, s15
	v_readlane_b32 s8, v217, s15
	v_readlane_b32 s9, v216, s15
	v_fma_f32 v15, -s6, v26, v15
	v_fma_f32 v29, -s7, v114, v29
	v_fma_f32 v28, -s8, v22, v28
	v_fma_f32 v14, -s9, v110, v14
	s_nop 0
	s_nop 0
	v_readlane_b32 s6, v215, s15
	v_readlane_b32 s7, v218, s23
	v_readlane_b32 s8, v217, s23
	v_readlane_b32 s9, v216, s23
	v_fma_f32 v15, -s6, v16, v15
	v_fma_f32 v29, -s7, v104, v29
	v_fma_f32 v28, -s8, v12, v28
	v_fma_f32 v14, -s9, v96, v14
	s_nop 0
	s_nop 0
	v_readlane_b32 s6, v215, s23
	v_readlane_b32 s7, v214, s15
	v_readlane_b32 s8, v213, s15
	v_readlane_b32 s9, v212, s15
	v_fma_f32 v15, -s6, v10, v15
	v_fma_f32 v29, -s7, v94, v29
	v_fma_f32 v28, -s8, v8, v28
	v_fma_f32 v14, -s9, v92, v14
	s_nop 0
	s_nop 0
	v_readlane_b32 s6, v211, s15
	v_readlane_b32 s7, v214, s23
	v_readlane_b32 s8, v213, s23
	v_readlane_b32 s9, v212, s23
	v_fma_f32 v15, -s6, v4, v15
	v_fma_f32 v29, -s7, v90, v29
	v_fma_f32 v28, -s8, v91, v28
	v_fma_f32 v14, -s9, v88, v14
	s_nop 0
	s_nop 0
	v_readlane_b32 s6, v211, s23
	s_nop 1
	v_fma_f32 v15, -s6, v89, v15
	s_nop 0
	v_pk_add_f32 v[14:15], v[28:29], v[14:15]
	s_nop 0
	v_pk_add_f32 v[188:189], v[14:15], v[14:15] op_sel:[0,1] op_sel_hi:[1,0]
	v_mov_b32_e32 v15, v123
	v_mov_b32_e32 v14, v123
	s_nop 0
	v_readlane_b32 s6, v195, s26
	v_readlane_b32 s7, v198, s26
	v_readlane_b32 s8, v194, s10
	v_readlane_b32 s9, v196, s10
	v_fma_f32 v7, -s6, v188, v7
	v_fma_f32 v15, -s7, v24, v15
	v_fma_f32 v14, -s8, v186, v14
	v_fma_f32 v6, -s9, v62, v6
	v_mov_b32_e32 v189, v24
	s_nop 0
	v_readlane_b32 s6, v195, s10
	v_readlane_b32 s7, v198, s10
	v_readlane_b32 s8, v197, s26
	v_readlane_b32 s9, v200, s26
	v_fma_f32 v7, -s6, v182, v7
	v_fma_f32 v15, -s7, v70, v15
	v_fma_f32 v14, -s8, v168, v14
	v_fma_f32 v6, -s9, v78, v6
	s_nop 0
	s_nop 0
	v_readlane_b32 s6, v199, s26
	v_readlane_b32 s7, v202, s26
	v_readlane_b32 s8, v197, s10
	v_readlane_b32 s9, v200, s10
	v_fma_f32 v7, -s6, v160, v7
	v_fma_f32 v15, -s7, v84, v15
	v_fma_f32 v14, -s8, v154, v14
	v_fma_f32 v6, -s9, v184, v6
	s_nop 0
	s_nop 0
	v_readlane_b32 s6, v199, s10
	v_readlane_b32 s7, v202, s10
	v_readlane_b32 s8, v201, s26
	v_readlane_b32 s9, v204, s26
	v_fma_f32 v7, -s6, v162, v7
	v_fma_f32 v15, -s7, v180, v15
	v_fma_f32 v14, -s8, v164, v14
	v_fma_f32 v6, -s9, v172, v6
	s_nop 0
	s_nop 0
	v_readlane_b32 s6, v203, s26
	v_readlane_b32 s7, v206, s26
	v_readlane_b32 s8, v201, s10
	v_readlane_b32 s9, v204, s10
	v_fma_f32 v7, -s6, v156, v7
	v_fma_f32 v15, -s7, v176, v15
	v_fma_f32 v14, -s8, v150, v14
	v_fma_f32 v6, -s9, v178, v6
	s_nop 0
	s_nop 0
	v_readlane_b32 s6, v203, s10
	v_readlane_b32 s7, v206, s10
	v_readlane_b32 s8, v205, s26
	v_readlane_b32 s9, v208, s26
	v_fma_f32 v7, -s6, v148, v7
	v_fma_f32 v15, -s7, v174, v15
	v_fma_f32 v14, -s8, v146, v14
	v_fma_f32 v6, -s9, v170, v6
	s_nop 0
	s_nop 0
	v_readlane_b32 s6, v207, s26
	v_readlane_b32 s7, v209, s26
	v_readlane_b32 s8, v205, s10
	v_readlane_b32 s9, v208, s10
	v_fma_f32 v7, -s6, v144, v7
	v_fma_f32 v15, -s7, v166, v15
	v_fma_f32 v14, -s8, v142, v14
	v_fma_f32 v6, -s9, v158, v6
	s_nop 0
	s_nop 0
	v_readlane_b32 s6, v207, s10
	v_readlane_b32 s7, v209, s10
	v_readlane_b32 s8, v226, s26
	v_readlane_b32 s9, v225, s26
	v_fma_f32 v7, -s6, v140, v7
	v_fma_f32 v15, -s7, v152, v15
	v_fma_f32 v14, -s8, v138, v14
	v_fma_f32 v6, -s9, v80, v6
	s_nop 0
	s_nop 0
	v_readlane_b32 s6, v224, s26
	v_readlane_b32 s7, v223, s26
	v_readlane_b32 s8, v226, s10
	v_readlane_b32 s9, v225, s10
	v_fma_f32 v7, -s6, v136, v7
	v_fma_f32 v15, -s7, v76, v15
	v_fma_f32 v14, -s8, v134, v14
	v_fma_f32 v6, -s9, v72, v6
	s_nop 0
	s_nop 0
	v_readlane_b32 s6, v224, s10
	v_readlane_b32 s7, v223, s10
	v_readlane_b32 s8, v222, s26
	v_readlane_b32 s9, v221, s26
	v_fma_f32 v7, -s6, v132, v7
	v_fma_f32 v15, -s7, v68, v15
	v_fma_f32 v14, -s8, v130, v14
	v_fma_f32 v6, -s9, v64, v6
	s_nop 0
	s_nop 0
	v_readlane_b32 s6, v220, s26
	v_readlane_b32 s7, v219, s26
	v_readlane_b32 s8, v222, s10
	v_readlane_b32 s9, v221, s10
	v_fma_f32 v7, -s6, v128, v7
	v_fma_f32 v15, -s7, v32, v15
	v_fma_f32 v14, -s8, v118, v14
	v_fma_f32 v6, -s9, v30, v6
	s_nop 0
	s_nop 0
	v_readlane_b32 s6, v220, s10
	v_readlane_b32 s7, v219, s10
	v_readlane_b32 s8, v218, s26
	v_readlane_b32 s9, v217, s26
	v_fma_f32 v7, -s6, v116, v7
	v_fma_f32 v15, -s7, v26, v15
	v_fma_f32 v14, -s8, v114, v14
	v_fma_f32 v6, -s9, v22, v6
	s_nop 0
	s_nop 0
	v_readlane_b32 s6, v216, s26
	v_readlane_b32 s7, v215, s26
	v_readlane_b32 s8, v218, s10
	v_readlane_b32 s9, v217, s10
	v_fma_f32 v7, -s6, v110, v7
	v_fma_f32 v15, -s7, v16, v15
	v_fma_f32 v14, -s8, v104, v14
	v_fma_f32 v6, -s9, v12, v6
	s_nop 0
	s_nop 0
	v_readlane_b32 s6, v216, s10
	v_readlane_b32 s7, v215, s10
	v_readlane_b32 s8, v214, s26
	v_readlane_b32 s9, v213, s26
	v_fma_f32 v7, -s6, v96, v7
	v_fma_f32 v15, -s7, v10, v15
	v_fma_f32 v14, -s8, v94, v14
	v_fma_f32 v6, -s9, v8, v6
	s_nop 0
	s_nop 0
	v_readlane_b32 s6, v212, s26
	v_readlane_b32 s7, v211, s26
	v_readlane_b32 s8, v214, s10
	v_readlane_b32 s9, v213, s10
	v_fma_f32 v7, -s6, v92, v7
	v_fma_f32 v15, -s7, v4, v15
	v_fma_f32 v14, -s8, v90, v14
	v_fma_f32 v6, -s9, v91, v6
	s_nop 0
	s_nop 0
	v_readlane_b32 s6, v212, s10
	s_nop 1
	v_fma_f32 v7, -s6, v88, v7
	s_nop 0
	s_nop 0
	v_readlane_b32 s6, v211, s10
	s_nop 1
	v_fma_f32 v7, -s6, v89, v7
	s_nop 0
	v_pk_add_f32 v[6:7], v[14:15], v[6:7]
	v_mov_b32_e32 v15, v123
	v_mov_b32_e32 v14, v123
	v_pk_add_f32 v[6:7], v[6:7], v[6:7] op_sel:[0,1] op_sel_hi:[1,0]
	s_nop 0
	s_nop 0
	v_readlane_b32 s6, v196, s13
	v_readlane_b32 s7, v195, s13
	v_readlane_b32 s8, v198, s13
	v_readlane_b32 s9, v194, s31
	v_fma_f32 v3, -s6, v6, v3
	v_fma_f32 v15, -s7, v188, v15
	v_fma_f32 v14, -s8, v24, v14
	v_fma_f32 v2, -s9, v186, v2
	s_nop 0
	s_nop 0
	v_readlane_b32 s6, v196, s31
	v_readlane_b32 s7, v195, s31
	v_readlane_b32 s8, v198, s31
	v_readlane_b32 s9, v197, s13
	v_fma_f32 v3, -s6, v62, v3
	v_fma_f32 v15, -s7, v182, v15
	v_fma_f32 v14, -s8, v70, v14
	v_fma_f32 v2, -s9, v168, v2
	s_nop 0
	s_nop 0
	v_readlane_b32 s6, v200, s13
	v_readlane_b32 s7, v199, s13
	v_readlane_b32 s8, v202, s13
	v_readlane_b32 s9, v197, s31
	v_fma_f32 v3, -s6, v78, v3
	v_fma_f32 v15, -s7, v160, v15
	v_fma_f32 v14, -s8, v84, v14
	v_fma_f32 v2, -s9, v154, v2
	s_nop 0
	s_nop 0
	v_readlane_b32 s6, v200, s31
	v_readlane_b32 s7, v199, s31
	v_readlane_b32 s8, v202, s31
	v_readlane_b32 s9, v201, s13
	v_fma_f32 v3, -s6, v184, v3
	v_fma_f32 v15, -s7, v162, v15
	v_fma_f32 v14, -s8, v180, v14
	v_fma_f32 v2, -s9, v164, v2
	s_nop 0
	s_nop 0
	v_readlane_b32 s6, v204, s13
	v_readlane_b32 s7, v203, s13
	v_readlane_b32 s8, v206, s13
	v_readlane_b32 s9, v201, s31
	v_fma_f32 v3, -s6, v172, v3
	v_fma_f32 v15, -s7, v156, v15
	v_fma_f32 v14, -s8, v176, v14
	v_fma_f32 v2, -s9, v150, v2
	s_nop 0
	s_nop 0
	v_readlane_b32 s6, v204, s31
	v_readlane_b32 s7, v203, s31
	v_readlane_b32 s8, v206, s31
	v_readlane_b32 s9, v205, s13
	v_fma_f32 v3, -s6, v178, v3
	v_fma_f32 v15, -s7, v148, v15
	v_fma_f32 v14, -s8, v174, v14
	v_fma_f32 v2, -s9, v146, v2
	s_nop 0
	s_nop 0
	v_readlane_b32 s6, v208, s13
	v_readlane_b32 s7, v207, s13
	v_readlane_b32 s8, v209, s13
	v_readlane_b32 s9, v205, s31
	v_fma_f32 v3, -s6, v170, v3
	v_fma_f32 v15, -s7, v144, v15
	v_fma_f32 v14, -s8, v166, v14
	v_fma_f32 v2, -s9, v142, v2
	s_nop 0
	s_nop 0
	v_readlane_b32 s6, v208, s31
	v_readlane_b32 s7, v207, s31
	v_readlane_b32 s8, v209, s31
	v_readlane_b32 s9, v226, s13
	v_fma_f32 v3, -s6, v158, v3
	v_fma_f32 v15, -s7, v140, v15
	v_fma_f32 v14, -s8, v152, v14
	v_fma_f32 v2, -s9, v138, v2
	s_nop 0
	s_nop 0
	v_readlane_b32 s6, v225, s13
	v_readlane_b32 s7, v224, s13
	v_readlane_b32 s8, v223, s13
	v_readlane_b32 s9, v226, s31
	v_fma_f32 v3, -s6, v80, v3
	v_fma_f32 v15, -s7, v136, v15
	v_fma_f32 v14, -s8, v76, v14
	v_fma_f32 v2, -s9, v134, v2
	s_nop 0
	s_nop 0
	v_readlane_b32 s6, v225, s31
	v_readlane_b32 s7, v224, s31
	v_readlane_b32 s8, v223, s31
	v_readlane_b32 s9, v222, s13
	v_fma_f32 v3, -s6, v72, v3
	v_fma_f32 v15, -s7, v132, v15
	v_fma_f32 v14, -s8, v68, v14
	v_fma_f32 v2, -s9, v130, v2
	s_nop 0
	s_nop 0
	v_readlane_b32 s6, v221, s13
	v_readlane_b32 s7, v220, s13
	v_readlane_b32 s8, v219, s13
	v_readlane_b32 s9, v222, s31
	v_fma_f32 v3, -s6, v64, v3
	v_fma_f32 v15, -s7, v128, v15
	v_fma_f32 v14, -s8, v32, v14
	v_fma_f32 v2, -s9, v118, v2
	s_nop 0
	s_nop 0
	v_readlane_b32 s6, v221, s31
	v_readlane_b32 s7, v220, s31
	v_readlane_b32 s8, v219, s31
	v_readlane_b32 s9, v218, s13
	v_fma_f32 v3, -s6, v30, v3
	v_fma_f32 v15, -s7, v116, v15
	v_fma_f32 v14, -s8, v26, v14
	v_fma_f32 v2, -s9, v114, v2
	s_nop 0
	s_nop 0
	v_readlane_b32 s6, v217, s13
	v_readlane_b32 s7, v216, s13
	v_readlane_b32 s8, v215, s13
	v_readlane_b32 s9, v218, s31
	v_fma_f32 v3, -s6, v22, v3
	v_fma_f32 v15, -s7, v110, v15
	v_fma_f32 v14, -s8, v16, v14
	v_fma_f32 v2, -s9, v104, v2
	s_nop 0
	s_nop 0
	v_readlane_b32 s6, v217, s31
	v_readlane_b32 s7, v216, s31
	v_readlane_b32 s8, v215, s31
	v_readlane_b32 s9, v214, s13
	v_fma_f32 v3, -s6, v12, v3
	v_fma_f32 v15, -s7, v96, v15
	v_fma_f32 v14, -s8, v10, v14
	v_fma_f32 v2, -s9, v94, v2
	s_nop 0
	s_nop 0
	v_readlane_b32 s6, v213, s13
	v_readlane_b32 s7, v212, s13
	v_readlane_b32 s8, v211, s13
	v_readlane_b32 s9, v214, s31
	v_fma_f32 v3, -s6, v8, v3
	v_fma_f32 v15, -s7, v92, v15
	v_fma_f32 v14, -s8, v4, v14
	v_fma_f32 v2, -s9, v90, v2
	s_nop 0
	s_nop 0
	v_readlane_b32 s6, v213, s31
	s_nop 1
	v_fma_f32 v3, -s6, v91, v3
	s_nop 0
	s_nop 0
	v_readlane_b32 s6, v212, s31
	s_nop 1
	v_fma_f32 v3, -s6, v88, v3
	s_nop 0
	s_nop 0
	v_readlane_b32 s6, v211, s31
	s_nop 1
	v_fma_f32 v3, -s6, v89, v3
	s_nop 0
	v_pk_add_f32 v[2:3], v[14:15], v[2:3]
	s_nop 0
	v_pk_add_f32 v[152:153], v[2:3], v[2:3] op_sel:[0,1] op_sel_hi:[1,0]
	v_readlane_b32 s6, v193, 0
	v_readlane_b32 s7, v193, 1
	v_mov_b32_e32 v153, v6
	s_nop 0
	v_pk_mul_f32 v[2:3], v[152:153], s[6:7]
	v_readlane_b32 s6, v193, 8
	v_readlane_b32 s7, v193, 9
	v_cvt_pk_bf16_f32 v62, v2, v3
	s_nop 0
	v_pk_mul_f32 v[4:5], v[168:169], s[6:7]
	v_readlane_b32 s6, v193, 2
	v_readlane_b32 s7, v193, 3
	v_cvt_pk_bf16_f32 v66, v4, v5
	s_nop 1
	v_permlane32_swap_b32_e32 v62, v66
	v_pk_mul_f32 v[6:7], v[188:189], s[6:7]
	v_readlane_b32 s6, v193, 10
	v_readlane_b32 s7, v193, 11
	v_cvt_pk_bf16_f32 v63, v6, v7
	s_nop 0
	v_pk_mul_f32 v[8:9], v[160:161], s[6:7]
	v_readlane_b32 s6, v193, 4
	v_readlane_b32 s7, v193, 5
	v_cvt_pk_bf16_f32 v67, v8, v9
	s_nop 1
	v_permlane32_swap_b32_e32 v63, v67
	v_pk_mul_f32 v[10:11], v[186:187], s[6:7]
	v_readlane_b32 s6, v193, 12
	v_readlane_b32 s7, v193, 13
	v_cvt_pk_bf16_f32 v64, v10, v11
	s_nop 0
	v_pk_mul_f32 v[12:13], v[154:155], s[6:7]
	v_readlane_b32 s6, v193, 6
	v_readlane_b32 s7, v193, 7
	v_cvt_pk_bf16_f32 v68, v12, v13
	s_nop 1
	v_permlane32_swap_b32_e32 v64, v68
	v_pk_mul_f32 v[14:15], v[182:183], s[6:7]
	v_readlane_b32 s6, v193, 14
	v_readlane_b32 s7, v193, 15
	v_cvt_pk_bf16_f32 v65, v14, v15
	s_nop 0
	v_pk_mul_f32 v[16:17], v[162:163], s[6:7]
	v_readlane_b32 s6, v193, 16
	v_readlane_b32 s7, v193, 17
	v_cvt_pk_bf16_f32 v69, v16, v17
	s_nop 1
	v_permlane32_swap_b32_e32 v65, v69
	v_pk_mul_f32 v[2:3], v[164:165], s[6:7]
	v_readlane_b32 s6, v193, 24
	v_readlane_b32 s7, v193, 25
	v_cvt_pk_bf16_f32 v70, v2, v3
	s_nop 0
	v_pk_mul_f32 v[4:5], v[146:147], s[6:7]
	v_readlane_b32 s6, v193, 18
	v_readlane_b32 s7, v193, 19
	v_cvt_pk_bf16_f32 v74, v4, v5
	s_nop 1
	v_permlane32_swap_b32_e32 v70, v74
	v_pk_mul_f32 v[6:7], v[156:157], s[6:7]
	v_readlane_b32 s6, v193, 26
	v_readlane_b32 s7, v193, 27
	v_cvt_pk_bf16_f32 v71, v6, v7
	s_nop 0
	v_pk_mul_f32 v[8:9], v[144:145], s[6:7]
	v_readlane_b32 s6, v193, 20
	v_readlane_b32 s7, v193, 21
	v_cvt_pk_bf16_f32 v75, v8, v9
	s_nop 1
	v_permlane32_swap_b32_e32 v71, v75
	v_pk_mul_f32 v[10:11], v[150:151], s[6:7]
	v_readlane_b32 s6, v193, 28
	v_readlane_b32 s7, v193, 29
	v_cvt_pk_bf16_f32 v72, v10, v11
	s_nop 0
	v_pk_mul_f32 v[12:13], v[142:143], s[6:7]
	v_readlane_b32 s6, v193, 22
	v_readlane_b32 s7, v193, 23
	v_cvt_pk_bf16_f32 v76, v12, v13
	s_nop 1
	v_permlane32_swap_b32_e32 v72, v76
	v_pk_mul_f32 v[14:15], v[148:149], s[6:7]
	v_readlane_b32 s6, v193, 30
	v_readlane_b32 s7, v193, 31
	v_cvt_pk_bf16_f32 v73, v14, v15
	s_nop 0
	v_pk_mul_f32 v[16:17], v[140:141], s[6:7]
	v_readlane_b32 s6, v193, 32
	v_readlane_b32 s7, v193, 33
	v_cvt_pk_bf16_f32 v77, v16, v17
	s_nop 1
	v_permlane32_swap_b32_e32 v73, v77
	v_pk_mul_f32 v[2:3], v[138:139], s[6:7]
	v_readlane_b32 s6, v193, 40
	v_readlane_b32 s7, v193, 41
	v_cvt_pk_bf16_f32 v2, v2, v3
	s_nop 0
	v_pk_mul_f32 v[4:5], v[130:131], s[6:7]
	v_readlane_b32 s6, v193, 34
	v_readlane_b32 s7, v193, 35
	v_cvt_pk_bf16_f32 v78, v4, v5
	s_nop 1
	v_permlane32_swap_b32_e32 v2, v78
	v_pk_mul_f32 v[6:7], v[136:137], s[6:7]
	v_readlane_b32 s6, v193, 42
	v_readlane_b32 s7, v193, 43
	v_cvt_pk_bf16_f32 v3, v6, v7
	s_nop 0
	v_pk_mul_f32 v[8:9], v[128:129], s[6:7]
	v_readlane_b32 s6, v193, 36
	v_readlane_b32 s7, v193, 37
	v_cvt_pk_bf16_f32 v79, v8, v9
	s_nop 1
	v_permlane32_swap_b32_e32 v3, v79
	v_pk_mul_f32 v[10:11], v[134:135], s[6:7]
	v_readlane_b32 s6, v193, 44
	v_readlane_b32 s7, v193, 45
	v_cvt_pk_bf16_f32 v6, v10, v11
	s_nop 0
	v_pk_mul_f32 v[12:13], v[118:119], s[6:7]
	v_readlane_b32 s6, v193, 38
	v_readlane_b32 s7, v193, 39
	v_cvt_pk_bf16_f32 v80, v12, v13
	s_nop 1
	v_permlane32_swap_b32_e32 v6, v80
	v_pk_mul_f32 v[14:15], v[132:133], s[6:7]
	v_readlane_b32 s6, v193, 46
	v_readlane_b32 s7, v193, 47
	v_cvt_pk_bf16_f32 v7, v14, v15
	s_nop 0
	v_pk_mul_f32 v[16:17], v[116:117], s[6:7]
	v_readlane_b32 s6, v193, 48
	v_readlane_b32 s7, v193, 49
	v_cvt_pk_bf16_f32 v81, v16, v17
	s_nop 1
	v_permlane32_swap_b32_e32 v7, v81
	v_pk_mul_f32 v[2:3], v[114:115], s[6:7]
	v_readlane_b32 s6, v193, 56
	v_readlane_b32 s7, v193, 57
	v_cvt_pk_bf16_f32 v2, v2, v3
	s_nop 0
	v_pk_mul_f32 v[4:5], v[94:95], s[6:7]
	v_readlane_b32 s6, v193, 50
	v_readlane_b32 s7, v193, 51
	v_cvt_pk_bf16_f32 v82, v4, v5
	s_nop 1
	v_permlane32_swap_b32_e32 v2, v82
	v_pk_mul_f32 v[6:7], v[110:111], s[6:7]
	v_readlane_b32 s6, v193, 58
	v_readlane_b32 s7, v193, 59
	v_cvt_pk_bf16_f32 v3, v6, v7
	s_nop 0
	v_pk_mul_f32 v[8:9], v[92:93], s[6:7]
	v_readlane_b32 s6, v193, 52
	v_readlane_b32 s7, v193, 53
	v_cvt_pk_bf16_f32 v83, v8, v9
	s_nop 1
	v_permlane32_swap_b32_e32 v3, v83
	v_pk_mul_f32 v[10:11], v[104:105], s[6:7]
	v_readlane_b32 s6, v193, 60
	v_readlane_b32 s7, v193, 61
	v_cvt_pk_bf16_f32 v6, v10, v11
	s_nop 0
	v_pk_mul_f32 v[12:13], v[90:91], s[6:7]
	v_readlane_b32 s6, v193, 54
	v_readlane_b32 s7, v193, 55
	v_cvt_pk_bf16_f32 v84, v12, v13
	s_nop 1
	v_permlane32_swap_b32_e32 v6, v84
	v_pk_mul_f32 v[14:15], v[96:97], s[6:7]
	v_readlane_b32 s6, v193, 62
	v_readlane_b32 s7, v193, 63
	v_cvt_pk_bf16_f32 v7, v14, v15
	s_nop 0
	v_pk_mul_f32 v[16:17], v[88:89], s[6:7]
	s_mov_b32 s7, 0x26400000
	v_cvt_pk_bf16_f32 v85, v16, v17
	s_nop 1
	v_permlane32_swap_b32_e32 v7, v85
	s_waitcnt vmcnt(5)
	v_mfma_f32_32x32x16_bf16 v[2:17], v[62:65], v[18:21], 0
	s_mov_b32 s6, 0x9002000
	v_mfma_f32_32x32x16_bf16 v[18:33], v[66:69], v[18:21], 0
	v_mfma_f32_32x32x16_bf16 v[18:33], v[74:77], v[58:61], v[18:33]
	v_mfma_f32_32x32x16_bf16 v[18:33], v[78:81], v[54:57], v[18:33]
	v_mfma_f32_32x32x16_bf16 v[2:17], v[70:73], v[58:61], v[2:17]
	s_waitcnt vmcnt(4)
	v_mfma_f32_32x32x16_bf16 v[18:33], v[82:85], v[50:53], v[18:33]
	v_add_co_u32_e32 v50, vcc, s7, v126
	s_nop 8
	v_cvt_pk_bf16_f32 v2, v2, v3
	v_cvt_pk_bf16_f32 v3, v4, v5
	v_cvt_pk_bf16_f32 v4, v6, v7
	v_cvt_pk_bf16_f32 v5, v8, v9
	v_addc_co_u32_e32 v51, vcc, 0, v127, vcc
	global_store_dwordx4 v[50:51], v[2:5], off
	v_add_co_u32_e32 v6, vcc, s7, v120
	s_nop 0
	v_cvt_pk_bf16_f32 v2, v10, v11
	v_cvt_pk_bf16_f32 v3, v12, v13
	v_cvt_pk_bf16_f32 v4, v14, v15
	v_cvt_pk_bf16_f32 v5, v16, v17
	global_store_dwordx4 v[50:51], v[2:5], off offset:16
	v_addc_co_u32_e32 v7, vcc, 0, v121, vcc
	s_nop 0
	v_cvt_pk_bf16_f32 v2, v18, v19
	v_cvt_pk_bf16_f32 v3, v20, v21
	v_cvt_pk_bf16_f32 v4, v22, v23
	v_cvt_pk_bf16_f32 v5, v24, v25
	global_store_dwordx4 v[6:7], v[2:5], off
	s_nop 1
	v_cvt_pk_bf16_f32 v2, v26, v27
	v_cvt_pk_bf16_f32 v3, v28, v29
	v_cvt_pk_bf16_f32 v4, v30, v31
	v_cvt_pk_bf16_f32 v5, v32, v33
	global_store_dwordx4 v[6:7], v[2:5], off offset:16
	s_waitcnt vmcnt(7)
	v_mfma_f32_32x32x16_bf16 v[18:33], v[62:65], v[46:49], 0
	v_mfma_f32_32x32x16_bf16 v[2:17], v[66:69], v[46:49], 0
	s_waitcnt vmcnt(6)
	v_mfma_f32_32x32x16_bf16 v[2:17], v[74:77], v[42:45], v[2:17]
	s_waitcnt vmcnt(5)
	v_mfma_f32_32x32x16_bf16 v[2:17], v[78:81], v[38:41], v[2:17]
	s_waitcnt vmcnt(4)
	v_mfma_f32_32x32x16_bf16 v[2:17], v[82:85], v[34:37], v[2:17]
	v_mfma_f32_32x32x16_bf16 v[18:33], v[70:73], v[42:45], v[18:33]
	s_nop 10
	v_cvt_pk_bf16_f32 v2, v2, v3
	v_cvt_pk_bf16_f32 v3, v4, v5
	v_cvt_pk_bf16_f32 v4, v6, v7
	v_add_co_u32_e32 v6, vcc, s7, v112
	v_cvt_pk_bf16_f32 v5, v8, v9
	s_nop 0
	v_addc_co_u32_e32 v7, vcc, 0, v113, vcc
	v_cvt_pk_bf16_f32 v18, v18, v19
	v_cvt_pk_bf16_f32 v19, v20, v21
	v_cvt_pk_bf16_f32 v20, v22, v23
	v_cvt_pk_bf16_f32 v21, v24, v25
	v_add_co_u32_e32 v38, vcc, s6, v98
	global_store_dwordx4 v[50:51], v[18:21], off offset:2048
	s_nop 0
	v_addc_co_u32_e32 v39, vcc, 0, v99, vcc
	v_cvt_pk_bf16_f32 v18, v26, v27
	v_cvt_pk_bf16_f32 v19, v28, v29
	v_cvt_pk_bf16_f32 v20, v30, v31
	v_cvt_pk_bf16_f32 v21, v32, v33
	s_mov_b32 s6, 0x9003000
	global_store_dwordx4 v[50:51], v[18:21], off offset:2064
	global_store_dwordx4 v[6:7], v[2:5], off
	v_add_co_u32_e32 v40, vcc, s6, v98
	s_nop 0
	v_cvt_pk_bf16_f32 v2, v10, v11
	v_cvt_pk_bf16_f32 v3, v12, v13
	v_cvt_pk_bf16_f32 v4, v14, v15
	v_cvt_pk_bf16_f32 v5, v16, v17
	global_store_dwordx4 v[6:7], v[2:5], off offset:16
	v_addc_co_u32_e32 v41, vcc, 0, v99, vcc
	global_load_dwordx4 v[2:5], v[40:41], off offset:-4096
	global_load_dwordx4 v[34:37], v[38:39], off offset:32
	s_waitcnt vmcnt(1)
	v_mfma_f32_32x32x16_bf16 v[18:33], v[62:65], v[2:5], 0
	v_mfma_f32_32x32x16_bf16 v[2:17], v[66:69], v[2:5], 0
	s_waitcnt vmcnt(0)
	v_mfma_f32_32x32x16_bf16 v[18:33], v[70:73], v[34:37], v[18:33]
	v_mfma_f32_32x32x16_bf16 v[2:17], v[74:77], v[34:37], v[2:17]
	global_load_dwordx4 v[34:37], v[38:39], off offset:64
	s_nop 9
	v_cvt_pk_bf16_f32 v18, v18, v19
	v_cvt_pk_bf16_f32 v19, v20, v21
	v_cvt_pk_bf16_f32 v20, v22, v23
	v_add_co_u32_e32 v22, vcc, s7, v108
	v_cvt_pk_bf16_f32 v21, v24, v25
	s_waitcnt vmcnt(0)
	v_mfma_f32_32x32x16_bf16 v[2:17], v[78:81], v[34:37], v[2:17]
	global_load_dwordx4 v[34:37], v[38:39], off offset:96
	v_addc_co_u32_e32 v23, vcc, 0, v109, vcc
	global_store_dwordx4 v[22:23], v[18:21], off
	s_nop 1
	v_cvt_pk_bf16_f32 v18, v26, v27
	s_waitcnt vmcnt(1)
	v_mfma_f32_32x32x16_bf16 v[2:17], v[82:85], v[34:37], v[2:17]
	v_cvt_pk_bf16_f32 v19, v28, v29
	v_cvt_pk_bf16_f32 v20, v30, v31
	v_cvt_pk_bf16_f32 v21, v32, v33
	global_store_dwordx4 v[22:23], v[18:21], off offset:16
	s_nop 7
	v_cvt_pk_bf16_f32 v2, v2, v3
	v_cvt_pk_bf16_f32 v3, v4, v5
	v_cvt_pk_bf16_f32 v4, v6, v7
	v_add_co_u32_e32 v6, vcc, s7, v106
	v_cvt_pk_bf16_f32 v5, v8, v9
	s_nop 0
	v_addc_co_u32_e32 v7, vcc, 0, v107, vcc
	global_store_dwordx4 v[6:7], v[2:5], off
	s_nop 1
	v_cvt_pk_bf16_f32 v2, v10, v11
	v_cvt_pk_bf16_f32 v3, v12, v13
	v_cvt_pk_bf16_f32 v4, v14, v15
	v_cvt_pk_bf16_f32 v5, v16, v17
	global_store_dwordx4 v[6:7], v[2:5], off offset:16
	global_load_dwordx4 v[2:5], v[40:41], off
	s_nop 0
	global_load_dwordx4 v[34:37], v[40:41], off offset:32
	s_waitcnt vmcnt(1)
	v_mfma_f32_32x32x16_bf16 v[18:33], v[62:65], v[2:5], 0
	v_mfma_f32_32x32x16_bf16 v[2:17], v[66:69], v[2:5], 0
	s_waitcnt vmcnt(0)
	v_mfma_f32_32x32x16_bf16 v[18:33], v[70:73], v[34:37], v[18:33]
	v_mfma_f32_32x32x16_bf16 v[2:17], v[74:77], v[34:37], v[2:17]
	global_load_dwordx4 v[34:37], v[40:41], off offset:64
	s_nop 9
	v_cvt_pk_bf16_f32 v18, v18, v19
	v_cvt_pk_bf16_f32 v19, v20, v21
	v_cvt_pk_bf16_f32 v20, v22, v23
	v_add_co_u32_e32 v22, vcc, s7, v102
	v_cvt_pk_bf16_f32 v21, v24, v25
	s_waitcnt vmcnt(0)
	v_mfma_f32_32x32x16_bf16 v[2:17], v[78:81], v[34:37], v[2:17]
	global_load_dwordx4 v[34:37], v[40:41], off offset:96
	v_addc_co_u32_e32 v23, vcc, 0, v103, vcc
	global_store_dwordx4 v[22:23], v[18:21], off
	s_nop 1
	v_cvt_pk_bf16_f32 v18, v26, v27
	s_waitcnt vmcnt(1)
	v_mfma_f32_32x32x16_bf16 v[2:17], v[82:85], v[34:37], v[2:17]
	v_cvt_pk_bf16_f32 v19, v28, v29
	v_cvt_pk_bf16_f32 v20, v30, v31
	v_cvt_pk_bf16_f32 v21, v32, v33
	global_store_dwordx4 v[22:23], v[18:21], off offset:16
	s_nop 7
	v_cvt_pk_bf16_f32 v2, v2, v3
	v_cvt_pk_bf16_f32 v3, v4, v5
	v_cvt_pk_bf16_f32 v4, v6, v7
	v_add_co_u32_e32 v6, vcc, s7, v100
	v_cvt_pk_bf16_f32 v5, v8, v9
	s_nop 0
	v_addc_co_u32_e32 v7, vcc, 0, v101, vcc
	global_store_dwordx4 v[6:7], v[2:5], off
	s_nop 1
	v_cvt_pk_bf16_f32 v2, v10, v11
	v_cvt_pk_bf16_f32 v3, v12, v13
	v_cvt_pk_bf16_f32 v4, v14, v15
	v_cvt_pk_bf16_f32 v5, v16, v17
	global_store_dwordx4 v[6:7], v[2:5], off offset:16
	v_readlane_b32 s6, v210, 0
	v_readlane_b32 s7, v210, 1
	s_lshl_b64 s[4:5], s[4:5], 20
	v_readlane_b32 s8, v250, 17
	v_pk_mul_f32 v[2:3], v[152:153], s[6:7]
	v_readlane_b32 s6, v210, 8
	v_readlane_b32 s7, v210, 9
	v_cvt_pk_bf16_f32 v34, v2, v3
	s_nop 0
	v_pk_mul_f32 v[4:5], v[168:169], s[6:7]
	v_readlane_b32 s6, v210, 2
	v_readlane_b32 s7, v210, 3
	v_cvt_pk_bf16_f32 v38, v4, v5
	s_nop 1
	v_permlane32_swap_b32_e32 v34, v38
	v_pk_mul_f32 v[6:7], v[188:189], s[6:7]
	v_readlane_b32 s6, v210, 10
	v_readlane_b32 s7, v210, 11
	v_cvt_pk_bf16_f32 v35, v6, v7
	s_nop 0
	v_pk_mul_f32 v[8:9], v[160:161], s[6:7]
	v_readlane_b32 s6, v210, 4
	v_readlane_b32 s7, v210, 5
	v_cvt_pk_bf16_f32 v39, v8, v9
	s_nop 1
	v_permlane32_swap_b32_e32 v35, v39
	v_pk_mul_f32 v[10:11], v[186:187], s[6:7]
	v_readlane_b32 s6, v210, 12
	v_readlane_b32 s7, v210, 13
	v_cvt_pk_bf16_f32 v36, v10, v11
	s_nop 0
	v_pk_mul_f32 v[12:13], v[154:155], s[6:7]
	v_readlane_b32 s6, v210, 6
	v_readlane_b32 s7, v210, 7
	v_cvt_pk_bf16_f32 v40, v12, v13
	s_nop 1
	v_permlane32_swap_b32_e32 v36, v40
	v_pk_mul_f32 v[14:15], v[182:183], s[6:7]
	v_readlane_b32 s6, v210, 14
	v_readlane_b32 s7, v210, 15
	v_cvt_pk_bf16_f32 v37, v14, v15
	s_nop 0
	v_pk_mul_f32 v[16:17], v[162:163], s[6:7]
	v_readlane_b32 s6, v210, 16
	v_readlane_b32 s7, v210, 17
	v_cvt_pk_bf16_f32 v41, v16, v17
	s_nop 1
	v_permlane32_swap_b32_e32 v37, v41
	v_pk_mul_f32 v[2:3], v[164:165], s[6:7]
	v_readlane_b32 s6, v210, 24
	v_readlane_b32 s7, v210, 25
	v_cvt_pk_bf16_f32 v42, v2, v3
	s_nop 0
	v_pk_mul_f32 v[4:5], v[146:147], s[6:7]
	v_readlane_b32 s6, v210, 18
	v_readlane_b32 s7, v210, 19
	v_cvt_pk_bf16_f32 v46, v4, v5
	s_nop 1
	v_permlane32_swap_b32_e32 v42, v46
	v_pk_mul_f32 v[6:7], v[156:157], s[6:7]
	v_readlane_b32 s6, v210, 26
	v_readlane_b32 s7, v210, 27
	v_cvt_pk_bf16_f32 v43, v6, v7
	s_nop 0
	v_pk_mul_f32 v[8:9], v[144:145], s[6:7]
	v_readlane_b32 s6, v210, 20
	v_readlane_b32 s7, v210, 21
	v_cvt_pk_bf16_f32 v47, v8, v9
	s_nop 1
	v_permlane32_swap_b32_e32 v43, v47
	v_pk_mul_f32 v[10:11], v[150:151], s[6:7]
	v_readlane_b32 s6, v210, 28
	v_readlane_b32 s7, v210, 29
	v_cvt_pk_bf16_f32 v44, v10, v11
	s_nop 0
	v_pk_mul_f32 v[12:13], v[142:143], s[6:7]
	v_readlane_b32 s6, v210, 22
	v_readlane_b32 s7, v210, 23
	v_cvt_pk_bf16_f32 v48, v12, v13
	s_nop 1
	v_permlane32_swap_b32_e32 v44, v48
	v_pk_mul_f32 v[14:15], v[148:149], s[6:7]
	v_readlane_b32 s6, v210, 30
	v_readlane_b32 s7, v210, 31
	v_cvt_pk_bf16_f32 v45, v14, v15
	s_nop 0
	v_pk_mul_f32 v[16:17], v[140:141], s[6:7]
	v_readlane_b32 s6, v210, 32
	v_readlane_b32 s7, v210, 33
	v_cvt_pk_bf16_f32 v49, v16, v17
	s_nop 1
	v_permlane32_swap_b32_e32 v45, v49
	v_pk_mul_f32 v[2:3], v[138:139], s[6:7]
	v_readlane_b32 s6, v210, 40
	v_readlane_b32 s7, v210, 41
	v_cvt_pk_bf16_f32 v2, v2, v3
	s_nop 0
	v_pk_mul_f32 v[4:5], v[130:131], s[6:7]
	v_readlane_b32 s6, v210, 34
	v_readlane_b32 s7, v210, 35
	v_cvt_pk_bf16_f32 v50, v4, v5
	s_nop 1
	v_permlane32_swap_b32_e32 v2, v50
	v_pk_mul_f32 v[6:7], v[136:137], s[6:7]
	v_readlane_b32 s6, v210, 42
	v_readlane_b32 s7, v210, 43
	v_cvt_pk_bf16_f32 v3, v6, v7
	s_nop 0
	v_pk_mul_f32 v[8:9], v[128:129], s[6:7]
	v_readlane_b32 s6, v210, 36
	v_readlane_b32 s7, v210, 37
	v_cvt_pk_bf16_f32 v51, v8, v9
	s_nop 1
	v_permlane32_swap_b32_e32 v3, v51
	v_pk_mul_f32 v[10:11], v[134:135], s[6:7]
	v_readlane_b32 s6, v210, 44
	v_readlane_b32 s7, v210, 45
	v_cvt_pk_bf16_f32 v6, v10, v11
	s_nop 0
	v_pk_mul_f32 v[12:13], v[118:119], s[6:7]
	v_readlane_b32 s6, v210, 38
	v_readlane_b32 s7, v210, 39
	v_cvt_pk_bf16_f32 v52, v12, v13
	s_nop 1
	v_permlane32_swap_b32_e32 v6, v52
	v_pk_mul_f32 v[14:15], v[132:133], s[6:7]
	v_readlane_b32 s6, v210, 46
	v_readlane_b32 s7, v210, 47
	v_cvt_pk_bf16_f32 v7, v14, v15
	s_nop 0
	v_pk_mul_f32 v[16:17], v[116:117], s[6:7]
	v_readlane_b32 s6, v210, 48
	v_readlane_b32 s7, v210, 49
	v_cvt_pk_bf16_f32 v53, v16, v17
	s_nop 1
	v_permlane32_swap_b32_e32 v7, v53
	v_pk_mul_f32 v[2:3], v[114:115], s[6:7]
	v_readlane_b32 s6, v210, 56
	v_readlane_b32 s7, v210, 57
	v_cvt_pk_bf16_f32 v2, v2, v3
	s_nop 0
	v_pk_mul_f32 v[4:5], v[94:95], s[6:7]
	v_readlane_b32 s6, v210, 50
	v_readlane_b32 s7, v210, 51
	v_cvt_pk_bf16_f32 v54, v4, v5
	s_nop 1
	v_permlane32_swap_b32_e32 v2, v54
	v_pk_mul_f32 v[6:7], v[110:111], s[6:7]
	v_readlane_b32 s6, v210, 58
	v_readlane_b32 s7, v210, 59
	v_cvt_pk_bf16_f32 v3, v6, v7
	v_lshlrev_b32_e32 v2, 8, v192
	v_pk_mul_f32 v[8:9], v[92:93], s[6:7]
	v_readlane_b32 s6, v210, 52
	v_readlane_b32 s7, v210, 53
	v_cvt_pk_bf16_f32 v55, v8, v9
	s_nop 1
	v_permlane32_swap_b32_e32 v3, v55
	v_pk_mul_f32 v[10:11], v[104:105], s[6:7]
	v_readlane_b32 s6, v210, 60
	v_readlane_b32 s7, v210, 61
	v_mov_b32_e32 v3, v123
	v_lshl_add_u64 v[2:3], v[2:3], 0, v[124:125]
	v_pk_mul_f32 v[12:13], v[90:91], s[6:7]
	v_readlane_b32 s6, v210, 54
	v_readlane_b32 s7, v210, 55
	v_lshl_add_u64 v[64:65], s[0:1], 0, v[2:3]
	v_cvt_pk_bf16_f32 v6, v10, v11
	v_pk_mul_f32 v[14:15], v[96:97], s[6:7]
	v_readlane_b32 s6, v210, 62
	v_readlane_b32 s7, v210, 63
	v_cvt_pk_bf16_f32 v7, v14, v15
	v_cvt_pk_bf16_f32 v56, v12, v13
	v_pk_mul_f32 v[16:17], v[88:89], s[6:7]
	v_readlane_b32 s6, v250, 3
	s_add_u32 s4, s6, s4
	v_readlane_b32 s6, v250, 4
	s_addc_u32 s5, s6, s5
	v_readlane_b32 s6, v250, 13
	s_lshl_b32 s6, s6, 14
	s_add_u32 s4, s4, s6
	s_addc_u32 s5, s5, 0
	v_lshl_add_u64 v[62:63], s[4:5], 0, v[86:87]
	v_lshl_add_u64 v[66:67], v[62:63], 0, v[122:123]
	v_mov_b32_e32 v142, 0x1000
	v_mov_b32_e32 v143, 0
	v_lshl_add_u64 v[130:131], v[66:67], 0, v[142:143]
	v_lshl_add_u64 v[134:135], v[130:131], 0, v[142:143]
	v_lshl_add_u64 v[138:139], v[134:135], 0, v[142:143]
	global_load_dwordx4 v[202:205], v[66:67], off
	global_load_dwordx4 v[208:211], v[66:67], off offset:32
	global_load_dwordx4 v[212:215], v[66:67], off offset:64
	global_load_dwordx4 v[216:219], v[66:67], off offset:96
	global_load_dwordx4 v[220:223], v[130:131], off
	global_load_dwordx4 v[234:237], v[130:131], off offset:32
	global_load_dwordx4 v[238:241], v[130:131], off offset:64
	global_load_dwordx4 v[242:245], v[130:131], off offset:96
	s_nop 0
	s_nop 0
	v_cvt_pk_bf16_f32 v57, v16, v17
	v_permlane32_swap_b32_e32 v6, v56
	s_nop 0
	v_permlane32_swap_b32_e32 v7, v57
	s_nop 0
	s_waitcnt vmcnt(7)
	v_mfma_f32_32x32x16_bf16 v[18:33], v[202:205], v[34:37], 0
	s_mov_b32 s0, 0x2e400000
	v_readlane_b32 s7, v250, 15
	v_mfma_f32_32x32x16_bf16 v[2:17], v[202:205], v[38:41], 0
	s_nop 0
	s_waitcnt vmcnt(6)
	v_mfma_f32_32x32x16_bf16 v[18:33], v[208:211], v[42:45], v[18:33]
	v_mfma_f32_32x32x16_bf16 v[2:17], v[208:211], v[46:49], v[2:17]
	s_nop 0
	s_nop 9
	v_cvt_pk_bf16_f32 v18, v18, v19
	v_cvt_pk_bf16_f32 v19, v20, v21
	s_nop 0
	s_waitcnt vmcnt(5)
	v_mfma_f32_32x32x16_bf16 v[2:17], v[212:215], v[50:53], v[2:17]
	s_nop 0
	s_nop 0
	s_waitcnt vmcnt(4)
	v_mfma_f32_32x32x16_bf16 v[2:17], v[216:219], v[54:57], v[2:17]
	v_add_co_u32_e32 v58, vcc, s0, v64
	s_mov_b32 s0, 0x2e402000
	s_nop 0
	v_addc_co_u32_e32 v59, vcc, 0, v65, vcc
	v_add_co_u32_e32 v60, vcc, s0, v64
	s_nop 6
	v_cvt_pk_bf16_f32 v2, v2, v3
	v_cvt_pk_bf16_f32 v3, v4, v5
	v_addc_co_u32_e32 v61, vcc, 0, v65, vcc
	global_store_dwordx2 v[60:61], v[2:3], off
	v_cvt_pk_bf16_f32 v2, v22, v23
	v_cvt_pk_bf16_f32 v3, v24, v25
	global_store_dwordx2 v[58:59], v[2:3], off offset:16
	v_cvt_pk_bf16_f32 v2, v6, v7
	v_cvt_pk_bf16_f32 v3, v8, v9
	global_store_dwordx2 v[60:61], v[2:3], off offset:16
	v_cvt_pk_bf16_f32 v2, v26, v27
	v_cvt_pk_bf16_f32 v3, v28, v29
	global_store_dwordx2 v[58:59], v[2:3], off offset:32
	v_cvt_pk_bf16_f32 v2, v10, v11
	v_cvt_pk_bf16_f32 v3, v12, v13
	global_store_dwordx2 v[60:61], v[2:3], off offset:32
	v_cvt_pk_bf16_f32 v2, v30, v31
	v_cvt_pk_bf16_f32 v3, v32, v33
	global_store_dwordx2 v[58:59], v[2:3], off offset:48
	v_cvt_pk_bf16_f32 v2, v14, v15
	v_cvt_pk_bf16_f32 v3, v16, v17
	global_store_dwordx2 v[60:61], v[2:3], off offset:48
	v_or_b32_e32 v2, 0x1000, v122
	v_mov_b32_e32 v3, v123
	global_store_dwordx2 v[58:59], v[18:19], off
	v_lshl_add_u64 v[68:69], v[62:63], 0, v[2:3]
	global_load_dwordx4 v[202:205], v[134:135], off
	global_load_dwordx4 v[208:211], v[134:135], off offset:32
	global_load_dwordx4 v[212:215], v[134:135], off offset:64
	global_load_dwordx4 v[216:219], v[134:135], off offset:96
	s_nop 0
	s_nop 0
	s_nop 0
	s_waitcnt vmcnt(15)
	v_mfma_f32_32x32x16_bf16 v[18:33], v[220:223], v[34:37], 0
	v_readlane_b32 s0, v250, 9
	v_readlane_b32 s1, v250, 10
	s_add_i32 s33, s33, s0
	v_readlane_b32 s0, v250, 5
	v_readlane_b32 s1, v250, 6
	s_add_u32 s24, s24, s0
	s_addc_u32 s25, s25, s1
	v_mfma_f32_32x32x16_bf16 v[2:17], v[220:223], v[38:41], 0
	v_readlane_b32 s0, v250, 7
	v_readlane_b32 s1, v250, 8
	s_add_u32 s28, s28, s0
	s_addc_u32 s29, s29, s1
	v_readlane_b32 s0, v250, 11
	v_readlane_b32 s1, v250, 12
	s_add_u32 s7, s7, s0
	s_nop 0
	s_waitcnt vmcnt(14)
	v_mfma_f32_32x32x16_bf16 v[18:33], v[234:237], v[42:45], v[18:33]
	s_addc_u32 s8, s8, s1
	s_cmpk_lt_i32 s33, 0x2000
	v_mfma_f32_32x32x16_bf16 v[2:17], v[234:237], v[46:49], v[2:17]
	s_nop 0
	s_nop 7
	v_cvt_pk_bf16_f32 v18, v18, v19
	v_cvt_pk_bf16_f32 v19, v20, v21
	s_nop 0
	s_waitcnt vmcnt(13)
	v_mfma_f32_32x32x16_bf16 v[2:17], v[238:241], v[50:53], v[2:17]
	s_nop 0
	s_nop 0
	global_store_dwordx2 v[58:59], v[18:19], off offset:64
	s_nop 0
	s_waitcnt vmcnt(13)
	v_mfma_f32_32x32x16_bf16 v[2:17], v[242:245], v[54:57], v[2:17]
	s_nop 11
	v_cvt_pk_bf16_f32 v2, v2, v3
	v_cvt_pk_bf16_f32 v3, v4, v5
	global_store_dwordx2 v[60:61], v[2:3], off offset:64
	v_cvt_pk_bf16_f32 v2, v22, v23
	v_cvt_pk_bf16_f32 v3, v24, v25
	global_store_dwordx2 v[58:59], v[2:3], off offset:80
	v_cvt_pk_bf16_f32 v2, v6, v7
	v_cvt_pk_bf16_f32 v3, v8, v9
	global_store_dwordx2 v[60:61], v[2:3], off offset:80
	v_cvt_pk_bf16_f32 v2, v26, v27
	v_cvt_pk_bf16_f32 v3, v28, v29
	global_store_dwordx2 v[58:59], v[2:3], off offset:96
	v_cvt_pk_bf16_f32 v2, v10, v11
	v_cvt_pk_bf16_f32 v3, v12, v13
	global_store_dwordx2 v[60:61], v[2:3], off offset:96
	v_cvt_pk_bf16_f32 v2, v30, v31
	v_cvt_pk_bf16_f32 v3, v32, v33
	global_store_dwordx2 v[58:59], v[2:3], off offset:112
	v_cvt_pk_bf16_f32 v2, v14, v15
	v_cvt_pk_bf16_f32 v3, v16, v17
	global_store_dwordx2 v[60:61], v[2:3], off offset:112
	v_or_b32_e32 v2, 0x2000, v122
	v_mov_b32_e32 v3, v123
	v_lshl_add_u64 v[68:69], v[62:63], 0, v[2:3]
	global_load_dwordx4 v[220:223], v[138:139], off
	global_load_dwordx4 v[234:237], v[138:139], off offset:32
	global_load_dwordx4 v[238:241], v[138:139], off offset:64
	global_load_dwordx4 v[242:245], v[138:139], off offset:96
	s_nop 0
	s_nop 0
	s_nop 0
	s_waitcnt vmcnt(15)
	v_mfma_f32_32x32x16_bf16 v[18:33], v[202:205], v[34:37], 0
	v_or_b32_e32 v122, 0x3000, v122
	v_lshl_add_u64 v[62:63], v[62:63], 0, v[122:123]
	v_mfma_f32_32x32x16_bf16 v[2:17], v[202:205], v[38:41], 0
	s_nop 0
	s_waitcnt vmcnt(14)
	v_mfma_f32_32x32x16_bf16 v[18:33], v[208:211], v[42:45], v[18:33]
	v_mfma_f32_32x32x16_bf16 v[2:17], v[208:211], v[46:49], v[2:17]
	s_nop 0
	s_nop 9
	v_cvt_pk_bf16_f32 v18, v18, v19
	v_cvt_pk_bf16_f32 v19, v20, v21
	s_nop 0
	s_waitcnt vmcnt(13)
	v_mfma_f32_32x32x16_bf16 v[2:17], v[212:215], v[50:53], v[2:17]
	s_nop 0
	s_nop 0
	global_store_dwordx2 v[58:59], v[18:19], off offset:128
	s_nop 0
	s_waitcnt vmcnt(13)
	v_mfma_f32_32x32x16_bf16 v[2:17], v[216:219], v[54:57], v[2:17]
	s_nop 11
	v_cvt_pk_bf16_f32 v2, v2, v3
	v_cvt_pk_bf16_f32 v3, v4, v5
	global_store_dwordx2 v[60:61], v[2:3], off offset:128
	v_cvt_pk_bf16_f32 v2, v22, v23
	v_cvt_pk_bf16_f32 v3, v24, v25
	global_store_dwordx2 v[58:59], v[2:3], off offset:144
	v_cvt_pk_bf16_f32 v2, v6, v7
	v_cvt_pk_bf16_f32 v3, v8, v9
	global_store_dwordx2 v[60:61], v[2:3], off offset:144
	v_cvt_pk_bf16_f32 v2, v26, v27
	v_cvt_pk_bf16_f32 v3, v28, v29
	global_store_dwordx2 v[58:59], v[2:3], off offset:160
	v_cvt_pk_bf16_f32 v2, v10, v11
	v_cvt_pk_bf16_f32 v3, v12, v13
	global_store_dwordx2 v[60:61], v[2:3], off offset:160
	v_cvt_pk_bf16_f32 v2, v30, v31
	v_cvt_pk_bf16_f32 v3, v32, v33
	global_store_dwordx2 v[58:59], v[2:3], off offset:176
	v_cvt_pk_bf16_f32 v2, v14, v15
	v_cvt_pk_bf16_f32 v3, v16, v17
	global_store_dwordx2 v[60:61], v[2:3], off offset:176
	s_nop 0
	s_nop 0
	s_waitcnt vmcnt(11)
	v_mfma_f32_32x32x16_bf16 v[18:33], v[220:223], v[34:37], 0
	s_nop 0
	v_mfma_f32_32x32x16_bf16 v[2:17], v[220:223], v[38:41], 0
	s_nop 0
	s_waitcnt vmcnt(10)
	v_mfma_f32_32x32x16_bf16 v[18:33], v[234:237], v[42:45], v[18:33]
	s_nop 11
	v_cvt_pk_bf16_f32 v18, v18, v19
	v_mfma_f32_32x32x16_bf16 v[2:17], v[234:237], v[46:49], v[2:17]
	s_nop 0
	v_cvt_pk_bf16_f32 v19, v20, v21
	s_nop 0
	s_waitcnt vmcnt(9)
	v_mfma_f32_32x32x16_bf16 v[2:17], v[238:241], v[50:53], v[2:17]
	s_nop 0
	s_nop 0
	global_store_dwordx2 v[58:59], v[18:19], off offset:192
	s_nop 0
	s_waitcnt vmcnt(9)
	v_mfma_f32_32x32x16_bf16 v[2:17], v[242:245], v[54:57], v[2:17]
	s_nop 11
	v_cvt_pk_bf16_f32 v2, v2, v3
	v_cvt_pk_bf16_f32 v3, v4, v5
	global_store_dwordx2 v[60:61], v[2:3], off offset:192
	v_cvt_pk_bf16_f32 v2, v22, v23
	v_cvt_pk_bf16_f32 v3, v24, v25
	global_store_dwordx2 v[58:59], v[2:3], off offset:208
	v_cvt_pk_bf16_f32 v2, v6, v7
	v_cvt_pk_bf16_f32 v3, v8, v9
	global_store_dwordx2 v[60:61], v[2:3], off offset:208
	v_cvt_pk_bf16_f32 v2, v26, v27
	v_cvt_pk_bf16_f32 v3, v28, v29
	global_store_dwordx2 v[58:59], v[2:3], off offset:224
	v_cvt_pk_bf16_f32 v2, v10, v11
	v_cvt_pk_bf16_f32 v3, v12, v13
	global_store_dwordx2 v[60:61], v[2:3], off offset:224
	v_cvt_pk_bf16_f32 v2, v30, v31
	v_cvt_pk_bf16_f32 v3, v32, v33
	global_store_dwordx2 v[58:59], v[2:3], off offset:240
	v_cvt_pk_bf16_f32 v2, v14, v15
	v_cvt_pk_bf16_f32 v3, v16, v17
	global_store_dwordx2 v[60:61], v[2:3], off offset:240
	s_waitcnt lgkmcnt(0)
	s_cbranch_scc0 .LBB0_782

.LBB0_782:
	s_nop 0
	s_nop 0
	s_nop 0
	s_nop 0
	s_nop 0
	s_nop 0
	s_nop 0
	s_nop 0
	s_nop 0
	s_nop 0
	s_nop 0
	s_nop 0
	s_nop 0
	s_nop 0
	s_nop 0
	s_nop 0
	s_nop 0
	s_nop 0
	s_nop 0
	s_nop 0
	s_nop 0
	s_nop 0
	s_nop 0
	v_readlane_b32 s4, v251, 53
	v_readlane_b32 s5, v251, 54
	v_readlane_b32 s86, v251, 51
	s_andn2_b64 vcc, exec, s[4:5]
	v_readlane_b32 s87, v251, 52
	s_cbranch_vccnz .LBB0_836
	s_waitcnt vmcnt(0)
	s_waitcnt vmcnt(0) lgkmcnt(0)
	s_barrier
	s_mov_b64 s[0:1], exec
	v_readlane_b32 s2, v252, 28
	v_readlane_b32 s3, v252, 29
	s_and_b64 s[2:3], s[0:1], s[2:3]
	s_mov_b64 exec, s[2:3]
	s_cbranch_execz .LBB0_835
	s_add_i32 s2, 0, 0x27020
	v_mov_b32_e32 v2, s2
	s_waitcnt vmcnt(0) expcnt(0) lgkmcnt(0)
	ds_read_b32 v4, v2
	s_add_i32 s2, 0, 0x27024
	v_mov_b32_e32 v2, s2
	ds_read_b32 v2, v2
	s_waitcnt lgkmcnt(1)
	v_cmp_ne_u32_e32 vcc, 0, v4
	s_cbranch_vccnz .LBB0_799
	v_readlane_b32 s4, v252, 0
	v_readlane_b32 s5, v252, 1
	s_load_dwordx2 s[2:3], s[4:5], 0x4
	v_readlane_b32 s4, v252, 2
	v_mov_b32_e32 v18, 0
	v_readlane_b32 s5, v252, 3
	s_waitcnt lgkmcnt(0)
	s_mul_i32 s2, s2, s4
	s_mul_i32 s2, s2, s3
	s_mov_b32 s3, 1
	s_branch .LBB0_787

.LBB0_1265:
	v_lshl_add_u32 v154, s24, 8, v1
	v_lshl_add_u64 v[50:51], v[154:155], 2, s[10:11]
	global_load_dword v200, v[50:51], off
	v_or_b32_e32 v198, 16, v154
	v_mov_b32_e32 v199, v155
	v_or_b32_e32 v194, 32, v154
	v_mov_b32_e32 v195, v155
	v_or_b32_e32 v190, 48, v154
	v_mov_b32_e32 v191, v155
	v_add_u32_e32 v186, 0x80, v154
	v_mov_b32_e32 v187, v155
	v_add_u32_e32 v182, 0x90, v154
	v_mov_b32_e32 v183, v155
	v_add_u32_e32 v178, 0xa0, v154
	v_mov_b32_e32 v179, v155
	v_add_u32_e32 v168, 0xb0, v154
	v_mov_b32_e32 v169, v155
	s_lshl_b32 s24, s25, 8
	v_lshl_or_b32 v202, s25, 7, v173
	s_ashr_i32 s25, s24, 31
	v_lshl_add_u64 v[142:143], s[24:25], 2, v[156:157]
	v_lshl_add_u64 v[50:51], v[198:199], 2, s[10:11]
	global_load_dword v196, v[50:51], off
	v_lshl_add_u64 v[50:51], v[194:195], 2, s[10:11]
	global_load_dword v192, v[50:51], off
	v_lshl_add_u64 v[50:51], v[190:191], 2, s[10:11]
	global_load_dword v188, v[50:51], off
	v_lshl_add_u64 v[50:51], v[186:187], 2, s[10:11]
	global_load_dword v184, v[50:51], off
	v_lshl_add_u64 v[50:51], v[182:183], 2, s[10:11]
	global_load_dword v180, v[50:51], off
	v_lshl_add_u64 v[50:51], v[178:179], 2, s[10:11]
	global_load_dword v172, v[50:51], off
	v_lshl_add_u64 v[50:51], v[168:169], 2, s[10:11]
	global_load_dword v166, v[50:51], off
	global_load_dwordx4 v[50:53], v[142:143], off offset:16
	global_load_dwordx4 v[54:57], v[142:143], off
	global_load_dwordx4 v[138:141], v[142:143], off offset:528
	s_nop 0
	global_load_dwordx4 v[142:145], v[142:143], off offset:512
	v_cvt_f32_i32_e32 v175, v134
	v_cvt_f32_i32_e32 v174, v126
	v_cvt_f32_i32_e32 v209, v130
	v_cvt_f32_i32_e32 v208, v122
	v_cvt_f32_i32_e32 v135, v135
	v_cvt_f32_i32_e32 v134, v127
	v_cvt_f32_i32_e32 v131, v131
	v_cvt_f32_i32_e32 v130, v123
	v_mov_b64_e32 v[176:177], s[8:9]
	v_mad_u64_u32 v[204:205], s[24:25], v154, s49, v[176:177]
	v_ashrrev_i32_e32 v203, 31, v202
	v_cvt_f32_i32_e32 v119, v119
	v_cvt_f32_i32_e32 v115, v115
	v_cvt_f32_i32_e32 v103, v103
	v_cvt_f32_i32_e32 v99, v99
	v_cvt_f32_i32_e32 v87, v87
	v_cvt_f32_i32_e32 v83, v83
	v_cvt_f32_i32_e32 v71, v71
	v_cvt_f32_i32_e32 v67, v67
	v_cvt_f32_i32_e32 v47, v47
	v_cvt_f32_i32_e32 v43, v43
	v_cvt_f32_i32_e32 v31, v31
	v_cvt_f32_i32_e32 v27, v27
	v_cvt_f32_i32_e32 v15, v15
	v_cvt_f32_i32_e32 v11, v11
	s_andn2_b64 vcc, exec, s[0:1]
	s_waitcnt vmcnt(4)
	s_nop 0
	s_nop 0
	s_nop 0
	s_nop 0
	s_nop 0
	s_nop 0
	s_nop 0
	v_mul_f32_e32 v200, 0x3c010204, v200
	v_mul_f32_e32 v196, 0x3c010204, v196
	v_mul_f32_e32 v192, 0x3c010204, v192
	v_mul_f32_e32 v188, 0x3c010204, v188
	v_mul_f32_e32 v184, 0x3c010204, v184
	v_mul_f32_e32 v180, 0x3c010204, v180
	v_mul_f32_e32 v172, 0x3c010204, v172
	v_mul_f32_e32 v166, 0x3c010204, v166
	s_waitcnt vmcnt(2)
	v_mov_b32_e32 v171, v54
	s_waitcnt vmcnt(0)
	v_mov_b32_e32 v170, v142
	v_pk_mul_f32 v[206:207], v[200:201], v[170:171] op_sel_hi:[0,1]
	v_pk_mul_f32 v[206:207], v[206:207], v[174:175]
	v_mov_b32_e32 v175, v50
	v_mul_f32_e32 v50, 0xbfb8aa3b, v207
	v_exp_f32_e32 v50, v50
	v_mov_b32_e32 v174, v138
	v_pk_mul_f32 v[210:211], v[200:201], v[174:175] op_sel_hi:[0,1]
	v_pk_mul_f32 v[208:209], v[210:211], v[208:209]
	v_add_f32_e32 v50, 1.0, v50
	v_rcp_f32_e32 v50, v50
	v_mov_b32_e32 v54, v143
	v_pk_mul_f32 v[126:127], v[200:201], v[54:55] op_sel_hi:[0,1]
	v_pk_mul_f32 v[126:127], v[126:127], v[134:135]
	v_mul_f32_e32 v50, v207, v50
	v_mul_f32_e32 v142, v206, v50
	v_mul_f32_e32 v50, 0xbfb8aa3b, v209
	v_exp_f32_e32 v50, v50
	v_cvt_f32_i32_e32 v135, v132
	v_cvt_f32_i32_e32 v134, v124
	v_add_f32_e32 v50, 1.0, v50
	v_rcp_f32_e32 v50, v50
	s_nop 0
	v_mul_f32_e32 v50, v209, v50
	v_mul_f32_e32 v154, v208, v50
	v_mov_b32_e32 v50, v139
	v_pk_mul_f32 v[122:123], v[200:201], v[50:51] op_sel_hi:[0,1]
	v_pk_mul_f32 v[122:123], v[122:123], v[130:131]
	v_mul_f32_e32 v130, 0xbfb8aa3b, v127
	v_exp_f32_e32 v130, v130
	s_nop 0
	v_add_f32_e32 v130, 1.0, v130
	v_rcp_f32_e32 v130, v130
	s_nop 0
	v_mul_f32_e32 v127, v127, v130
	v_mul_f32_e32 v143, v126, v127
	v_mul_f32_e32 v126, 0xbfb8aa3b, v123
	v_exp_f32_e32 v126, v126
	v_cvt_f32_i32_e32 v127, v136
	v_add_f32_e32 v126, 1.0, v126
	v_rcp_f32_e32 v126, v126
	s_nop 0
	v_mul_f32_e32 v123, v123, v126
	v_cvt_f32_i32_e32 v126, v128
	v_mul_f32_e32 v169, v122, v123
	v_mov_b32_e32 v122, v144
	v_mov_b32_e32 v123, v56
	v_pk_mul_f32 v[130:131], v[200:201], v[122:123] op_sel_hi:[0,1]
	v_pk_mul_f32 v[130:131], v[130:131], v[126:127]
	v_mov_b32_e32 v127, v52
	v_mul_f32_e32 v52, 0xbfb8aa3b, v131
	v_exp_f32_e32 v52, v52
	v_mov_b32_e32 v126, v140
	v_pk_mul_f32 v[138:139], v[200:201], v[126:127] op_sel_hi:[0,1]
	v_pk_mul_f32 v[134:135], v[138:139], v[134:135]
	v_add_f32_e32 v52, 1.0, v52
	v_rcp_f32_e32 v52, v52
	v_mov_b32_e32 v56, v145
	v_mul_f32_e32 v52, v131, v52
	v_mul_f32_e32 v136, v130, v52
	v_mul_f32_e32 v52, 0xbfb8aa3b, v135
	v_exp_f32_e32 v52, v52
	v_cvt_f32_i32_e32 v131, v137
	v_cvt_f32_i32_e32 v130, v129
	v_pk_mul_f32 v[128:129], v[200:201], v[56:57] op_sel_hi:[0,1]
	v_add_f32_e32 v52, 1.0, v52
	v_rcp_f32_e32 v52, v52
	v_pk_mul_f32 v[128:129], v[128:129], v[130:131]
	v_cvt_f32_i32_e32 v131, v133
	v_cvt_f32_i32_e32 v130, v125
	v_mul_f32_e32 v52, v135, v52
	v_mul_f32_e32 v134, v134, v52
	v_mov_b32_e32 v52, v141
	v_pk_mul_f32 v[124:125], v[200:201], v[52:53] op_sel_hi:[0,1]
	v_pk_mul_f32 v[124:125], v[124:125], v[130:131]
	v_mul_f32_e32 v130, 0xbfb8aa3b, v129
	v_exp_f32_e32 v130, v130
	s_nop 0
	v_add_f32_e32 v130, 1.0, v130
	v_rcp_f32_e32 v130, v130
	s_nop 0
	v_mul_f32_e32 v129, v129, v130
	v_mul_f32_e32 v129, v128, v129
	v_mul_f32_e32 v128, 0xbfb8aa3b, v125
	v_exp_f32_e32 v128, v128
	s_nop 0
	v_add_f32_e32 v128, 1.0, v128
	v_rcp_f32_e32 v128, v128
	s_nop 0
	v_mul_f32_e32 v125, v125, v128
	v_mul_f32_e32 v131, v124, v125
	v_lshlrev_b64 v[124:125], 1, v[202:203]
	v_lshl_add_u64 v[132:133], v[204:205], 0, v[124:125]
	v_cvt_pk_bf16_f32 v128, v142, v143
	v_cvt_pk_bf16_f32 v129, v136, v129
	v_cvt_pk_bf16_f32 v130, v154, v169
	v_cvt_pk_bf16_f32 v131, v134, v131
	global_store_dwordx4 v[132:133], v[128:131], off
	v_pk_mul_f32 v[132:133], v[196:197], v[170:171] op_sel_hi:[0,1]
	v_pk_mul_f32 v[134:135], v[196:197], v[174:175] op_sel_hi:[0,1]
	v_cvt_f32_i32_e32 v131, v118
	v_cvt_f32_i32_e32 v130, v110
	v_cvt_f32_i32_e32 v118, v111
	v_pk_mul_f32 v[110:111], v[196:197], v[54:55] op_sel_hi:[0,1]
	v_mad_u64_u32 v[128:129], s[24:25], v198, s49, v[176:177]
	v_pk_mul_f32 v[130:131], v[132:133], v[130:131]
	v_cvt_f32_i32_e32 v132, v106
	v_mul_f32_e32 v106, 0xbfb8aa3b, v131
	v_exp_f32_e32 v106, v106
	v_cvt_f32_i32_e32 v133, v114
	v_cvt_f32_i32_e32 v114, v107
	v_pk_mul_f32 v[110:111], v[110:111], v[118:119]
	v_add_f32_e32 v106, 1.0, v106
	v_rcp_f32_e32 v106, v106
	v_pk_mul_f32 v[132:133], v[134:135], v[132:133]
	v_mul_f32_e32 v106, v131, v106
	v_mul_f32_e32 v130, v130, v106
	v_mul_f32_e32 v106, 0xbfb8aa3b, v133
	v_exp_f32_e32 v106, v106
	s_nop 0
	v_add_f32_e32 v106, 1.0, v106
	v_rcp_f32_e32 v106, v106
	s_nop 0
	v_mul_f32_e32 v106, v133, v106
	v_mul_f32_e32 v131, v132, v106
	v_pk_mul_f32 v[106:107], v[196:197], v[50:51] op_sel_hi:[0,1]
	v_pk_mul_f32 v[106:107], v[106:107], v[114:115]
	v_mul_f32_e32 v114, 0xbfb8aa3b, v111
	v_exp_f32_e32 v114, v114
	s_nop 0
	v_add_f32_e32 v114, 1.0, v114
	v_rcp_f32_e32 v114, v114
	s_nop 0
	v_mul_f32_e32 v111, v111, v114
	v_mul_f32_e32 v118, v110, v111
	v_mul_f32_e32 v110, 0xbfb8aa3b, v107
	v_exp_f32_e32 v110, v110
	v_pk_mul_f32 v[114:115], v[196:197], v[126:127] op_sel_hi:[0,1]
	v_add_f32_e32 v110, 1.0, v110
	v_rcp_f32_e32 v110, v110
	s_nop 0
	v_mul_f32_e32 v107, v107, v110
	v_mul_f32_e32 v119, v106, v107
	v_cvt_f32_i32_e32 v107, v120
	v_cvt_f32_i32_e32 v106, v112
	v_pk_mul_f32 v[110:111], v[196:197], v[122:123] op_sel_hi:[0,1]
	v_pk_mul_f32 v[106:107], v[110:111], v[106:107]
	v_cvt_f32_i32_e32 v110, v108
	v_mul_f32_e32 v108, 0xbfb8aa3b, v107
	v_exp_f32_e32 v108, v108
	v_cvt_f32_i32_e32 v111, v116
	v_add_f32_e32 v108, 1.0, v108
	v_rcp_f32_e32 v108, v108
	v_pk_mul_f32 v[110:111], v[114:115], v[110:111]
	v_mul_f32_e32 v107, v107, v108
	v_mul_f32_e32 v112, v106, v107
	v_mul_f32_e32 v106, 0xbfb8aa3b, v111
	v_exp_f32_e32 v106, v106
	v_cvt_f32_i32_e32 v107, v121
	v_add_f32_e32 v106, 1.0, v106
	v_rcp_f32_e32 v106, v106
	s_nop 0
	v_mul_f32_e32 v106, v111, v106
	v_mul_f32_e32 v114, v110, v106
	v_cvt_f32_i32_e32 v106, v113
	v_pk_mul_f32 v[110:111], v[196:197], v[56:57] op_sel_hi:[0,1]
	v_pk_mul_f32 v[106:107], v[110:111], v[106:107]
	v_cvt_f32_i32_e32 v111, v117
	v_cvt_f32_i32_e32 v110, v109
	v_pk_mul_f32 v[108:109], v[196:197], v[52:53] op_sel_hi:[0,1]
	v_pk_mul_f32 v[108:109], v[108:109], v[110:111]
	v_mul_f32_e32 v110, 0xbfb8aa3b, v107
	v_exp_f32_e32 v110, v110
	s_nop 0
	v_add_f32_e32 v110, 1.0, v110
	v_rcp_f32_e32 v110, v110
	s_nop 0
	v_mul_f32_e32 v107, v107, v110
	v_mul_f32_e32 v107, v106, v107
	v_mul_f32_e32 v106, 0xbfb8aa3b, v109
	v_exp_f32_e32 v106, v106
	v_lshl_add_u64 v[110:111], v[128:129], 0, v[124:125]
	v_add_f32_e32 v106, 1.0, v106
	v_rcp_f32_e32 v106, v106
	s_nop 0
	v_mul_f32_e32 v106, v109, v106
	v_mul_f32_e32 v109, v108, v106
	v_cvt_pk_bf16_f32 v106, v130, v118
	v_cvt_pk_bf16_f32 v107, v112, v107
	v_cvt_pk_bf16_f32 v108, v131, v119
	v_cvt_pk_bf16_f32 v109, v114, v109
	global_store_dwordx4 v[110:111], v[106:109], off
	v_pk_mul_f32 v[110:111], v[192:193], v[170:171] op_sel_hi:[0,1]
	v_pk_mul_f32 v[112:113], v[192:193], v[174:175] op_sel_hi:[0,1]
	v_cvt_f32_i32_e32 v109, v102
	v_cvt_f32_i32_e32 v108, v94
	v_cvt_f32_i32_e32 v102, v95
	v_pk_mul_f32 v[94:95], v[192:193], v[54:55] op_sel_hi:[0,1]
	v_mad_u64_u32 v[106:107], s[24:25], v194, s49, v[176:177]
	v_pk_mul_f32 v[108:109], v[110:111], v[108:109]
	v_cvt_f32_i32_e32 v110, v90
	v_mul_f32_e32 v90, 0xbfb8aa3b, v109
	v_exp_f32_e32 v90, v90
	v_cvt_f32_i32_e32 v111, v98
	v_cvt_f32_i32_e32 v98, v91
	v_pk_mul_f32 v[94:95], v[94:95], v[102:103]
	v_add_f32_e32 v90, 1.0, v90
	v_rcp_f32_e32 v90, v90
	v_pk_mul_f32 v[110:111], v[112:113], v[110:111]
	v_mul_f32_e32 v90, v109, v90
	v_mul_f32_e32 v108, v108, v90
	v_mul_f32_e32 v90, 0xbfb8aa3b, v111
	v_exp_f32_e32 v90, v90
	s_nop 0
	v_add_f32_e32 v90, 1.0, v90
	v_rcp_f32_e32 v90, v90
	s_nop 0
	v_mul_f32_e32 v90, v111, v90
	v_mul_f32_e32 v109, v110, v90
	v_pk_mul_f32 v[90:91], v[192:193], v[50:51] op_sel_hi:[0,1]
	v_pk_mul_f32 v[90:91], v[90:91], v[98:99]
	v_mul_f32_e32 v98, 0xbfb8aa3b, v95
	v_exp_f32_e32 v98, v98
	s_nop 0
	v_add_f32_e32 v98, 1.0, v98
	v_rcp_f32_e32 v98, v98
	s_nop 0
	v_mul_f32_e32 v95, v95, v98
	v_mul_f32_e32 v102, v94, v95
	v_mul_f32_e32 v94, 0xbfb8aa3b, v91
	v_exp_f32_e32 v94, v94
	v_pk_mul_f32 v[98:99], v[192:193], v[126:127] op_sel_hi:[0,1]
	v_add_f32_e32 v94, 1.0, v94
	v_rcp_f32_e32 v94, v94
	s_nop 0
	v_mul_f32_e32 v91, v91, v94
	v_mul_f32_e32 v103, v90, v91
	v_cvt_f32_i32_e32 v91, v104
	v_cvt_f32_i32_e32 v90, v96
	v_pk_mul_f32 v[94:95], v[192:193], v[122:123] op_sel_hi:[0,1]
	v_pk_mul_f32 v[90:91], v[94:95], v[90:91]
	v_cvt_f32_i32_e32 v94, v92
	v_mul_f32_e32 v92, 0xbfb8aa3b, v91
	v_exp_f32_e32 v92, v92
	v_cvt_f32_i32_e32 v95, v100
	v_add_f32_e32 v92, 1.0, v92
	v_rcp_f32_e32 v92, v92
	v_pk_mul_f32 v[94:95], v[98:99], v[94:95]
	v_mul_f32_e32 v91, v91, v92
	v_mul_f32_e32 v96, v90, v91
	v_mul_f32_e32 v90, 0xbfb8aa3b, v95
	v_exp_f32_e32 v90, v90
	v_cvt_f32_i32_e32 v91, v105
	v_add_f32_e32 v90, 1.0, v90
	v_rcp_f32_e32 v90, v90
	s_nop 0
	v_mul_f32_e32 v90, v95, v90
	v_mul_f32_e32 v98, v94, v90
	v_cvt_f32_i32_e32 v90, v97
	v_pk_mul_f32 v[94:95], v[192:193], v[56:57] op_sel_hi:[0,1]
	v_pk_mul_f32 v[90:91], v[94:95], v[90:91]
	v_cvt_f32_i32_e32 v95, v101
	v_cvt_f32_i32_e32 v94, v93
	v_pk_mul_f32 v[92:93], v[192:193], v[52:53] op_sel_hi:[0,1]
	v_pk_mul_f32 v[92:93], v[92:93], v[94:95]
	v_mul_f32_e32 v94, 0xbfb8aa3b, v91
	v_exp_f32_e32 v94, v94
	s_nop 0
	v_add_f32_e32 v94, 1.0, v94
	v_rcp_f32_e32 v94, v94
	s_nop 0
	v_mul_f32_e32 v91, v91, v94
	v_mul_f32_e32 v91, v90, v91
	v_mul_f32_e32 v90, 0xbfb8aa3b, v93
	v_exp_f32_e32 v90, v90
	v_lshl_add_u64 v[94:95], v[106:107], 0, v[124:125]
	v_add_f32_e32 v90, 1.0, v90
	v_rcp_f32_e32 v90, v90
	s_nop 0
	v_mul_f32_e32 v90, v93, v90
	v_mul_f32_e32 v93, v92, v90
	v_cvt_pk_bf16_f32 v90, v108, v102
	v_cvt_pk_bf16_f32 v91, v96, v91
	v_cvt_pk_bf16_f32 v92, v109, v103
	v_cvt_pk_bf16_f32 v93, v98, v93
	global_store_dwordx4 v[94:95], v[90:93], off
	v_pk_mul_f32 v[94:95], v[188:189], v[170:171] op_sel_hi:[0,1]
	v_pk_mul_f32 v[96:97], v[188:189], v[174:175] op_sel_hi:[0,1]
	v_cvt_f32_i32_e32 v93, v86
	v_cvt_f32_i32_e32 v92, v78
	v_cvt_f32_i32_e32 v86, v79
	v_pk_mul_f32 v[78:79], v[188:189], v[54:55] op_sel_hi:[0,1]
	v_mad_u64_u32 v[90:91], s[24:25], v190, s49, v[176:177]
	v_pk_mul_f32 v[92:93], v[94:95], v[92:93]
	v_cvt_f32_i32_e32 v94, v74
	v_mul_f32_e32 v74, 0xbfb8aa3b, v93
	v_exp_f32_e32 v74, v74
	v_cvt_f32_i32_e32 v95, v82
	v_cvt_f32_i32_e32 v82, v75
	v_pk_mul_f32 v[78:79], v[78:79], v[86:87]
	v_add_f32_e32 v74, 1.0, v74
	v_rcp_f32_e32 v74, v74
	v_pk_mul_f32 v[94:95], v[96:97], v[94:95]
	v_mul_f32_e32 v74, v93, v74
	v_mul_f32_e32 v92, v92, v74
	v_mul_f32_e32 v74, 0xbfb8aa3b, v95
	v_exp_f32_e32 v74, v74
	s_nop 0
	v_add_f32_e32 v74, 1.0, v74
	v_rcp_f32_e32 v74, v74
	s_nop 0
	v_mul_f32_e32 v74, v95, v74
	v_mul_f32_e32 v93, v94, v74
	v_pk_mul_f32 v[74:75], v[188:189], v[50:51] op_sel_hi:[0,1]
	v_pk_mul_f32 v[74:75], v[74:75], v[82:83]
	v_mul_f32_e32 v82, 0xbfb8aa3b, v79
	v_exp_f32_e32 v82, v82
	s_nop 0
	v_add_f32_e32 v82, 1.0, v82
	v_rcp_f32_e32 v82, v82
	s_nop 0
	v_mul_f32_e32 v79, v79, v82
	v_mul_f32_e32 v86, v78, v79
	v_mul_f32_e32 v78, 0xbfb8aa3b, v75
	v_exp_f32_e32 v78, v78
	v_pk_mul_f32 v[82:83], v[188:189], v[126:127] op_sel_hi:[0,1]
	v_add_f32_e32 v78, 1.0, v78
	v_rcp_f32_e32 v78, v78
	s_nop 0
	v_mul_f32_e32 v75, v75, v78
	v_mul_f32_e32 v87, v74, v75
	v_cvt_f32_i32_e32 v75, v88
	v_cvt_f32_i32_e32 v74, v80
	v_pk_mul_f32 v[78:79], v[188:189], v[122:123] op_sel_hi:[0,1]
	v_pk_mul_f32 v[74:75], v[78:79], v[74:75]
	v_cvt_f32_i32_e32 v78, v76
	v_mul_f32_e32 v76, 0xbfb8aa3b, v75
	v_exp_f32_e32 v76, v76
	v_cvt_f32_i32_e32 v79, v84
	v_add_f32_e32 v76, 1.0, v76
	v_rcp_f32_e32 v76, v76
	v_pk_mul_f32 v[78:79], v[82:83], v[78:79]
	v_mul_f32_e32 v75, v75, v76
	v_mul_f32_e32 v80, v74, v75
	v_mul_f32_e32 v74, 0xbfb8aa3b, v79
	v_exp_f32_e32 v74, v74
	v_cvt_f32_i32_e32 v75, v89
	v_add_f32_e32 v74, 1.0, v74
	v_rcp_f32_e32 v74, v74
	s_nop 0
	v_mul_f32_e32 v74, v79, v74
	v_mul_f32_e32 v82, v78, v74
	v_cvt_f32_i32_e32 v74, v81
	v_pk_mul_f32 v[78:79], v[188:189], v[56:57] op_sel_hi:[0,1]
	v_pk_mul_f32 v[74:75], v[78:79], v[74:75]
	v_cvt_f32_i32_e32 v79, v85
	v_cvt_f32_i32_e32 v78, v77
	v_pk_mul_f32 v[76:77], v[188:189], v[52:53] op_sel_hi:[0,1]
	v_pk_mul_f32 v[76:77], v[76:77], v[78:79]
	v_mul_f32_e32 v78, 0xbfb8aa3b, v75
	v_exp_f32_e32 v78, v78
	s_nop 0
	v_add_f32_e32 v78, 1.0, v78
	v_rcp_f32_e32 v78, v78
	s_nop 0
	v_mul_f32_e32 v75, v75, v78
	v_mul_f32_e32 v75, v74, v75
	v_mul_f32_e32 v74, 0xbfb8aa3b, v77
	v_exp_f32_e32 v74, v74
	v_lshl_add_u64 v[78:79], v[90:91], 0, v[124:125]
	v_add_f32_e32 v74, 1.0, v74
	v_rcp_f32_e32 v74, v74
	s_nop 0
	v_mul_f32_e32 v74, v77, v74
	v_mul_f32_e32 v77, v76, v74
	v_cvt_pk_bf16_f32 v74, v92, v86
	v_cvt_pk_bf16_f32 v75, v80, v75
	v_cvt_pk_bf16_f32 v76, v93, v87
	v_cvt_pk_bf16_f32 v77, v82, v77
	global_store_dwordx4 v[78:79], v[74:77], off
	v_pk_mul_f32 v[78:79], v[184:185], v[170:171] op_sel_hi:[0,1]
	v_pk_mul_f32 v[80:81], v[184:185], v[174:175] op_sel_hi:[0,1]
	v_cvt_f32_i32_e32 v77, v70
	v_cvt_f32_i32_e32 v76, v62
	v_cvt_f32_i32_e32 v70, v63
	v_pk_mul_f32 v[62:63], v[184:185], v[54:55] op_sel_hi:[0,1]
	v_mad_u64_u32 v[74:75], s[24:25], v186, s49, v[176:177]
	v_pk_mul_f32 v[76:77], v[78:79], v[76:77]
	v_cvt_f32_i32_e32 v78, v58
	v_mul_f32_e32 v58, 0xbfb8aa3b, v77
	v_exp_f32_e32 v58, v58
	v_cvt_f32_i32_e32 v79, v66
	v_cvt_f32_i32_e32 v66, v59
	v_pk_mul_f32 v[62:63], v[62:63], v[70:71]
	v_add_f32_e32 v58, 1.0, v58
	v_rcp_f32_e32 v58, v58
	v_pk_mul_f32 v[78:79], v[80:81], v[78:79]
	v_mul_f32_e32 v58, v77, v58
	v_mul_f32_e32 v76, v76, v58
	v_mul_f32_e32 v58, 0xbfb8aa3b, v79
	v_exp_f32_e32 v58, v58
	s_nop 0
	v_add_f32_e32 v58, 1.0, v58
	v_rcp_f32_e32 v58, v58
	s_nop 0
	v_mul_f32_e32 v58, v79, v58
	v_mul_f32_e32 v77, v78, v58
	v_pk_mul_f32 v[58:59], v[184:185], v[50:51] op_sel_hi:[0,1]
	v_pk_mul_f32 v[58:59], v[58:59], v[66:67]
	v_mul_f32_e32 v66, 0xbfb8aa3b, v63
	v_exp_f32_e32 v66, v66
	s_nop 0
	v_add_f32_e32 v66, 1.0, v66
	v_rcp_f32_e32 v66, v66
	s_nop 0
	v_mul_f32_e32 v63, v63, v66
	v_mul_f32_e32 v70, v62, v63
	v_mul_f32_e32 v62, 0xbfb8aa3b, v59
	v_exp_f32_e32 v62, v62
	v_pk_mul_f32 v[66:67], v[184:185], v[126:127] op_sel_hi:[0,1]
	v_add_f32_e32 v62, 1.0, v62
	v_rcp_f32_e32 v62, v62
	s_nop 0
	v_mul_f32_e32 v59, v59, v62
	v_mul_f32_e32 v71, v58, v59
	v_cvt_f32_i32_e32 v59, v72
	v_cvt_f32_i32_e32 v58, v64
	v_pk_mul_f32 v[62:63], v[184:185], v[122:123] op_sel_hi:[0,1]
	v_pk_mul_f32 v[58:59], v[62:63], v[58:59]
	v_cvt_f32_i32_e32 v62, v60
	v_mul_f32_e32 v60, 0xbfb8aa3b, v59
	v_exp_f32_e32 v60, v60
	v_cvt_f32_i32_e32 v63, v68
	v_add_f32_e32 v60, 1.0, v60
	v_rcp_f32_e32 v60, v60
	v_pk_mul_f32 v[62:63], v[66:67], v[62:63]
	v_mul_f32_e32 v59, v59, v60
	v_mul_f32_e32 v64, v58, v59
	v_mul_f32_e32 v58, 0xbfb8aa3b, v63
	v_exp_f32_e32 v58, v58
	v_cvt_f32_i32_e32 v59, v73
	v_add_f32_e32 v58, 1.0, v58
	v_rcp_f32_e32 v58, v58
	s_nop 0
	v_mul_f32_e32 v58, v63, v58
	v_mul_f32_e32 v66, v62, v58
	v_cvt_f32_i32_e32 v58, v65
	v_pk_mul_f32 v[62:63], v[184:185], v[56:57] op_sel_hi:[0,1]
	v_pk_mul_f32 v[58:59], v[62:63], v[58:59]
	v_cvt_f32_i32_e32 v63, v69
	v_cvt_f32_i32_e32 v62, v61
	v_pk_mul_f32 v[60:61], v[184:185], v[52:53] op_sel_hi:[0,1]
	v_pk_mul_f32 v[60:61], v[60:61], v[62:63]
	v_mul_f32_e32 v62, 0xbfb8aa3b, v59
	v_exp_f32_e32 v62, v62
	s_nop 0
	v_add_f32_e32 v62, 1.0, v62
	v_rcp_f32_e32 v62, v62
	s_nop 0
	v_mul_f32_e32 v59, v59, v62
	v_mul_f32_e32 v59, v58, v59
	v_mul_f32_e32 v58, 0xbfb8aa3b, v61
	v_exp_f32_e32 v58, v58
	v_lshl_add_u64 v[62:63], v[74:75], 0, v[124:125]
	v_add_f32_e32 v58, 1.0, v58
	v_rcp_f32_e32 v58, v58
	s_nop 0
	v_mul_f32_e32 v58, v61, v58
	v_mul_f32_e32 v61, v60, v58
	v_cvt_pk_bf16_f32 v58, v76, v70
	v_cvt_pk_bf16_f32 v59, v64, v59
	v_cvt_pk_bf16_f32 v60, v77, v71
	v_cvt_pk_bf16_f32 v61, v66, v61
	global_store_dwordx4 v[62:63], v[58:61], off
	v_pk_mul_f32 v[62:63], v[180:181], v[170:171] op_sel_hi:[0,1]
	v_pk_mul_f32 v[64:65], v[180:181], v[174:175] op_sel_hi:[0,1]
	v_cvt_f32_i32_e32 v61, v46
	v_cvt_f32_i32_e32 v60, v38
	v_cvt_f32_i32_e32 v46, v39
	v_pk_mul_f32 v[38:39], v[180:181], v[54:55] op_sel_hi:[0,1]
	v_mad_u64_u32 v[58:59], s[24:25], v182, s49, v[176:177]
	v_pk_mul_f32 v[60:61], v[62:63], v[60:61]
	v_cvt_f32_i32_e32 v62, v34
	v_mul_f32_e32 v34, 0xbfb8aa3b, v61
	v_exp_f32_e32 v34, v34
	v_cvt_f32_i32_e32 v63, v42
	v_cvt_f32_i32_e32 v42, v35
	v_pk_mul_f32 v[38:39], v[38:39], v[46:47]
	v_add_f32_e32 v34, 1.0, v34
	v_rcp_f32_e32 v34, v34
	v_pk_mul_f32 v[62:63], v[64:65], v[62:63]
	v_mul_f32_e32 v34, v61, v34
	v_mul_f32_e32 v60, v60, v34
	v_mul_f32_e32 v34, 0xbfb8aa3b, v63
	v_exp_f32_e32 v34, v34
	s_nop 0
	v_add_f32_e32 v34, 1.0, v34
	v_rcp_f32_e32 v34, v34
	s_nop 0
	v_mul_f32_e32 v34, v63, v34
	v_mul_f32_e32 v61, v62, v34
	v_pk_mul_f32 v[34:35], v[180:181], v[50:51] op_sel_hi:[0,1]
	v_pk_mul_f32 v[34:35], v[34:35], v[42:43]
	v_mul_f32_e32 v42, 0xbfb8aa3b, v39
	v_exp_f32_e32 v42, v42
	s_nop 0
	v_add_f32_e32 v42, 1.0, v42
	v_rcp_f32_e32 v42, v42
	s_nop 0
	v_mul_f32_e32 v39, v39, v42
	v_mul_f32_e32 v46, v38, v39
	v_mul_f32_e32 v38, 0xbfb8aa3b, v35
	v_exp_f32_e32 v38, v38
	v_pk_mul_f32 v[42:43], v[180:181], v[126:127] op_sel_hi:[0,1]
	v_add_f32_e32 v38, 1.0, v38
	v_rcp_f32_e32 v38, v38
	s_nop 0
	v_mul_f32_e32 v35, v35, v38
	v_mul_f32_e32 v47, v34, v35
	v_cvt_f32_i32_e32 v35, v48
	v_cvt_f32_i32_e32 v34, v40
	v_pk_mul_f32 v[38:39], v[180:181], v[122:123] op_sel_hi:[0,1]
	v_pk_mul_f32 v[34:35], v[38:39], v[34:35]
	v_cvt_f32_i32_e32 v38, v36
	v_mul_f32_e32 v36, 0xbfb8aa3b, v35
	v_exp_f32_e32 v36, v36
	v_cvt_f32_i32_e32 v39, v44
	v_add_f32_e32 v36, 1.0, v36
	v_rcp_f32_e32 v36, v36
	v_pk_mul_f32 v[38:39], v[42:43], v[38:39]
	v_mul_f32_e32 v35, v35, v36
	v_mul_f32_e32 v40, v34, v35
	v_mul_f32_e32 v34, 0xbfb8aa3b, v39
	v_exp_f32_e32 v34, v34
	v_cvt_f32_i32_e32 v35, v49
	v_add_f32_e32 v34, 1.0, v34
	v_rcp_f32_e32 v34, v34
	s_nop 0
	v_mul_f32_e32 v34, v39, v34
	v_mul_f32_e32 v42, v38, v34
	v_cvt_f32_i32_e32 v34, v41
	v_pk_mul_f32 v[38:39], v[180:181], v[56:57] op_sel_hi:[0,1]
	v_pk_mul_f32 v[34:35], v[38:39], v[34:35]
	v_cvt_f32_i32_e32 v39, v45
	v_cvt_f32_i32_e32 v38, v37
	v_pk_mul_f32 v[36:37], v[180:181], v[52:53] op_sel_hi:[0,1]
	v_pk_mul_f32 v[36:37], v[36:37], v[38:39]
	v_mul_f32_e32 v38, 0xbfb8aa3b, v35
	v_exp_f32_e32 v38, v38
	s_nop 0
	v_add_f32_e32 v38, 1.0, v38
	v_rcp_f32_e32 v38, v38
	s_nop 0
	v_mul_f32_e32 v35, v35, v38
	v_mul_f32_e32 v35, v34, v35
	v_mul_f32_e32 v34, 0xbfb8aa3b, v37
	v_exp_f32_e32 v34, v34
	v_lshl_add_u64 v[38:39], v[58:59], 0, v[124:125]
	v_add_f32_e32 v34, 1.0, v34
	v_rcp_f32_e32 v34, v34
	s_nop 0
	v_mul_f32_e32 v34, v37, v34
	v_mul_f32_e32 v37, v36, v34
	v_cvt_pk_bf16_f32 v34, v60, v46
	v_cvt_pk_bf16_f32 v35, v40, v35
	v_cvt_pk_bf16_f32 v36, v61, v47
	v_cvt_pk_bf16_f32 v37, v42, v37
	global_store_dwordx4 v[38:39], v[34:37], off
	v_pk_mul_f32 v[38:39], v[172:173], v[170:171] op_sel_hi:[0,1]
	v_pk_mul_f32 v[40:41], v[172:173], v[174:175] op_sel_hi:[0,1]
	v_cvt_f32_i32_e32 v37, v30
	v_cvt_f32_i32_e32 v36, v22
	v_cvt_f32_i32_e32 v30, v23
	v_pk_mul_f32 v[22:23], v[172:173], v[54:55] op_sel_hi:[0,1]
	v_mad_u64_u32 v[34:35], s[24:25], v178, s49, v[176:177]
	v_pk_mul_f32 v[36:37], v[38:39], v[36:37]
	v_cvt_f32_i32_e32 v38, v18
	v_mul_f32_e32 v18, 0xbfb8aa3b, v37
	v_exp_f32_e32 v18, v18
	v_cvt_f32_i32_e32 v39, v26
	v_cvt_f32_i32_e32 v26, v19
	v_pk_mul_f32 v[22:23], v[22:23], v[30:31]
	v_add_f32_e32 v18, 1.0, v18
	v_rcp_f32_e32 v18, v18
	v_pk_mul_f32 v[38:39], v[40:41], v[38:39]
	v_mul_f32_e32 v18, v37, v18
	v_mul_f32_e32 v36, v36, v18
	v_mul_f32_e32 v18, 0xbfb8aa3b, v39
	v_exp_f32_e32 v18, v18
	s_nop 0
	v_add_f32_e32 v18, 1.0, v18
	v_rcp_f32_e32 v18, v18
	s_nop 0
	v_mul_f32_e32 v18, v39, v18
	v_mul_f32_e32 v37, v38, v18
	v_pk_mul_f32 v[18:19], v[172:173], v[50:51] op_sel_hi:[0,1]
	v_pk_mul_f32 v[18:19], v[18:19], v[26:27]
	v_mul_f32_e32 v26, 0xbfb8aa3b, v23
	v_exp_f32_e32 v26, v26
	s_nop 0
	v_add_f32_e32 v26, 1.0, v26
	v_rcp_f32_e32 v26, v26
	s_nop 0
	v_mul_f32_e32 v23, v23, v26
	v_mul_f32_e32 v30, v22, v23
	v_mul_f32_e32 v22, 0xbfb8aa3b, v19
	v_exp_f32_e32 v22, v22
	v_pk_mul_f32 v[26:27], v[172:173], v[126:127] op_sel_hi:[0,1]
	v_add_f32_e32 v22, 1.0, v22
	v_rcp_f32_e32 v22, v22
	s_nop 0
	v_mul_f32_e32 v19, v19, v22
	v_mul_f32_e32 v31, v18, v19
	v_cvt_f32_i32_e32 v19, v32
	v_cvt_f32_i32_e32 v18, v24
	v_pk_mul_f32 v[22:23], v[172:173], v[122:123] op_sel_hi:[0,1]
	v_pk_mul_f32 v[18:19], v[22:23], v[18:19]
	v_cvt_f32_i32_e32 v22, v20
	v_mul_f32_e32 v20, 0xbfb8aa3b, v19
	v_exp_f32_e32 v20, v20
	v_cvt_f32_i32_e32 v23, v28
	v_add_f32_e32 v20, 1.0, v20
	v_rcp_f32_e32 v20, v20
	v_pk_mul_f32 v[22:23], v[26:27], v[22:23]
	v_mul_f32_e32 v19, v19, v20
	v_mul_f32_e32 v24, v18, v19
	v_mul_f32_e32 v18, 0xbfb8aa3b, v23
	v_exp_f32_e32 v18, v18
	v_cvt_f32_i32_e32 v19, v33
	v_add_f32_e32 v18, 1.0, v18
	v_rcp_f32_e32 v18, v18
	s_nop 0
	v_mul_f32_e32 v18, v23, v18
	v_mul_f32_e32 v26, v22, v18
	v_cvt_f32_i32_e32 v18, v25
	v_pk_mul_f32 v[22:23], v[172:173], v[56:57] op_sel_hi:[0,1]
	v_pk_mul_f32 v[18:19], v[22:23], v[18:19]
	v_cvt_f32_i32_e32 v23, v29
	v_cvt_f32_i32_e32 v22, v21
	v_pk_mul_f32 v[20:21], v[172:173], v[52:53] op_sel_hi:[0,1]
	v_pk_mul_f32 v[20:21], v[20:21], v[22:23]
	v_mul_f32_e32 v22, 0xbfb8aa3b, v19
	v_exp_f32_e32 v22, v22
	s_nop 0
	v_add_f32_e32 v22, 1.0, v22
	v_rcp_f32_e32 v22, v22
	s_nop 0
	v_mul_f32_e32 v19, v19, v22
	v_mul_f32_e32 v19, v18, v19
	v_mul_f32_e32 v18, 0xbfb8aa3b, v21
	v_exp_f32_e32 v18, v18
	v_lshl_add_u64 v[22:23], v[34:35], 0, v[124:125]
	v_add_f32_e32 v18, 1.0, v18
	v_rcp_f32_e32 v18, v18
	s_nop 0
	v_mul_f32_e32 v18, v21, v18
	v_mul_f32_e32 v21, v20, v18
	v_cvt_pk_bf16_f32 v18, v36, v30
	v_cvt_pk_bf16_f32 v19, v24, v19
	v_cvt_pk_bf16_f32 v20, v37, v31
	v_cvt_pk_bf16_f32 v21, v26, v21
	global_store_dwordx4 v[22:23], v[18:21], off
	v_pk_mul_f32 v[22:23], v[166:167], v[170:171] op_sel_hi:[0,1]
	v_pk_mul_f32 v[24:25], v[166:167], v[174:175] op_sel_hi:[0,1]
	v_cvt_f32_i32_e32 v21, v14
	v_cvt_f32_i32_e32 v20, v6
	v_cvt_f32_i32_e32 v14, v7
	v_pk_mul_f32 v[6:7], v[166:167], v[54:55] op_sel_hi:[0,1]
	v_mad_u64_u32 v[18:19], s[24:25], v168, s49, v[176:177]
	v_pk_mul_f32 v[20:21], v[22:23], v[20:21]
	v_cvt_f32_i32_e32 v22, v2
	v_mul_f32_e32 v2, 0xbfb8aa3b, v21
	v_exp_f32_e32 v2, v2
	v_cvt_f32_i32_e32 v23, v10
	v_cvt_f32_i32_e32 v10, v3
	v_pk_mul_f32 v[6:7], v[6:7], v[14:15]
	v_add_f32_e32 v2, 1.0, v2
	v_rcp_f32_e32 v2, v2
	v_pk_mul_f32 v[22:23], v[24:25], v[22:23]
	s_mov_b64 s[24:25], -1
	v_mul_f32_e32 v2, v21, v2
	v_mul_f32_e32 v20, v20, v2
	v_mul_f32_e32 v2, 0xbfb8aa3b, v23
	v_exp_f32_e32 v2, v2
	s_nop 0
	v_add_f32_e32 v2, 1.0, v2
	v_rcp_f32_e32 v2, v2
	s_nop 0
	v_mul_f32_e32 v2, v23, v2
	v_mul_f32_e32 v21, v22, v2
	v_pk_mul_f32 v[2:3], v[166:167], v[50:51] op_sel_hi:[0,1]
	v_pk_mul_f32 v[2:3], v[2:3], v[10:11]
	v_mul_f32_e32 v10, 0xbfb8aa3b, v7
	v_exp_f32_e32 v10, v10
	s_nop 0
	v_add_f32_e32 v10, 1.0, v10
	v_rcp_f32_e32 v10, v10
	s_nop 0
	v_mul_f32_e32 v7, v7, v10
	v_mul_f32_e32 v14, v6, v7
	v_mul_f32_e32 v6, 0xbfb8aa3b, v3
	v_exp_f32_e32 v6, v6
	v_pk_mul_f32 v[10:11], v[166:167], v[126:127] op_sel_hi:[0,1]
	v_add_f32_e32 v6, 1.0, v6
	v_rcp_f32_e32 v6, v6
	s_nop 0
	v_mul_f32_e32 v3, v3, v6
	v_mul_f32_e32 v15, v2, v3
	v_cvt_f32_i32_e32 v3, v16
	v_cvt_f32_i32_e32 v2, v8
	v_pk_mul_f32 v[6:7], v[166:167], v[122:123] op_sel_hi:[0,1]
	v_pk_mul_f32 v[2:3], v[6:7], v[2:3]
	v_cvt_f32_i32_e32 v6, v4
	v_mul_f32_e32 v4, 0xbfb8aa3b, v3
	v_exp_f32_e32 v4, v4
	v_cvt_f32_i32_e32 v7, v12
	v_add_f32_e32 v4, 1.0, v4
	v_rcp_f32_e32 v4, v4
	v_pk_mul_f32 v[6:7], v[10:11], v[6:7]
	v_mul_f32_e32 v3, v3, v4
	v_mul_f32_e32 v8, v2, v3
	v_mul_f32_e32 v2, 0xbfb8aa3b, v7
	v_exp_f32_e32 v2, v2
	v_cvt_f32_i32_e32 v3, v17
	v_add_f32_e32 v2, 1.0, v2
	v_rcp_f32_e32 v2, v2
	s_nop 0
	v_mul_f32_e32 v2, v7, v2
	v_mul_f32_e32 v10, v6, v2
	v_cvt_f32_i32_e32 v2, v9
	v_pk_mul_f32 v[6:7], v[166:167], v[56:57] op_sel_hi:[0,1]
	v_pk_mul_f32 v[2:3], v[6:7], v[2:3]
	v_cvt_f32_i32_e32 v7, v13
	v_cvt_f32_i32_e32 v6, v5
	v_pk_mul_f32 v[4:5], v[166:167], v[52:53] op_sel_hi:[0,1]
	v_pk_mul_f32 v[4:5], v[4:5], v[6:7]
	v_mul_f32_e32 v6, 0xbfb8aa3b, v3
	v_exp_f32_e32 v6, v6
	s_nop 0
	v_add_f32_e32 v6, 1.0, v6
	v_rcp_f32_e32 v6, v6
	s_nop 0
	v_mul_f32_e32 v3, v3, v6
	v_mul_f32_e32 v3, v2, v3
	v_mul_f32_e32 v2, 0xbfb8aa3b, v5
	v_exp_f32_e32 v2, v2
	v_lshl_add_u64 v[6:7], v[18:19], 0, v[124:125]
	v_add_f32_e32 v2, 1.0, v2
	v_rcp_f32_e32 v2, v2
	s_nop 0
	v_mul_f32_e32 v2, v5, v2
	v_mul_f32_e32 v5, v4, v2
	v_cvt_pk_bf16_f32 v2, v20, v14
	v_cvt_pk_bf16_f32 v3, v8, v3
	v_cvt_pk_bf16_f32 v4, v21, v15
	v_cvt_pk_bf16_f32 v5, v10, v5
	global_store_dwordx4 v[6:7], v[2:5], off
	s_cbranch_vccnz .LBB0_1258
	s_andn2_b64 vcc, exec, s[6:7]
	s_cbranch_vccnz .LBB0_1257
	s_barrier
	s_branch .LBB0_1257
